# V10 + packed f32 v_pk_mul/v_pk_add in GEMM-phase epilogues and hooks split into scalar pairs (A/B of packed vs scalar)
# baseline (speedup 1.0000x reference)
; __device__ __forceinline__ unsigned cvt_pk_bf16(float lo, float hi) { f32x2 v = {lo, hi}; bf16x2_t b = __builtin_convertvector(v, bf16x2_t); return __builtin_bit_cast(unsigned, b); }
; __device__ __forceinline__ float silu_f(float x) { return x * fast_sigmoid(x); }
;     __device__ __forceinline__ void operator()(const f32x4 (&acc)[2][2][4][2], const Unit& u, int wr, int wc, int fr, int fq) const {
;     ...
;         for (int ai = 0; ai < 2; ++ai)
; #pragma unroll
;             for (int m = 0; m < 4; ++m) { const int row = row0 + ai * HALF + m * 16; const float rs = rsv[ai * 4 + m];
;                 float o[8];
; #pragma unroll
;                 for (int n = 0; n < 2; ++n)
; #pragma unroll
;                     for (int i = 0; i < 4; ++i) { const float g = acc[ai][0][m][n][i] * rs, up = acc[ai][1][m][n][i] * rs; o[4 * n + i] = silu_f(g) * up; }
;                 u32x4 w; w.x = cvt_pk_bf16(o[0], o[1]); w.y = cvt_pk_bf16(o[2], o[3]); w.z = cvt_pk_bf16(o[4], o[5]); w.w = cvt_pk_bf16(o[6], o[7]);
;                 *(u32x4*)(H + (size_t)row * ldh + col0) = w; }
.LBB0_379:
	v_mul_f32_e32 v150, 0xbfb8aa3b, v124
	v_mul_f32_e32 v151, 0xbfb8aa3b, v125
	v_exp_f32_e32 v150, v150
	v_exp_f32_e32 v151, v151
	v_lshl_or_b32 v154, s51, 7, v146
	v_ashrrev_i32_e32 v155, 31, v154
	v_add_f32_e32 v150, 1.0, v150
	v_add_f32_e32 v151, 1.0, v151
	v_rcp_f32_e32 v152, v150
	v_rcp_f32_e32 v153, v151
	v_mul_f32_e32 v151, 0xbfb8aa3b, v126
	v_exp_f32_e32 v151, v151
	v_lshl_add_u32 v150, s22, 8, v144
	v_mul_f32_e32 v124, v124, v152
	v_mul_f32_e32 v125, v125, v153
	v_mul_f32_e32 v152, 0xbfb8aa3b, v127
	v_exp_f32_e32 v152, v152
	v_mul_f32_e32 v116, v124, v116
	v_mul_f32_e32 v117, v125, v117
	v_add_f32_e32 v124, 1.0, v151
	v_mul_f32_e32 v151, 0xbfb8aa3b, v120
	v_add_f32_e32 v125, 1.0, v152
	v_rcp_f32_e32 v124, v124
	v_rcp_f32_e32 v125, v125
	v_exp_f32_e32 v151, v151
	v_mul_f32_e32 v152, 0xbfb8aa3b, v121
	v_exp_f32_e32 v152, v152
	v_mul_f32_e32 v124, v126, v124
	v_mul_f32_e32 v125, v127, v125
	v_add_f32_e32 v126, 1.0, v151
	v_mul_f32_e32 v151, 0xbfb8aa3b, v122
	v_add_f32_e32 v127, 1.0, v152
	v_exp_f32_e32 v151, v151
	v_mul_f32_e32 v152, 0xbfb8aa3b, v123
	v_exp_f32_e32 v153, v152
	v_rcp_f32_e32 v126, v126
	v_add_f32_e32 v151, 1.0, v151
	v_rcp_f32_e32 v127, v127
	v_rcp_f32_e32 v152, v151
	v_add_f32_e32 v151, 1.0, v153
	v_rcp_f32_e32 v153, v151
	v_mul_f32_e32 v120, v120, v126
	v_mul_f32_e32 v121, v121, v127
	v_mul_f32_e32 v118, v124, v118
	v_mul_f32_e32 v119, v125, v119
	v_mul_f32_e32 v112, v120, v112
	v_mul_f32_e32 v113, v121, v113
	v_mul_f32_e32 v120, v122, v152
	v_mul_f32_e32 v121, v123, v153
	v_cvt_pk_bf16_f32 v116, v116, v117
	v_mul_f32_e32 v114, v120, v114
	v_mul_f32_e32 v115, v121, v115
	v_cvt_pk_bf16_f32 v117, v118, v119
	v_cvt_pk_bf16_f32 v119, v114, v115
	v_mul_f32_e32 v114, 0xbfb8aa3b, v108
	v_exp_f32_e32 v114, v114
	v_mul_f32_e32 v115, 0xbfb8aa3b, v109
	v_exp_f32_e32 v115, v115
	v_cvt_pk_bf16_f32 v118, v112, v113
	v_add_f32_e32 v114, 1.0, v114
	v_mov_b64_e32 v[112:113], s[8:9]
	v_rcp_f32_e32 v122, v114
	v_add_f32_e32 v114, 1.0, v115
	v_mad_i64_i32 v[120:121], s[24:25], v150, s50, v[112:113]
	v_rcp_f32_e32 v123, v114
	v_lshlrev_b64 v[114:115], 1, v[154:155]
	v_lshl_add_u64 v[120:121], v[120:121], 0, v[114:115]
	global_store_dwordx4 v[120:121], v[116:119], off
	v_mul_f32_e32 v108, v108, v122
	v_mul_f32_e32 v109, v109, v123
	s_andn2_b64 vcc, exec, s[2:3]
	v_mul_f32_e32 v116, 0xbfb8aa3b, v110
	v_mul_f32_e32 v117, 0xbfb8aa3b, v111
	v_exp_f32_e32 v116, v116
	v_exp_f32_e32 v117, v117
	v_mul_f32_e32 v100, v108, v100
	v_mul_f32_e32 v101, v109, v101
	s_mov_b64 s[2:3], -1
	v_add_f32_e32 v108, 1.0, v116
	v_add_f32_e32 v109, 1.0, v117
	v_mul_f32_e32 v116, 0xbfb8aa3b, v104
	v_mul_f32_e32 v117, 0xbfb8aa3b, v105
	v_rcp_f32_e32 v108, v108
	v_rcp_f32_e32 v109, v109
	v_exp_f32_e32 v116, v116
	v_exp_f32_e32 v117, v117
	v_mul_f32_e32 v108, v110, v108
	v_mul_f32_e32 v109, v111, v109
	v_add_f32_e32 v110, 1.0, v116
	v_add_f32_e32 v111, 1.0, v117
	v_mul_f32_e32 v116, 0xbfb8aa3b, v106
	v_mul_f32_e32 v117, 0xbfb8aa3b, v107
	v_exp_f32_e32 v116, v116
	v_exp_f32_e32 v117, v117
	v_rcp_f32_e32 v110, v110
	v_rcp_f32_e32 v111, v111
	v_add_f32_e32 v116, 1.0, v116
	v_add_f32_e32 v117, 1.0, v117
	v_rcp_f32_e32 v116, v116
	v_rcp_f32_e32 v117, v117
	v_mul_f32_e32 v104, v104, v110
	v_mul_f32_e32 v105, v105, v111
	v_mul_f32_e32 v102, v108, v102
	v_mul_f32_e32 v103, v109, v103
	v_mul_f32_e32 v104, v104, v96
	v_mul_f32_e32 v105, v105, v97
	v_mul_f32_e32 v96, v106, v116
	v_mul_f32_e32 v97, v107, v117
	v_or_b32_e32 v108, 16, v150
	v_mul_f32_e32 v106, v96, v98
	v_mul_f32_e32 v107, v97, v99
	v_mul_f32_e32 v99, 0xbfb8aa3b, v92
	v_cvt_pk_bf16_f32 v96, v100, v101
	v_exp_f32_e32 v100, v99
	v_mul_f32_e32 v99, 0xbfb8aa3b, v93
	v_exp_f32_e32 v101, v99
	v_cvt_pk_bf16_f32 v97, v102, v103
	v_mad_i64_i32 v[102:103], s[24:25], v108, s50, v[112:113]
	v_cvt_pk_bf16_f32 v98, v104, v105
	v_cvt_pk_bf16_f32 v99, v106, v107
	v_add_f32_e32 v100, 1.0, v100
	v_add_f32_e32 v101, 1.0, v101
	v_lshl_add_u64 v[102:103], v[102:103], 0, v[114:115]
	v_rcp_f32_e32 v100, v100
	v_rcp_f32_e32 v101, v101
	global_store_dwordx4 v[102:103], v[96:99], off
	v_mul_f32_e32 v92, v92, v100
	v_mul_f32_e32 v93, v93, v101
	s_nop 0
	v_mul_f32_e32 v96, 0xbfb8aa3b, v94
	v_mul_f32_e32 v97, 0xbfb8aa3b, v95
	v_exp_f32_e32 v96, v96
	v_exp_f32_e32 v97, v97
	v_mul_f32_e32 v84, v92, v84
	v_mul_f32_e32 v85, v93, v85
	v_add_f32_e32 v92, 1.0, v96
	v_add_f32_e32 v93, 1.0, v97
	v_mul_f32_e32 v96, 0xbfb8aa3b, v88
	v_mul_f32_e32 v97, 0xbfb8aa3b, v89
	v_rcp_f32_e32 v92, v92
	v_rcp_f32_e32 v93, v93
	v_exp_f32_e32 v96, v96
	v_exp_f32_e32 v97, v97
	v_mul_f32_e32 v92, v94, v92
	v_mul_f32_e32 v93, v95, v93
	v_add_f32_e32 v94, 1.0, v96
	v_add_f32_e32 v95, 1.0, v97
	v_mul_f32_e32 v96, 0xbfb8aa3b, v90
	v_mul_f32_e32 v97, 0xbfb8aa3b, v91
	v_exp_f32_e32 v96, v96
	v_exp_f32_e32 v97, v97
	v_rcp_f32_e32 v94, v94
	v_rcp_f32_e32 v95, v95
	v_add_f32_e32 v96, 1.0, v96
	v_add_f32_e32 v97, 1.0, v97
	v_rcp_f32_e32 v96, v96
	v_rcp_f32_e32 v97, v97
	v_mul_f32_e32 v88, v88, v94
	v_mul_f32_e32 v89, v89, v95
	v_mul_f32_e32 v86, v92, v86
	v_mul_f32_e32 v87, v93, v87
	v_mul_f32_e32 v88, v88, v80
	v_mul_f32_e32 v89, v89, v81
	v_mul_f32_e32 v80, v90, v96
	v_mul_f32_e32 v81, v91, v97
	v_or_b32_e32 v92, 32, v150
	v_mul_f32_e32 v90, v80, v82
	v_mul_f32_e32 v91, v81, v83
	v_mul_f32_e32 v83, 0xbfb8aa3b, v76
	v_cvt_pk_bf16_f32 v80, v84, v85
	v_exp_f32_e32 v84, v83
	v_mul_f32_e32 v83, 0xbfb8aa3b, v77
	v_exp_f32_e32 v85, v83
	v_cvt_pk_bf16_f32 v81, v86, v87
	v_mad_i64_i32 v[86:87], s[24:25], v92, s50, v[112:113]
	v_cvt_pk_bf16_f32 v82, v88, v89
	v_cvt_pk_bf16_f32 v83, v90, v91
	v_add_f32_e32 v84, 1.0, v84
	v_add_f32_e32 v85, 1.0, v85
	v_lshl_add_u64 v[86:87], v[86:87], 0, v[114:115]
; __device__ __forceinline__ unsigned cvt_pk_bf16(float lo, float hi) { f32x2 v = {lo, hi}; bf16x2_t b = __builtin_convertvector(v, bf16x2_t); return __builtin_bit_cast(unsigned, b); }
; __device__ __forceinline__ float silu_f(float x) { return x * fast_sigmoid(x); }
;     __device__ __forceinline__ void operator()(const f32x4 (&acc)[2][2][4][2], const Unit& u, int wr, int wc, int fr, int fq) const {
;     ...
;         for (int ai = 0; ai < 2; ++ai)
; #pragma unroll
;             for (int m = 0; m < 4; ++m) { const int row = row0 + ai * HALF + m * 16; const float rs = rsv[ai * 4 + m];
;                 float o[8];
; #pragma unroll
;                 for (int n = 0; n < 2; ++n)
; #pragma unroll
;                     for (int i = 0; i < 4; ++i) { const float g = acc[ai][0][m][n][i] * rs, up = acc[ai][1][m][n][i] * rs; o[4 * n + i] = silu_f(g) * up; }
;                 u32x4 w; w.x = cvt_pk_bf16(o[0], o[1]); w.y = cvt_pk_bf16(o[2], o[3]); w.z = cvt_pk_bf16(o[4], o[5]); w.w = cvt_pk_bf16(o[6], o[7]);
;                 *(u32x4*)(H + (size_t)row * ldh + col0) = w; }
	v_rcp_f32_e32 v84, v84
	v_rcp_f32_e32 v85, v85
	global_store_dwordx4 v[86:87], v[80:83], off
	v_mul_f32_e32 v76, v76, v84
	v_mul_f32_e32 v77, v77, v85
	s_nop 0
	v_mul_f32_e32 v80, 0xbfb8aa3b, v78
	v_mul_f32_e32 v81, 0xbfb8aa3b, v79
	v_exp_f32_e32 v80, v80
	v_exp_f32_e32 v81, v81
	v_mul_f32_e32 v68, v76, v68
	v_mul_f32_e32 v69, v77, v69
	v_add_f32_e32 v76, 1.0, v80
	v_add_f32_e32 v77, 1.0, v81
	v_mul_f32_e32 v80, 0xbfb8aa3b, v72
	v_mul_f32_e32 v81, 0xbfb8aa3b, v73
	v_rcp_f32_e32 v76, v76
	v_rcp_f32_e32 v77, v77
	v_exp_f32_e32 v80, v80
	v_exp_f32_e32 v81, v81
	v_mul_f32_e32 v76, v78, v76
	v_mul_f32_e32 v77, v79, v77
	v_add_f32_e32 v78, 1.0, v80
	v_add_f32_e32 v79, 1.0, v81
	v_mul_f32_e32 v80, 0xbfb8aa3b, v74
	v_mul_f32_e32 v81, 0xbfb8aa3b, v75
	v_exp_f32_e32 v80, v80
	v_exp_f32_e32 v81, v81
	v_rcp_f32_e32 v78, v78
	v_rcp_f32_e32 v79, v79
	v_add_f32_e32 v80, 1.0, v80
	v_add_f32_e32 v81, 1.0, v81
	v_rcp_f32_e32 v80, v80
	v_rcp_f32_e32 v81, v81
	v_mul_f32_e32 v72, v72, v78
	v_mul_f32_e32 v73, v73, v79
	v_mul_f32_e32 v70, v76, v70
	v_mul_f32_e32 v71, v77, v71
	v_mul_f32_e32 v72, v72, v64
	v_mul_f32_e32 v73, v73, v65
	v_mul_f32_e32 v64, v74, v80
	v_mul_f32_e32 v65, v75, v81
	v_or_b32_e32 v76, 48, v150
	v_mul_f32_e32 v74, v64, v66
	v_mul_f32_e32 v75, v65, v67
	v_cvt_pk_bf16_f32 v64, v68, v69
	v_mul_f32_e32 v68, 0xbfb8aa3b, v60
	v_cvt_pk_bf16_f32 v65, v70, v71
	v_exp_f32_e32 v70, v68
	v_mul_f32_e32 v68, 0xbfb8aa3b, v61
	v_exp_f32_e32 v71, v68
	v_mad_i64_i32 v[68:69], s[24:25], v76, s50, v[112:113]
	v_cvt_pk_bf16_f32 v66, v72, v73
	v_cvt_pk_bf16_f32 v67, v74, v75
	v_add_f32_e32 v70, 1.0, v70
	v_add_f32_e32 v71, 1.0, v71
	v_lshl_add_u64 v[68:69], v[68:69], 0, v[114:115]
	v_rcp_f32_e32 v70, v70
	v_rcp_f32_e32 v71, v71
	global_store_dwordx4 v[68:69], v[64:67], off
	v_mul_f32_e32 v60, v60, v70
	v_mul_f32_e32 v61, v61, v71
	s_nop 0
	v_mul_f32_e32 v64, 0xbfb8aa3b, v62
	v_mul_f32_e32 v65, 0xbfb8aa3b, v63
	v_exp_f32_e32 v64, v64
	v_exp_f32_e32 v65, v65
	v_mul_f32_e32 v52, v60, v52
	v_mul_f32_e32 v53, v61, v53
	v_add_u32_e32 v66, 0x80, v150
	v_add_f32_e32 v60, 1.0, v64
	v_add_f32_e32 v61, 1.0, v65
	v_mul_f32_e32 v64, 0xbfb8aa3b, v56
	v_mul_f32_e32 v65, 0xbfb8aa3b, v57
	v_rcp_f32_e32 v60, v60
	v_rcp_f32_e32 v61, v61
	v_exp_f32_e32 v64, v64
	v_exp_f32_e32 v65, v65
	v_mul_f32_e32 v60, v62, v60
	v_mul_f32_e32 v61, v63, v61
	v_add_f32_e32 v62, 1.0, v64
	v_add_f32_e32 v63, 1.0, v65
	v_mul_f32_e32 v64, 0xbfb8aa3b, v58
	v_mul_f32_e32 v65, 0xbfb8aa3b, v59
	v_exp_f32_e32 v64, v64
	v_exp_f32_e32 v65, v65
	v_rcp_f32_e32 v62, v62
	v_rcp_f32_e32 v63, v63
	v_add_f32_e32 v64, 1.0, v64
	v_add_f32_e32 v65, 1.0, v65
	v_rcp_f32_e32 v64, v64
	v_rcp_f32_e32 v65, v65
	v_mul_f32_e32 v56, v56, v62
	v_mul_f32_e32 v57, v57, v63
	v_mul_f32_e32 v54, v60, v54
	v_mul_f32_e32 v55, v61, v55
	v_mul_f32_e32 v56, v56, v48
	v_mul_f32_e32 v57, v57, v49
	v_mul_f32_e32 v48, v58, v64
	v_mul_f32_e32 v49, v59, v65
	s_nop 0
	v_mul_f32_e32 v58, v48, v50
	v_mul_f32_e32 v59, v49, v51
	v_mul_f32_e32 v51, 0xbfb8aa3b, v44
	v_cvt_pk_bf16_f32 v48, v52, v53
	v_exp_f32_e32 v52, v51
	v_mul_f32_e32 v51, 0xbfb8aa3b, v45
	v_exp_f32_e32 v53, v51
	v_cvt_pk_bf16_f32 v49, v54, v55
	v_mad_i64_i32 v[54:55], s[24:25], v66, s50, v[112:113]
	v_cvt_pk_bf16_f32 v50, v56, v57
	v_cvt_pk_bf16_f32 v51, v58, v59
	v_add_f32_e32 v52, 1.0, v52
	v_add_f32_e32 v53, 1.0, v53
	v_lshl_add_u64 v[54:55], v[54:55], 0, v[114:115]
	v_rcp_f32_e32 v52, v52
	v_rcp_f32_e32 v53, v53
	global_store_dwordx4 v[54:55], v[48:51], off
	v_mul_f32_e32 v44, v44, v52
	v_mul_f32_e32 v45, v45, v53
	s_nop 0
	v_mul_f32_e32 v48, 0xbfb8aa3b, v46
	v_mul_f32_e32 v49, 0xbfb8aa3b, v47
	v_exp_f32_e32 v48, v48
	v_exp_f32_e32 v49, v49
	v_mul_f32_e32 v36, v44, v36
	v_mul_f32_e32 v37, v45, v37
	v_add_f32_e32 v44, 1.0, v48
	v_add_f32_e32 v45, 1.0, v49
	v_mul_f32_e32 v48, 0xbfb8aa3b, v40
	v_mul_f32_e32 v49, 0xbfb8aa3b, v41
	v_rcp_f32_e32 v44, v44
	v_rcp_f32_e32 v45, v45
	v_exp_f32_e32 v48, v48
	v_exp_f32_e32 v49, v49
	v_mul_f32_e32 v44, v46, v44
	v_mul_f32_e32 v45, v47, v45
	v_add_f32_e32 v46, 1.0, v48
	v_add_f32_e32 v47, 1.0, v49
	v_mul_f32_e32 v48, 0xbfb8aa3b, v42
	v_mul_f32_e32 v49, 0xbfb8aa3b, v43
	v_exp_f32_e32 v48, v48
	v_exp_f32_e32 v49, v49
; __device__ __forceinline__ unsigned cvt_pk_bf16(float lo, float hi) { f32x2 v = {lo, hi}; bf16x2_t b = __builtin_convertvector(v, bf16x2_t); return __builtin_bit_cast(unsigned, b); }
; __device__ __forceinline__ float silu_f(float x) { return x * fast_sigmoid(x); }
;     __device__ __forceinline__ void operator()(const f32x4 (&acc)[2][2][4][2], const Unit& u, int wr, int wc, int fr, int fq) const {
;     ...
;         for (int ai = 0; ai < 2; ++ai)
; #pragma unroll
;             for (int m = 0; m < 4; ++m) { const int row = row0 + ai * HALF + m * 16; const float rs = rsv[ai * 4 + m];
;                 float o[8];
; #pragma unroll
;                 for (int n = 0; n < 2; ++n)
; #pragma unroll
;                     for (int i = 0; i < 4; ++i) { const float g = acc[ai][0][m][n][i] * rs, up = acc[ai][1][m][n][i] * rs; o[4 * n + i] = silu_f(g) * up; }
;                 u32x4 w; w.x = cvt_pk_bf16(o[0], o[1]); w.y = cvt_pk_bf16(o[2], o[3]); w.z = cvt_pk_bf16(o[4], o[5]); w.w = cvt_pk_bf16(o[6], o[7]);
;                 *(u32x4*)(H + (size_t)row * ldh + col0) = w; }
	v_rcp_f32_e32 v46, v46
	v_rcp_f32_e32 v47, v47
	v_add_f32_e32 v48, 1.0, v48
	v_add_f32_e32 v49, 1.0, v49
	v_rcp_f32_e32 v48, v48
	v_rcp_f32_e32 v49, v49
	v_mul_f32_e32 v40, v40, v46
	v_mul_f32_e32 v41, v41, v47
	v_mul_f32_e32 v38, v44, v38
	v_mul_f32_e32 v39, v45, v39
	v_mul_f32_e32 v40, v40, v32
	v_mul_f32_e32 v41, v41, v33
	v_mul_f32_e32 v32, v42, v48
	v_mul_f32_e32 v33, v43, v49
	v_add_u32_e32 v44, 0x90, v150
	v_mul_f32_e32 v42, v32, v34
	v_mul_f32_e32 v43, v33, v35
	v_mul_f32_e32 v35, 0xbfb8aa3b, v28
	v_cvt_pk_bf16_f32 v32, v36, v37
	v_exp_f32_e32 v36, v35
	v_mul_f32_e32 v35, 0xbfb8aa3b, v29
	v_exp_f32_e32 v37, v35
	v_cvt_pk_bf16_f32 v33, v38, v39
	v_mad_i64_i32 v[38:39], s[24:25], v44, s50, v[112:113]
	v_cvt_pk_bf16_f32 v34, v40, v41
	v_cvt_pk_bf16_f32 v35, v42, v43
	v_add_f32_e32 v36, 1.0, v36
	v_add_f32_e32 v37, 1.0, v37
	v_lshl_add_u64 v[38:39], v[38:39], 0, v[114:115]
	v_rcp_f32_e32 v36, v36
	v_rcp_f32_e32 v37, v37
	global_store_dwordx4 v[38:39], v[32:35], off
	v_mul_f32_e32 v28, v28, v36
	v_mul_f32_e32 v29, v29, v37
	s_nop 0
	v_mul_f32_e32 v32, 0xbfb8aa3b, v30
	v_mul_f32_e32 v33, 0xbfb8aa3b, v31
	v_exp_f32_e32 v32, v32
	v_exp_f32_e32 v33, v33
	v_mul_f32_e32 v20, v28, v20
	v_mul_f32_e32 v21, v29, v21
	v_add_f32_e32 v28, 1.0, v32
	v_add_f32_e32 v29, 1.0, v33
	v_mul_f32_e32 v32, 0xbfb8aa3b, v24
	v_mul_f32_e32 v33, 0xbfb8aa3b, v25
	v_rcp_f32_e32 v28, v28
	v_rcp_f32_e32 v29, v29
	v_exp_f32_e32 v32, v32
	v_exp_f32_e32 v33, v33
	v_mul_f32_e32 v28, v30, v28
	v_mul_f32_e32 v29, v31, v29
	v_add_f32_e32 v30, 1.0, v32
	v_add_f32_e32 v31, 1.0, v33
	v_mul_f32_e32 v32, 0xbfb8aa3b, v26
	v_mul_f32_e32 v33, 0xbfb8aa3b, v27
	v_exp_f32_e32 v32, v32
	v_exp_f32_e32 v33, v33
	v_rcp_f32_e32 v30, v30
	v_rcp_f32_e32 v31, v31
	v_add_f32_e32 v32, 1.0, v32
	v_add_f32_e32 v33, 1.0, v33
	v_rcp_f32_e32 v32, v32
	v_rcp_f32_e32 v33, v33
	v_mul_f32_e32 v24, v24, v30
	v_mul_f32_e32 v25, v25, v31
	v_mul_f32_e32 v22, v28, v22
	v_mul_f32_e32 v23, v29, v23
	v_mul_f32_e32 v24, v24, v16
	v_mul_f32_e32 v25, v25, v17
	v_mul_f32_e32 v16, v26, v32
	v_mul_f32_e32 v17, v27, v33
	v_add_u32_e32 v28, 0xa0, v150
	v_mul_f32_e32 v26, v16, v18
	v_mul_f32_e32 v27, v17, v19
	v_mul_f32_e32 v19, 0xbfb8aa3b, v12
	v_cvt_pk_bf16_f32 v16, v20, v21
	v_exp_f32_e32 v20, v19
	v_mul_f32_e32 v19, 0xbfb8aa3b, v13
	v_exp_f32_e32 v21, v19
	v_cvt_pk_bf16_f32 v17, v22, v23
	v_mad_i64_i32 v[22:23], s[24:25], v28, s50, v[112:113]
	v_cvt_pk_bf16_f32 v18, v24, v25
	v_cvt_pk_bf16_f32 v19, v26, v27
	v_add_f32_e32 v20, 1.0, v20
	v_add_f32_e32 v21, 1.0, v21
	v_lshl_add_u64 v[22:23], v[22:23], 0, v[114:115]
	v_rcp_f32_e32 v20, v20
	v_rcp_f32_e32 v21, v21
	global_store_dwordx4 v[22:23], v[16:19], off
	v_mul_f32_e32 v12, v12, v20
	v_mul_f32_e32 v13, v13, v21
	s_nop 0
	v_mul_f32_e32 v16, 0xbfb8aa3b, v14
	v_mul_f32_e32 v17, 0xbfb8aa3b, v15
	v_exp_f32_e32 v16, v16
	v_exp_f32_e32 v17, v17
	v_mul_f32_e32 v4, v12, v4
	v_mul_f32_e32 v5, v13, v5
	v_add_f32_e32 v12, 1.0, v16
	v_add_f32_e32 v13, 1.0, v17
	v_mul_f32_e32 v16, 0xbfb8aa3b, v8
	v_mul_f32_e32 v17, 0xbfb8aa3b, v9
	v_rcp_f32_e32 v12, v12
	v_rcp_f32_e32 v13, v13
	v_exp_f32_e32 v16, v16
	v_exp_f32_e32 v17, v17
	v_mul_f32_e32 v12, v14, v12
	v_mul_f32_e32 v13, v15, v13
	v_add_f32_e32 v14, 1.0, v16
	v_add_f32_e32 v15, 1.0, v17
	v_mul_f32_e32 v16, 0xbfb8aa3b, v10
	v_mul_f32_e32 v17, 0xbfb8aa3b, v11
	v_exp_f32_e32 v16, v16
	v_exp_f32_e32 v17, v17
	v_rcp_f32_e32 v14, v14
	v_rcp_f32_e32 v15, v15
	v_add_f32_e32 v16, 1.0, v16
	v_add_f32_e32 v17, 1.0, v17
	v_rcp_f32_e32 v16, v16
	v_rcp_f32_e32 v17, v17
	v_mul_f32_e32 v8, v8, v14
	v_mul_f32_e32 v9, v9, v15
	v_mul_f32_e32 v6, v12, v6
	v_mul_f32_e32 v7, v13, v7
	v_mul_f32_e32 v8, v8, v0
	v_mul_f32_e32 v9, v9, v1
	v_mul_f32_e32 v0, v10, v16
	v_mul_f32_e32 v1, v11, v17
	v_add_u32_e32 v12, 0xb0, v150
	v_mul_f32_e32 v10, v0, v2
	v_mul_f32_e32 v11, v1, v3
	v_cvt_pk_bf16_f32 v0, v4, v5
	v_mad_i64_i32 v[4:5], s[24:25], v12, s50, v[112:113]
	v_cvt_pk_bf16_f32 v1, v6, v7
	v_cvt_pk_bf16_f32 v2, v8, v9
	v_cvt_pk_bf16_f32 v3, v10, v11
	v_lshl_add_u64 v[4:5], v[4:5], 0, v[114:115]
	global_store_dwordx4 v[4:5], v[0:3], off
	s_cbranch_vccnz .LBB0_372
	s_andn2_b64 vcc, exec, s[6:7]
	s_cbranch_vccnz .LBB0_371
	s_barrier
	s_branch .LBB0_371

.Lfrs_wait_p3:
	s_mov_b64 s[100:101], exec
	s_waitcnt vmcnt(0)
	s_mov_b64 exec, s[14:15]
	v_mov_b32_e32 v6, v26
	v_mov_b32_e32 v7, v30
	v_mov_b32_e32 v30, v27
	v_mov_b32_e32 v26, v28
	v_mov_b32_e32 v27, v32
	v_mov_b32_e32 v32, v29
	v_mov_b32_e32 v28, v34
	v_mov_b32_e32 v29, v38
	v_mov_b32_e32 v38, v35
	v_mov_b32_e32 v34, v36
	v_mov_b32_e32 v35, v40
	v_mov_b32_e32 v40, v37
	v_add_f32_e32 v6, v6, v30
	v_add_f32_e32 v7, v7, v31
	v_add_f32_e32 v26, v26, v32
	v_add_f32_e32 v27, v27, v33
	v_add_f32_e32 v28, v28, v38
	v_add_f32_e32 v29, v29, v39
	v_add_f32_e32 v30, v34, v40
	v_add_f32_e32 v31, v35, v41
	v_add_f32_e32 v6, v6, v26
	v_add_f32_e32 v7, v7, v27
	v_add_f32_e32 v26, v28, v30
	v_add_f32_e32 v27, v29, v31
	s_nop 0
	v_add_f32_e32 v6, v6, v26
	v_add_f32_e32 v7, v7, v27
	s_nop 0
	v_add_f32_e32 v6, v6, v7
	v_fmamk_f32 v6, v6, 0x3a800000, v5
	v_rsq_f32_e32 v6, v6
	ds_write_b32 v122, v6
	v_add_u32_e32 v122, 0x800, v122
	s_mov_b64 exec, s[16:17]
	v_mov_b32_e32 v6, v42
	v_mov_b32_e32 v7, v46
	v_mov_b32_e32 v46, v43
	v_mov_b32_e32 v42, v44
	v_mov_b32_e32 v43, v48
	v_mov_b32_e32 v48, v45
	v_mov_b32_e32 v44, v50
	v_mov_b32_e32 v45, v54
	v_mov_b32_e32 v54, v51
	v_mov_b32_e32 v50, v52
	v_mov_b32_e32 v51, v56
	v_mov_b32_e32 v56, v53
	v_add_f32_e32 v6, v6, v46
	v_add_f32_e32 v7, v7, v47
	v_add_f32_e32 v42, v42, v48
	v_add_f32_e32 v43, v43, v49
	v_add_f32_e32 v44, v44, v54
	v_add_f32_e32 v45, v45, v55
	v_add_f32_e32 v46, v50, v56
	v_add_f32_e32 v47, v51, v57
	v_add_f32_e32 v6, v6, v42
	v_add_f32_e32 v7, v7, v43
	v_add_f32_e32 v42, v44, v46
	v_add_f32_e32 v43, v45, v47
	s_nop 0
	v_add_f32_e32 v6, v6, v42
	v_add_f32_e32 v7, v7, v43
	s_nop 0
	v_add_f32_e32 v6, v6, v7
	v_fmamk_f32 v6, v6, 0x3a800000, v5
	v_rsq_f32_e32 v6, v6
	ds_write_b32 v122, v6
	v_add_u32_e32 v122, 0x800, v122
	s_mov_b64 exec, s[22:23]
	v_mov_b32_e32 v6, v58
	v_mov_b32_e32 v7, v62
	v_mov_b32_e32 v62, v59
	v_mov_b32_e32 v58, v60
	v_mov_b32_e32 v59, v64
	v_mov_b32_e32 v64, v61
	v_mov_b32_e32 v60, v66
	v_mov_b32_e32 v61, v70
	v_mov_b32_e32 v70, v67
	v_mov_b32_e32 v66, v68
	v_mov_b32_e32 v67, v72
	v_mov_b32_e32 v72, v69
	v_add_f32_e32 v6, v6, v62
	v_add_f32_e32 v7, v7, v63
	v_add_f32_e32 v58, v58, v64
	v_add_f32_e32 v59, v59, v65
	v_add_f32_e32 v60, v60, v70
	v_add_f32_e32 v61, v61, v71
	v_add_f32_e32 v62, v66, v72
	v_add_f32_e32 v63, v67, v73
	v_add_f32_e32 v6, v6, v58
	v_add_f32_e32 v7, v7, v59
	v_add_f32_e32 v58, v60, v62
	v_add_f32_e32 v59, v61, v63
	s_nop 0
	v_add_f32_e32 v6, v6, v58
	v_add_f32_e32 v7, v7, v59
	s_nop 0
	v_add_f32_e32 v6, v6, v7
	v_fmamk_f32 v6, v6, 0x3a800000, v5
	v_rsq_f32_e32 v6, v6
	ds_write_b32 v122, v6
	v_add_u32_e32 v122, 0x800, v122
	s_mov_b64 exec, s[24:25]
	v_mov_b32_e32 v6, v74
	v_mov_b32_e32 v7, v78
	v_mov_b32_e32 v78, v75
	v_mov_b32_e32 v74, v76
	v_mov_b32_e32 v75, v80
	v_mov_b32_e32 v80, v77
	v_mov_b32_e32 v76, v82
	v_mov_b32_e32 v77, v86
	v_mov_b32_e32 v86, v83
	v_mov_b32_e32 v82, v84
	v_mov_b32_e32 v83, v88
	v_mov_b32_e32 v88, v85
	v_add_f32_e32 v6, v6, v78
	v_add_f32_e32 v7, v7, v79
	v_add_f32_e32 v74, v74, v80
	v_add_f32_e32 v75, v75, v81
	v_add_f32_e32 v76, v76, v86
	v_add_f32_e32 v77, v77, v87
	v_add_f32_e32 v78, v82, v88
	v_add_f32_e32 v79, v83, v89
	v_add_f32_e32 v6, v6, v74
	v_add_f32_e32 v7, v7, v75
	v_add_f32_e32 v74, v76, v78
	v_add_f32_e32 v75, v77, v79
	s_nop 0
	v_add_f32_e32 v6, v6, v74
	v_add_f32_e32 v7, v7, v75
	s_nop 0
	v_add_f32_e32 v6, v6, v7
	v_fmamk_f32 v6, v6, 0x3a800000, v5
	v_rsq_f32_e32 v6, v6
	ds_write_b32 v122, v6
	v_add_u32_e32 v122, 0x800, v122
	s_mov_b64 exec, s[26:27]
	v_mov_b32_e32 v6, v90
	v_mov_b32_e32 v7, v94
	v_mov_b32_e32 v94, v91
	v_mov_b32_e32 v90, v92
	v_mov_b32_e32 v91, v96
	v_mov_b32_e32 v96, v93
	v_mov_b32_e32 v92, v98
	v_mov_b32_e32 v93, v102
	v_mov_b32_e32 v102, v99
	v_mov_b32_e32 v98, v100
	v_mov_b32_e32 v99, v104
	v_mov_b32_e32 v104, v101
	v_add_f32_e32 v6, v6, v94
	v_add_f32_e32 v7, v7, v95
	v_add_f32_e32 v90, v90, v96
	v_add_f32_e32 v91, v91, v97
	v_add_f32_e32 v92, v92, v102
	v_add_f32_e32 v93, v93, v103
	v_add_f32_e32 v94, v98, v104
	v_add_f32_e32 v95, v99, v105
	v_add_f32_e32 v6, v6, v90
	v_add_f32_e32 v7, v7, v91
	v_add_f32_e32 v90, v92, v94
	v_add_f32_e32 v91, v93, v95
	s_nop 0
	v_add_f32_e32 v6, v6, v90
	v_add_f32_e32 v7, v7, v91
	s_nop 0
	v_add_f32_e32 v6, v6, v7
	v_fmamk_f32 v6, v6, 0x3a800000, v5
	v_rsq_f32_e32 v6, v6
	ds_write_b32 v122, v6
	v_add_u32_e32 v122, 0x800, v122
	s_mov_b64 exec, s[98:99]
	v_mov_b32_e32 v6, v106
	v_mov_b32_e32 v7, v110
	v_mov_b32_e32 v110, v107
	v_mov_b32_e32 v106, v108
	v_mov_b32_e32 v107, v112
	v_mov_b32_e32 v112, v109
	v_mov_b32_e32 v108, v114
	v_mov_b32_e32 v109, v118
	v_mov_b32_e32 v118, v115
	v_mov_b32_e32 v114, v116
	v_mov_b32_e32 v115, v120
	v_mov_b32_e32 v120, v117
	v_add_f32_e32 v6, v6, v110
	v_add_f32_e32 v7, v7, v111
	v_add_f32_e32 v106, v106, v112
	v_add_f32_e32 v107, v107, v113
	v_add_f32_e32 v108, v108, v118
	v_add_f32_e32 v109, v109, v119
	v_add_f32_e32 v110, v114, v120
	v_add_f32_e32 v111, v115, v121
	v_add_f32_e32 v6, v6, v106
	v_add_f32_e32 v7, v7, v107
	v_add_f32_e32 v106, v108, v110
	v_add_f32_e32 v107, v109, v111
	s_nop 0
	v_add_f32_e32 v6, v6, v106
	v_add_f32_e32 v7, v7, v107
	s_nop 0
	v_add_f32_e32 v6, v6, v7
	v_fmamk_f32 v6, v6, 0x3a800000, v5
	v_rsq_f32_e32 v6, v6
	ds_write_b32 v122, v6
	v_add_u32_e32 v122, 0x800, v122
	s_mov_b64 exec, s[100:101]
	v_add_u32_e32 v2, 0x3000, v2
	s_cbranch_execz .LBB0_553
.LBB0_552:
	v_ashrrev_i32_e32 v6, 8, v0
	v_mul_lo_u32 v6, v6, s66
	v_add_u32_e32 v7, s33, v6
	v_ashrrev_i32_e32 v6, 31, v7
	v_lshrrev_b32_e32 v6, 29, v6
	v_add_u32_e32 v9, v7, v6
	v_ashrrev_i32_e32 v6, 3, v9
	v_and_b32_e32 v9, -8, v9
	v_sub_u32_e32 v7, v7, v9
	v_cmp_gt_i32_e32 vcc, 0, v7
	v_add_u32_e32 v0, 0x200, v0
	s_nop 0
	v_cndmask_b32_e32 v9, v3, v4, vcc
	v_mad_u64_u32 v[6:7], s[12:13], v7, v9, v[6:7]
	v_mul_hi_i32 v7, v6, s1
	v_lshrrev_b32_e32 v9, 31, v7
	v_ashrrev_i32_e32 v7, 6, v7
	v_add_u32_e32 v7, v7, v9
	v_lshlrev_b32_e32 v9, 3, v7
	v_mul_lo_u32 v7, v7, s10
	v_sub_u32_e32 v10, 0x80, v9
	v_sub_u32_e32 v6, v6, v7
	v_min_i32_e32 v7, 8, v10
	v_sub_u32_e32 v11, 0, v6
	v_ashrrev_i32_e32 v10, 31, v6
	v_max_i32_e32 v6, v6, v11
	v_sub_u32_e32 v11, 0, v7
	v_max_i32_e32 v7, v7, v11
	v_cvt_f32_u32_e32 v11, v7
	v_sub_u32_e32 v12, 0, v7
	v_rcp_iflag_f32_e32 v11, v11
	s_nop 0
	v_mul_f32_e32 v11, 0x4f7ffffe, v11
	v_cvt_u32_f32_e32 v11, v11
	v_mul_lo_u32 v12, v12, v11
	v_mul_hi_u32 v12, v11, v12
	v_add_u32_e32 v11, v11, v12
	v_mul_hi_u32 v11, v6, v11
	v_mul_lo_u32 v11, v11, v7
	v_sub_u32_e32 v6, v6, v11
	v_sub_u32_e32 v11, v6, v7
	v_cmp_ge_u32_e32 vcc, v6, v7
	s_nop 1
	v_cndmask_b32_e32 v6, v6, v11, vcc
	v_sub_u32_e32 v11, v6, v7
	v_cmp_ge_u32_e32 vcc, v6, v7
	s_nop 1
	v_cndmask_b32_e32 v6, v6, v11, vcc
	v_xor_b32_e32 v6, v6, v10
	v_sub_u32_e32 v6, v6, v10
	v_add_u32_e32 v6, v9, v6
	v_lshl_or_b32 v6, v6, 8, v1
	v_ashrrev_i32_e32 v7, 31, v6
	v_lshlrev_b64 v[6:7], 6, v[6:7]
	v_lshl_add_u64 v[6:7], s[4:5], 0, v[6:7]
	global_load_dwordx4 v[10:13], v[6:7], off
	global_load_dwordx4 v[14:17], v[6:7], off offset:32
	global_load_dwordx4 v[18:21], v[6:7], off offset:16
	global_load_dwordx4 v[22:25], v[6:7], off offset:48
	v_cmp_le_i32_e32 vcc, s0, v0
	s_or_b64 s[6:7], vcc, s[6:7]
	s_waitcnt vmcnt(0)
	v_mov_b32_e32 v6, v10
	v_mov_b32_e32 v7, v14
	v_mov_b32_e32 v14, v11
	v_mov_b32_e32 v10, v12
	v_mov_b32_e32 v11, v16
	v_mov_b32_e32 v16, v13
	v_mov_b32_e32 v12, v18
	v_mov_b32_e32 v13, v22
	v_mov_b32_e32 v22, v19
	v_mov_b32_e32 v18, v20
	v_mov_b32_e32 v19, v24
	v_mov_b32_e32 v24, v21
	v_add_f32_e32 v6, v6, v14
	v_add_f32_e32 v7, v7, v15
	v_add_f32_e32 v10, v10, v16
	v_add_f32_e32 v11, v11, v17
	v_add_f32_e32 v12, v12, v22
	v_add_f32_e32 v13, v13, v23
	v_add_f32_e32 v14, v18, v24
	v_add_f32_e32 v15, v19, v25
	v_add_f32_e32 v6, v6, v10
	v_add_f32_e32 v7, v7, v11
	v_add_f32_e32 v10, v12, v14
	v_add_f32_e32 v11, v13, v15
	s_nop 0
	v_add_f32_e32 v6, v6, v10
	v_add_f32_e32 v7, v7, v11
	s_nop 0
	v_add_f32_e32 v6, v6, v7
	v_fmamk_f32 v6, v6, 0x3a800000, v5
	v_rsq_f32_e32 v6, v6
	ds_write_b32 v2, v6
	v_add_u32_e32 v2, 0x800, v2
	s_andn2_b64 exec, exec, s[6:7]
	s_cbranch_execnz .LBB0_552

; __device__ __forceinline__ unsigned cvt_pk_bf16(float lo, float hi) { f32x2 v = {lo, hi}; bf16x2_t b = __builtin_convertvector(v, bf16x2_t); return __builtin_bit_cast(unsigned, b); }
; __device__ __forceinline__ float xor16_sum(float x) { auto r = __builtin_amdgcn_permlane16_swap(__float_as_uint(x), __float_as_uint(x), false, false); return __uint_as_float(r[0]) + __uint_as_float(r[1]); }
; __device__ __forceinline__ float xor32_sum(float x) { auto r = __builtin_amdgcn_permlane32_swap(__float_as_uint(x), __float_as_uint(x), false, false); return __uint_as_float(r[0]) + __uint_as_float(r[1]); }
;     __device__ __forceinline__ void operator()(const f32x4 (&acc)[2][2][4][2], const Unit& u, int wr, int wc, int fr, int fq) const {
;     ...
;         for (int ai = 0; ai < 2; ++ai)
; #pragma unroll
;             for (int m = 0; m < 4; ++m) { const int row = row0 + ai * HALF + m * 16; const float rs = rsv[ai * 4 + m];
;                 float hs = rs;
;                 if (kind == 1) { float ss = 0.f;
; #pragma unroll
;                     for (int bj = 0; bj < 2; ++bj)
; #pragma unroll
;                         for (int n = 0; n < 2; ++n) { const f32x4 v = acc[ai][bj][m][n] * rs; ss += (v[0] * v[0] + v[1] * v[1]) + (v[2] * v[2] + v[3] * v[3]); }
;                     ss = xor16_sum(ss); ss = xor32_sum(ss); hs = rs * __builtin_amdgcn_rsqf(ss * (1.0f / 64.0f) + RMS_EPS) * mul; }
; #pragma unroll
;                 for (int bj = 0; bj < 2; ++bj) { float o[8];
; #pragma unroll
;                     for (int n = 0; n < 2; ++n) { const f32x4 gvn = gv[bj][n];
; #pragma unroll
;                         for (int i = 0; i < 4; ++i) o[4 * n + i] = acc[ai][bj][m][n][i] * hs * gvn[i]; }
;                     u32x4 w; w.x = cvt_pk_bf16(o[0], o[1]); w.y = cvt_pk_bf16(o[2], o[3]); w.z = cvt_pk_bf16(o[4], o[5]); w.w = cvt_pk_bf16(o[6], o[7]);
;                     *(u32x4*)(dst + (size_t)row * pitch + 32 * bj + 8 * fq) = w; } }
.LBB0_601:
	v_lshl_add_u32 v167, s67, 10, v155
	ds_read2_b32 v[176:177], v167 offset1:16
	ds_read2_b32 v[174:175], v167 offset0:32 offset1:48
	ds_read2_b32 v[172:173], v167 offset0:128 offset1:144
	ds_read2_b32 v[168:169], v167 offset0:160 offset1:176
	s_and_b64 vcc, exec, s[6:7]
	s_cbranch_vccnz .LBB0_603
	s_waitcnt lgkmcnt(0)
	v_mul_f32_e32 v170, v70, v176
	v_mul_f32_e32 v171, v71, v176
	v_mul_f32_e32 v184, v68, v176
	v_mul_f32_e32 v185, v69, v176
	v_mul_f32_e32 v171, v171, v171
	v_mul_f32_e32 v167, v185, v185
	v_fmac_f32_e32 v167, v184, v184
	v_fmac_f32_e32 v171, v170, v170
	v_add_f32_e32 v167, v167, v171
	v_mul_f32_e32 v170, v58, v176
	v_mul_f32_e32 v171, v59, v176
	v_mul_f32_e32 v184, v56, v176
	v_mul_f32_e32 v185, v57, v176
	v_mul_f32_e32 v171, v171, v171
	v_mul_f32_e32 v185, v185, v185
	v_fmac_f32_e32 v185, v184, v184
	v_fmac_f32_e32 v171, v170, v170
	v_add_f32_e32 v170, v185, v171
	v_add_f32_e32 v167, v167, v170
	v_mul_f32_e32 v170, v126, v176
	v_mul_f32_e32 v171, v127, v176
	v_mul_f32_e32 v184, v124, v176
	v_mul_f32_e32 v185, v125, v176
	v_mul_f32_e32 v171, v171, v171
	v_mul_f32_e32 v185, v185, v185
	v_fmac_f32_e32 v185, v184, v184
	v_fmac_f32_e32 v171, v170, v170
	v_add_f32_e32 v170, v185, v171
	v_add_f32_e32 v167, v170, v167
	v_mul_f32_e32 v170, v122, v176
	v_mul_f32_e32 v171, v123, v176
	v_mul_f32_e32 v184, v120, v176
	v_mul_f32_e32 v185, v121, v176
	v_mul_f32_e32 v171, v171, v171
	v_mul_f32_e32 v185, v185, v185
	v_fmac_f32_e32 v185, v184, v184
	v_fmac_f32_e32 v171, v170, v170
	v_add_f32_e32 v170, v185, v171
	v_add_f32_e32 v167, v170, v167
	v_mov_b32_e32 v170, v167
	s_nop 1
	v_permlane16_swap_b32_e32 v167, v170
	v_add_f32_e32 v167, v167, v170
	v_mov_b32_e32 v170, v167
	s_nop 1
	v_permlane32_swap_b32_e32 v167, v170
	v_add_f32_e32 v167, v167, v170
	v_fmamk_f32 v167, v167, 0x3c800000, v183
	v_rsq_f32_e32 v167, v167
	s_nop 0
	v_mul_f32_e32 v167, v176, v167
	v_mul_f32_e32 v176, s0, v167
.LBB0_603:
	v_ashrrev_i32_e32 v167, 31, v166
	v_lshl_add_u64 v[170:171], s[46:47], 0, v[152:153]
	v_mul_lo_u32 v186, s45, v166
	v_mul_lo_u32 v167, s44, v167
	v_mad_u64_u32 v[184:185], s[46:47], s44, v166, 0
	v_add3_u32 v185, v185, v167, v186
	v_lshl_add_u64 v[188:189], v[184:185], 1, v[170:171]
	s_waitcnt lgkmcnt(0)
	v_mul_f32_e32 v184, v68, v176
	v_mul_f32_e32 v185, v69, v176
	v_mul_f32_e32 v186, v70, v176
	v_mul_f32_e32 v187, v71, v176
	v_mul_f32_e32 v190, v56, v176
	v_mul_f32_e32 v191, v57, v176
	v_mul_f32_e32 v192, v58, v176
	v_mul_f32_e32 v193, v59, v176
	v_mul_f32_e32 v184, v132, v184
	v_mul_f32_e32 v185, v133, v185
	v_mul_f32_e32 v186, v134, v186
	v_mul_f32_e32 v187, v135, v187
	v_mul_f32_e32 v190, v128, v190
	v_mul_f32_e32 v191, v129, v191
	v_mul_f32_e32 v192, v130, v192
	v_mul_f32_e32 v193, v131, v193
	v_cvt_pk_bf16_f32 v184, v184, v185
	v_cvt_pk_bf16_f32 v185, v186, v187
	v_cvt_pk_bf16_f32 v186, v190, v191
	v_cvt_pk_bf16_f32 v187, v192, v193
	v_mul_f32_e32 v120, v120, v176
	v_mul_f32_e32 v121, v121, v176
	global_store_dwordx4 v[188:189], v[184:187], off
	v_mul_f32_e32 v124, v124, v176
	v_mul_f32_e32 v125, v125, v176
	v_mul_f32_e32 v126, v126, v176
	v_mul_f32_e32 v127, v127, v176
	v_mul_f32_e32 v184, v136, v120
	v_mul_f32_e32 v185, v137, v121
	v_mul_f32_e32 v120, v122, v176
	v_mul_f32_e32 v121, v123, v176
	v_mul_f32_e32 v124, v140, v124
	v_mul_f32_e32 v125, v141, v125
	v_mul_f32_e32 v126, v142, v126
	v_mul_f32_e32 v127, v143, v127
	v_mul_f32_e32 v186, v138, v120
	v_mul_f32_e32 v187, v139, v121
	v_cvt_pk_bf16_f32 v120, v124, v125
	v_cvt_pk_bf16_f32 v121, v126, v127
	v_cvt_pk_bf16_f32 v122, v184, v185
	v_cvt_pk_bf16_f32 v123, v186, v187
	s_and_b64 vcc, exec, s[6:7]
	global_store_dwordx4 v[188:189], v[120:123], off offset:64
	s_cbranch_vccnz .LBB0_605
	s_nop 0
	v_mov_b32_e32 v120, v177
	v_mul_f32_e32 v122, v54, v120
	v_mul_f32_e32 v123, v55, v120
	v_mul_f32_e32 v124, v52, v120
	v_mul_f32_e32 v125, v53, v120
	v_mul_f32_e32 v123, v123, v123
	v_mul_f32_e32 v121, v125, v125
	v_fmac_f32_e32 v121, v124, v124
	v_fmac_f32_e32 v123, v122, v122
	v_add_f32_e32 v121, v121, v123
	v_mul_f32_e32 v122, v50, v120
	v_mul_f32_e32 v123, v51, v120
	v_mul_f32_e32 v124, v48, v120
	v_mul_f32_e32 v125, v49, v120
	v_mul_f32_e32 v123, v123, v123
	v_mul_f32_e32 v125, v125, v125
	v_fmac_f32_e32 v125, v124, v124
	v_fmac_f32_e32 v123, v122, v122
	v_add_f32_e32 v122, v125, v123
	v_add_f32_e32 v121, v121, v122
	v_mul_f32_e32 v122, v118, v120
	v_mul_f32_e32 v123, v119, v120
	v_mul_f32_e32 v124, v116, v120
	v_mul_f32_e32 v125, v117, v120
	v_mul_f32_e32 v123, v123, v123
	v_mul_f32_e32 v125, v125, v125
	v_fmac_f32_e32 v125, v124, v124
	v_fmac_f32_e32 v123, v122, v122
	v_add_f32_e32 v122, v125, v123
	v_add_f32_e32 v124, v122, v121
	v_mul_f32_e32 v122, v114, v120
	v_mul_f32_e32 v123, v115, v120
	v_mul_f32_e32 v121, v113, v120
	v_mul_f32_e32 v120, v112, v120
	s_nop 0
	v_mul_f32_e32 v121, v121, v121
	v_fmac_f32_e32 v121, v120, v120
	v_mul_f32_e32 v120, v123, v123
	v_fmac_f32_e32 v120, v122, v122
	v_add_f32_e32 v120, v121, v120
	v_add_f32_e32 v120, v120, v124
	v_mov_b32_e32 v121, v120
	s_nop 1
	v_permlane16_swap_b32_e32 v120, v121
	v_add_f32_e32 v120, v120, v121
	v_mov_b32_e32 v121, v120
	s_nop 1
	v_permlane32_swap_b32_e32 v120, v121
	v_add_f32_e32 v120, v120, v121
	v_fmamk_f32 v120, v120, 0x3c800000, v183
	v_rsq_f32_e32 v120, v120
	s_nop 0
	v_mul_f32_e32 v120, v177, v120
	v_mul_f32_e32 v177, s0, v120
; __device__ __forceinline__ unsigned cvt_pk_bf16(float lo, float hi) { f32x2 v = {lo, hi}; bf16x2_t b = __builtin_convertvector(v, bf16x2_t); return __builtin_bit_cast(unsigned, b); }
; __device__ __forceinline__ float xor16_sum(float x) { auto r = __builtin_amdgcn_permlane16_swap(__float_as_uint(x), __float_as_uint(x), false, false); return __uint_as_float(r[0]) + __uint_as_float(r[1]); }
; __device__ __forceinline__ float xor32_sum(float x) { auto r = __builtin_amdgcn_permlane32_swap(__float_as_uint(x), __float_as_uint(x), false, false); return __uint_as_float(r[0]) + __uint_as_float(r[1]); }
;     __device__ __forceinline__ void operator()(const f32x4 (&acc)[2][2][4][2], const Unit& u, int wr, int wc, int fr, int fq) const {
;     ...
;         for (int ai = 0; ai < 2; ++ai)
; #pragma unroll
;             for (int m = 0; m < 4; ++m) { const int row = row0 + ai * HALF + m * 16; const float rs = rsv[ai * 4 + m];
;                 float hs = rs;
;                 if (kind == 1) { float ss = 0.f;
; #pragma unroll
;                     for (int bj = 0; bj < 2; ++bj)
; #pragma unroll
;                         for (int n = 0; n < 2; ++n) { const f32x4 v = acc[ai][bj][m][n] * rs; ss += (v[0] * v[0] + v[1] * v[1]) + (v[2] * v[2] + v[3] * v[3]); }
;                     ss = xor16_sum(ss); ss = xor32_sum(ss); hs = rs * __builtin_amdgcn_rsqf(ss * (1.0f / 64.0f) + RMS_EPS) * mul; }
; #pragma unroll
;                 for (int bj = 0; bj < 2; ++bj) { float o[8];
; #pragma unroll
;                     for (int n = 0; n < 2; ++n) { const f32x4 gvn = gv[bj][n];
; #pragma unroll
;                         for (int i = 0; i < 4; ++i) o[4 * n + i] = acc[ai][bj][m][n][i] * hs * gvn[i]; }
;                     u32x4 w; w.x = cvt_pk_bf16(o[0], o[1]); w.y = cvt_pk_bf16(o[2], o[3]); w.z = cvt_pk_bf16(o[4], o[5]); w.w = cvt_pk_bf16(o[6], o[7]);
;                     *(u32x4*)(dst + (size_t)row * pitch + 32 * bj + 8 * fq) = w; } }
.LBB0_605:
	s_nop 0
	v_or_b32_e32 v120, 16, v166
	v_mul_lo_u32 v122, s45, v120
	v_mad_u64_u32 v[120:121], s[46:47], s44, v120, 0
	v_add3_u32 v121, v121, v167, v122
	v_mov_b32_e32 v126, v177
	v_lshl_add_u64 v[124:125], v[120:121], 1, v[170:171]
	v_mul_f32_e32 v120, v52, v126
	v_mul_f32_e32 v121, v53, v126
	v_mul_f32_e32 v122, v54, v126
	v_mul_f32_e32 v123, v55, v126
	v_mul_f32_e32 v176, v48, v126
	v_mul_f32_e32 v177, v49, v126
	v_mul_f32_e32 v184, v50, v126
	v_mul_f32_e32 v185, v51, v126
	v_mul_f32_e32 v120, v132, v120
	v_mul_f32_e32 v121, v133, v121
	v_mul_f32_e32 v122, v134, v122
	v_mul_f32_e32 v123, v135, v123
	v_mul_f32_e32 v176, v128, v176
	v_mul_f32_e32 v177, v129, v177
	v_mul_f32_e32 v184, v130, v184
	v_mul_f32_e32 v185, v131, v185
	v_cvt_pk_bf16_f32 v120, v120, v121
	v_cvt_pk_bf16_f32 v121, v122, v123
	v_cvt_pk_bf16_f32 v122, v176, v177
	v_cvt_pk_bf16_f32 v123, v184, v185
	v_mul_f32_e32 v112, v112, v126
	v_mul_f32_e32 v113, v113, v126
	global_store_dwordx4 v[124:125], v[120:123], off
	v_mul_f32_e32 v116, v116, v126
	v_mul_f32_e32 v117, v117, v126
	v_mul_f32_e32 v118, v118, v126
	v_mul_f32_e32 v119, v119, v126
	v_mul_f32_e32 v120, v136, v112
	v_mul_f32_e32 v121, v137, v113
	v_mul_f32_e32 v112, v114, v126
	v_mul_f32_e32 v113, v115, v126
	v_mul_f32_e32 v116, v140, v116
	v_mul_f32_e32 v117, v141, v117
	v_mul_f32_e32 v118, v142, v118
	v_mul_f32_e32 v119, v143, v119
	v_mul_f32_e32 v122, v138, v112
	v_mul_f32_e32 v123, v139, v113
	v_cvt_pk_bf16_f32 v112, v116, v117
	v_cvt_pk_bf16_f32 v113, v118, v119
	v_cvt_pk_bf16_f32 v114, v120, v121
	v_cvt_pk_bf16_f32 v115, v122, v123
	s_and_b64 vcc, exec, s[6:7]
	global_store_dwordx4 v[124:125], v[112:115], off offset:64
	s_cbranch_vccnz .LBB0_607
	s_nop 0
	v_mul_f32_e32 v112, v46, v174
	v_mul_f32_e32 v113, v47, v174
	v_mul_f32_e32 v114, v44, v174
	v_mul_f32_e32 v115, v45, v174
	v_mul_f32_e32 v113, v113, v113
	v_mul_f32_e32 v115, v115, v115
	v_fmac_f32_e32 v115, v114, v114
	v_fmac_f32_e32 v113, v112, v112
	v_add_f32_e32 v116, v115, v113
	v_mul_f32_e32 v112, v42, v174
	v_mul_f32_e32 v113, v43, v174
	v_mul_f32_e32 v114, v40, v174
	v_mul_f32_e32 v115, v41, v174
	v_mul_f32_e32 v113, v113, v113
	v_mul_f32_e32 v115, v115, v115
	v_fmac_f32_e32 v115, v114, v114
	v_fmac_f32_e32 v113, v112, v112
	v_add_f32_e32 v112, v115, v113
	v_add_f32_e32 v116, v116, v112
	v_mul_f32_e32 v112, v110, v174
	v_mul_f32_e32 v113, v111, v174
	v_mul_f32_e32 v114, v108, v174
	v_mul_f32_e32 v115, v109, v174
	v_mul_f32_e32 v113, v113, v113
	v_mul_f32_e32 v115, v115, v115
	v_fmac_f32_e32 v115, v114, v114
	v_fmac_f32_e32 v113, v112, v112
	v_add_f32_e32 v112, v115, v113
	v_add_f32_e32 v116, v112, v116
	v_mul_f32_e32 v112, v106, v174
	v_mul_f32_e32 v113, v107, v174
	v_mul_f32_e32 v114, v104, v174
	v_mul_f32_e32 v115, v105, v174
	v_mul_f32_e32 v113, v113, v113
	v_mul_f32_e32 v115, v115, v115
	v_fmac_f32_e32 v115, v114, v114
	v_fmac_f32_e32 v113, v112, v112
	v_add_f32_e32 v112, v115, v113
	v_add_f32_e32 v112, v112, v116
	v_mov_b32_e32 v113, v112
	s_nop 1
	v_permlane16_swap_b32_e32 v112, v113
	v_add_f32_e32 v112, v112, v113
	v_mov_b32_e32 v113, v112
	s_nop 1
	v_permlane32_swap_b32_e32 v112, v113
	v_add_f32_e32 v112, v112, v113
	v_fmamk_f32 v112, v112, 0x3c800000, v183
	v_rsq_f32_e32 v112, v112
	s_nop 0
	v_mul_f32_e32 v112, v174, v112
	v_mul_f32_e32 v174, s0, v112
.LBB0_607:
	s_nop 0
	v_or_b32_e32 v112, 32, v166
	v_mul_lo_u32 v114, s45, v112
	v_mad_u64_u32 v[112:113], s[46:47], s44, v112, 0
	v_add3_u32 v113, v113, v167, v114
	v_lshl_add_u64 v[116:117], v[112:113], 1, v[170:171]
	v_mul_f32_e32 v112, v44, v174
	v_mul_f32_e32 v113, v45, v174
	v_mul_f32_e32 v114, v46, v174
	v_mul_f32_e32 v115, v47, v174
	v_mul_f32_e32 v118, v40, v174
	v_mul_f32_e32 v119, v41, v174
	v_mul_f32_e32 v120, v42, v174
	v_mul_f32_e32 v121, v43, v174
	v_mul_f32_e32 v112, v132, v112
	v_mul_f32_e32 v113, v133, v113
	v_mul_f32_e32 v114, v134, v114
	v_mul_f32_e32 v115, v135, v115
	v_mul_f32_e32 v118, v128, v118
	v_mul_f32_e32 v119, v129, v119
	v_mul_f32_e32 v120, v130, v120
	v_mul_f32_e32 v121, v131, v121
	v_cvt_pk_bf16_f32 v112, v112, v113
	v_cvt_pk_bf16_f32 v113, v114, v115
	v_cvt_pk_bf16_f32 v114, v118, v119
	v_cvt_pk_bf16_f32 v115, v120, v121
	v_mul_f32_e32 v104, v104, v174
	v_mul_f32_e32 v105, v105, v174
	global_store_dwordx4 v[116:117], v[112:115], off
	v_mul_f32_e32 v108, v108, v174
	v_mul_f32_e32 v109, v109, v174
	v_mul_f32_e32 v110, v110, v174
	v_mul_f32_e32 v111, v111, v174
	v_mul_f32_e32 v112, v136, v104
	v_mul_f32_e32 v113, v137, v105
	v_mul_f32_e32 v104, v106, v174
	v_mul_f32_e32 v105, v107, v174
	v_mul_f32_e32 v108, v140, v108
	v_mul_f32_e32 v109, v141, v109
	v_mul_f32_e32 v110, v142, v110
	v_mul_f32_e32 v111, v143, v111
	v_mul_f32_e32 v114, v138, v104
	v_mul_f32_e32 v115, v139, v105
	v_cvt_pk_bf16_f32 v104, v108, v109
	v_cvt_pk_bf16_f32 v105, v110, v111
	v_cvt_pk_bf16_f32 v106, v112, v113
	v_cvt_pk_bf16_f32 v107, v114, v115
	s_and_b64 vcc, exec, s[6:7]
	global_store_dwordx4 v[116:117], v[104:107], off offset:64
	s_cbranch_vccnz .LBB0_609
	s_nop 0
	v_mov_b32_e32 v104, v175
	v_mul_f32_e32 v106, v38, v104
	v_mul_f32_e32 v107, v39, v104
	v_mul_f32_e32 v108, v36, v104
	v_mul_f32_e32 v109, v37, v104
	v_mul_f32_e32 v107, v107, v107
	v_mul_f32_e32 v105, v109, v109
	v_fmac_f32_e32 v105, v108, v108
	v_fmac_f32_e32 v107, v106, v106
	v_add_f32_e32 v105, v105, v107
	v_mul_f32_e32 v106, v34, v104
	v_mul_f32_e32 v107, v35, v104
	v_mul_f32_e32 v108, v32, v104
	v_mul_f32_e32 v109, v33, v104
	v_mul_f32_e32 v107, v107, v107
	v_mul_f32_e32 v109, v109, v109
	v_fmac_f32_e32 v109, v108, v108
	v_fmac_f32_e32 v107, v106, v106
	v_add_f32_e32 v106, v109, v107
	v_add_f32_e32 v105, v105, v106
	v_mul_f32_e32 v106, v102, v104
	v_mul_f32_e32 v107, v103, v104
	v_mul_f32_e32 v108, v100, v104
	v_mul_f32_e32 v109, v101, v104
	v_mul_f32_e32 v107, v107, v107
	v_mul_f32_e32 v109, v109, v109
	v_fmac_f32_e32 v109, v108, v108
	v_fmac_f32_e32 v107, v106, v106
	v_add_f32_e32 v106, v109, v107
	v_add_f32_e32 v108, v106, v105
	v_mul_f32_e32 v106, v98, v104
	v_mul_f32_e32 v107, v99, v104
	v_mul_f32_e32 v105, v97, v104
	v_mul_f32_e32 v104, v96, v104
	s_nop 0
	v_mul_f32_e32 v105, v105, v105
	v_fmac_f32_e32 v105, v104, v104
	v_mul_f32_e32 v104, v107, v107
	v_fmac_f32_e32 v104, v106, v106
	v_add_f32_e32 v104, v105, v104
	v_add_f32_e32 v104, v104, v108
	v_mov_b32_e32 v105, v104
	s_nop 1
	v_permlane16_swap_b32_e32 v104, v105
	v_add_f32_e32 v104, v104, v105
	v_mov_b32_e32 v105, v104
	s_nop 1
	v_permlane32_swap_b32_e32 v104, v105
	v_add_f32_e32 v104, v104, v105
	v_fmamk_f32 v104, v104, 0x3c800000, v183
	v_rsq_f32_e32 v104, v104
	s_nop 0
	v_mul_f32_e32 v104, v175, v104
	v_mul_f32_e32 v175, s0, v104
; __device__ __forceinline__ unsigned cvt_pk_bf16(float lo, float hi) { f32x2 v = {lo, hi}; bf16x2_t b = __builtin_convertvector(v, bf16x2_t); return __builtin_bit_cast(unsigned, b); }
; __device__ __forceinline__ float xor16_sum(float x) { auto r = __builtin_amdgcn_permlane16_swap(__float_as_uint(x), __float_as_uint(x), false, false); return __uint_as_float(r[0]) + __uint_as_float(r[1]); }
; __device__ __forceinline__ float xor32_sum(float x) { auto r = __builtin_amdgcn_permlane32_swap(__float_as_uint(x), __float_as_uint(x), false, false); return __uint_as_float(r[0]) + __uint_as_float(r[1]); }
;     __device__ __forceinline__ void operator()(const f32x4 (&acc)[2][2][4][2], const Unit& u, int wr, int wc, int fr, int fq) const {
;     ...
;         for (int ai = 0; ai < 2; ++ai)
; #pragma unroll
;             for (int m = 0; m < 4; ++m) { const int row = row0 + ai * HALF + m * 16; const float rs = rsv[ai * 4 + m];
;                 float hs = rs;
;                 if (kind == 1) { float ss = 0.f;
; #pragma unroll
;                     for (int bj = 0; bj < 2; ++bj)
; #pragma unroll
;                         for (int n = 0; n < 2; ++n) { const f32x4 v = acc[ai][bj][m][n] * rs; ss += (v[0] * v[0] + v[1] * v[1]) + (v[2] * v[2] + v[3] * v[3]); }
;                     ss = xor16_sum(ss); ss = xor32_sum(ss); hs = rs * __builtin_amdgcn_rsqf(ss * (1.0f / 64.0f) + RMS_EPS) * mul; }
; #pragma unroll
;                 for (int bj = 0; bj < 2; ++bj) { float o[8];
; #pragma unroll
;                     for (int n = 0; n < 2; ++n) { const f32x4 gvn = gv[bj][n];
; #pragma unroll
;                         for (int i = 0; i < 4; ++i) o[4 * n + i] = acc[ai][bj][m][n][i] * hs * gvn[i]; }
;                     u32x4 w; w.x = cvt_pk_bf16(o[0], o[1]); w.y = cvt_pk_bf16(o[2], o[3]); w.z = cvt_pk_bf16(o[4], o[5]); w.w = cvt_pk_bf16(o[6], o[7]);
;                     *(u32x4*)(dst + (size_t)row * pitch + 32 * bj + 8 * fq) = w; } }
.LBB0_609:
	s_nop 0
	v_or_b32_e32 v104, 48, v166
	v_mul_lo_u32 v106, s45, v104
	v_mad_u64_u32 v[104:105], s[46:47], s44, v104, 0
	v_add3_u32 v105, v105, v167, v106
	v_mov_b32_e32 v110, v175
	v_lshl_add_u64 v[108:109], v[104:105], 1, v[170:171]
	v_mul_f32_e32 v104, v36, v110
	v_mul_f32_e32 v105, v37, v110
	v_mul_f32_e32 v106, v38, v110
	v_mul_f32_e32 v107, v39, v110
	v_mul_f32_e32 v112, v32, v110
	v_mul_f32_e32 v113, v33, v110
	v_mul_f32_e32 v114, v34, v110
	v_mul_f32_e32 v115, v35, v110
	v_mul_f32_e32 v104, v132, v104
	v_mul_f32_e32 v105, v133, v105
	v_mul_f32_e32 v106, v134, v106
	v_mul_f32_e32 v107, v135, v107
	v_mul_f32_e32 v112, v128, v112
	v_mul_f32_e32 v113, v129, v113
	v_mul_f32_e32 v114, v130, v114
	v_mul_f32_e32 v115, v131, v115
	v_cvt_pk_bf16_f32 v104, v104, v105
	v_cvt_pk_bf16_f32 v105, v106, v107
	v_cvt_pk_bf16_f32 v106, v112, v113
	v_cvt_pk_bf16_f32 v107, v114, v115
	v_mul_f32_e32 v96, v96, v110
	v_mul_f32_e32 v97, v97, v110
	global_store_dwordx4 v[108:109], v[104:107], off
	v_mul_f32_e32 v100, v100, v110
	v_mul_f32_e32 v101, v101, v110
	v_mul_f32_e32 v102, v102, v110
	v_mul_f32_e32 v103, v103, v110
	v_mul_f32_e32 v104, v136, v96
	v_mul_f32_e32 v105, v137, v97
	v_mul_f32_e32 v96, v98, v110
	v_mul_f32_e32 v97, v99, v110
	v_mul_f32_e32 v100, v140, v100
	v_mul_f32_e32 v101, v141, v101
	v_mul_f32_e32 v102, v142, v102
	v_mul_f32_e32 v103, v143, v103
	v_mul_f32_e32 v106, v138, v96
	v_mul_f32_e32 v107, v139, v97
	v_cvt_pk_bf16_f32 v96, v100, v101
	v_cvt_pk_bf16_f32 v97, v102, v103
	v_cvt_pk_bf16_f32 v98, v104, v105
	v_cvt_pk_bf16_f32 v99, v106, v107
	s_and_b64 vcc, exec, s[6:7]
	global_store_dwordx4 v[108:109], v[96:99], off offset:64
	s_cbranch_vccnz .LBB0_611
	s_nop 0
	v_mul_f32_e32 v96, v30, v172
	v_mul_f32_e32 v97, v31, v172
	v_mul_f32_e32 v98, v28, v172
	v_mul_f32_e32 v99, v29, v172
	v_mul_f32_e32 v97, v97, v97
	v_mul_f32_e32 v99, v99, v99
	v_fmac_f32_e32 v99, v98, v98
	v_fmac_f32_e32 v97, v96, v96
	v_add_f32_e32 v100, v99, v97
	v_mul_f32_e32 v96, v26, v172
	v_mul_f32_e32 v97, v27, v172
	v_mul_f32_e32 v98, v24, v172
	v_mul_f32_e32 v99, v25, v172
	v_mul_f32_e32 v97, v97, v97
	v_mul_f32_e32 v99, v99, v99
	v_fmac_f32_e32 v99, v98, v98
	v_fmac_f32_e32 v97, v96, v96
	v_add_f32_e32 v96, v99, v97
	v_add_f32_e32 v100, v100, v96
	v_mul_f32_e32 v96, v94, v172
	v_mul_f32_e32 v97, v95, v172
	v_mul_f32_e32 v98, v92, v172
	v_mul_f32_e32 v99, v93, v172
	v_mul_f32_e32 v97, v97, v97
	v_mul_f32_e32 v99, v99, v99
	v_fmac_f32_e32 v99, v98, v98
	v_fmac_f32_e32 v97, v96, v96
	v_add_f32_e32 v96, v99, v97
	v_add_f32_e32 v100, v96, v100
	v_mul_f32_e32 v96, v90, v172
	v_mul_f32_e32 v97, v91, v172
	v_mul_f32_e32 v98, v88, v172
	v_mul_f32_e32 v99, v89, v172
	v_mul_f32_e32 v97, v97, v97
	v_mul_f32_e32 v99, v99, v99
	v_fmac_f32_e32 v99, v98, v98
	v_fmac_f32_e32 v97, v96, v96
	v_add_f32_e32 v96, v99, v97
	v_add_f32_e32 v96, v96, v100
	v_mov_b32_e32 v97, v96
	s_nop 1
	v_permlane16_swap_b32_e32 v96, v97
	v_add_f32_e32 v96, v96, v97
	v_mov_b32_e32 v97, v96
	s_nop 1
	v_permlane32_swap_b32_e32 v96, v97
	v_add_f32_e32 v96, v96, v97
	v_fmamk_f32 v96, v96, 0x3c800000, v183
	v_rsq_f32_e32 v96, v96
	s_nop 0
	v_mul_f32_e32 v96, v172, v96
	v_mul_f32_e32 v172, s0, v96
.LBB0_611:
	s_nop 0
	v_add_u32_e32 v96, 0x80, v166
	v_ashrrev_i32_e32 v97, 31, v96
	v_mul_lo_u32 v98, s44, v97
	v_mul_lo_u32 v99, s45, v96
	v_mad_u64_u32 v[96:97], s[46:47], s44, v96, 0
	v_add3_u32 v97, v97, v98, v99
	v_lshl_add_u64 v[100:101], v[96:97], 1, v[170:171]
	v_mul_f32_e32 v96, v28, v172
	v_mul_f32_e32 v97, v29, v172
	v_mul_f32_e32 v98, v30, v172
	v_mul_f32_e32 v99, v31, v172
	v_mul_f32_e32 v102, v24, v172
	v_mul_f32_e32 v103, v25, v172
	v_mul_f32_e32 v104, v26, v172
	v_mul_f32_e32 v105, v27, v172
	v_mul_f32_e32 v96, v132, v96
	v_mul_f32_e32 v97, v133, v97
	v_mul_f32_e32 v98, v134, v98
	v_mul_f32_e32 v99, v135, v99
	v_mul_f32_e32 v102, v128, v102
	v_mul_f32_e32 v103, v129, v103
	v_mul_f32_e32 v104, v130, v104
	v_mul_f32_e32 v105, v131, v105
	v_cvt_pk_bf16_f32 v96, v96, v97
	v_cvt_pk_bf16_f32 v97, v98, v99
	v_cvt_pk_bf16_f32 v98, v102, v103
	v_cvt_pk_bf16_f32 v99, v104, v105
	v_mul_f32_e32 v88, v88, v172
	v_mul_f32_e32 v89, v89, v172
	global_store_dwordx4 v[100:101], v[96:99], off
	v_mul_f32_e32 v92, v92, v172
	v_mul_f32_e32 v93, v93, v172
	v_mul_f32_e32 v94, v94, v172
	v_mul_f32_e32 v95, v95, v172
	v_mul_f32_e32 v96, v136, v88
	v_mul_f32_e32 v97, v137, v89
	v_mul_f32_e32 v88, v90, v172
	v_mul_f32_e32 v89, v91, v172
	v_mul_f32_e32 v92, v140, v92
	v_mul_f32_e32 v93, v141, v93
	v_mul_f32_e32 v94, v142, v94
	v_mul_f32_e32 v95, v143, v95
	v_mul_f32_e32 v98, v138, v88
	v_mul_f32_e32 v99, v139, v89
	v_cvt_pk_bf16_f32 v88, v92, v93
	v_cvt_pk_bf16_f32 v89, v94, v95
	v_cvt_pk_bf16_f32 v90, v96, v97
	v_cvt_pk_bf16_f32 v91, v98, v99
	s_and_b64 vcc, exec, s[6:7]
	global_store_dwordx4 v[100:101], v[88:91], off offset:64
	s_cbranch_vccnz .LBB0_613
	s_nop 0
	v_mov_b32_e32 v88, v173
	v_mul_f32_e32 v90, v22, v88
	v_mul_f32_e32 v91, v23, v88
	v_mul_f32_e32 v92, v20, v88
	v_mul_f32_e32 v93, v21, v88
	v_mul_f32_e32 v91, v91, v91
	v_mul_f32_e32 v89, v93, v93
	v_fmac_f32_e32 v89, v92, v92
	v_fmac_f32_e32 v91, v90, v90
	v_add_f32_e32 v89, v89, v91
	v_mul_f32_e32 v90, v18, v88
	v_mul_f32_e32 v91, v19, v88
	v_mul_f32_e32 v92, v16, v88
	v_mul_f32_e32 v93, v17, v88
	v_mul_f32_e32 v91, v91, v91
	v_mul_f32_e32 v93, v93, v93
	v_fmac_f32_e32 v93, v92, v92
	v_fmac_f32_e32 v91, v90, v90
	v_add_f32_e32 v90, v93, v91
	v_add_f32_e32 v89, v89, v90
	v_mul_f32_e32 v90, v86, v88
	v_mul_f32_e32 v91, v87, v88
	v_mul_f32_e32 v92, v84, v88
	v_mul_f32_e32 v93, v85, v88
	v_mul_f32_e32 v91, v91, v91
	v_mul_f32_e32 v93, v93, v93
	v_fmac_f32_e32 v93, v92, v92
	v_fmac_f32_e32 v91, v90, v90
	v_add_f32_e32 v90, v93, v91
	v_add_f32_e32 v92, v90, v89
	v_mul_f32_e32 v90, v82, v88
	v_mul_f32_e32 v91, v83, v88
	v_mul_f32_e32 v89, v81, v88
	v_mul_f32_e32 v88, v80, v88
	s_nop 0
	v_mul_f32_e32 v89, v89, v89
	v_fmac_f32_e32 v89, v88, v88
	v_mul_f32_e32 v88, v91, v91
	v_fmac_f32_e32 v88, v90, v90
	v_add_f32_e32 v88, v89, v88
	v_add_f32_e32 v88, v88, v92
	v_mov_b32_e32 v89, v88
	s_nop 1
	v_permlane16_swap_b32_e32 v88, v89
	v_add_f32_e32 v88, v88, v89
	v_mov_b32_e32 v89, v88
	s_nop 1
	v_permlane32_swap_b32_e32 v88, v89
	v_add_f32_e32 v88, v88, v89
	v_fmamk_f32 v88, v88, 0x3c800000, v183
	v_rsq_f32_e32 v88, v88
	s_nop 0
	v_mul_f32_e32 v88, v173, v88
	v_mul_f32_e32 v173, s0, v88
; __device__ __forceinline__ unsigned cvt_pk_bf16(float lo, float hi) { f32x2 v = {lo, hi}; bf16x2_t b = __builtin_convertvector(v, bf16x2_t); return __builtin_bit_cast(unsigned, b); }
; __device__ __forceinline__ float xor16_sum(float x) { auto r = __builtin_amdgcn_permlane16_swap(__float_as_uint(x), __float_as_uint(x), false, false); return __uint_as_float(r[0]) + __uint_as_float(r[1]); }
; __device__ __forceinline__ float xor32_sum(float x) { auto r = __builtin_amdgcn_permlane32_swap(__float_as_uint(x), __float_as_uint(x), false, false); return __uint_as_float(r[0]) + __uint_as_float(r[1]); }
;     __device__ __forceinline__ void operator()(const f32x4 (&acc)[2][2][4][2], const Unit& u, int wr, int wc, int fr, int fq) const {
;     ...
;         for (int ai = 0; ai < 2; ++ai)
; #pragma unroll
;             for (int m = 0; m < 4; ++m) { const int row = row0 + ai * HALF + m * 16; const float rs = rsv[ai * 4 + m];
;                 float hs = rs;
;                 if (kind == 1) { float ss = 0.f;
; #pragma unroll
;                     for (int bj = 0; bj < 2; ++bj)
; #pragma unroll
;                         for (int n = 0; n < 2; ++n) { const f32x4 v = acc[ai][bj][m][n] * rs; ss += (v[0] * v[0] + v[1] * v[1]) + (v[2] * v[2] + v[3] * v[3]); }
;                     ss = xor16_sum(ss); ss = xor32_sum(ss); hs = rs * __builtin_amdgcn_rsqf(ss * (1.0f / 64.0f) + RMS_EPS) * mul; }
; #pragma unroll
;                 for (int bj = 0; bj < 2; ++bj) { float o[8];
; #pragma unroll
;                     for (int n = 0; n < 2; ++n) { const f32x4 gvn = gv[bj][n];
; #pragma unroll
;                         for (int i = 0; i < 4; ++i) o[4 * n + i] = acc[ai][bj][m][n][i] * hs * gvn[i]; }
;                     u32x4 w; w.x = cvt_pk_bf16(o[0], o[1]); w.y = cvt_pk_bf16(o[2], o[3]); w.z = cvt_pk_bf16(o[4], o[5]); w.w = cvt_pk_bf16(o[6], o[7]);
;                     *(u32x4*)(dst + (size_t)row * pitch + 32 * bj + 8 * fq) = w; } }
.LBB0_613:
	s_nop 0
	v_add_u32_e32 v88, 0x90, v166
	v_ashrrev_i32_e32 v89, 31, v88
	v_mul_lo_u32 v90, s44, v89
	v_mul_lo_u32 v91, s45, v88
	v_mad_u64_u32 v[88:89], s[46:47], s44, v88, 0
	v_add3_u32 v89, v89, v90, v91
	v_mov_b32_e32 v94, v173
	v_lshl_add_u64 v[92:93], v[88:89], 1, v[170:171]
	v_mul_f32_e32 v88, v20, v94
	v_mul_f32_e32 v89, v21, v94
	v_mul_f32_e32 v90, v22, v94
	v_mul_f32_e32 v91, v23, v94
	v_mul_f32_e32 v96, v16, v94
	v_mul_f32_e32 v97, v17, v94
	v_mul_f32_e32 v98, v18, v94
	v_mul_f32_e32 v99, v19, v94
	v_mul_f32_e32 v88, v132, v88
	v_mul_f32_e32 v89, v133, v89
	v_mul_f32_e32 v90, v134, v90
	v_mul_f32_e32 v91, v135, v91
	v_mul_f32_e32 v96, v128, v96
	v_mul_f32_e32 v97, v129, v97
	v_mul_f32_e32 v98, v130, v98
	v_mul_f32_e32 v99, v131, v99
	v_cvt_pk_bf16_f32 v88, v88, v89
	v_cvt_pk_bf16_f32 v89, v90, v91
	v_cvt_pk_bf16_f32 v90, v96, v97
	v_cvt_pk_bf16_f32 v91, v98, v99
	v_mul_f32_e32 v80, v80, v94
	v_mul_f32_e32 v81, v81, v94
	global_store_dwordx4 v[92:93], v[88:91], off
	v_mul_f32_e32 v84, v84, v94
	v_mul_f32_e32 v85, v85, v94
	v_mul_f32_e32 v86, v86, v94
	v_mul_f32_e32 v87, v87, v94
	v_mul_f32_e32 v88, v136, v80
	v_mul_f32_e32 v89, v137, v81
	v_mul_f32_e32 v80, v82, v94
	v_mul_f32_e32 v81, v83, v94
	v_mul_f32_e32 v84, v140, v84
	v_mul_f32_e32 v85, v141, v85
	v_mul_f32_e32 v86, v142, v86
	v_mul_f32_e32 v87, v143, v87
	v_mul_f32_e32 v90, v138, v80
	v_mul_f32_e32 v91, v139, v81
	v_cvt_pk_bf16_f32 v80, v84, v85
	v_cvt_pk_bf16_f32 v81, v86, v87
	v_cvt_pk_bf16_f32 v82, v88, v89
	v_cvt_pk_bf16_f32 v83, v90, v91
	s_and_b64 vcc, exec, s[6:7]
	global_store_dwordx4 v[92:93], v[80:83], off offset:64
	s_cbranch_vccnz .LBB0_615
	s_nop 0
	v_mul_f32_e32 v80, v14, v168
	v_mul_f32_e32 v81, v15, v168
	v_mul_f32_e32 v82, v12, v168
	v_mul_f32_e32 v83, v13, v168
	v_mul_f32_e32 v81, v81, v81
	v_mul_f32_e32 v83, v83, v83
	v_fmac_f32_e32 v83, v82, v82
	v_fmac_f32_e32 v81, v80, v80
	v_add_f32_e32 v84, v83, v81
	v_mul_f32_e32 v80, v10, v168
	v_mul_f32_e32 v81, v11, v168
	v_mul_f32_e32 v82, v8, v168
	v_mul_f32_e32 v83, v9, v168
	v_mul_f32_e32 v81, v81, v81
	v_mul_f32_e32 v83, v83, v83
	v_fmac_f32_e32 v83, v82, v82
	v_fmac_f32_e32 v81, v80, v80
	v_add_f32_e32 v80, v83, v81
	v_add_f32_e32 v84, v84, v80
	v_mul_f32_e32 v80, v78, v168
	v_mul_f32_e32 v81, v79, v168
	v_mul_f32_e32 v82, v76, v168
	v_mul_f32_e32 v83, v77, v168
	v_mul_f32_e32 v81, v81, v81
	v_mul_f32_e32 v83, v83, v83
	v_fmac_f32_e32 v83, v82, v82
	v_fmac_f32_e32 v81, v80, v80
	v_add_f32_e32 v80, v83, v81
	v_add_f32_e32 v84, v80, v84
	v_mul_f32_e32 v80, v74, v168
	v_mul_f32_e32 v81, v75, v168
	v_mul_f32_e32 v82, v72, v168
	v_mul_f32_e32 v83, v73, v168
	v_mul_f32_e32 v81, v81, v81
	v_mul_f32_e32 v83, v83, v83
	v_fmac_f32_e32 v83, v82, v82
	v_fmac_f32_e32 v81, v80, v80
	v_add_f32_e32 v80, v83, v81
	v_add_f32_e32 v80, v80, v84
	v_mov_b32_e32 v81, v80
	s_nop 1
	v_permlane16_swap_b32_e32 v80, v81
	v_add_f32_e32 v80, v80, v81
	v_mov_b32_e32 v81, v80
	s_nop 1
	v_permlane32_swap_b32_e32 v80, v81
	v_add_f32_e32 v80, v80, v81
	v_fmamk_f32 v80, v80, 0x3c800000, v183
	v_rsq_f32_e32 v80, v80
	s_nop 0
	v_mul_f32_e32 v80, v168, v80
	v_mul_f32_e32 v168, s0, v80
; __device__ __forceinline__ unsigned cvt_pk_bf16(float lo, float hi) { f32x2 v = {lo, hi}; bf16x2_t b = __builtin_convertvector(v, bf16x2_t); return __builtin_bit_cast(unsigned, b); }
; __device__ __forceinline__ float xor16_sum(float x) { auto r = __builtin_amdgcn_permlane16_swap(__float_as_uint(x), __float_as_uint(x), false, false); return __uint_as_float(r[0]) + __uint_as_float(r[1]); }
; __device__ __forceinline__ float xor32_sum(float x) { auto r = __builtin_amdgcn_permlane32_swap(__float_as_uint(x), __float_as_uint(x), false, false); return __uint_as_float(r[0]) + __uint_as_float(r[1]); }
;     __device__ __forceinline__ void operator()(const f32x4 (&acc)[2][2][4][2], const Unit& u, int wr, int wc, int fr, int fq) const {
;     ...
;         for (int ai = 0; ai < 2; ++ai)
; #pragma unroll
;             for (int m = 0; m < 4; ++m) { const int row = row0 + ai * HALF + m * 16; const float rs = rsv[ai * 4 + m];
;                 float hs = rs;
;                 if (kind == 1) { float ss = 0.f;
; #pragma unroll
;                     for (int bj = 0; bj < 2; ++bj)
; #pragma unroll
;                         for (int n = 0; n < 2; ++n) { const f32x4 v = acc[ai][bj][m][n] * rs; ss += (v[0] * v[0] + v[1] * v[1]) + (v[2] * v[2] + v[3] * v[3]); }
;                     ss = xor16_sum(ss); ss = xor32_sum(ss); hs = rs * __builtin_amdgcn_rsqf(ss * (1.0f / 64.0f) + RMS_EPS) * mul; }
; #pragma unroll
;                 for (int bj = 0; bj < 2; ++bj) { float o[8];
; #pragma unroll
;                     for (int n = 0; n < 2; ++n) { const f32x4 gvn = gv[bj][n];
; #pragma unroll
;                         for (int i = 0; i < 4; ++i) o[4 * n + i] = acc[ai][bj][m][n][i] * hs * gvn[i]; }
;                     u32x4 w; w.x = cvt_pk_bf16(o[0], o[1]); w.y = cvt_pk_bf16(o[2], o[3]); w.z = cvt_pk_bf16(o[4], o[5]); w.w = cvt_pk_bf16(o[6], o[7]);
;                     *(u32x4*)(dst + (size_t)row * pitch + 32 * bj + 8 * fq) = w; } }
.LBB0_615:
	s_nop 0
	v_add_u32_e32 v80, 0xa0, v166
	v_ashrrev_i32_e32 v81, 31, v80
	v_mul_lo_u32 v82, s44, v81
	v_mul_lo_u32 v83, s45, v80
	v_mad_u64_u32 v[80:81], s[46:47], s44, v80, 0
	v_add3_u32 v81, v81, v82, v83
	v_lshl_add_u64 v[84:85], v[80:81], 1, v[170:171]
	v_mul_f32_e32 v80, v12, v168
	v_mul_f32_e32 v81, v13, v168
	v_mul_f32_e32 v82, v14, v168
	v_mul_f32_e32 v83, v15, v168
	v_mul_f32_e32 v86, v8, v168
	v_mul_f32_e32 v87, v9, v168
	v_mul_f32_e32 v88, v10, v168
	v_mul_f32_e32 v89, v11, v168
	v_mul_f32_e32 v80, v132, v80
	v_mul_f32_e32 v81, v133, v81
	v_mul_f32_e32 v82, v134, v82
	v_mul_f32_e32 v83, v135, v83
	v_mul_f32_e32 v86, v128, v86
	v_mul_f32_e32 v87, v129, v87
	v_mul_f32_e32 v88, v130, v88
	v_mul_f32_e32 v89, v131, v89
	v_cvt_pk_bf16_f32 v80, v80, v81
	v_cvt_pk_bf16_f32 v81, v82, v83
	v_cvt_pk_bf16_f32 v82, v86, v87
	v_cvt_pk_bf16_f32 v83, v88, v89
	v_mul_f32_e32 v72, v72, v168
	v_mul_f32_e32 v73, v73, v168
	global_store_dwordx4 v[84:85], v[80:83], off
	v_mul_f32_e32 v76, v76, v168
	v_mul_f32_e32 v77, v77, v168
	v_mul_f32_e32 v78, v78, v168
	v_mul_f32_e32 v79, v79, v168
	v_mul_f32_e32 v80, v136, v72
	v_mul_f32_e32 v81, v137, v73
	v_mul_f32_e32 v72, v74, v168
	v_mul_f32_e32 v73, v75, v168
	v_mul_f32_e32 v76, v140, v76
	v_mul_f32_e32 v77, v141, v77
	v_mul_f32_e32 v78, v142, v78
	v_mul_f32_e32 v79, v143, v79
	v_mul_f32_e32 v82, v138, v72
	v_mul_f32_e32 v83, v139, v73
	v_cvt_pk_bf16_f32 v72, v76, v77
	v_cvt_pk_bf16_f32 v73, v78, v79
	v_cvt_pk_bf16_f32 v74, v80, v81
	v_cvt_pk_bf16_f32 v75, v82, v83
	s_and_b64 vcc, exec, s[6:7]
	global_store_dwordx4 v[84:85], v[72:75], off offset:64
	s_cbranch_vccnz .LBB0_617
	s_nop 0
	v_mov_b32_e32 v72, v169
	v_mul_f32_e32 v74, v6, v72
	v_mul_f32_e32 v75, v7, v72
	v_mul_f32_e32 v76, v4, v72
	v_mul_f32_e32 v77, v5, v72
	v_mul_f32_e32 v75, v75, v75
	v_mul_f32_e32 v73, v77, v77
	v_fmac_f32_e32 v73, v76, v76
	v_fmac_f32_e32 v75, v74, v74
	v_add_f32_e32 v73, v73, v75
	v_mul_f32_e32 v74, v2, v72
	v_mul_f32_e32 v75, v3, v72
	v_mul_f32_e32 v76, v0, v72
	v_mul_f32_e32 v77, v1, v72
	v_mul_f32_e32 v75, v75, v75
	v_mul_f32_e32 v77, v77, v77
	v_fmac_f32_e32 v77, v76, v76
	v_fmac_f32_e32 v75, v74, v74
	v_add_f32_e32 v74, v77, v75
	v_add_f32_e32 v73, v73, v74
	v_mul_f32_e32 v74, v66, v72
	v_mul_f32_e32 v75, v67, v72
	v_mul_f32_e32 v76, v64, v72
	v_mul_f32_e32 v77, v65, v72
	v_mul_f32_e32 v75, v75, v75
	v_mul_f32_e32 v77, v77, v77
	v_fmac_f32_e32 v77, v76, v76
	v_fmac_f32_e32 v75, v74, v74
	v_add_f32_e32 v74, v77, v75
	v_add_f32_e32 v76, v74, v73
	v_mul_f32_e32 v74, v62, v72
	v_mul_f32_e32 v75, v63, v72
	v_mul_f32_e32 v73, v61, v72
	v_mul_f32_e32 v72, v60, v72
	s_nop 0
	v_mul_f32_e32 v73, v73, v73
	v_fmac_f32_e32 v73, v72, v72
	v_mul_f32_e32 v72, v75, v75
	v_fmac_f32_e32 v72, v74, v74
	v_add_f32_e32 v72, v73, v72
	v_add_f32_e32 v72, v72, v76
	v_mov_b32_e32 v73, v72
	s_nop 1
	v_permlane16_swap_b32_e32 v72, v73
	v_add_f32_e32 v72, v72, v73
	v_mov_b32_e32 v73, v72
	s_nop 1
	v_permlane32_swap_b32_e32 v72, v73
	v_add_f32_e32 v72, v72, v73
	v_fmamk_f32 v72, v72, 0x3c800000, v183
	v_rsq_f32_e32 v72, v72
	s_nop 0
	v_mul_f32_e32 v72, v169, v72
	v_mul_f32_e32 v169, s0, v72
.LBB0_617:
	s_nop 0
	v_add_u32_e32 v72, 0xb0, v166
	v_ashrrev_i32_e32 v73, 31, v72
	v_mul_lo_u32 v74, s44, v73
	v_mul_lo_u32 v75, s45, v72
	v_mad_u64_u32 v[72:73], s[0:1], s44, v72, 0
	v_add3_u32 v73, v73, v74, v75
	v_mov_b32_e32 v78, v169
	v_lshl_add_u64 v[76:77], v[72:73], 1, v[170:171]
	v_mul_f32_e32 v72, v4, v78
	v_mul_f32_e32 v73, v5, v78
	v_mul_f32_e32 v74, v6, v78
	v_mul_f32_e32 v75, v7, v78
	v_mul_f32_e32 v80, v0, v78
	v_mul_f32_e32 v81, v1, v78
	v_mul_f32_e32 v82, v2, v78
	v_mul_f32_e32 v83, v3, v78
	v_mul_f32_e32 v72, v132, v72
	v_mul_f32_e32 v73, v133, v73
	v_mul_f32_e32 v74, v134, v74
	v_mul_f32_e32 v75, v135, v75
	v_mul_f32_e32 v80, v128, v80
	v_mul_f32_e32 v81, v129, v81
	v_mul_f32_e32 v82, v130, v82
	v_mul_f32_e32 v83, v131, v83
	v_cvt_pk_bf16_f32 v72, v72, v73
	v_cvt_pk_bf16_f32 v73, v74, v75
	v_cvt_pk_bf16_f32 v74, v80, v81
	v_cvt_pk_bf16_f32 v75, v82, v83
	v_mul_f32_e32 v60, v60, v78
	v_mul_f32_e32 v61, v61, v78
	global_store_dwordx4 v[76:77], v[72:75], off
	v_mul_f32_e32 v64, v64, v78
	v_mul_f32_e32 v65, v65, v78
	v_mul_f32_e32 v66, v66, v78
	v_mul_f32_e32 v67, v67, v78
	v_mul_f32_e32 v72, v136, v60
	v_mul_f32_e32 v73, v137, v61
	v_mul_f32_e32 v60, v62, v78
	v_mul_f32_e32 v61, v63, v78
	v_mul_f32_e32 v64, v140, v64
	v_mul_f32_e32 v65, v141, v65
	v_mul_f32_e32 v66, v142, v66
	v_mul_f32_e32 v67, v143, v67
	v_mul_f32_e32 v74, v138, v60
	v_mul_f32_e32 v75, v139, v61
	v_cvt_pk_bf16_f32 v60, v64, v65
	v_cvt_pk_bf16_f32 v61, v66, v67
	v_cvt_pk_bf16_f32 v62, v72, v73
	v_cvt_pk_bf16_f32 v63, v74, v75
	global_store_dwordx4 v[76:77], v[60:63], off offset:64
	s_branch .LBB0_619

; #define PG8_LAS __attribute__((address_space(3)))
; __device__ __forceinline__ float fast_sigmoid(float x) { return __builtin_amdgcn_rcpf(1.0f + __builtin_amdgcn_exp2f(-x * LOG2E)); }
;     __device__ __forceinline__ void operator()(const f32x4 (&acc)[2][2][4][2], const Unit& u, int wr, int wc, int fr, int fq) const {
;     ...
;         if (pn == 19) {
;             if (wc != 0) return;
;             f32x4 bfv[2]; bfv[0] = *(const PG8_LAS f32x4*)(gt + 320); bfv[1] = *(const PG8_LAS f32x4*)(gt + 324);
;             float rsv[8];
; #pragma unroll
;             for (int q8 = 0; q8 < 8; ++q8) rsv[q8] = rt[u.ord * BM + (q8 >> 2) * HALF + wr * 64 + (q8 & 3) * 16 + fr];
; #pragma unroll
;             for (int ai = 0; ai < 2; ++ai)
; #pragma unroll
;                 for (int m = 0; m < 4; ++m) { const int row = row0 + ai * HALF + m * 16; const float rs = rsv[ai * 4 + m];
; #pragma unroll
;                     for (int n = 0; n < 2; ++n) { const f32x4 v = acc[ai][0][m][n] * rs; f32x4 o;
;                         if (fq < 3) {
; #pragma unroll
;                             for (int i = 0; i < 4; ++i) o[i] = fast_sigmoid(v[i]);
;                             *(f32x4*)(P.GA + (size_t)row * 24 + 8 * fq + 4 * n) = o;
.LBB0_622:
	v_mov_b32_e32 v60, s82
	v_mov_b32_e32 v61, s83
	v_lshl_add_u32 v62, s67, 10, v155
	ds_read2_b32 v[86:87], v62 offset1:16
	ds_read2_b32 v[82:83], v62 offset0:32 offset1:48
	ds_read2_b32 v[78:79], v62 offset0:128 offset1:144
	ds_read2_b32 v[74:75], v62 offset0:160 offset1:176
	ds_read_b128 v[64:67], v60
	ds_read_b128 v[60:63], v61
	v_mad_i64_i32 v[90:91], s[0:1], v166, s84, 0
	s_waitcnt lgkmcnt(0)
	v_mov_b32_e32 v84, v87
	v_mov_b32_e32 v80, v83
	v_mov_b32_e32 v76, v79
	v_mov_b32_e32 v72, v75
	v_mul_f32_e32 v88, v70, v86
	v_mul_f32_e32 v89, v71, v86
	v_mul_f32_e32 v92, v68, v86
	v_mul_f32_e32 v93, v69, v86
	v_lshl_add_u64 v[68:69], v[156:157], 0, v[90:91]
	s_and_saveexec_b64 s[0:1], s[2:3]
	s_xor_b64 s[6:7], exec, s[0:1]
	s_cbranch_execz .LBB0_624
	v_mul_f32_e32 v70, 0xbfb8aa3b, v92
	v_exp_f32_e32 v70, v70
	v_mul_f32_e32 v71, 0xbfb8aa3b, v93
	v_mul_f32_e32 v73, 0xbfb8aa3b, v89
	v_exp_f32_e32 v71, v71
	v_add_f32_e32 v70, 1.0, v70
	v_rcp_f32_e32 v92, v70
	v_mul_f32_e32 v70, 0xbfb8aa3b, v88
	v_exp_f32_e32 v70, v70
	v_exp_f32_e32 v73, v73
	v_add_f32_e32 v71, 1.0, v71
	v_rcp_f32_e32 v93, v71
	v_add_f32_e32 v70, 1.0, v70
	v_rcp_f32_e32 v94, v70
	v_add_f32_e32 v70, 1.0, v73
	v_rcp_f32_e32 v95, v70
	v_lshl_add_u64 v[70:71], v[156:157], 0, v[90:91]
	global_store_dwordx4 v[70:71], v[92:95], off

; __device__ __forceinline__ float fast_sigmoid(float x) { return __builtin_amdgcn_rcpf(1.0f + __builtin_amdgcn_exp2f(-x * LOG2E)); }
;     __device__ __forceinline__ void operator()(const f32x4 (&acc)[2][2][4][2], const Unit& u, int wr, int wc, int fr, int fq) const {
;     ...
;                 for (int m = 0; m < 4; ++m) { const int row = row0 + ai * HALF + m * 16; const float rs = rsv[ai * 4 + m];
; #pragma unroll
;                     for (int n = 0; n < 2; ++n) { const f32x4 v = acc[ai][0][m][n] * rs; f32x4 o;
;                         if (fq < 3) {
; #pragma unroll
;                             for (int i = 0; i < 4; ++i) o[i] = fast_sigmoid(v[i]);
;                             *(f32x4*)(P.GA + (size_t)row * 24 + 8 * fq + 4 * n) = o;
.LBB0_626:
	s_or_b64 exec, exec, s[6:7]
	v_mov_b32_e32 v87, v86
	v_mov_b32_e32 v88, v86
	v_mov_b32_e32 v89, v86
	v_mul_f32_e32 v88, v58, v88
	v_mul_f32_e32 v89, v59, v89
	v_mul_f32_e32 v86, v56, v86
	v_mul_f32_e32 v87, v57, v87
	s_and_saveexec_b64 s[0:1], s[2:3]
	s_xor_b64 s[6:7], exec, s[0:1]
	s_cbranch_execz .LBB0_628
	v_mul_f32_e32 v56, 0xbfb8aa3b, v86
	v_mul_f32_e32 v57, 0xbfb8aa3b, v87
	v_mul_f32_e32 v58, 0xbfb8aa3b, v88
	v_mul_f32_e32 v59, 0xbfb8aa3b, v89
	v_exp_f32_e32 v56, v56
	v_exp_f32_e32 v57, v57
	v_exp_f32_e32 v58, v58
	v_exp_f32_e32 v59, v59
	v_add_f32_e32 v56, 1.0, v56
	v_add_f32_e32 v57, 1.0, v57
	v_add_f32_e32 v58, 1.0, v58
	v_add_f32_e32 v59, 1.0, v59
	v_rcp_f32_e32 v56, v56
	v_rcp_f32_e32 v57, v57
	v_rcp_f32_e32 v58, v58
	v_rcp_f32_e32 v59, v59

; __device__ __forceinline__ float fast_sigmoid(float x) { return __builtin_amdgcn_rcpf(1.0f + __builtin_amdgcn_exp2f(-x * LOG2E)); }
;     __device__ __forceinline__ void operator()(const f32x4 (&acc)[2][2][4][2], const Unit& u, int wr, int wc, int fr, int fq) const {
;     ...
;                 for (int m = 0; m < 4; ++m) { const int row = row0 + ai * HALF + m * 16; const float rs = rsv[ai * 4 + m];
; #pragma unroll
;                     for (int n = 0; n < 2; ++n) { const f32x4 v = acc[ai][0][m][n] * rs; f32x4 o;
;                         if (fq < 3) {
; #pragma unroll
;                             for (int i = 0; i < 4; ++i) o[i] = fast_sigmoid(v[i]);
;                             *(f32x4*)(P.GA + (size_t)row * 24 + 8 * fq + 4 * n) = o;
.LBB0_630:
	s_or_b64 exec, exec, s[6:7]
	global_store_dwordx4 v[68:69], v[56:59], off offset:16
	v_mul_f32_e32 v70, v52, v84
	v_mul_f32_e32 v71, v53, v84
	s_nop 0
	v_or_b32_e32 v58, 16, v166
	v_mad_i64_i32 v[68:69], s[0:1], v58, s84, 0
	v_mul_f32_e32 v56, v54, v84
	v_mul_f32_e32 v57, v55, v84
	v_lshl_add_u64 v[52:53], v[156:157], 0, v[68:69]
	s_and_saveexec_b64 s[0:1], s[2:3]
	s_xor_b64 s[6:7], exec, s[0:1]
	s_cbranch_execz .LBB0_632
	v_mul_f32_e32 v54, 0xbfb8aa3b, v70
	v_mul_f32_e32 v55, 0xbfb8aa3b, v71
	v_mul_f32_e32 v56, 0xbfb8aa3b, v56
	v_mul_f32_e32 v57, 0xbfb8aa3b, v57
	v_exp_f32_e32 v54, v54
	v_exp_f32_e32 v55, v55
	v_exp_f32_e32 v56, v56
	v_exp_f32_e32 v57, v57
	v_add_f32_e32 v54, 1.0, v54
	v_add_f32_e32 v55, 1.0, v55
	v_add_f32_e32 v56, 1.0, v56
	v_add_f32_e32 v57, 1.0, v57
	v_rcp_f32_e32 v54, v54
	v_rcp_f32_e32 v55, v55
	v_rcp_f32_e32 v56, v56
	v_rcp_f32_e32 v57, v57
	v_lshl_add_u64 v[68:69], v[156:157], 0, v[68:69]
	global_store_dwordx4 v[68:69], v[54:57], off

; __device__ __forceinline__ float fast_sigmoid(float x) { return __builtin_amdgcn_rcpf(1.0f + __builtin_amdgcn_exp2f(-x * LOG2E)); }
;     __device__ __forceinline__ void operator()(const f32x4 (&acc)[2][2][4][2], const Unit& u, int wr, int wc, int fr, int fq) const {
;     ...
;                 for (int m = 0; m < 4; ++m) { const int row = row0 + ai * HALF + m * 16; const float rs = rsv[ai * 4 + m];
; #pragma unroll
;                     for (int n = 0; n < 2; ++n) { const f32x4 v = acc[ai][0][m][n] * rs; f32x4 o;
;                         if (fq < 3) {
; #pragma unroll
;                             for (int i = 0; i < 4; ++i) o[i] = fast_sigmoid(v[i]);
;                             *(f32x4*)(P.GA + (size_t)row * 24 + 8 * fq + 4 * n) = o;
.LBB0_634:
	s_or_b64 exec, exec, s[6:7]
	v_mov_b32_e32 v85, v84
	v_mov_b32_e32 v56, v84
	v_mov_b32_e32 v57, v84
	v_mul_f32_e32 v56, v50, v56
	v_mul_f32_e32 v57, v51, v57
	v_mul_f32_e32 v58, v48, v84
	v_mul_f32_e32 v59, v49, v85
	s_and_saveexec_b64 s[0:1], s[2:3]
	s_xor_b64 s[6:7], exec, s[0:1]
	s_cbranch_execz .LBB0_636
	v_mul_f32_e32 v48, 0xbfb8aa3b, v58
	v_mul_f32_e32 v49, 0xbfb8aa3b, v59
	v_mul_f32_e32 v50, 0xbfb8aa3b, v56
	v_mul_f32_e32 v51, 0xbfb8aa3b, v57
	v_exp_f32_e32 v48, v48
	v_exp_f32_e32 v49, v49
	v_exp_f32_e32 v50, v50
	v_exp_f32_e32 v51, v51
	v_add_f32_e32 v48, 1.0, v48
	v_add_f32_e32 v49, 1.0, v49
	v_add_f32_e32 v50, 1.0, v50
	v_add_f32_e32 v51, 1.0, v51
	v_rcp_f32_e32 v48, v48
	v_rcp_f32_e32 v49, v49
	v_rcp_f32_e32 v50, v50
	v_rcp_f32_e32 v51, v51

; __device__ __forceinline__ float fast_sigmoid(float x) { return __builtin_amdgcn_rcpf(1.0f + __builtin_amdgcn_exp2f(-x * LOG2E)); }
;     __device__ __forceinline__ void operator()(const f32x4 (&acc)[2][2][4][2], const Unit& u, int wr, int wc, int fr, int fq) const {
;     ...
;                 for (int m = 0; m < 4; ++m) { const int row = row0 + ai * HALF + m * 16; const float rs = rsv[ai * 4 + m];
; #pragma unroll
;                     for (int n = 0; n < 2; ++n) { const f32x4 v = acc[ai][0][m][n] * rs; f32x4 o;
;                         if (fq < 3) {
; #pragma unroll
;                             for (int i = 0; i < 4; ++i) o[i] = fast_sigmoid(v[i]);
;                             *(f32x4*)(P.GA + (size_t)row * 24 + 8 * fq + 4 * n) = o;
.LBB0_638:
	s_or_b64 exec, exec, s[6:7]
	global_store_dwordx4 v[52:53], v[48:51], off offset:16
	v_mul_f32_e32 v54, v44, v82
	v_mul_f32_e32 v55, v45, v82
	s_nop 0
	v_or_b32_e32 v50, 32, v166
	v_mad_i64_i32 v[52:53], s[0:1], v50, s84, 0
	v_mul_f32_e32 v48, v46, v82
	v_mul_f32_e32 v49, v47, v82
	v_lshl_add_u64 v[44:45], v[156:157], 0, v[52:53]
	s_and_saveexec_b64 s[0:1], s[2:3]
	s_xor_b64 s[6:7], exec, s[0:1]
	s_cbranch_execz .LBB0_640
	v_mul_f32_e32 v46, 0xbfb8aa3b, v54
	v_mul_f32_e32 v47, 0xbfb8aa3b, v55
	v_mul_f32_e32 v48, 0xbfb8aa3b, v48
	v_mul_f32_e32 v49, 0xbfb8aa3b, v49
	v_exp_f32_e32 v46, v46
	v_exp_f32_e32 v47, v47
	v_exp_f32_e32 v48, v48
	v_exp_f32_e32 v49, v49
	v_add_f32_e32 v46, 1.0, v46
	v_add_f32_e32 v47, 1.0, v47
	v_add_f32_e32 v48, 1.0, v48
	v_add_f32_e32 v49, 1.0, v49
	v_rcp_f32_e32 v46, v46
	v_rcp_f32_e32 v47, v47
	v_rcp_f32_e32 v48, v48
	v_rcp_f32_e32 v49, v49
	v_lshl_add_u64 v[52:53], v[156:157], 0, v[52:53]
	global_store_dwordx4 v[52:53], v[46:49], off

; __device__ __forceinline__ float fast_sigmoid(float x) { return __builtin_amdgcn_rcpf(1.0f + __builtin_amdgcn_exp2f(-x * LOG2E)); }
;     __device__ __forceinline__ void operator()(const f32x4 (&acc)[2][2][4][2], const Unit& u, int wr, int wc, int fr, int fq) const {
;     ...
;                 for (int m = 0; m < 4; ++m) { const int row = row0 + ai * HALF + m * 16; const float rs = rsv[ai * 4 + m];
; #pragma unroll
;                     for (int n = 0; n < 2; ++n) { const f32x4 v = acc[ai][0][m][n] * rs; f32x4 o;
;                         if (fq < 3) {
; #pragma unroll
;                             for (int i = 0; i < 4; ++i) o[i] = fast_sigmoid(v[i]);
;                             *(f32x4*)(P.GA + (size_t)row * 24 + 8 * fq + 4 * n) = o;
.LBB0_642:
	s_or_b64 exec, exec, s[6:7]
	v_mov_b32_e32 v83, v82
	v_mov_b32_e32 v48, v82
	v_mov_b32_e32 v49, v82
	v_mul_f32_e32 v48, v42, v48
	v_mul_f32_e32 v49, v43, v49
	v_mul_f32_e32 v50, v40, v82
	v_mul_f32_e32 v51, v41, v83
	s_and_saveexec_b64 s[0:1], s[2:3]
	s_xor_b64 s[6:7], exec, s[0:1]
	s_cbranch_execz .LBB0_644
	v_mul_f32_e32 v40, 0xbfb8aa3b, v50
	v_mul_f32_e32 v41, 0xbfb8aa3b, v51
	v_mul_f32_e32 v42, 0xbfb8aa3b, v48
	v_mul_f32_e32 v43, 0xbfb8aa3b, v49
	v_exp_f32_e32 v40, v40
	v_exp_f32_e32 v41, v41
	v_exp_f32_e32 v42, v42
	v_exp_f32_e32 v43, v43
	v_add_f32_e32 v40, 1.0, v40
	v_add_f32_e32 v41, 1.0, v41
	v_add_f32_e32 v42, 1.0, v42
	v_add_f32_e32 v43, 1.0, v43
	v_rcp_f32_e32 v40, v40
	v_rcp_f32_e32 v41, v41
	v_rcp_f32_e32 v42, v42
	v_rcp_f32_e32 v43, v43

; __device__ __forceinline__ float fast_sigmoid(float x) { return __builtin_amdgcn_rcpf(1.0f + __builtin_amdgcn_exp2f(-x * LOG2E)); }
;     __device__ __forceinline__ void operator()(const f32x4 (&acc)[2][2][4][2], const Unit& u, int wr, int wc, int fr, int fq) const {
;     ...
;                 for (int m = 0; m < 4; ++m) { const int row = row0 + ai * HALF + m * 16; const float rs = rsv[ai * 4 + m];
; #pragma unroll
;                     for (int n = 0; n < 2; ++n) { const f32x4 v = acc[ai][0][m][n] * rs; f32x4 o;
;                         if (fq < 3) {
; #pragma unroll
;                             for (int i = 0; i < 4; ++i) o[i] = fast_sigmoid(v[i]);
;                             *(f32x4*)(P.GA + (size_t)row * 24 + 8 * fq + 4 * n) = o;
.LBB0_646:
	s_or_b64 exec, exec, s[6:7]
	global_store_dwordx4 v[44:45], v[40:43], off offset:16
	v_mul_f32_e32 v46, v36, v80
	v_mul_f32_e32 v47, v37, v80
	s_nop 0
	v_or_b32_e32 v42, 48, v166
	v_mad_i64_i32 v[44:45], s[0:1], v42, s84, 0
	v_mul_f32_e32 v40, v38, v80
	v_mul_f32_e32 v41, v39, v80
	v_lshl_add_u64 v[36:37], v[156:157], 0, v[44:45]
	s_and_saveexec_b64 s[0:1], s[2:3]
	s_xor_b64 s[6:7], exec, s[0:1]
	s_cbranch_execz .LBB0_648
	v_mul_f32_e32 v38, 0xbfb8aa3b, v46
	v_mul_f32_e32 v39, 0xbfb8aa3b, v47
	v_mul_f32_e32 v40, 0xbfb8aa3b, v40
	v_mul_f32_e32 v41, 0xbfb8aa3b, v41
	v_exp_f32_e32 v38, v38
	v_exp_f32_e32 v39, v39
	v_exp_f32_e32 v40, v40
	v_exp_f32_e32 v41, v41
	v_add_f32_e32 v38, 1.0, v38
	v_add_f32_e32 v39, 1.0, v39
	v_add_f32_e32 v40, 1.0, v40
	v_add_f32_e32 v41, 1.0, v41
	v_rcp_f32_e32 v38, v38
	v_rcp_f32_e32 v39, v39
	v_rcp_f32_e32 v40, v40
	v_rcp_f32_e32 v41, v41
	v_lshl_add_u64 v[44:45], v[156:157], 0, v[44:45]
	global_store_dwordx4 v[44:45], v[38:41], off

; __device__ __forceinline__ float fast_sigmoid(float x) { return __builtin_amdgcn_rcpf(1.0f + __builtin_amdgcn_exp2f(-x * LOG2E)); }
;     __device__ __forceinline__ void operator()(const f32x4 (&acc)[2][2][4][2], const Unit& u, int wr, int wc, int fr, int fq) const {
;     ...
;                 for (int m = 0; m < 4; ++m) { const int row = row0 + ai * HALF + m * 16; const float rs = rsv[ai * 4 + m];
; #pragma unroll
;                     for (int n = 0; n < 2; ++n) { const f32x4 v = acc[ai][0][m][n] * rs; f32x4 o;
;                         if (fq < 3) {
; #pragma unroll
;                             for (int i = 0; i < 4; ++i) o[i] = fast_sigmoid(v[i]);
;                             *(f32x4*)(P.GA + (size_t)row * 24 + 8 * fq + 4 * n) = o;
.LBB0_650:
	s_or_b64 exec, exec, s[6:7]
	v_mov_b32_e32 v81, v80
	v_mov_b32_e32 v40, v80
	v_mov_b32_e32 v41, v80
	v_mul_f32_e32 v40, v34, v40
	v_mul_f32_e32 v41, v35, v41
	v_mul_f32_e32 v42, v32, v80
	v_mul_f32_e32 v43, v33, v81
	s_and_saveexec_b64 s[0:1], s[2:3]
	s_xor_b64 s[6:7], exec, s[0:1]
	s_cbranch_execz .LBB0_652
	v_mul_f32_e32 v32, 0xbfb8aa3b, v42
	v_mul_f32_e32 v33, 0xbfb8aa3b, v43
	v_mul_f32_e32 v34, 0xbfb8aa3b, v40
	v_mul_f32_e32 v35, 0xbfb8aa3b, v41
	v_exp_f32_e32 v32, v32
	v_exp_f32_e32 v33, v33
	v_exp_f32_e32 v34, v34
	v_exp_f32_e32 v35, v35
	v_add_f32_e32 v32, 1.0, v32
	v_add_f32_e32 v33, 1.0, v33
	v_add_f32_e32 v34, 1.0, v34
	v_add_f32_e32 v35, 1.0, v35
	v_rcp_f32_e32 v32, v32
	v_rcp_f32_e32 v33, v33
	v_rcp_f32_e32 v34, v34
	v_rcp_f32_e32 v35, v35

; __device__ __forceinline__ float fast_sigmoid(float x) { return __builtin_amdgcn_rcpf(1.0f + __builtin_amdgcn_exp2f(-x * LOG2E)); }
;     __device__ __forceinline__ void operator()(const f32x4 (&acc)[2][2][4][2], const Unit& u, int wr, int wc, int fr, int fq) const {
;     ...
;                 for (int m = 0; m < 4; ++m) { const int row = row0 + ai * HALF + m * 16; const float rs = rsv[ai * 4 + m];
; #pragma unroll
;                     for (int n = 0; n < 2; ++n) { const f32x4 v = acc[ai][0][m][n] * rs; f32x4 o;
;                         if (fq < 3) {
; #pragma unroll
;                             for (int i = 0; i < 4; ++i) o[i] = fast_sigmoid(v[i]);
;                             *(f32x4*)(P.GA + (size_t)row * 24 + 8 * fq + 4 * n) = o;
.LBB0_654:
	s_or_b64 exec, exec, s[6:7]
	global_store_dwordx4 v[36:37], v[32:35], off offset:16
	v_mul_f32_e32 v38, v28, v78
	v_mul_f32_e32 v39, v29, v78
	s_nop 0
	v_add_u32_e32 v34, 0x80, v166
	v_mad_i64_i32 v[36:37], s[0:1], v34, s84, 0
	v_mul_f32_e32 v32, v30, v78
	v_mul_f32_e32 v33, v31, v78
	v_lshl_add_u64 v[28:29], v[156:157], 0, v[36:37]
	s_and_saveexec_b64 s[0:1], s[2:3]
	s_xor_b64 s[6:7], exec, s[0:1]
	s_cbranch_execz .LBB0_656
	v_mul_f32_e32 v30, 0xbfb8aa3b, v38
	v_mul_f32_e32 v31, 0xbfb8aa3b, v39
	v_mul_f32_e32 v32, 0xbfb8aa3b, v32
	v_mul_f32_e32 v33, 0xbfb8aa3b, v33
	v_exp_f32_e32 v30, v30
	v_exp_f32_e32 v31, v31
	v_exp_f32_e32 v32, v32
	v_exp_f32_e32 v33, v33
	v_add_f32_e32 v30, 1.0, v30
	v_add_f32_e32 v31, 1.0, v31
	v_add_f32_e32 v32, 1.0, v32
	v_add_f32_e32 v33, 1.0, v33
	v_rcp_f32_e32 v30, v30
	v_rcp_f32_e32 v31, v31
	v_rcp_f32_e32 v32, v32
	v_rcp_f32_e32 v33, v33
	v_lshl_add_u64 v[36:37], v[156:157], 0, v[36:37]
	global_store_dwordx4 v[36:37], v[30:33], off

; __device__ __forceinline__ float fast_sigmoid(float x) { return __builtin_amdgcn_rcpf(1.0f + __builtin_amdgcn_exp2f(-x * LOG2E)); }
;     __device__ __forceinline__ void operator()(const f32x4 (&acc)[2][2][4][2], const Unit& u, int wr, int wc, int fr, int fq) const {
;     ...
;                 for (int m = 0; m < 4; ++m) { const int row = row0 + ai * HALF + m * 16; const float rs = rsv[ai * 4 + m];
; #pragma unroll
;                     for (int n = 0; n < 2; ++n) { const f32x4 v = acc[ai][0][m][n] * rs; f32x4 o;
;                         if (fq < 3) {
; #pragma unroll
;                             for (int i = 0; i < 4; ++i) o[i] = fast_sigmoid(v[i]);
;                             *(f32x4*)(P.GA + (size_t)row * 24 + 8 * fq + 4 * n) = o;
.LBB0_658:
	s_or_b64 exec, exec, s[6:7]
	v_mov_b32_e32 v79, v78
	v_mov_b32_e32 v32, v78
	v_mov_b32_e32 v33, v78
	v_mul_f32_e32 v32, v26, v32
	v_mul_f32_e32 v33, v27, v33
	v_mul_f32_e32 v34, v24, v78
	v_mul_f32_e32 v35, v25, v79
	s_and_saveexec_b64 s[0:1], s[2:3]
	s_xor_b64 s[6:7], exec, s[0:1]
	s_cbranch_execz .LBB0_660
	v_mul_f32_e32 v24, 0xbfb8aa3b, v34
	v_mul_f32_e32 v25, 0xbfb8aa3b, v35
	v_mul_f32_e32 v26, 0xbfb8aa3b, v32
	v_mul_f32_e32 v27, 0xbfb8aa3b, v33
	v_exp_f32_e32 v24, v24
	v_exp_f32_e32 v25, v25
	v_exp_f32_e32 v26, v26
	v_exp_f32_e32 v27, v27
	v_add_f32_e32 v24, 1.0, v24
	v_add_f32_e32 v25, 1.0, v25
	v_add_f32_e32 v26, 1.0, v26
	v_add_f32_e32 v27, 1.0, v27
	v_rcp_f32_e32 v24, v24
	v_rcp_f32_e32 v25, v25
	v_rcp_f32_e32 v26, v26
	v_rcp_f32_e32 v27, v27

; __device__ __forceinline__ float fast_sigmoid(float x) { return __builtin_amdgcn_rcpf(1.0f + __builtin_amdgcn_exp2f(-x * LOG2E)); }
;     __device__ __forceinline__ void operator()(const f32x4 (&acc)[2][2][4][2], const Unit& u, int wr, int wc, int fr, int fq) const {
;     ...
;                 for (int m = 0; m < 4; ++m) { const int row = row0 + ai * HALF + m * 16; const float rs = rsv[ai * 4 + m];
; #pragma unroll
;                     for (int n = 0; n < 2; ++n) { const f32x4 v = acc[ai][0][m][n] * rs; f32x4 o;
;                         if (fq < 3) {
; #pragma unroll
;                             for (int i = 0; i < 4; ++i) o[i] = fast_sigmoid(v[i]);
;                             *(f32x4*)(P.GA + (size_t)row * 24 + 8 * fq + 4 * n) = o;
.LBB0_662:
	s_or_b64 exec, exec, s[6:7]
	global_store_dwordx4 v[28:29], v[24:27], off offset:16
	v_mul_f32_e32 v30, v20, v76
	v_mul_f32_e32 v31, v21, v76
	s_nop 0
	v_add_u32_e32 v26, 0x90, v166
	v_mad_i64_i32 v[28:29], s[0:1], v26, s84, 0
	v_mul_f32_e32 v24, v22, v76
	v_mul_f32_e32 v25, v23, v76
	v_lshl_add_u64 v[20:21], v[156:157], 0, v[28:29]
	s_and_saveexec_b64 s[0:1], s[2:3]
	s_xor_b64 s[6:7], exec, s[0:1]
	s_cbranch_execz .LBB0_664
	v_mul_f32_e32 v22, 0xbfb8aa3b, v30
	v_mul_f32_e32 v23, 0xbfb8aa3b, v31
	v_mul_f32_e32 v24, 0xbfb8aa3b, v24
	v_mul_f32_e32 v25, 0xbfb8aa3b, v25
	v_exp_f32_e32 v22, v22
	v_exp_f32_e32 v23, v23
	v_exp_f32_e32 v24, v24
	v_exp_f32_e32 v25, v25
	v_add_f32_e32 v22, 1.0, v22
	v_add_f32_e32 v23, 1.0, v23
	v_add_f32_e32 v24, 1.0, v24
	v_add_f32_e32 v25, 1.0, v25
	v_rcp_f32_e32 v22, v22
	v_rcp_f32_e32 v23, v23
	v_rcp_f32_e32 v24, v24
	v_rcp_f32_e32 v25, v25
	v_lshl_add_u64 v[28:29], v[156:157], 0, v[28:29]
	global_store_dwordx4 v[28:29], v[22:25], off

; __device__ __forceinline__ float fast_sigmoid(float x) { return __builtin_amdgcn_rcpf(1.0f + __builtin_amdgcn_exp2f(-x * LOG2E)); }
;     __device__ __forceinline__ void operator()(const f32x4 (&acc)[2][2][4][2], const Unit& u, int wr, int wc, int fr, int fq) const {
;     ...
;                 for (int m = 0; m < 4; ++m) { const int row = row0 + ai * HALF + m * 16; const float rs = rsv[ai * 4 + m];
; #pragma unroll
;                     for (int n = 0; n < 2; ++n) { const f32x4 v = acc[ai][0][m][n] * rs; f32x4 o;
;                         if (fq < 3) {
; #pragma unroll
;                             for (int i = 0; i < 4; ++i) o[i] = fast_sigmoid(v[i]);
;                             *(f32x4*)(P.GA + (size_t)row * 24 + 8 * fq + 4 * n) = o;
.LBB0_666:
	s_or_b64 exec, exec, s[6:7]
	v_mov_b32_e32 v77, v76
	v_mov_b32_e32 v24, v76
	v_mov_b32_e32 v25, v76
	v_mul_f32_e32 v24, v18, v24
	v_mul_f32_e32 v25, v19, v25
	v_mul_f32_e32 v26, v16, v76
	v_mul_f32_e32 v27, v17, v77
	s_and_saveexec_b64 s[0:1], s[2:3]
	s_xor_b64 s[6:7], exec, s[0:1]
	s_cbranch_execz .LBB0_668
	v_mul_f32_e32 v16, 0xbfb8aa3b, v26
	v_mul_f32_e32 v17, 0xbfb8aa3b, v27
	v_mul_f32_e32 v18, 0xbfb8aa3b, v24
	v_mul_f32_e32 v19, 0xbfb8aa3b, v25
	v_exp_f32_e32 v16, v16
	v_exp_f32_e32 v17, v17
	v_exp_f32_e32 v18, v18
	v_exp_f32_e32 v19, v19
	v_add_f32_e32 v16, 1.0, v16
	v_add_f32_e32 v17, 1.0, v17
	v_add_f32_e32 v18, 1.0, v18
	v_add_f32_e32 v19, 1.0, v19
	v_rcp_f32_e32 v16, v16
	v_rcp_f32_e32 v17, v17
	v_rcp_f32_e32 v18, v18
	v_rcp_f32_e32 v19, v19

; __device__ __forceinline__ float fast_sigmoid(float x) { return __builtin_amdgcn_rcpf(1.0f + __builtin_amdgcn_exp2f(-x * LOG2E)); }
;     __device__ __forceinline__ void operator()(const f32x4 (&acc)[2][2][4][2], const Unit& u, int wr, int wc, int fr, int fq) const {
;     ...
;                 for (int m = 0; m < 4; ++m) { const int row = row0 + ai * HALF + m * 16; const float rs = rsv[ai * 4 + m];
; #pragma unroll
;                     for (int n = 0; n < 2; ++n) { const f32x4 v = acc[ai][0][m][n] * rs; f32x4 o;
;                         if (fq < 3) {
; #pragma unroll
;                             for (int i = 0; i < 4; ++i) o[i] = fast_sigmoid(v[i]);
;                             *(f32x4*)(P.GA + (size_t)row * 24 + 8 * fq + 4 * n) = o;
.LBB0_670:
	s_or_b64 exec, exec, s[6:7]
	global_store_dwordx4 v[20:21], v[16:19], off offset:16
	v_mul_f32_e32 v22, v12, v74
	v_mul_f32_e32 v23, v13, v74
	s_nop 0
	v_add_u32_e32 v18, 0xa0, v166
	v_mad_i64_i32 v[20:21], s[0:1], v18, s84, 0
	v_mul_f32_e32 v16, v14, v74
	v_mul_f32_e32 v17, v15, v74
	v_lshl_add_u64 v[12:13], v[156:157], 0, v[20:21]
	s_and_saveexec_b64 s[0:1], s[2:3]
	s_xor_b64 s[6:7], exec, s[0:1]
	s_cbranch_execz .LBB0_672
	v_mul_f32_e32 v14, 0xbfb8aa3b, v22
	v_mul_f32_e32 v15, 0xbfb8aa3b, v23
	v_mul_f32_e32 v16, 0xbfb8aa3b, v16
	v_mul_f32_e32 v17, 0xbfb8aa3b, v17
	v_exp_f32_e32 v14, v14
	v_exp_f32_e32 v15, v15
	v_exp_f32_e32 v16, v16
	v_exp_f32_e32 v17, v17
	v_add_f32_e32 v14, 1.0, v14
	v_add_f32_e32 v15, 1.0, v15
	v_add_f32_e32 v16, 1.0, v16
	v_add_f32_e32 v17, 1.0, v17
	v_rcp_f32_e32 v14, v14
	v_rcp_f32_e32 v15, v15
	v_rcp_f32_e32 v16, v16
	v_rcp_f32_e32 v17, v17
	v_lshl_add_u64 v[20:21], v[156:157], 0, v[20:21]
	global_store_dwordx4 v[20:21], v[14:17], off

; __device__ __forceinline__ float fast_sigmoid(float x) { return __builtin_amdgcn_rcpf(1.0f + __builtin_amdgcn_exp2f(-x * LOG2E)); }
;     __device__ __forceinline__ void operator()(const f32x4 (&acc)[2][2][4][2], const Unit& u, int wr, int wc, int fr, int fq) const {
;     ...
;                 for (int m = 0; m < 4; ++m) { const int row = row0 + ai * HALF + m * 16; const float rs = rsv[ai * 4 + m];
; #pragma unroll
;                     for (int n = 0; n < 2; ++n) { const f32x4 v = acc[ai][0][m][n] * rs; f32x4 o;
;                         if (fq < 3) {
; #pragma unroll
;                             for (int i = 0; i < 4; ++i) o[i] = fast_sigmoid(v[i]);
;                             *(f32x4*)(P.GA + (size_t)row * 24 + 8 * fq + 4 * n) = o;
.LBB0_674:
	s_or_b64 exec, exec, s[6:7]
	v_mov_b32_e32 v75, v74
	v_mov_b32_e32 v16, v74
	v_mov_b32_e32 v17, v74
	v_mul_f32_e32 v16, v10, v16
	v_mul_f32_e32 v17, v11, v17
	v_mul_f32_e32 v18, v8, v74
	v_mul_f32_e32 v19, v9, v75
	s_and_saveexec_b64 s[0:1], s[2:3]
	s_xor_b64 s[6:7], exec, s[0:1]
	s_cbranch_execz .LBB0_676
	v_mul_f32_e32 v8, 0xbfb8aa3b, v18
	v_mul_f32_e32 v9, 0xbfb8aa3b, v19
	v_mul_f32_e32 v10, 0xbfb8aa3b, v16
	v_mul_f32_e32 v11, 0xbfb8aa3b, v17
	v_exp_f32_e32 v8, v8
	v_exp_f32_e32 v9, v9
	v_exp_f32_e32 v10, v10
	v_exp_f32_e32 v11, v11
	v_add_f32_e32 v8, 1.0, v8
	v_add_f32_e32 v9, 1.0, v9
	v_add_f32_e32 v10, 1.0, v10
	v_add_f32_e32 v11, 1.0, v11
	v_rcp_f32_e32 v8, v8
	v_rcp_f32_e32 v9, v9
	v_rcp_f32_e32 v10, v10
	v_rcp_f32_e32 v11, v11

; __device__ __forceinline__ float fast_sigmoid(float x) { return __builtin_amdgcn_rcpf(1.0f + __builtin_amdgcn_exp2f(-x * LOG2E)); }
;     __device__ __forceinline__ void operator()(const f32x4 (&acc)[2][2][4][2], const Unit& u, int wr, int wc, int fr, int fq) const {
;     ...
;                 for (int m = 0; m < 4; ++m) { const int row = row0 + ai * HALF + m * 16; const float rs = rsv[ai * 4 + m];
; #pragma unroll
;                     for (int n = 0; n < 2; ++n) { const f32x4 v = acc[ai][0][m][n] * rs; f32x4 o;
;                         if (fq < 3) {
; #pragma unroll
;                             for (int i = 0; i < 4; ++i) o[i] = fast_sigmoid(v[i]);
;                             *(f32x4*)(P.GA + (size_t)row * 24 + 8 * fq + 4 * n) = o;
.LBB0_678:
	s_or_b64 exec, exec, s[6:7]
	global_store_dwordx4 v[12:13], v[8:11], off offset:16
	v_mul_f32_e32 v14, v4, v72
	v_mul_f32_e32 v15, v5, v72
	s_nop 0
	v_add_u32_e32 v10, 0xb0, v166
	v_mad_i64_i32 v[12:13], s[0:1], v10, s84, 0
	v_mul_f32_e32 v8, v6, v72
	v_mul_f32_e32 v9, v7, v72
	v_lshl_add_u64 v[4:5], v[156:157], 0, v[12:13]
	s_and_saveexec_b64 s[0:1], s[2:3]
	s_xor_b64 s[6:7], exec, s[0:1]
	s_cbranch_execz .LBB0_680
	v_mul_f32_e32 v6, 0xbfb8aa3b, v14
	v_mul_f32_e32 v7, 0xbfb8aa3b, v15
	v_mul_f32_e32 v8, 0xbfb8aa3b, v8
	v_mul_f32_e32 v9, 0xbfb8aa3b, v9
	v_exp_f32_e32 v6, v6
	v_exp_f32_e32 v7, v7
	v_exp_f32_e32 v8, v8
	v_exp_f32_e32 v9, v9
	v_add_f32_e32 v6, 1.0, v6
	v_add_f32_e32 v7, 1.0, v7
	v_add_f32_e32 v8, 1.0, v8
	v_add_f32_e32 v9, 1.0, v9
	v_rcp_f32_e32 v6, v6
	v_rcp_f32_e32 v7, v7
	v_rcp_f32_e32 v8, v8
	v_rcp_f32_e32 v9, v9
	v_lshl_add_u64 v[12:13], v[156:157], 0, v[12:13]
	global_store_dwordx4 v[12:13], v[6:9], off

; __device__ __forceinline__ float fast_sigmoid(float x) { return __builtin_amdgcn_rcpf(1.0f + __builtin_amdgcn_exp2f(-x * LOG2E)); }
;     __device__ __forceinline__ void operator()(const f32x4 (&acc)[2][2][4][2], const Unit& u, int wr, int wc, int fr, int fq) const {
;     ...
;                 for (int m = 0; m < 4; ++m) { const int row = row0 + ai * HALF + m * 16; const float rs = rsv[ai * 4 + m];
; #pragma unroll
;                     for (int n = 0; n < 2; ++n) { const f32x4 v = acc[ai][0][m][n] * rs; f32x4 o;
;                         if (fq < 3) {
; #pragma unroll
;                             for (int i = 0; i < 4; ++i) o[i] = fast_sigmoid(v[i]);
;                             *(f32x4*)(P.GA + (size_t)row * 24 + 8 * fq + 4 * n) = o;
.LBB0_682:
	s_or_b64 exec, exec, s[6:7]
	v_mov_b32_e32 v73, v72
	v_mov_b32_e32 v8, v72
	v_mov_b32_e32 v9, v72
	v_mul_f32_e32 v8, v2, v8
	v_mul_f32_e32 v9, v3, v9
	v_mul_f32_e32 v10, v0, v72
	v_mul_f32_e32 v11, v1, v73
	s_and_saveexec_b64 s[0:1], s[2:3]
	s_xor_b64 s[6:7], exec, s[0:1]
	s_cbranch_execz .LBB0_684
	v_mul_f32_e32 v0, 0xbfb8aa3b, v10
	v_mul_f32_e32 v1, 0xbfb8aa3b, v11
	v_mul_f32_e32 v2, 0xbfb8aa3b, v8
	v_mul_f32_e32 v3, 0xbfb8aa3b, v9
	v_exp_f32_e32 v0, v0
	v_exp_f32_e32 v1, v1
	v_exp_f32_e32 v2, v2
	v_exp_f32_e32 v3, v3
	v_add_f32_e32 v0, 1.0, v0
	v_add_f32_e32 v1, 1.0, v1
	v_add_f32_e32 v2, 1.0, v2
	v_add_f32_e32 v3, 1.0, v3
	v_rcp_f32_e32 v0, v0
	v_rcp_f32_e32 v1, v1
	v_rcp_f32_e32 v2, v2
	v_rcp_f32_e32 v3, v3

; __device__ __forceinline__ float bf_lo(unsigned w) { return __uint_as_float(w << 16); }
; __device__ __forceinline__ float bf_hi(unsigned w) { return __uint_as_float(w & 0xffff0000u); }
;     __device__ __forceinline__ static float e2(float x) { return __builtin_amdgcn_exp2f(fminf(fmaxf(-x * LOG2E, -60.f), 60.f)); }
;     __device__ __forceinline__ void mid(f32x4 (&acc)[2][2][4][2], const Unit& u, int wr, int wc, int fr_in, int fq) const {
;     ...
;             u32x4 ga[4][2], gb[4][2];
; #pragma unroll
;             for (int m = 0; m < 4; ++m)
; #pragma unroll
;                 for (int bj = 0; bj < 2; ++bj) { const bf16_t* gp = gate + (size_t)(row0 + ai * HALF + m * 16) * 2048 + col0 + bj * HALF; ga[m][bj] = *(const u32x4*)gp; gb[m][bj] = *(const u32x4*)(gp + 1024); }
;             asm volatile("" ::: "memory");
; #pragma unroll
;             for (int m = 0; m < 4; ++m)
; #pragma unroll
;                 for (int bj = 0; bj < 2; ++bj)
; #pragma unroll
;                     for (int q = 0; q < 4; ++q) {
;                         const float r0 = (1.0f + e2(bf_lo(gb[m][bj][q]))) * __builtin_amdgcn_rcpf(1.0f + e2(bf_lo(ga[m][bj][q]))), r1 = (1.0f + e2(bf_hi(gb[m][bj][q]))) * __builtin_amdgcn_rcpf(1.0f + e2(bf_hi(ga[m][bj][q])));
;                         acc[ai][bj][m][q >> 1][(2 * q) & 3] *= r0; acc[ai][bj][m][q >> 1][(2 * q + 1) & 3] *= r1; }
.LBB0_1066:
	v_mov_b32_e32 v1, v212
	s_nop 0
	v_add_u32_e32 v2, s77, v1
	v_ashrrev_i32_e32 v3, 31, v2
	v_lshlrev_b64 v[2:3], 12, v[2:3]
	v_lshl_add_u64 v[2:3], v[206:207], 0, v[2:3]
	global_load_dwordx4 v[218:221], v[2:3], off offset:2048
	global_load_dwordx4 v[222:225], v[2:3], off
	global_load_dwordx4 v[180:183], v[2:3], off offset:256
	global_load_dwordx4 v[184:187], v[2:3], off offset:2304
	v_add_co_u32_e32 v138, vcc, 0x10000, v2
	v_lshl_add_u64 v[136:137], v[2:3], 0, s[16:17]
	s_nop 0
	v_addc_co_u32_e32 v139, vcc, 0, v3, vcc
	v_add_co_u32_e32 v146, vcc, 0x20000, v2
	v_lshl_add_u64 v[144:145], v[2:3], 0, s[18:19]
	s_nop 0
	v_addc_co_u32_e32 v147, vcc, 0, v3, vcc
	v_lshl_add_u64 v[226:227], v[2:3], 0, s[20:21]
	global_load_dwordx4 v[172:175], v[136:137], off offset:2048
	global_load_dwordx4 v[164:167], v[136:137], off offset:256
	global_load_dwordx4 v[156:159], v[144:145], off offset:2048
	global_load_dwordx4 v[148:151], v[144:145], off offset:256
	global_load_dwordx4 v[140:143], v[226:227], off offset:2048
	global_load_dwordx4 v[132:135], v[226:227], off offset:256
	global_load_dwordx4 v[176:179], v[138:139], off
	global_load_dwordx4 v[168:171], v[136:137], off offset:2304
	v_add_co_u32_e32 v136, vcc, 0x30000, v2
	global_load_dwordx4 v[160:163], v[146:147], off
	global_load_dwordx4 v[152:155], v[144:145], off offset:2304
	v_addc_co_u32_e32 v137, vcc, 0, v3, vcc
	global_load_dwordx4 v[144:147], v[136:137], off
	s_nop 0
	global_load_dwordx4 v[136:139], v[226:227], off offset:2304
	s_waitcnt vmcnt(0)
	v_lshlrev_b32_e32 v1, 16, v218
	v_lshlrev_b32_e32 v226, 16, v222
	v_and_b32_e32 v218, 0xffff0000, v218
	v_and_b32_e32 v222, 0xffff0000, v222
	v_lshlrev_b32_e32 v227, 16, v219
	v_lshlrev_b32_e32 v228, 16, v223
	v_and_b32_e32 v219, 0xffff0000, v219
	v_and_b32_e32 v223, 0xffff0000, v223
	v_mul_f32_e32 v1, 0xbfb8aa3b, v1
	v_mul_f32_e32 v226, 0xbfb8aa3b, v226
	v_mul_f32_e32 v218, 0xbfb8aa3b, v218
	v_mul_f32_e32 v222, 0xbfb8aa3b, v222
	v_mul_f32_e32 v227, 0xbfb8aa3b, v227
	v_mul_f32_e32 v228, 0xbfb8aa3b, v228
	v_mul_f32_e32 v219, 0xbfb8aa3b, v219
	v_mul_f32_e32 v223, 0xbfb8aa3b, v223
	v_med3_f32 v1, v1, s69, v217
	v_med3_f32 v226, v226, s69, v217
	v_med3_f32 v232, v218, s69, v217
	v_med3_f32 v222, v222, s69, v217
	v_med3_f32 v227, v227, s69, v217
	v_med3_f32 v228, v228, s69, v217
	v_med3_f32 v233, v219, s69, v217
	v_med3_f32 v234, v223, s69, v217
	v_exp_f32_e32 v218, v1
	v_exp_f32_e32 v1, v226
	v_exp_f32_e32 v219, v232
	v_exp_f32_e32 v232, v222
	v_lshlrev_b32_e32 v229, 16, v220
	v_exp_f32_e32 v222, v227
	v_exp_f32_e32 v227, v228
	v_exp_f32_e32 v228, v234
	v_lshlrev_b32_e32 v231, 16, v224
	v_mul_f32_e32 v229, 0xbfb8aa3b, v229
	v_mul_f32_e32 v231, 0xbfb8aa3b, v231
	v_med3_f32 v229, v229, s69, v217
	v_med3_f32 v231, v231, s69, v217
	v_exp_f32_e32 v226, v229
	v_add_f32_e32 v1, 1.0, v1
	v_add_f32_e32 v229, 1.0, v232
	v_exp_f32_e32 v223, v233
	v_exp_f32_e32 v231, v231
	v_add_f32_e32 v233, 1.0, v228
	v_rcp_f32_e32 v228, v1
	v_rcp_f32_e32 v229, v229
	v_and_b32_e32 v224, 0xffff0000, v224
	v_pk_add_f32 v[218:219], v[218:219], 1.0 op_sel_hi:[1,0]
	v_and_b32_e32 v220, 0xffff0000, v220
	v_mul_f32_e32 v224, 0xbfb8aa3b, v224
	v_add_f32_e32 v1, 1.0, v231
	v_mul_f32_e32 v218, v218, v228
	v_mul_f32_e32 v219, v219, v229
	v_rcp_f32_e32 v234, v1
	v_mul_f32_e32 v128, v128, v218
	v_mul_f32_e32 v129, v129, v219
	v_med3_f32 v1, v224, s69, v217
	v_mul_f32_e32 v218, 0xbfb8aa3b, v220
	v_add_f32_e32 v227, 1.0, v227
	v_exp_f32_e32 v1, v1
	v_med3_f32 v218, v218, s69, v217
	v_rcp_f32_e32 v232, v227
	v_exp_f32_e32 v227, v218
	v_lshlrev_b32_e32 v218, 16, v225
	v_mul_f32_e32 v218, 0xbfb8aa3b, v218
	v_med3_f32 v218, v218, s69, v217
	v_add_f32_e32 v1, 1.0, v1
	v_exp_f32_e32 v219, v218
	v_rcp_f32_e32 v235, v1
	v_lshlrev_b32_e32 v1, 16, v221
	v_and_b32_e32 v220, 0xffff0000, v225
	v_mul_f32_e32 v1, 0xbfb8aa3b, v1
	v_mul_f32_e32 v220, 0xbfb8aa3b, v220
	v_med3_f32 v1, v1, s69, v217
	v_med3_f32 v220, v220, s69, v217
	v_exp_f32_e32 v218, v1
	v_add_f32_e32 v1, 1.0, v219
	v_and_b32_e32 v219, 0xffff0000, v221
	v_exp_f32_e32 v221, v220
	v_mul_f32_e32 v219, 0xbfb8aa3b, v219
	v_med3_f32 v219, v219, s69, v217
	v_exp_f32_e32 v219, v219
	v_rcp_f32_e32 v220, v1
	v_add_f32_e32 v1, 1.0, v221
	v_rcp_f32_e32 v221, v1
	v_pk_add_f32 v[218:219], v[218:219], 1.0 op_sel_hi:[1,0]
	v_lshlrev_b32_e32 v1, 16, v184
	v_mul_f32_e32 v1, 0xbfb8aa3b, v1
	v_mul_f32_e32 v218, v218, v220
	v_mul_f32_e32 v219, v219, v221
	v_med3_f32 v1, v1, s69, v217
	v_mul_f32_e32 v126, v126, v218
	v_mul_f32_e32 v127, v127, v219
	v_lshlrev_b32_e32 v218, 16, v180
	v_mul_f32_e32 v218, 0xbfb8aa3b, v218
	v_med3_f32 v218, v218, s69, v217
	v_exp_f32_e32 v219, v218
	v_and_b32_e32 v180, 0xffff0000, v180
	v_mul_f32_e32 v180, 0xbfb8aa3b, v180
	v_med3_f32 v180, v180, s69, v217
	v_exp_f32_e32 v218, v1
	v_add_f32_e32 v1, 1.0, v219
	v_exp_f32_e32 v180, v180
	v_rcp_f32_e32 v220, v1
	v_and_b32_e32 v1, 0xffff0000, v184
	v_mul_f32_e32 v1, 0xbfb8aa3b, v1
	v_med3_f32 v1, v1, s69, v217
	v_exp_f32_e32 v219, v1
	v_add_f32_e32 v1, 1.0, v180
	v_lshlrev_b32_e32 v180, 16, v181
	v_mul_f32_e32 v180, 0xbfb8aa3b, v180
	v_med3_f32 v180, v180, s69, v217
	v_exp_f32_e32 v184, v180
	v_rcp_f32_e32 v221, v1
	v_lshlrev_b32_e32 v1, 16, v185
	v_and_b32_e32 v181, 0xffff0000, v181
	v_mul_f32_e32 v1, 0xbfb8aa3b, v1
	v_mul_f32_e32 v181, 0xbfb8aa3b, v181
	v_med3_f32 v1, v1, s69, v217
	v_med3_f32 v181, v181, s69, v217
	v_exp_f32_e32 v180, v1
	v_add_f32_e32 v1, 1.0, v184
	v_and_b32_e32 v184, 0xffff0000, v185
	v_exp_f32_e32 v185, v181
	v_mul_f32_e32 v184, 0xbfb8aa3b, v184
	v_med3_f32 v181, v184, s69, v217
	v_exp_f32_e32 v181, v181
	v_rcp_f32_e32 v184, v1
	v_add_f32_e32 v1, 1.0, v185
; __device__ __forceinline__ float bf_lo(unsigned w) { return __uint_as_float(w << 16); }
; __device__ __forceinline__ float bf_hi(unsigned w) { return __uint_as_float(w & 0xffff0000u); }
;     __device__ __forceinline__ static float e2(float x) { return __builtin_amdgcn_exp2f(fminf(fmaxf(-x * LOG2E, -60.f), 60.f)); }
;     __device__ __forceinline__ void mid(f32x4 (&acc)[2][2][4][2], const Unit& u, int wr, int wc, int fr_in, int fq) const {
;     ...
;             u32x4 ga[4][2], gb[4][2];
; #pragma unroll
;             for (int m = 0; m < 4; ++m)
; #pragma unroll
;                 for (int bj = 0; bj < 2; ++bj) { const bf16_t* gp = gate + (size_t)(row0 + ai * HALF + m * 16) * 2048 + col0 + bj * HALF; ga[m][bj] = *(const u32x4*)gp; gb[m][bj] = *(const u32x4*)(gp + 1024); }
;             asm volatile("" ::: "memory");
; #pragma unroll
;             for (int m = 0; m < 4; ++m)
; #pragma unroll
;                 for (int bj = 0; bj < 2; ++bj)
; #pragma unroll
;                     for (int q = 0; q < 4; ++q) {
;                         const float r0 = (1.0f + e2(bf_lo(gb[m][bj][q]))) * __builtin_amdgcn_rcpf(1.0f + e2(bf_lo(ga[m][bj][q]))), r1 = (1.0f + e2(bf_hi(gb[m][bj][q]))) * __builtin_amdgcn_rcpf(1.0f + e2(bf_hi(ga[m][bj][q])));
;                         acc[ai][bj][m][q >> 1][(2 * q) & 3] *= r0; acc[ai][bj][m][q >> 1][(2 * q + 1) & 3] *= r1; }
	v_rcp_f32_e32 v185, v1
	v_pk_add_f32 v[180:181], v[180:181], 1.0 op_sel_hi:[1,0]
	v_lshlrev_b32_e32 v1, 16, v186
	v_mul_f32_e32 v1, 0xbfb8aa3b, v1
	v_mul_f32_e32 v180, v180, v184
	v_mul_f32_e32 v181, v181, v185
	v_med3_f32 v1, v1, s69, v217
	v_mul_f32_e32 v122, v122, v180
	v_mul_f32_e32 v123, v123, v181
	v_lshlrev_b32_e32 v180, 16, v182
	v_mul_f32_e32 v180, 0xbfb8aa3b, v180
	v_med3_f32 v180, v180, s69, v217
	v_exp_f32_e32 v181, v180
	v_exp_f32_e32 v180, v1
	v_rcp_f32_e32 v233, v233
	v_pk_add_f32 v[222:223], v[222:223], 1.0 op_sel_hi:[1,0]
	v_add_f32_e32 v1, 1.0, v181
	v_and_b32_e32 v181, 0xffff0000, v182
	v_mul_f32_e32 v181, 0xbfb8aa3b, v181
	v_med3_f32 v181, v181, s69, v217
	v_exp_f32_e32 v182, v181
	v_rcp_f32_e32 v184, v1
	v_and_b32_e32 v1, 0xffff0000, v186
	v_mul_f32_e32 v1, 0xbfb8aa3b, v1
	v_med3_f32 v1, v1, s69, v217
	v_exp_f32_e32 v181, v1
	v_add_f32_e32 v1, 1.0, v182
	v_lshlrev_b32_e32 v182, 16, v183
	v_mul_f32_e32 v182, 0xbfb8aa3b, v182
	v_med3_f32 v182, v182, s69, v217
	v_exp_f32_e32 v186, v182
	v_rcp_f32_e32 v185, v1
	v_lshlrev_b32_e32 v1, 16, v187
	v_and_b32_e32 v183, 0xffff0000, v183
	v_mul_f32_e32 v1, 0xbfb8aa3b, v1
	v_mul_f32_e32 v183, 0xbfb8aa3b, v183
	v_med3_f32 v1, v1, s69, v217
	v_med3_f32 v183, v183, s69, v217
	v_exp_f32_e32 v182, v1
	v_add_f32_e32 v1, 1.0, v186
	v_and_b32_e32 v186, 0xffff0000, v187
	v_exp_f32_e32 v187, v183
	v_pk_add_f32 v[180:181], v[180:181], 1.0 op_sel_hi:[1,0]
	v_mul_f32_e32 v186, 0xbfb8aa3b, v186
	v_mul_f32_e32 v180, v180, v184
	v_mul_f32_e32 v181, v181, v185
	v_med3_f32 v183, v186, s69, v217
	v_mul_f32_e32 v116, v116, v180
	v_mul_f32_e32 v117, v117, v181
	v_lshlrev_b32_e32 v180, 16, v176
	v_mul_f32_e32 v180, 0xbfb8aa3b, v180
	v_exp_f32_e32 v183, v183
	v_rcp_f32_e32 v186, v1
	v_add_f32_e32 v1, 1.0, v187
	v_med3_f32 v180, v180, s69, v217
	v_rcp_f32_e32 v187, v1
	v_exp_f32_e32 v181, v180
	v_lshlrev_b32_e32 v1, 16, v172
	v_mul_f32_e32 v1, 0xbfb8aa3b, v1
	v_pk_add_f32 v[182:183], v[182:183], 1.0 op_sel_hi:[1,0]
	v_med3_f32 v1, v1, s69, v217
	v_mul_f32_e32 v182, v182, v186
	v_mul_f32_e32 v183, v183, v187
	v_exp_f32_e32 v180, v1
	v_add_f32_e32 v1, 1.0, v181
	v_mul_f32_e32 v118, v118, v182
	v_mul_f32_e32 v119, v119, v183
	v_rcp_f32_e32 v182, v1
	v_and_b32_e32 v1, 0xffff0000, v172
	v_and_b32_e32 v172, 0xffff0000, v176
	v_mul_f32_e32 v172, 0xbfb8aa3b, v172
	v_med3_f32 v172, v172, s69, v217
	v_exp_f32_e32 v172, v172
	v_mul_f32_e32 v1, 0xbfb8aa3b, v1
	v_med3_f32 v1, v1, s69, v217
	v_exp_f32_e32 v181, v1
	v_add_f32_e32 v1, 1.0, v172
	v_lshlrev_b32_e32 v172, 16, v177
	v_mul_f32_e32 v172, 0xbfb8aa3b, v172
	v_med3_f32 v172, v172, s69, v217
	v_exp_f32_e32 v176, v172
	v_rcp_f32_e32 v183, v1
	v_lshlrev_b32_e32 v1, 16, v173
	v_mul_f32_e32 v1, 0xbfb8aa3b, v1
	v_med3_f32 v1, v1, s69, v217
	v_exp_f32_e32 v172, v1
	v_add_f32_e32 v1, 1.0, v176
	v_and_b32_e32 v176, 0xffff0000, v177
	v_mul_f32_e32 v176, 0xbfb8aa3b, v176
	v_med3_f32 v176, v176, s69, v217
	v_exp_f32_e32 v177, v176
	v_and_b32_e32 v173, 0xffff0000, v173
	v_mul_f32_e32 v173, 0xbfb8aa3b, v173
	v_med3_f32 v173, v173, s69, v217
	v_exp_f32_e32 v173, v173
	v_rcp_f32_e32 v176, v1
	v_add_f32_e32 v1, 1.0, v177
	v_rcp_f32_e32 v177, v1
	v_pk_add_f32 v[172:173], v[172:173], 1.0 op_sel_hi:[1,0]
	v_lshlrev_b32_e32 v1, 16, v174
	v_mul_f32_e32 v1, 0xbfb8aa3b, v1
	v_mul_f32_e32 v172, v172, v176
	v_mul_f32_e32 v173, v173, v177
	v_med3_f32 v1, v1, s69, v217
	v_mul_f32_e32 v114, v114, v172
	v_mul_f32_e32 v115, v115, v173
	v_lshlrev_b32_e32 v172, 16, v178
	v_mul_f32_e32 v172, 0xbfb8aa3b, v172
	v_med3_f32 v172, v172, s69, v217
	v_exp_f32_e32 v173, v172
	v_exp_f32_e32 v172, v1
	v_mul_f32_e32 v222, v222, v232
	v_mul_f32_e32 v223, v223, v233
	v_pk_add_f32 v[218:219], v[218:219], 1.0 op_sel_hi:[1,0]
	v_add_f32_e32 v1, 1.0, v173
	v_and_b32_e32 v173, 0xffff0000, v178
	v_mul_f32_e32 v173, 0xbfb8aa3b, v173
	v_med3_f32 v173, v173, s69, v217
	v_rcp_f32_e32 v176, v1
	v_and_b32_e32 v1, 0xffff0000, v174
	v_exp_f32_e32 v174, v173
	v_mul_f32_e32 v1, 0xbfb8aa3b, v1
	v_med3_f32 v1, v1, s69, v217
	v_exp_f32_e32 v173, v1
	v_add_f32_e32 v1, 1.0, v174
	v_lshlrev_b32_e32 v174, 16, v179
	v_mul_f32_e32 v174, 0xbfb8aa3b, v174
	v_med3_f32 v174, v174, s69, v217
	v_exp_f32_e32 v178, v174
	v_rcp_f32_e32 v177, v1
	v_lshlrev_b32_e32 v1, 16, v175
	v_mul_f32_e32 v1, 0xbfb8aa3b, v1
	v_med3_f32 v1, v1, s69, v217
	v_exp_f32_e32 v174, v1
	v_add_f32_e32 v1, 1.0, v178
	v_and_b32_e32 v178, 0xffff0000, v179
	v_mul_f32_e32 v178, 0xbfb8aa3b, v178
	v_med3_f32 v178, v178, s69, v217
	v_exp_f32_e32 v179, v178
	v_pk_add_f32 v[172:173], v[172:173], 1.0 op_sel_hi:[1,0]
	v_and_b32_e32 v175, 0xffff0000, v175
	v_mul_f32_e32 v172, v172, v176
	v_mul_f32_e32 v173, v173, v177
	v_mul_f32_e32 v175, 0xbfb8aa3b, v175
	v_mul_f32_e32 v108, v108, v172
	v_mul_f32_e32 v109, v109, v173
	v_lshlrev_b32_e32 v172, 16, v164
	v_med3_f32 v175, v175, s69, v217
	v_mul_f32_e32 v172, 0xbfb8aa3b, v172
	v_exp_f32_e32 v175, v175
	v_rcp_f32_e32 v178, v1
	v_add_f32_e32 v1, 1.0, v179
	v_med3_f32 v172, v172, s69, v217
	v_rcp_f32_e32 v179, v1
	v_exp_f32_e32 v173, v172
	v_lshlrev_b32_e32 v1, 16, v168
	v_and_b32_e32 v164, 0xffff0000, v164
	v_mul_f32_e32 v1, 0xbfb8aa3b, v1
	v_mul_f32_e32 v164, 0xbfb8aa3b, v164
	v_pk_add_f32 v[174:175], v[174:175], 1.0 op_sel_hi:[1,0]
	v_med3_f32 v1, v1, s69, v217
	v_med3_f32 v164, v164, s69, v217
	v_mul_f32_e32 v174, v174, v178
	v_mul_f32_e32 v175, v175, v179
	v_exp_f32_e32 v172, v1
	v_add_f32_e32 v1, 1.0, v173
	v_exp_f32_e32 v164, v164
	v_mul_f32_e32 v110, v110, v174
	v_mul_f32_e32 v111, v111, v175
	v_rcp_f32_e32 v174, v1
	v_and_b32_e32 v1, 0xffff0000, v168
	v_mul_f32_e32 v1, 0xbfb8aa3b, v1
	v_med3_f32 v1, v1, s69, v217
; __device__ __forceinline__ float bf_lo(unsigned w) { return __uint_as_float(w << 16); }
; __device__ __forceinline__ float bf_hi(unsigned w) { return __uint_as_float(w & 0xffff0000u); }
;     __device__ __forceinline__ static float e2(float x) { return __builtin_amdgcn_exp2f(fminf(fmaxf(-x * LOG2E, -60.f), 60.f)); }
;     __device__ __forceinline__ void mid(f32x4 (&acc)[2][2][4][2], const Unit& u, int wr, int wc, int fr_in, int fq) const {
;     ...
;             u32x4 ga[4][2], gb[4][2];
; #pragma unroll
;             for (int m = 0; m < 4; ++m)
; #pragma unroll
;                 for (int bj = 0; bj < 2; ++bj) { const bf16_t* gp = gate + (size_t)(row0 + ai * HALF + m * 16) * 2048 + col0 + bj * HALF; ga[m][bj] = *(const u32x4*)gp; gb[m][bj] = *(const u32x4*)(gp + 1024); }
;             asm volatile("" ::: "memory");
; #pragma unroll
;             for (int m = 0; m < 4; ++m)
; #pragma unroll
;                 for (int bj = 0; bj < 2; ++bj)
; #pragma unroll
;                     for (int q = 0; q < 4; ++q) {
;                         const float r0 = (1.0f + e2(bf_lo(gb[m][bj][q]))) * __builtin_amdgcn_rcpf(1.0f + e2(bf_lo(ga[m][bj][q]))), r1 = (1.0f + e2(bf_hi(gb[m][bj][q]))) * __builtin_amdgcn_rcpf(1.0f + e2(bf_hi(ga[m][bj][q])));
;                         acc[ai][bj][m][q >> 1][(2 * q) & 3] *= r0; acc[ai][bj][m][q >> 1][(2 * q + 1) & 3] *= r1; }
	v_exp_f32_e32 v173, v1
	v_add_f32_e32 v1, 1.0, v164
	v_lshlrev_b32_e32 v164, 16, v165
	v_mul_f32_e32 v164, 0xbfb8aa3b, v164
	v_med3_f32 v164, v164, s69, v217
	v_exp_f32_e32 v168, v164
	v_rcp_f32_e32 v175, v1
	v_lshlrev_b32_e32 v1, 16, v169
	v_and_b32_e32 v165, 0xffff0000, v165
	v_mul_f32_e32 v1, 0xbfb8aa3b, v1
	v_mul_f32_e32 v165, 0xbfb8aa3b, v165
	v_med3_f32 v1, v1, s69, v217
	v_med3_f32 v165, v165, s69, v217
	v_exp_f32_e32 v164, v1
	v_add_f32_e32 v1, 1.0, v168
	v_and_b32_e32 v168, 0xffff0000, v169
	v_exp_f32_e32 v169, v165
	v_mul_f32_e32 v168, 0xbfb8aa3b, v168
	v_med3_f32 v165, v168, s69, v217
	v_exp_f32_e32 v165, v165
	v_rcp_f32_e32 v168, v1
	v_add_f32_e32 v1, 1.0, v169
	v_rcp_f32_e32 v169, v1
	v_pk_add_f32 v[164:165], v[164:165], 1.0 op_sel_hi:[1,0]
	v_lshlrev_b32_e32 v1, 16, v170
	v_mul_f32_e32 v1, 0xbfb8aa3b, v1
	v_mul_f32_e32 v164, v164, v168
	v_mul_f32_e32 v165, v165, v169
	v_med3_f32 v1, v1, s69, v217
	v_mul_f32_e32 v106, v106, v164
	v_mul_f32_e32 v107, v107, v165
	v_lshlrev_b32_e32 v164, 16, v166
	v_mul_f32_e32 v164, 0xbfb8aa3b, v164
	v_med3_f32 v164, v164, s69, v217
	v_exp_f32_e32 v165, v164
	v_exp_f32_e32 v164, v1
	v_mul_f32_e32 v130, v130, v222
	v_mul_f32_e32 v131, v131, v223
	v_pk_add_f32 v[222:223], v[226:227], 1.0 op_sel_hi:[1,0]
	v_add_f32_e32 v1, 1.0, v165
	v_and_b32_e32 v165, 0xffff0000, v166
	v_mul_f32_e32 v165, 0xbfb8aa3b, v165
	v_med3_f32 v165, v165, s69, v217
	v_exp_f32_e32 v166, v165
	v_rcp_f32_e32 v168, v1
	v_and_b32_e32 v1, 0xffff0000, v170
	v_mul_f32_e32 v1, 0xbfb8aa3b, v1
	v_med3_f32 v1, v1, s69, v217
	v_exp_f32_e32 v165, v1
	v_add_f32_e32 v1, 1.0, v166
	v_lshlrev_b32_e32 v166, 16, v167
	v_mul_f32_e32 v166, 0xbfb8aa3b, v166
	v_med3_f32 v166, v166, s69, v217
	v_exp_f32_e32 v170, v166
	v_rcp_f32_e32 v169, v1
	v_lshlrev_b32_e32 v1, 16, v171
	v_and_b32_e32 v167, 0xffff0000, v167
	v_mul_f32_e32 v1, 0xbfb8aa3b, v1
	v_mul_f32_e32 v167, 0xbfb8aa3b, v167
	v_med3_f32 v1, v1, s69, v217
	v_med3_f32 v167, v167, s69, v217
	v_exp_f32_e32 v166, v1
	v_add_f32_e32 v1, 1.0, v170
	v_and_b32_e32 v170, 0xffff0000, v171
	v_exp_f32_e32 v171, v167
	v_pk_add_f32 v[164:165], v[164:165], 1.0 op_sel_hi:[1,0]
	v_mul_f32_e32 v170, 0xbfb8aa3b, v170
	v_mul_f32_e32 v164, v164, v168
	v_mul_f32_e32 v165, v165, v169
	v_med3_f32 v167, v170, s69, v217
	v_mul_f32_e32 v100, v100, v164
	v_mul_f32_e32 v101, v101, v165
	v_lshlrev_b32_e32 v164, 16, v160
	v_mul_f32_e32 v164, 0xbfb8aa3b, v164
	v_exp_f32_e32 v167, v167
	v_rcp_f32_e32 v170, v1
	v_add_f32_e32 v1, 1.0, v171
	v_med3_f32 v164, v164, s69, v217
	v_rcp_f32_e32 v171, v1
	v_exp_f32_e32 v165, v164
	v_lshlrev_b32_e32 v1, 16, v156
	v_mul_f32_e32 v1, 0xbfb8aa3b, v1
	v_pk_add_f32 v[166:167], v[166:167], 1.0 op_sel_hi:[1,0]
	v_med3_f32 v1, v1, s69, v217
	v_mul_f32_e32 v166, v166, v170
	v_mul_f32_e32 v167, v167, v171
	v_exp_f32_e32 v164, v1
	v_add_f32_e32 v1, 1.0, v165
	v_mul_f32_e32 v102, v102, v166
	v_mul_f32_e32 v103, v103, v167
	v_rcp_f32_e32 v166, v1
	v_and_b32_e32 v1, 0xffff0000, v156
	v_and_b32_e32 v156, 0xffff0000, v160
	v_mul_f32_e32 v156, 0xbfb8aa3b, v156
	v_med3_f32 v156, v156, s69, v217
	v_exp_f32_e32 v156, v156
	v_mul_f32_e32 v1, 0xbfb8aa3b, v1
	v_med3_f32 v1, v1, s69, v217
	v_exp_f32_e32 v165, v1
	v_add_f32_e32 v1, 1.0, v156
	v_lshlrev_b32_e32 v156, 16, v161
	v_mul_f32_e32 v156, 0xbfb8aa3b, v156
	v_med3_f32 v156, v156, s69, v217
	v_exp_f32_e32 v160, v156
	v_rcp_f32_e32 v167, v1
	v_lshlrev_b32_e32 v1, 16, v157
	v_mul_f32_e32 v1, 0xbfb8aa3b, v1
	v_med3_f32 v1, v1, s69, v217
	v_exp_f32_e32 v156, v1
	v_add_f32_e32 v1, 1.0, v160
	v_and_b32_e32 v160, 0xffff0000, v161
	v_mul_f32_e32 v160, 0xbfb8aa3b, v160
	v_med3_f32 v160, v160, s69, v217
	v_exp_f32_e32 v161, v160
	v_and_b32_e32 v157, 0xffff0000, v157
	v_mul_f32_e32 v157, 0xbfb8aa3b, v157
	v_med3_f32 v157, v157, s69, v217
	v_exp_f32_e32 v157, v157
	v_rcp_f32_e32 v160, v1
	v_add_f32_e32 v1, 1.0, v161
	v_rcp_f32_e32 v161, v1
	v_pk_add_f32 v[156:157], v[156:157], 1.0 op_sel_hi:[1,0]
	v_lshlrev_b32_e32 v1, 16, v158
	v_mul_f32_e32 v1, 0xbfb8aa3b, v1
	v_mul_f32_e32 v156, v156, v160
	v_mul_f32_e32 v157, v157, v161
	v_med3_f32 v1, v1, s69, v217
	v_mul_f32_e32 v98, v98, v156
	v_mul_f32_e32 v99, v99, v157
	v_lshlrev_b32_e32 v156, 16, v162
	v_mul_f32_e32 v156, 0xbfb8aa3b, v156
	v_med3_f32 v156, v156, s69, v217
	v_exp_f32_e32 v157, v156
	v_exp_f32_e32 v156, v1
	v_mul_f32_e32 v222, v222, v234
	v_mul_f32_e32 v223, v223, v235
	v_mul_f32_e32 v218, v218, v220
	v_mul_f32_e32 v219, v219, v221
	v_add_f32_e32 v1, 1.0, v157
	v_and_b32_e32 v157, 0xffff0000, v162
	v_mul_f32_e32 v157, 0xbfb8aa3b, v157
	v_med3_f32 v157, v157, s69, v217
	v_rcp_f32_e32 v160, v1
	v_and_b32_e32 v1, 0xffff0000, v158
	v_exp_f32_e32 v158, v157
	v_mul_f32_e32 v1, 0xbfb8aa3b, v1
	v_med3_f32 v1, v1, s69, v217
	v_exp_f32_e32 v157, v1
	v_add_f32_e32 v1, 1.0, v158
	v_lshlrev_b32_e32 v158, 16, v163
	v_mul_f32_e32 v158, 0xbfb8aa3b, v158
	v_med3_f32 v158, v158, s69, v217
	v_exp_f32_e32 v162, v158
	v_rcp_f32_e32 v161, v1
	v_lshlrev_b32_e32 v1, 16, v159
	v_mul_f32_e32 v1, 0xbfb8aa3b, v1
	v_med3_f32 v1, v1, s69, v217
	v_exp_f32_e32 v158, v1
	v_add_f32_e32 v1, 1.0, v162
	v_and_b32_e32 v162, 0xffff0000, v163
	v_mul_f32_e32 v162, 0xbfb8aa3b, v162
	v_med3_f32 v162, v162, s69, v217
	v_exp_f32_e32 v163, v162
	v_pk_add_f32 v[156:157], v[156:157], 1.0 op_sel_hi:[1,0]
	v_and_b32_e32 v159, 0xffff0000, v159
	v_mul_f32_e32 v156, v156, v160
	v_mul_f32_e32 v157, v157, v161
	v_mul_f32_e32 v159, 0xbfb8aa3b, v159
	v_mul_f32_e32 v92, v92, v156
	v_mul_f32_e32 v93, v93, v157
	v_lshlrev_b32_e32 v156, 16, v148
	v_med3_f32 v159, v159, s69, v217
	v_mul_f32_e32 v156, 0xbfb8aa3b, v156
	v_exp_f32_e32 v159, v159
	v_rcp_f32_e32 v162, v1
; __device__ __forceinline__ float bf_lo(unsigned w) { return __uint_as_float(w << 16); }
; __device__ __forceinline__ float bf_hi(unsigned w) { return __uint_as_float(w & 0xffff0000u); }
;     __device__ __forceinline__ static float e2(float x) { return __builtin_amdgcn_exp2f(fminf(fmaxf(-x * LOG2E, -60.f), 60.f)); }
;     __device__ __forceinline__ void mid(f32x4 (&acc)[2][2][4][2], const Unit& u, int wr, int wc, int fr_in, int fq) const {
;     ...
;             u32x4 ga[4][2], gb[4][2];
; #pragma unroll
;             for (int m = 0; m < 4; ++m)
; #pragma unroll
;                 for (int bj = 0; bj < 2; ++bj) { const bf16_t* gp = gate + (size_t)(row0 + ai * HALF + m * 16) * 2048 + col0 + bj * HALF; ga[m][bj] = *(const u32x4*)gp; gb[m][bj] = *(const u32x4*)(gp + 1024); }
;             asm volatile("" ::: "memory");
; #pragma unroll
;             for (int m = 0; m < 4; ++m)
; #pragma unroll
;                 for (int bj = 0; bj < 2; ++bj)
; #pragma unroll
;                     for (int q = 0; q < 4; ++q) {
;                         const float r0 = (1.0f + e2(bf_lo(gb[m][bj][q]))) * __builtin_amdgcn_rcpf(1.0f + e2(bf_lo(ga[m][bj][q]))), r1 = (1.0f + e2(bf_hi(gb[m][bj][q]))) * __builtin_amdgcn_rcpf(1.0f + e2(bf_hi(ga[m][bj][q])));
;                         acc[ai][bj][m][q >> 1][(2 * q) & 3] *= r0; acc[ai][bj][m][q >> 1][(2 * q + 1) & 3] *= r1; }
	v_add_f32_e32 v1, 1.0, v163
	v_med3_f32 v156, v156, s69, v217
	v_rcp_f32_e32 v163, v1
	v_exp_f32_e32 v157, v156
	v_lshlrev_b32_e32 v1, 16, v152
	v_and_b32_e32 v148, 0xffff0000, v148
	v_mul_f32_e32 v1, 0xbfb8aa3b, v1
	v_mul_f32_e32 v148, 0xbfb8aa3b, v148
	v_pk_add_f32 v[158:159], v[158:159], 1.0 op_sel_hi:[1,0]
	v_med3_f32 v1, v1, s69, v217
	v_med3_f32 v148, v148, s69, v217
	v_mul_f32_e32 v158, v158, v162
	v_mul_f32_e32 v159, v159, v163
	v_exp_f32_e32 v156, v1
	v_add_f32_e32 v1, 1.0, v157
	v_exp_f32_e32 v148, v148
	v_mul_f32_e32 v94, v94, v158
	v_mul_f32_e32 v95, v95, v159
	v_rcp_f32_e32 v158, v1
	v_and_b32_e32 v1, 0xffff0000, v152
	v_mul_f32_e32 v1, 0xbfb8aa3b, v1
	v_med3_f32 v1, v1, s69, v217
	v_exp_f32_e32 v157, v1
	v_add_f32_e32 v1, 1.0, v148
	v_lshlrev_b32_e32 v148, 16, v149
	v_mul_f32_e32 v148, 0xbfb8aa3b, v148
	v_med3_f32 v148, v148, s69, v217
	v_exp_f32_e32 v152, v148
	v_rcp_f32_e32 v159, v1
	v_lshlrev_b32_e32 v1, 16, v153
	v_and_b32_e32 v149, 0xffff0000, v149
	v_mul_f32_e32 v1, 0xbfb8aa3b, v1
	v_mul_f32_e32 v149, 0xbfb8aa3b, v149
	v_med3_f32 v1, v1, s69, v217
	v_med3_f32 v149, v149, s69, v217
	v_exp_f32_e32 v148, v1
	v_add_f32_e32 v1, 1.0, v152
	v_and_b32_e32 v152, 0xffff0000, v153
	v_exp_f32_e32 v153, v149
	v_mul_f32_e32 v152, 0xbfb8aa3b, v152
	v_med3_f32 v149, v152, s69, v217
	v_exp_f32_e32 v149, v149
	v_rcp_f32_e32 v152, v1
	v_add_f32_e32 v1, 1.0, v153
	v_rcp_f32_e32 v153, v1
	v_pk_add_f32 v[148:149], v[148:149], 1.0 op_sel_hi:[1,0]
	v_lshlrev_b32_e32 v1, 16, v154
	v_mul_f32_e32 v1, 0xbfb8aa3b, v1
	v_mul_f32_e32 v148, v148, v152
	v_mul_f32_e32 v149, v149, v153
	v_med3_f32 v1, v1, s69, v217
	v_mul_f32_e32 v90, v90, v148
	v_mul_f32_e32 v91, v91, v149
	v_lshlrev_b32_e32 v148, 16, v150
	v_mul_f32_e32 v148, 0xbfb8aa3b, v148
	v_med3_f32 v148, v148, s69, v217
	v_exp_f32_e32 v149, v148
	v_exp_f32_e32 v148, v1
	v_mul_f32_e32 v124, v124, v222
	v_mul_f32_e32 v125, v125, v223
	v_mul_f32_e32 v120, v120, v218
	v_mul_f32_e32 v121, v121, v219
	v_add_f32_e32 v1, 1.0, v149
	v_and_b32_e32 v149, 0xffff0000, v150
	v_mul_f32_e32 v149, 0xbfb8aa3b, v149
	v_med3_f32 v149, v149, s69, v217
	v_exp_f32_e32 v150, v149
	v_rcp_f32_e32 v152, v1
	v_and_b32_e32 v1, 0xffff0000, v154
	v_mul_f32_e32 v1, 0xbfb8aa3b, v1
	v_med3_f32 v1, v1, s69, v217
	v_exp_f32_e32 v149, v1
	v_add_f32_e32 v1, 1.0, v150
	v_lshlrev_b32_e32 v150, 16, v151
	v_mul_f32_e32 v150, 0xbfb8aa3b, v150
	v_med3_f32 v150, v150, s69, v217
	v_exp_f32_e32 v154, v150
	v_rcp_f32_e32 v153, v1
	v_lshlrev_b32_e32 v1, 16, v155
	v_and_b32_e32 v151, 0xffff0000, v151
	v_mul_f32_e32 v1, 0xbfb8aa3b, v1
	v_mul_f32_e32 v151, 0xbfb8aa3b, v151
	v_med3_f32 v1, v1, s69, v217
	v_med3_f32 v151, v151, s69, v217
	v_exp_f32_e32 v150, v1
	v_add_f32_e32 v1, 1.0, v154
	v_and_b32_e32 v154, 0xffff0000, v155
	v_exp_f32_e32 v155, v151
	v_pk_add_f32 v[148:149], v[148:149], 1.0 op_sel_hi:[1,0]
	v_mul_f32_e32 v154, 0xbfb8aa3b, v154
	v_mul_f32_e32 v148, v148, v152
	v_mul_f32_e32 v149, v149, v153
	v_med3_f32 v151, v154, s69, v217
	v_mul_f32_e32 v84, v84, v148
	v_mul_f32_e32 v85, v85, v149
	v_lshlrev_b32_e32 v148, 16, v144
	v_mul_f32_e32 v148, 0xbfb8aa3b, v148
	v_exp_f32_e32 v151, v151
	v_rcp_f32_e32 v154, v1
	v_add_f32_e32 v1, 1.0, v155
	v_med3_f32 v148, v148, s69, v217
	v_rcp_f32_e32 v155, v1
	v_exp_f32_e32 v149, v148
	v_lshlrev_b32_e32 v1, 16, v140
	v_mul_f32_e32 v1, 0xbfb8aa3b, v1
	v_pk_add_f32 v[150:151], v[150:151], 1.0 op_sel_hi:[1,0]
	v_med3_f32 v1, v1, s69, v217
	v_mul_f32_e32 v150, v150, v154
	v_mul_f32_e32 v151, v151, v155
	v_exp_f32_e32 v148, v1
	v_add_f32_e32 v1, 1.0, v149
	v_mul_f32_e32 v86, v86, v150
	v_mul_f32_e32 v87, v87, v151
	v_rcp_f32_e32 v150, v1
	v_and_b32_e32 v1, 0xffff0000, v140
	v_and_b32_e32 v140, 0xffff0000, v144
	v_mul_f32_e32 v140, 0xbfb8aa3b, v140
	v_med3_f32 v140, v140, s69, v217
	v_exp_f32_e32 v140, v140
	v_mul_f32_e32 v1, 0xbfb8aa3b, v1
	v_med3_f32 v1, v1, s69, v217
	v_exp_f32_e32 v149, v1
	v_add_f32_e32 v1, 1.0, v140
	v_lshlrev_b32_e32 v140, 16, v145
	v_mul_f32_e32 v140, 0xbfb8aa3b, v140
	v_med3_f32 v140, v140, s69, v217
	v_exp_f32_e32 v144, v140
	v_rcp_f32_e32 v151, v1
	v_lshlrev_b32_e32 v1, 16, v141
	v_mul_f32_e32 v1, 0xbfb8aa3b, v1
	v_med3_f32 v1, v1, s69, v217
	v_exp_f32_e32 v140, v1
	v_add_f32_e32 v1, 1.0, v144
	v_and_b32_e32 v144, 0xffff0000, v145
	v_mul_f32_e32 v144, 0xbfb8aa3b, v144
	v_med3_f32 v144, v144, s69, v217
	v_exp_f32_e32 v145, v144
	v_and_b32_e32 v141, 0xffff0000, v141
	v_mul_f32_e32 v141, 0xbfb8aa3b, v141
	v_med3_f32 v141, v141, s69, v217
	v_exp_f32_e32 v141, v141
	v_rcp_f32_e32 v144, v1
	v_add_f32_e32 v1, 1.0, v145
	v_rcp_f32_e32 v145, v1
	v_pk_add_f32 v[140:141], v[140:141], 1.0 op_sel_hi:[1,0]
	v_lshlrev_b32_e32 v1, 16, v142
	v_mul_f32_e32 v1, 0xbfb8aa3b, v1
	v_mul_f32_e32 v140, v140, v144
	v_mul_f32_e32 v141, v141, v145
	v_med3_f32 v1, v1, s69, v217
	v_mul_f32_e32 v82, v82, v140
	v_mul_f32_e32 v83, v83, v141
	v_lshlrev_b32_e32 v140, 16, v146
	v_mul_f32_e32 v140, 0xbfb8aa3b, v140
	v_med3_f32 v140, v140, s69, v217
	v_exp_f32_e32 v141, v140
	v_exp_f32_e32 v140, v1
	v_pk_add_f32 v[180:181], v[180:181], 1.0 op_sel_hi:[1,0]
	v_pk_add_f32 v[172:173], v[172:173], 1.0 op_sel_hi:[1,0]
	v_add_f32_e32 v1, 1.0, v141
	v_and_b32_e32 v141, 0xffff0000, v146
	v_mul_f32_e32 v141, 0xbfb8aa3b, v141
	v_med3_f32 v141, v141, s69, v217
	v_rcp_f32_e32 v144, v1
	v_and_b32_e32 v1, 0xffff0000, v142
	v_exp_f32_e32 v142, v141
	v_mul_f32_e32 v1, 0xbfb8aa3b, v1
	v_med3_f32 v1, v1, s69, v217
	v_exp_f32_e32 v141, v1
	v_add_f32_e32 v1, 1.0, v142
	v_lshlrev_b32_e32 v142, 16, v147
	v_mul_f32_e32 v142, 0xbfb8aa3b, v142
	v_med3_f32 v142, v142, s69, v217
	v_exp_f32_e32 v146, v142
	v_rcp_f32_e32 v145, v1
; __device__ __forceinline__ float bf_lo(unsigned w) { return __uint_as_float(w << 16); }
; __device__ __forceinline__ float bf_hi(unsigned w) { return __uint_as_float(w & 0xffff0000u); }
;     __device__ __forceinline__ static float e2(float x) { return __builtin_amdgcn_exp2f(fminf(fmaxf(-x * LOG2E, -60.f), 60.f)); }
;     __device__ __forceinline__ void mid(f32x4 (&acc)[2][2][4][2], const Unit& u, int wr, int wc, int fr_in, int fq) const {
;     ...
;             u32x4 ga[4][2], gb[4][2];
; #pragma unroll
;             for (int m = 0; m < 4; ++m)
; #pragma unroll
;                 for (int bj = 0; bj < 2; ++bj) { const bf16_t* gp = gate + (size_t)(row0 + ai * HALF + m * 16) * 2048 + col0 + bj * HALF; ga[m][bj] = *(const u32x4*)gp; gb[m][bj] = *(const u32x4*)(gp + 1024); }
;             asm volatile("" ::: "memory");
; #pragma unroll
;             for (int m = 0; m < 4; ++m)
; #pragma unroll
;                 for (int bj = 0; bj < 2; ++bj)
; #pragma unroll
;                     for (int q = 0; q < 4; ++q) {
;                         const float r0 = (1.0f + e2(bf_lo(gb[m][bj][q]))) * __builtin_amdgcn_rcpf(1.0f + e2(bf_lo(ga[m][bj][q]))), r1 = (1.0f + e2(bf_hi(gb[m][bj][q]))) * __builtin_amdgcn_rcpf(1.0f + e2(bf_hi(ga[m][bj][q])));
;                         acc[ai][bj][m][q >> 1][(2 * q) & 3] *= r0; acc[ai][bj][m][q >> 1][(2 * q + 1) & 3] *= r1; }
	v_lshlrev_b32_e32 v1, 16, v143
	v_mul_f32_e32 v1, 0xbfb8aa3b, v1
	v_med3_f32 v1, v1, s69, v217
	v_exp_f32_e32 v142, v1
	v_add_f32_e32 v1, 1.0, v146
	v_and_b32_e32 v146, 0xffff0000, v147
	v_mul_f32_e32 v146, 0xbfb8aa3b, v146
	v_med3_f32 v146, v146, s69, v217
	v_exp_f32_e32 v147, v146
	v_pk_add_f32 v[140:141], v[140:141], 1.0 op_sel_hi:[1,0]
	v_and_b32_e32 v143, 0xffff0000, v143
	v_mul_f32_e32 v140, v140, v144
	v_mul_f32_e32 v141, v141, v145
	v_mul_f32_e32 v143, 0xbfb8aa3b, v143
	v_mul_f32_e32 v76, v76, v140
	v_mul_f32_e32 v77, v77, v141
	v_lshlrev_b32_e32 v140, 16, v132
	v_med3_f32 v143, v143, s69, v217
	v_mul_f32_e32 v140, 0xbfb8aa3b, v140
	v_exp_f32_e32 v143, v143
	v_rcp_f32_e32 v146, v1
	v_add_f32_e32 v1, 1.0, v147
	v_med3_f32 v140, v140, s69, v217
	v_rcp_f32_e32 v147, v1
	v_exp_f32_e32 v141, v140
	v_lshlrev_b32_e32 v1, 16, v136
	v_and_b32_e32 v132, 0xffff0000, v132
	v_mul_f32_e32 v1, 0xbfb8aa3b, v1
	v_mul_f32_e32 v132, 0xbfb8aa3b, v132
	v_pk_add_f32 v[142:143], v[142:143], 1.0 op_sel_hi:[1,0]
	v_med3_f32 v1, v1, s69, v217
	v_med3_f32 v132, v132, s69, v217
	v_mul_f32_e32 v142, v142, v146
	v_mul_f32_e32 v143, v143, v147
	v_exp_f32_e32 v140, v1
	v_add_f32_e32 v1, 1.0, v141
	v_exp_f32_e32 v132, v132
	v_mul_f32_e32 v78, v78, v142
	v_mul_f32_e32 v79, v79, v143
	v_rcp_f32_e32 v142, v1
	v_and_b32_e32 v1, 0xffff0000, v136
	v_mul_f32_e32 v1, 0xbfb8aa3b, v1
	v_med3_f32 v1, v1, s69, v217
	v_exp_f32_e32 v141, v1
	v_add_f32_e32 v1, 1.0, v132
	v_lshlrev_b32_e32 v132, 16, v133
	v_mul_f32_e32 v132, 0xbfb8aa3b, v132
	v_med3_f32 v132, v132, s69, v217
	v_exp_f32_e32 v136, v132
	v_rcp_f32_e32 v143, v1
	v_lshlrev_b32_e32 v1, 16, v137
	v_and_b32_e32 v133, 0xffff0000, v133
	v_mul_f32_e32 v1, 0xbfb8aa3b, v1
	v_mul_f32_e32 v133, 0xbfb8aa3b, v133
	v_med3_f32 v1, v1, s69, v217
	v_med3_f32 v133, v133, s69, v217
	v_exp_f32_e32 v132, v1
	v_add_f32_e32 v1, 1.0, v136
	v_and_b32_e32 v136, 0xffff0000, v137
	v_exp_f32_e32 v137, v133
	v_mul_f32_e32 v136, 0xbfb8aa3b, v136
	v_med3_f32 v133, v136, s69, v217
	v_exp_f32_e32 v133, v133
	v_rcp_f32_e32 v136, v1
	v_add_f32_e32 v1, 1.0, v137
	v_rcp_f32_e32 v137, v1
	v_pk_add_f32 v[132:133], v[132:133], 1.0 op_sel_hi:[1,0]
	v_pk_add_f32 v[140:141], v[140:141], 1.0 op_sel_hi:[1,0]
	v_mul_f32_e32 v180, v180, v182
	v_mul_f32_e32 v181, v181, v183
	v_mul_f32_e32 v140, v140, v142
	v_mul_f32_e32 v141, v141, v143
	v_mul_f32_e32 v132, v132, v136
	v_mul_f32_e32 v133, v133, v137
	v_lshl_add_u64 v[136:137], v[2:3], 0, s[22:23]
	v_add_co_u32_e32 v142, vcc, s70, v2
	v_mul_f32_e32 v74, v74, v132
	v_mul_f32_e32 v75, v75, v133
	s_nop 0
	v_addc_co_u32_e32 v143, vcc, 0, v3, vcc
	global_load_dwordx4 v[218:221], v[136:137], off offset:2048
	global_load_dwordx4 v[222:225], v[142:143], off
	v_lshlrev_b32_e32 v132, 16, v134
	v_mul_f32_e32 v132, 0xbfb8aa3b, v132
	v_med3_f32 v132, v132, s69, v217
	v_exp_f32_e32 v133, v132
	v_mul_f32_e32 v112, v112, v180
	v_mul_f32_e32 v113, v113, v181
	v_lshlrev_b32_e32 v1, 16, v138
	global_load_dwordx4 v[180:183], v[136:137], off offset:256
	global_load_dwordx4 v[184:187], v[136:137], off offset:2304
	v_mul_f32_e32 v1, 0xbfb8aa3b, v1
	v_med3_f32 v1, v1, s69, v217
	v_exp_f32_e32 v132, v1
	v_add_f32_e32 v1, 1.0, v133
	v_and_b32_e32 v133, 0xffff0000, v134
	v_mul_f32_e32 v133, 0xbfb8aa3b, v133
	v_med3_f32 v133, v133, s69, v217
	v_exp_f32_e32 v134, v133
	v_mul_f32_e32 v72, v72, v140
	v_mul_f32_e32 v73, v73, v141
	v_rcp_f32_e32 v140, v1
	v_and_b32_e32 v1, 0xffff0000, v138
	v_mul_f32_e32 v1, 0xbfb8aa3b, v1
	v_med3_f32 v1, v1, s69, v217
	v_exp_f32_e32 v133, v1
	v_add_f32_e32 v1, 1.0, v134
	v_lshlrev_b32_e32 v134, 16, v135
	v_mul_f32_e32 v134, 0xbfb8aa3b, v134
	v_med3_f32 v134, v134, s69, v217
	v_exp_f32_e32 v138, v134
	v_rcp_f32_e32 v141, v1
	v_lshlrev_b32_e32 v1, 16, v139
	v_and_b32_e32 v135, 0xffff0000, v135
	v_mul_f32_e32 v1, 0xbfb8aa3b, v1
	v_mul_f32_e32 v135, 0xbfb8aa3b, v135
	v_med3_f32 v1, v1, s69, v217
	v_med3_f32 v135, v135, s69, v217
	v_exp_f32_e32 v134, v1
	v_add_f32_e32 v1, 1.0, v138
	v_and_b32_e32 v138, 0xffff0000, v139
	v_exp_f32_e32 v139, v135
	v_mul_f32_e32 v138, 0xbfb8aa3b, v138
	v_med3_f32 v135, v138, s69, v217
	v_exp_f32_e32 v135, v135
	v_rcp_f32_e32 v138, v1
	v_add_f32_e32 v1, 1.0, v139
	v_rcp_f32_e32 v139, v1
	v_pk_add_f32 v[134:135], v[134:135], 1.0 op_sel_hi:[1,0]
	v_pk_add_f32 v[132:133], v[132:133], 1.0 op_sel_hi:[1,0]
	v_pk_add_f32 v[164:165], v[164:165], 1.0 op_sel_hi:[1,0]
	v_mul_f32_e32 v134, v134, v138
	v_mul_f32_e32 v135, v135, v139
	v_mul_f32_e32 v132, v132, v140
	v_mul_f32_e32 v133, v133, v141
	v_mul_f32_e32 v70, v70, v134
	v_mul_f32_e32 v71, v71, v135
	v_add_co_u32_e32 v134, vcc, s71, v2
	v_mul_f32_e32 v172, v172, v174
	v_mul_f32_e32 v173, v173, v175
	v_mul_f32_e32 v164, v164, v166
	v_mul_f32_e32 v165, v165, v167
	v_mul_f32_e32 v68, v68, v132
	v_mul_f32_e32 v69, v69, v133
	v_lshl_add_u64 v[132:133], v[2:3], 0, s[24:25]
	v_addc_co_u32_e32 v135, vcc, 0, v3, vcc
	v_mul_f32_e32 v104, v104, v172
	v_mul_f32_e32 v105, v105, v173
	v_mul_f32_e32 v96, v96, v164
	v_mul_f32_e32 v97, v97, v165
	global_load_dwordx4 v[176:179], v[132:133], off offset:2048
	global_load_dwordx4 v[164:167], v[132:133], off offset:256
	global_load_dwordx4 v[172:175], v[134:135], off
	global_load_dwordx4 v[168:171], v[132:133], off offset:2304
	v_add_co_u32_e32 v134, vcc, s72, v2
	v_pk_add_f32 v[156:157], v[156:157], 1.0 op_sel_hi:[1,0]
	v_pk_add_f32 v[148:149], v[148:149], 1.0 op_sel_hi:[1,0]
	v_addc_co_u32_e32 v135, vcc, 0, v3, vcc
	v_mul_f32_e32 v156, v156, v158
	v_mul_f32_e32 v157, v157, v159
	v_mul_f32_e32 v148, v148, v150
	v_mul_f32_e32 v149, v149, v151
	v_lshl_add_u64 v[132:133], v[2:3], 0, s[26:27]
	v_lshl_add_u64 v[136:137], v[2:3], 0, s[28:29]
	v_add_co_u32_e32 v2, vcc, s73, v2
	v_mul_f32_e32 v88, v88, v156
	v_mul_f32_e32 v89, v89, v157
	v_mul_f32_e32 v80, v80, v148
	v_mul_f32_e32 v81, v81, v149
	global_load_dwordx4 v[160:163], v[132:133], off offset:2048
	global_load_dwordx4 v[148:151], v[132:133], off offset:256
	global_load_dwordx4 v[156:159], v[134:135], off
	global_load_dwordx4 v[152:155], v[132:133], off offset:2304
	v_addc_co_u32_e32 v3, vcc, 0, v3, vcc
	global_load_dwordx4 v[144:147], v[136:137], off offset:2048
	global_load_dwordx4 v[132:135], v[136:137], off offset:256
	global_load_dwordx4 v[140:143], v[2:3], off
	s_nop 0
	global_load_dwordx4 v[136:139], v[136:137], off offset:2304
	s_waitcnt vmcnt(0)
; __device__ __forceinline__ float bf_lo(unsigned w) { return __uint_as_float(w << 16); }
; __device__ __forceinline__ float bf_hi(unsigned w) { return __uint_as_float(w & 0xffff0000u); }
;     __device__ __forceinline__ static float e2(float x) { return __builtin_amdgcn_exp2f(fminf(fmaxf(-x * LOG2E, -60.f), 60.f)); }
;     __device__ __forceinline__ void mid(f32x4 (&acc)[2][2][4][2], const Unit& u, int wr, int wc, int fr_in, int fq) const {
;     ...
;             u32x4 ga[4][2], gb[4][2];
; #pragma unroll
;             for (int m = 0; m < 4; ++m)
; #pragma unroll
;                 for (int bj = 0; bj < 2; ++bj) { const bf16_t* gp = gate + (size_t)(row0 + ai * HALF + m * 16) * 2048 + col0 + bj * HALF; ga[m][bj] = *(const u32x4*)gp; gb[m][bj] = *(const u32x4*)(gp + 1024); }
;             asm volatile("" ::: "memory");
; #pragma unroll
;             for (int m = 0; m < 4; ++m)
; #pragma unroll
;                 for (int bj = 0; bj < 2; ++bj)
; #pragma unroll
;                     for (int q = 0; q < 4; ++q) {
;                         const float r0 = (1.0f + e2(bf_lo(gb[m][bj][q]))) * __builtin_amdgcn_rcpf(1.0f + e2(bf_lo(ga[m][bj][q]))), r1 = (1.0f + e2(bf_hi(gb[m][bj][q]))) * __builtin_amdgcn_rcpf(1.0f + e2(bf_hi(ga[m][bj][q])));
;                         acc[ai][bj][m][q >> 1][(2 * q) & 3] *= r0; acc[ai][bj][m][q >> 1][(2 * q + 1) & 3] *= r1; }
	v_lshlrev_b32_e32 v1, 16, v218
	v_lshlrev_b32_e32 v2, 16, v222
	v_mul_f32_e32 v2, 0xbfb8aa3b, v2
	v_med3_f32 v2, v2, s69, v217
	v_exp_f32_e32 v3, v2
	v_mul_f32_e32 v1, 0xbfb8aa3b, v1
	v_med3_f32 v1, v1, s69, v217
	v_exp_f32_e32 v2, v1
	v_add_f32_e32 v1, 1.0, v3
	v_and_b32_e32 v3, 0xffff0000, v222
	v_mul_f32_e32 v3, 0xbfb8aa3b, v3
	v_med3_f32 v3, v3, s69, v217
	v_rcp_f32_e32 v226, v1
	v_and_b32_e32 v1, 0xffff0000, v218
	v_exp_f32_e32 v218, v3
	v_mul_f32_e32 v1, 0xbfb8aa3b, v1
	v_med3_f32 v1, v1, s69, v217
	v_exp_f32_e32 v3, v1
	v_add_f32_e32 v1, 1.0, v218
	v_lshlrev_b32_e32 v218, 16, v223
	v_mul_f32_e32 v218, 0xbfb8aa3b, v218
	v_med3_f32 v218, v218, s69, v217
	v_exp_f32_e32 v222, v218
	v_rcp_f32_e32 v227, v1
	v_lshlrev_b32_e32 v1, 16, v219
	v_mul_f32_e32 v1, 0xbfb8aa3b, v1
	v_med3_f32 v1, v1, s69, v217
	v_exp_f32_e32 v218, v1
	v_add_f32_e32 v1, 1.0, v222
	v_and_b32_e32 v222, 0xffff0000, v223
	v_mul_f32_e32 v222, 0xbfb8aa3b, v222
	v_med3_f32 v222, v222, s69, v217
	v_pk_add_f32 v[2:3], v[2:3], 1.0 op_sel_hi:[1,0]
	v_exp_f32_e32 v223, v222
	v_mul_f32_e32 v2, v2, v226
	v_mul_f32_e32 v3, v3, v227
	v_and_b32_e32 v219, 0xffff0000, v219
	v_mul_f32_e32 v64, v64, v2
	v_mul_f32_e32 v65, v65, v3
	v_lshlrev_b32_e32 v2, 16, v224
	v_mul_f32_e32 v2, 0xbfb8aa3b, v2
	v_mul_f32_e32 v219, 0xbfb8aa3b, v219
	v_med3_f32 v2, v2, s69, v217
	v_med3_f32 v219, v219, s69, v217
	v_rcp_f32_e32 v222, v1
	v_add_f32_e32 v1, 1.0, v223
	v_exp_f32_e32 v3, v2
	v_exp_f32_e32 v219, v219
	v_rcp_f32_e32 v223, v1
	v_lshlrev_b32_e32 v1, 16, v220
	v_mul_f32_e32 v1, 0xbfb8aa3b, v1
	v_med3_f32 v1, v1, s69, v217
	v_exp_f32_e32 v2, v1
	v_add_f32_e32 v1, 1.0, v3
	v_and_b32_e32 v3, 0xffff0000, v224
	v_pk_add_f32 v[218:219], v[218:219], 1.0 op_sel_hi:[1,0]
	v_mul_f32_e32 v3, 0xbfb8aa3b, v3
	v_mul_f32_e32 v218, v218, v222
	v_mul_f32_e32 v219, v219, v223
	v_med3_f32 v3, v3, s69, v217
	v_mul_f32_e32 v66, v66, v218
	v_mul_f32_e32 v67, v67, v219
	v_exp_f32_e32 v219, v3
	v_rcp_f32_e32 v218, v1
	v_and_b32_e32 v1, 0xffff0000, v220
	v_lshlrev_b32_e32 v220, 16, v225
	v_mul_f32_e32 v1, 0xbfb8aa3b, v1
	v_mul_f32_e32 v220, 0xbfb8aa3b, v220
	v_med3_f32 v1, v1, s69, v217
	v_med3_f32 v220, v220, s69, v217
	v_exp_f32_e32 v3, v1
	v_add_f32_e32 v1, 1.0, v219
	v_exp_f32_e32 v222, v220
	v_rcp_f32_e32 v219, v1
	v_lshlrev_b32_e32 v1, 16, v221
	v_mul_f32_e32 v1, 0xbfb8aa3b, v1
	v_med3_f32 v1, v1, s69, v217
	v_exp_f32_e32 v220, v1
	v_add_f32_e32 v1, 1.0, v222
	v_and_b32_e32 v222, 0xffff0000, v225
	v_mul_f32_e32 v222, 0xbfb8aa3b, v222
	v_med3_f32 v222, v222, s69, v217
	v_pk_add_f32 v[2:3], v[2:3], 1.0 op_sel_hi:[1,0]
	v_exp_f32_e32 v223, v222
	v_mul_f32_e32 v2, v2, v218
	v_mul_f32_e32 v3, v3, v219
	v_and_b32_e32 v221, 0xffff0000, v221
	v_mul_f32_e32 v60, v60, v2
	v_mul_f32_e32 v61, v61, v3
	v_lshlrev_b32_e32 v2, 16, v180
	v_mul_f32_e32 v2, 0xbfb8aa3b, v2
	v_med3_f32 v2, v2, s69, v217
	v_mul_f32_e32 v221, 0xbfb8aa3b, v221
	v_rcp_f32_e32 v222, v1
	v_add_f32_e32 v1, 1.0, v223
	v_exp_f32_e32 v3, v2
	v_med3_f32 v221, v221, s69, v217
	v_rcp_f32_e32 v223, v1
	v_lshlrev_b32_e32 v1, 16, v184
	v_exp_f32_e32 v221, v221
	v_mul_f32_e32 v1, 0xbfb8aa3b, v1
	v_med3_f32 v1, v1, s69, v217
	v_exp_f32_e32 v2, v1
	v_add_f32_e32 v1, 1.0, v3
	v_and_b32_e32 v3, 0xffff0000, v180
	v_mul_f32_e32 v3, 0xbfb8aa3b, v3
	v_pk_add_f32 v[220:221], v[220:221], 1.0 op_sel_hi:[1,0]
	v_med3_f32 v3, v3, s69, v217
	v_mul_f32_e32 v218, v220, v222
	v_mul_f32_e32 v219, v221, v223
	v_exp_f32_e32 v180, v3
	v_mul_f32_e32 v62, v62, v218
	v_mul_f32_e32 v63, v63, v219
	v_rcp_f32_e32 v218, v1
	v_and_b32_e32 v1, 0xffff0000, v184
	v_mul_f32_e32 v1, 0xbfb8aa3b, v1
	v_med3_f32 v1, v1, s69, v217
	v_exp_f32_e32 v3, v1
	v_add_f32_e32 v1, 1.0, v180
	v_lshlrev_b32_e32 v180, 16, v181
	v_mul_f32_e32 v180, 0xbfb8aa3b, v180
	v_med3_f32 v180, v180, s69, v217
	v_rcp_f32_e32 v219, v1
	v_exp_f32_e32 v184, v180
	v_lshlrev_b32_e32 v1, 16, v185
	v_and_b32_e32 v181, 0xffff0000, v181
	v_mul_f32_e32 v1, 0xbfb8aa3b, v1
	v_mul_f32_e32 v181, 0xbfb8aa3b, v181
	v_med3_f32 v1, v1, s69, v217
	v_med3_f32 v181, v181, s69, v217
	v_pk_add_f32 v[2:3], v[2:3], 1.0 op_sel_hi:[1,0]
	v_exp_f32_e32 v180, v1
	v_add_f32_e32 v1, 1.0, v184
	v_and_b32_e32 v184, 0xffff0000, v185
	v_exp_f32_e32 v185, v181
	v_mul_f32_e32 v2, v2, v218
	v_mul_f32_e32 v3, v3, v219
	v_mul_f32_e32 v184, 0xbfb8aa3b, v184
	v_mul_f32_e32 v56, v56, v2
	v_mul_f32_e32 v57, v57, v3
	v_lshlrev_b32_e32 v2, 16, v182
	v_mul_f32_e32 v2, 0xbfb8aa3b, v2
	v_med3_f32 v2, v2, s69, v217
	v_med3_f32 v181, v184, s69, v217
	v_rcp_f32_e32 v184, v1
	v_add_f32_e32 v1, 1.0, v185
	v_exp_f32_e32 v3, v2
	v_exp_f32_e32 v181, v181
	v_rcp_f32_e32 v185, v1
	v_lshlrev_b32_e32 v1, 16, v186
	v_mul_f32_e32 v1, 0xbfb8aa3b, v1
	v_med3_f32 v1, v1, s69, v217
	v_exp_f32_e32 v2, v1
	v_add_f32_e32 v1, 1.0, v3
	v_and_b32_e32 v3, 0xffff0000, v182
	v_pk_add_f32 v[180:181], v[180:181], 1.0 op_sel_hi:[1,0]
	v_mul_f32_e32 v3, 0xbfb8aa3b, v3
	v_mul_f32_e32 v180, v180, v184
	v_mul_f32_e32 v181, v181, v185
	v_med3_f32 v3, v3, s69, v217
	v_mul_f32_e32 v58, v58, v180
	v_mul_f32_e32 v59, v59, v181
	v_exp_f32_e32 v181, v3
	v_rcp_f32_e32 v180, v1
	v_and_b32_e32 v1, 0xffff0000, v186
	v_mul_f32_e32 v1, 0xbfb8aa3b, v1
	v_med3_f32 v1, v1, s69, v217
	v_exp_f32_e32 v3, v1
	v_add_f32_e32 v1, 1.0, v181
	v_lshlrev_b32_e32 v182, 16, v183
	v_rcp_f32_e32 v181, v1
	v_mul_f32_e32 v182, 0xbfb8aa3b, v182
	v_med3_f32 v182, v182, s69, v217
	v_and_b32_e32 v183, 0xffff0000, v183
	v_exp_f32_e32 v184, v182
	v_mul_f32_e32 v183, 0xbfb8aa3b, v183
	v_lshlrev_b32_e32 v1, 16, v187
	v_med3_f32 v183, v183, s69, v217
	v_pk_add_f32 v[2:3], v[2:3], 1.0 op_sel_hi:[1,0]
	v_mul_f32_e32 v1, 0xbfb8aa3b, v1
	v_exp_f32_e32 v185, v183
; __device__ __forceinline__ float bf_lo(unsigned w) { return __uint_as_float(w << 16); }
; __device__ __forceinline__ float bf_hi(unsigned w) { return __uint_as_float(w & 0xffff0000u); }
;     __device__ __forceinline__ static float e2(float x) { return __builtin_amdgcn_exp2f(fminf(fmaxf(-x * LOG2E, -60.f), 60.f)); }
;     __device__ __forceinline__ void mid(f32x4 (&acc)[2][2][4][2], const Unit& u, int wr, int wc, int fr_in, int fq) const {
;     ...
;             for (int m = 0; m < 4; ++m)
; #pragma unroll
;                 for (int bj = 0; bj < 2; ++bj)
; #pragma unroll
;                     for (int q = 0; q < 4; ++q) {
;                         const float r0 = (1.0f + e2(bf_lo(gb[m][bj][q]))) * __builtin_amdgcn_rcpf(1.0f + e2(bf_lo(ga[m][bj][q]))), r1 = (1.0f + e2(bf_hi(gb[m][bj][q]))) * __builtin_amdgcn_rcpf(1.0f + e2(bf_hi(ga[m][bj][q])));
;                         acc[ai][bj][m][q >> 1][(2 * q) & 3] *= r0; acc[ai][bj][m][q >> 1][(2 * q + 1) & 3] *= r1; }
	v_mul_f32_e32 v2, v2, v180
	v_mul_f32_e32 v3, v3, v181
	v_med3_f32 v1, v1, s69, v217
	v_mul_f32_e32 v52, v52, v2
	v_mul_f32_e32 v53, v53, v3
	v_lshlrev_b32_e32 v2, 16, v172
	v_exp_f32_e32 v182, v1
	v_add_f32_e32 v1, 1.0, v184
	v_and_b32_e32 v184, 0xffff0000, v187
	v_mul_f32_e32 v2, 0xbfb8aa3b, v2
	v_mul_f32_e32 v184, 0xbfb8aa3b, v184
	v_med3_f32 v2, v2, s69, v217
	v_med3_f32 v183, v184, s69, v217
	v_rcp_f32_e32 v184, v1
	v_add_f32_e32 v1, 1.0, v185
	v_exp_f32_e32 v3, v2
	v_rcp_f32_e32 v185, v1
	v_lshlrev_b32_e32 v1, 16, v176
	v_exp_f32_e32 v183, v183
	v_mul_f32_e32 v1, 0xbfb8aa3b, v1
	v_med3_f32 v1, v1, s69, v217
	v_exp_f32_e32 v2, v1
	v_add_f32_e32 v1, 1.0, v3
	v_and_b32_e32 v3, 0xffff0000, v172
	v_mul_f32_e32 v3, 0xbfb8aa3b, v3
	v_pk_add_f32 v[182:183], v[182:183], 1.0 op_sel_hi:[1,0]
	v_med3_f32 v3, v3, s69, v217
	v_mul_f32_e32 v180, v182, v184
	v_mul_f32_e32 v181, v183, v185
	v_exp_f32_e32 v172, v3
	v_mul_f32_e32 v54, v54, v180
	v_mul_f32_e32 v55, v55, v181
	v_rcp_f32_e32 v180, v1
	v_and_b32_e32 v1, 0xffff0000, v176
	v_mul_f32_e32 v1, 0xbfb8aa3b, v1
	v_med3_f32 v1, v1, s69, v217
	v_exp_f32_e32 v3, v1
	v_add_f32_e32 v1, 1.0, v172
	v_lshlrev_b32_e32 v172, 16, v173
	v_mul_f32_e32 v172, 0xbfb8aa3b, v172
	v_med3_f32 v172, v172, s69, v217
	v_rcp_f32_e32 v181, v1
	v_exp_f32_e32 v176, v172
	v_lshlrev_b32_e32 v1, 16, v177
	v_and_b32_e32 v173, 0xffff0000, v173
	v_mul_f32_e32 v1, 0xbfb8aa3b, v1
	v_mul_f32_e32 v173, 0xbfb8aa3b, v173
	v_med3_f32 v1, v1, s69, v217
	v_med3_f32 v173, v173, s69, v217
	v_pk_add_f32 v[2:3], v[2:3], 1.0 op_sel_hi:[1,0]
	v_exp_f32_e32 v172, v1
	v_add_f32_e32 v1, 1.0, v176
	v_and_b32_e32 v176, 0xffff0000, v177
	v_exp_f32_e32 v177, v173
	v_mul_f32_e32 v2, v2, v180
	v_mul_f32_e32 v3, v3, v181
	v_mul_f32_e32 v176, 0xbfb8aa3b, v176
	v_mul_f32_e32 v48, v48, v2
	v_mul_f32_e32 v49, v49, v3
	v_lshlrev_b32_e32 v2, 16, v174
	v_mul_f32_e32 v2, 0xbfb8aa3b, v2
	v_med3_f32 v2, v2, s69, v217
	v_med3_f32 v173, v176, s69, v217
	v_rcp_f32_e32 v176, v1
	v_add_f32_e32 v1, 1.0, v177
	v_exp_f32_e32 v3, v2
	v_exp_f32_e32 v173, v173
	v_rcp_f32_e32 v177, v1
	v_lshlrev_b32_e32 v1, 16, v178
	v_mul_f32_e32 v1, 0xbfb8aa3b, v1
	v_med3_f32 v1, v1, s69, v217
	v_exp_f32_e32 v2, v1
	v_add_f32_e32 v1, 1.0, v3
	v_and_b32_e32 v3, 0xffff0000, v174
	v_pk_add_f32 v[172:173], v[172:173], 1.0 op_sel_hi:[1,0]
	v_mul_f32_e32 v3, 0xbfb8aa3b, v3
	v_mul_f32_e32 v172, v172, v176
	v_mul_f32_e32 v173, v173, v177
	v_med3_f32 v3, v3, s69, v217
	v_mul_f32_e32 v50, v50, v172
	v_mul_f32_e32 v51, v51, v173
	v_exp_f32_e32 v173, v3
	v_rcp_f32_e32 v172, v1
	v_and_b32_e32 v1, 0xffff0000, v178
	v_mul_f32_e32 v1, 0xbfb8aa3b, v1
	v_med3_f32 v1, v1, s69, v217
	v_exp_f32_e32 v3, v1
	v_add_f32_e32 v1, 1.0, v173
	v_lshlrev_b32_e32 v174, 16, v175
	v_rcp_f32_e32 v173, v1
	v_mul_f32_e32 v174, 0xbfb8aa3b, v174
	v_med3_f32 v174, v174, s69, v217
	v_and_b32_e32 v175, 0xffff0000, v175
	v_exp_f32_e32 v176, v174
	v_mul_f32_e32 v175, 0xbfb8aa3b, v175
	v_lshlrev_b32_e32 v1, 16, v179
	v_med3_f32 v175, v175, s69, v217
	v_pk_add_f32 v[2:3], v[2:3], 1.0 op_sel_hi:[1,0]
	v_mul_f32_e32 v1, 0xbfb8aa3b, v1
	v_exp_f32_e32 v177, v175
	v_mul_f32_e32 v2, v2, v172
	v_mul_f32_e32 v3, v3, v173
	v_med3_f32 v1, v1, s69, v217
	v_mul_f32_e32 v44, v44, v2
	v_mul_f32_e32 v45, v45, v3
	v_lshlrev_b32_e32 v2, 16, v164
	v_exp_f32_e32 v174, v1
	v_add_f32_e32 v1, 1.0, v176
	v_and_b32_e32 v176, 0xffff0000, v179
	v_mul_f32_e32 v2, 0xbfb8aa3b, v2
	v_mul_f32_e32 v176, 0xbfb8aa3b, v176
	v_med3_f32 v2, v2, s69, v217
	v_med3_f32 v175, v176, s69, v217
	v_rcp_f32_e32 v176, v1
	v_add_f32_e32 v1, 1.0, v177
	v_exp_f32_e32 v3, v2
	v_rcp_f32_e32 v177, v1
	v_lshlrev_b32_e32 v1, 16, v168
	v_exp_f32_e32 v175, v175
	v_mul_f32_e32 v1, 0xbfb8aa3b, v1
	v_med3_f32 v1, v1, s69, v217
	v_exp_f32_e32 v2, v1
	v_add_f32_e32 v1, 1.0, v3
	v_and_b32_e32 v3, 0xffff0000, v164
	v_mul_f32_e32 v3, 0xbfb8aa3b, v3
	v_pk_add_f32 v[174:175], v[174:175], 1.0 op_sel_hi:[1,0]
	v_med3_f32 v3, v3, s69, v217
	v_mul_f32_e32 v172, v174, v176
	v_mul_f32_e32 v173, v175, v177
	v_exp_f32_e32 v164, v3
	v_mul_f32_e32 v46, v46, v172
	v_mul_f32_e32 v47, v47, v173
	v_rcp_f32_e32 v172, v1
	v_and_b32_e32 v1, 0xffff0000, v168
	v_mul_f32_e32 v1, 0xbfb8aa3b, v1
	v_med3_f32 v1, v1, s69, v217
	v_exp_f32_e32 v3, v1
	v_add_f32_e32 v1, 1.0, v164
	v_lshlrev_b32_e32 v164, 16, v165
	v_mul_f32_e32 v164, 0xbfb8aa3b, v164
	v_med3_f32 v164, v164, s69, v217
	v_rcp_f32_e32 v173, v1
	v_exp_f32_e32 v168, v164
	v_lshlrev_b32_e32 v1, 16, v169
	v_and_b32_e32 v165, 0xffff0000, v165
	v_mul_f32_e32 v1, 0xbfb8aa3b, v1
	v_mul_f32_e32 v165, 0xbfb8aa3b, v165
	v_med3_f32 v1, v1, s69, v217
	v_med3_f32 v165, v165, s69, v217
	v_pk_add_f32 v[2:3], v[2:3], 1.0 op_sel_hi:[1,0]
	v_exp_f32_e32 v164, v1
	v_add_f32_e32 v1, 1.0, v168
	v_and_b32_e32 v168, 0xffff0000, v169
	v_exp_f32_e32 v169, v165
	v_mul_f32_e32 v2, v2, v172
	v_mul_f32_e32 v3, v3, v173
	v_mul_f32_e32 v168, 0xbfb8aa3b, v168
	v_mul_f32_e32 v40, v40, v2
	v_mul_f32_e32 v41, v41, v3
	v_lshlrev_b32_e32 v2, 16, v166
	v_mul_f32_e32 v2, 0xbfb8aa3b, v2
	v_med3_f32 v2, v2, s69, v217
	v_med3_f32 v165, v168, s69, v217
	v_rcp_f32_e32 v168, v1
	v_add_f32_e32 v1, 1.0, v169
	v_exp_f32_e32 v3, v2
	v_exp_f32_e32 v165, v165
	v_rcp_f32_e32 v169, v1
	v_lshlrev_b32_e32 v1, 16, v170
	v_mul_f32_e32 v1, 0xbfb8aa3b, v1
	v_med3_f32 v1, v1, s69, v217
	v_exp_f32_e32 v2, v1
	v_add_f32_e32 v1, 1.0, v3
	v_and_b32_e32 v3, 0xffff0000, v166
	v_pk_add_f32 v[164:165], v[164:165], 1.0 op_sel_hi:[1,0]
	v_mul_f32_e32 v3, 0xbfb8aa3b, v3
	v_mul_f32_e32 v164, v164, v168
	v_mul_f32_e32 v165, v165, v169
	v_med3_f32 v3, v3, s69, v217
	v_mul_f32_e32 v42, v42, v164
	v_mul_f32_e32 v43, v43, v165
; __device__ __forceinline__ float bf_lo(unsigned w) { return __uint_as_float(w << 16); }
; __device__ __forceinline__ float bf_hi(unsigned w) { return __uint_as_float(w & 0xffff0000u); }
;     __device__ __forceinline__ static float e2(float x) { return __builtin_amdgcn_exp2f(fminf(fmaxf(-x * LOG2E, -60.f), 60.f)); }
;     __device__ __forceinline__ void mid(f32x4 (&acc)[2][2][4][2], const Unit& u, int wr, int wc, int fr_in, int fq) const {
;     ...
;             for (int m = 0; m < 4; ++m)
; #pragma unroll
;                 for (int bj = 0; bj < 2; ++bj)
; #pragma unroll
;                     for (int q = 0; q < 4; ++q) {
;                         const float r0 = (1.0f + e2(bf_lo(gb[m][bj][q]))) * __builtin_amdgcn_rcpf(1.0f + e2(bf_lo(ga[m][bj][q]))), r1 = (1.0f + e2(bf_hi(gb[m][bj][q]))) * __builtin_amdgcn_rcpf(1.0f + e2(bf_hi(ga[m][bj][q])));
;                         acc[ai][bj][m][q >> 1][(2 * q) & 3] *= r0; acc[ai][bj][m][q >> 1][(2 * q + 1) & 3] *= r1; }
	v_exp_f32_e32 v165, v3
	v_rcp_f32_e32 v164, v1
	v_and_b32_e32 v1, 0xffff0000, v170
	v_mul_f32_e32 v1, 0xbfb8aa3b, v1
	v_med3_f32 v1, v1, s69, v217
	v_exp_f32_e32 v3, v1
	v_add_f32_e32 v1, 1.0, v165
	v_lshlrev_b32_e32 v166, 16, v167
	v_rcp_f32_e32 v165, v1
	v_mul_f32_e32 v166, 0xbfb8aa3b, v166
	v_med3_f32 v166, v166, s69, v217
	v_and_b32_e32 v167, 0xffff0000, v167
	v_exp_f32_e32 v168, v166
	v_mul_f32_e32 v167, 0xbfb8aa3b, v167
	v_lshlrev_b32_e32 v1, 16, v171
	v_med3_f32 v167, v167, s69, v217
	v_pk_add_f32 v[2:3], v[2:3], 1.0 op_sel_hi:[1,0]
	v_mul_f32_e32 v1, 0xbfb8aa3b, v1
	v_exp_f32_e32 v169, v167
	v_mul_f32_e32 v2, v2, v164
	v_mul_f32_e32 v3, v3, v165
	v_med3_f32 v1, v1, s69, v217
	v_mul_f32_e32 v36, v36, v2
	v_mul_f32_e32 v37, v37, v3
	v_lshlrev_b32_e32 v2, 16, v156
	v_exp_f32_e32 v166, v1
	v_add_f32_e32 v1, 1.0, v168
	v_and_b32_e32 v168, 0xffff0000, v171
	v_mul_f32_e32 v2, 0xbfb8aa3b, v2
	v_mul_f32_e32 v168, 0xbfb8aa3b, v168
	v_med3_f32 v2, v2, s69, v217
	v_med3_f32 v167, v168, s69, v217
	v_rcp_f32_e32 v168, v1
	v_add_f32_e32 v1, 1.0, v169
	v_exp_f32_e32 v3, v2
	v_rcp_f32_e32 v169, v1
	v_lshlrev_b32_e32 v1, 16, v160
	v_exp_f32_e32 v167, v167
	v_mul_f32_e32 v1, 0xbfb8aa3b, v1
	v_med3_f32 v1, v1, s69, v217
	v_exp_f32_e32 v2, v1
	v_add_f32_e32 v1, 1.0, v3
	v_and_b32_e32 v3, 0xffff0000, v156
	v_mul_f32_e32 v3, 0xbfb8aa3b, v3
	v_pk_add_f32 v[166:167], v[166:167], 1.0 op_sel_hi:[1,0]
	v_med3_f32 v3, v3, s69, v217
	v_mul_f32_e32 v164, v166, v168
	v_mul_f32_e32 v165, v167, v169
	v_exp_f32_e32 v156, v3
	v_mul_f32_e32 v38, v38, v164
	v_mul_f32_e32 v39, v39, v165
	v_rcp_f32_e32 v164, v1
	v_and_b32_e32 v1, 0xffff0000, v160
	v_mul_f32_e32 v1, 0xbfb8aa3b, v1
	v_med3_f32 v1, v1, s69, v217
	v_exp_f32_e32 v3, v1
	v_add_f32_e32 v1, 1.0, v156
	v_lshlrev_b32_e32 v156, 16, v157
	v_mul_f32_e32 v156, 0xbfb8aa3b, v156
	v_med3_f32 v156, v156, s69, v217
	v_rcp_f32_e32 v165, v1
	v_exp_f32_e32 v160, v156
	v_lshlrev_b32_e32 v1, 16, v161
	v_and_b32_e32 v157, 0xffff0000, v157
	v_mul_f32_e32 v1, 0xbfb8aa3b, v1
	v_mul_f32_e32 v157, 0xbfb8aa3b, v157
	v_med3_f32 v1, v1, s69, v217
	v_med3_f32 v157, v157, s69, v217
	v_pk_add_f32 v[2:3], v[2:3], 1.0 op_sel_hi:[1,0]
	v_exp_f32_e32 v156, v1
	v_add_f32_e32 v1, 1.0, v160
	v_and_b32_e32 v160, 0xffff0000, v161
	v_exp_f32_e32 v161, v157
	v_mul_f32_e32 v2, v2, v164
	v_mul_f32_e32 v3, v3, v165
	v_mul_f32_e32 v160, 0xbfb8aa3b, v160
	v_mul_f32_e32 v32, v32, v2
	v_mul_f32_e32 v33, v33, v3
	v_lshlrev_b32_e32 v2, 16, v158
	v_mul_f32_e32 v2, 0xbfb8aa3b, v2
	v_med3_f32 v2, v2, s69, v217
	v_med3_f32 v157, v160, s69, v217
	v_rcp_f32_e32 v160, v1
	v_add_f32_e32 v1, 1.0, v161
	v_exp_f32_e32 v3, v2
	v_exp_f32_e32 v157, v157
	v_rcp_f32_e32 v161, v1
	v_lshlrev_b32_e32 v1, 16, v162
	v_mul_f32_e32 v1, 0xbfb8aa3b, v1
	v_med3_f32 v1, v1, s69, v217
	v_exp_f32_e32 v2, v1
	v_add_f32_e32 v1, 1.0, v3
	v_and_b32_e32 v3, 0xffff0000, v158
	v_pk_add_f32 v[156:157], v[156:157], 1.0 op_sel_hi:[1,0]
	v_mul_f32_e32 v3, 0xbfb8aa3b, v3
	v_mul_f32_e32 v156, v156, v160
	v_mul_f32_e32 v157, v157, v161
	v_med3_f32 v3, v3, s69, v217
	v_mul_f32_e32 v34, v34, v156
	v_mul_f32_e32 v35, v35, v157
	v_exp_f32_e32 v157, v3
	v_rcp_f32_e32 v156, v1
	v_and_b32_e32 v1, 0xffff0000, v162
	v_mul_f32_e32 v1, 0xbfb8aa3b, v1
	v_med3_f32 v1, v1, s69, v217
	v_exp_f32_e32 v3, v1
	v_add_f32_e32 v1, 1.0, v157
	v_lshlrev_b32_e32 v158, 16, v159
	v_rcp_f32_e32 v157, v1
	v_mul_f32_e32 v158, 0xbfb8aa3b, v158
	v_med3_f32 v158, v158, s69, v217
	v_and_b32_e32 v159, 0xffff0000, v159
	v_exp_f32_e32 v160, v158
	v_mul_f32_e32 v159, 0xbfb8aa3b, v159
	v_lshlrev_b32_e32 v1, 16, v163
	v_med3_f32 v159, v159, s69, v217
	v_pk_add_f32 v[2:3], v[2:3], 1.0 op_sel_hi:[1,0]
	v_mul_f32_e32 v1, 0xbfb8aa3b, v1
	v_exp_f32_e32 v161, v159
	v_mul_f32_e32 v2, v2, v156
	v_mul_f32_e32 v3, v3, v157
	v_med3_f32 v1, v1, s69, v217
	v_mul_f32_e32 v28, v28, v2
	v_mul_f32_e32 v29, v29, v3
	v_lshlrev_b32_e32 v2, 16, v148
	v_exp_f32_e32 v158, v1
	v_add_f32_e32 v1, 1.0, v160
	v_and_b32_e32 v160, 0xffff0000, v163
	v_mul_f32_e32 v2, 0xbfb8aa3b, v2
	v_mul_f32_e32 v160, 0xbfb8aa3b, v160
	v_med3_f32 v2, v2, s69, v217
	v_med3_f32 v159, v160, s69, v217
	v_rcp_f32_e32 v160, v1
	v_add_f32_e32 v1, 1.0, v161
	v_exp_f32_e32 v3, v2
	v_rcp_f32_e32 v161, v1
	v_lshlrev_b32_e32 v1, 16, v152
	v_exp_f32_e32 v159, v159
	v_mul_f32_e32 v1, 0xbfb8aa3b, v1
	v_med3_f32 v1, v1, s69, v217
	v_exp_f32_e32 v2, v1
	v_add_f32_e32 v1, 1.0, v3
	v_and_b32_e32 v3, 0xffff0000, v148
	v_mul_f32_e32 v3, 0xbfb8aa3b, v3
	v_pk_add_f32 v[158:159], v[158:159], 1.0 op_sel_hi:[1,0]
	v_med3_f32 v3, v3, s69, v217
	v_mul_f32_e32 v156, v158, v160
	v_mul_f32_e32 v157, v159, v161
	v_exp_f32_e32 v148, v3
	v_mul_f32_e32 v30, v30, v156
	v_mul_f32_e32 v31, v31, v157
	v_rcp_f32_e32 v156, v1
	v_and_b32_e32 v1, 0xffff0000, v152
	v_mul_f32_e32 v1, 0xbfb8aa3b, v1
	v_med3_f32 v1, v1, s69, v217
	v_exp_f32_e32 v3, v1
	v_add_f32_e32 v1, 1.0, v148
	v_lshlrev_b32_e32 v148, 16, v149
	v_mul_f32_e32 v148, 0xbfb8aa3b, v148
	v_med3_f32 v148, v148, s69, v217
	v_rcp_f32_e32 v157, v1
	v_exp_f32_e32 v152, v148
	v_lshlrev_b32_e32 v1, 16, v153
	v_and_b32_e32 v149, 0xffff0000, v149
	v_mul_f32_e32 v1, 0xbfb8aa3b, v1
	v_mul_f32_e32 v149, 0xbfb8aa3b, v149
	v_med3_f32 v1, v1, s69, v217
	v_med3_f32 v149, v149, s69, v217
	v_pk_add_f32 v[2:3], v[2:3], 1.0 op_sel_hi:[1,0]
	v_exp_f32_e32 v148, v1
	v_add_f32_e32 v1, 1.0, v152
	v_and_b32_e32 v152, 0xffff0000, v153
	v_exp_f32_e32 v153, v149
	v_mul_f32_e32 v2, v2, v156
	v_mul_f32_e32 v3, v3, v157
	v_mul_f32_e32 v152, 0xbfb8aa3b, v152
	v_mul_f32_e32 v24, v24, v2
	v_mul_f32_e32 v25, v25, v3
	v_lshlrev_b32_e32 v2, 16, v150
	v_mul_f32_e32 v2, 0xbfb8aa3b, v2
	v_med3_f32 v2, v2, s69, v217
; __device__ __forceinline__ float bf_lo(unsigned w) { return __uint_as_float(w << 16); }
; __device__ __forceinline__ float bf_hi(unsigned w) { return __uint_as_float(w & 0xffff0000u); }
;     __device__ __forceinline__ static float e2(float x) { return __builtin_amdgcn_exp2f(fminf(fmaxf(-x * LOG2E, -60.f), 60.f)); }
;     __device__ __forceinline__ void mid(f32x4 (&acc)[2][2][4][2], const Unit& u, int wr, int wc, int fr_in, int fq) const {
;     ...
;             for (int m = 0; m < 4; ++m)
; #pragma unroll
;                 for (int bj = 0; bj < 2; ++bj)
; #pragma unroll
;                     for (int q = 0; q < 4; ++q) {
;                         const float r0 = (1.0f + e2(bf_lo(gb[m][bj][q]))) * __builtin_amdgcn_rcpf(1.0f + e2(bf_lo(ga[m][bj][q]))), r1 = (1.0f + e2(bf_hi(gb[m][bj][q]))) * __builtin_amdgcn_rcpf(1.0f + e2(bf_hi(ga[m][bj][q])));
;                         acc[ai][bj][m][q >> 1][(2 * q) & 3] *= r0; acc[ai][bj][m][q >> 1][(2 * q + 1) & 3] *= r1; }
	v_med3_f32 v149, v152, s69, v217
	v_rcp_f32_e32 v152, v1
	v_add_f32_e32 v1, 1.0, v153
	v_exp_f32_e32 v3, v2
	v_exp_f32_e32 v149, v149
	v_rcp_f32_e32 v153, v1
	v_lshlrev_b32_e32 v1, 16, v154
	v_mul_f32_e32 v1, 0xbfb8aa3b, v1
	v_med3_f32 v1, v1, s69, v217
	v_exp_f32_e32 v2, v1
	v_add_f32_e32 v1, 1.0, v3
	v_and_b32_e32 v3, 0xffff0000, v150
	v_pk_add_f32 v[148:149], v[148:149], 1.0 op_sel_hi:[1,0]
	v_mul_f32_e32 v3, 0xbfb8aa3b, v3
	v_mul_f32_e32 v148, v148, v152
	v_mul_f32_e32 v149, v149, v153
	v_med3_f32 v3, v3, s69, v217
	v_mul_f32_e32 v26, v26, v148
	v_mul_f32_e32 v27, v27, v149
	v_exp_f32_e32 v149, v3
	v_rcp_f32_e32 v148, v1
	v_and_b32_e32 v1, 0xffff0000, v154
	v_mul_f32_e32 v1, 0xbfb8aa3b, v1
	v_med3_f32 v1, v1, s69, v217
	v_exp_f32_e32 v3, v1
	v_add_f32_e32 v1, 1.0, v149
	v_lshlrev_b32_e32 v150, 16, v151
	v_rcp_f32_e32 v149, v1
	v_mul_f32_e32 v150, 0xbfb8aa3b, v150
	v_med3_f32 v150, v150, s69, v217
	v_and_b32_e32 v151, 0xffff0000, v151
	v_exp_f32_e32 v152, v150
	v_mul_f32_e32 v151, 0xbfb8aa3b, v151
	v_lshlrev_b32_e32 v1, 16, v155
	v_med3_f32 v151, v151, s69, v217
	v_pk_add_f32 v[2:3], v[2:3], 1.0 op_sel_hi:[1,0]
	v_mul_f32_e32 v1, 0xbfb8aa3b, v1
	v_exp_f32_e32 v153, v151
	v_mul_f32_e32 v2, v2, v148
	v_mul_f32_e32 v3, v3, v149
	v_med3_f32 v1, v1, s69, v217
	v_mul_f32_e32 v20, v20, v2
	v_mul_f32_e32 v21, v21, v3
	v_lshlrev_b32_e32 v2, 16, v140
	v_exp_f32_e32 v150, v1
	v_add_f32_e32 v1, 1.0, v152
	v_and_b32_e32 v152, 0xffff0000, v155
	v_mul_f32_e32 v2, 0xbfb8aa3b, v2
	v_mul_f32_e32 v152, 0xbfb8aa3b, v152
	v_med3_f32 v2, v2, s69, v217
	v_med3_f32 v151, v152, s69, v217
	v_rcp_f32_e32 v152, v1
	v_add_f32_e32 v1, 1.0, v153
	v_exp_f32_e32 v3, v2
	v_rcp_f32_e32 v153, v1
	v_lshlrev_b32_e32 v1, 16, v144
	v_exp_f32_e32 v151, v151
	v_mul_f32_e32 v1, 0xbfb8aa3b, v1
	v_med3_f32 v1, v1, s69, v217
	v_exp_f32_e32 v2, v1
	v_add_f32_e32 v1, 1.0, v3
	v_and_b32_e32 v3, 0xffff0000, v140
	v_mul_f32_e32 v3, 0xbfb8aa3b, v3
	v_pk_add_f32 v[150:151], v[150:151], 1.0 op_sel_hi:[1,0]
	v_med3_f32 v3, v3, s69, v217
	v_mul_f32_e32 v148, v150, v152
	v_mul_f32_e32 v149, v151, v153
	v_exp_f32_e32 v140, v3
	v_mul_f32_e32 v22, v22, v148
	v_mul_f32_e32 v23, v23, v149
	v_rcp_f32_e32 v148, v1
	v_and_b32_e32 v1, 0xffff0000, v144
	v_mul_f32_e32 v1, 0xbfb8aa3b, v1
	v_med3_f32 v1, v1, s69, v217
	v_exp_f32_e32 v3, v1
	v_add_f32_e32 v1, 1.0, v140
	v_lshlrev_b32_e32 v140, 16, v141
	v_mul_f32_e32 v140, 0xbfb8aa3b, v140
	v_med3_f32 v140, v140, s69, v217
	v_rcp_f32_e32 v149, v1
	v_exp_f32_e32 v144, v140
	v_lshlrev_b32_e32 v1, 16, v145
	v_and_b32_e32 v141, 0xffff0000, v141
	v_mul_f32_e32 v1, 0xbfb8aa3b, v1
	v_mul_f32_e32 v141, 0xbfb8aa3b, v141
	v_med3_f32 v1, v1, s69, v217
	v_med3_f32 v141, v141, s69, v217
	v_pk_add_f32 v[2:3], v[2:3], 1.0 op_sel_hi:[1,0]
	v_exp_f32_e32 v140, v1
	v_add_f32_e32 v1, 1.0, v144
	v_and_b32_e32 v144, 0xffff0000, v145
	v_exp_f32_e32 v145, v141
	v_mul_f32_e32 v2, v2, v148
	v_mul_f32_e32 v3, v3, v149
	v_mul_f32_e32 v144, 0xbfb8aa3b, v144
	v_mul_f32_e32 v16, v16, v2
	v_mul_f32_e32 v17, v17, v3
	v_lshlrev_b32_e32 v2, 16, v142
	v_mul_f32_e32 v2, 0xbfb8aa3b, v2
	v_med3_f32 v2, v2, s69, v217
	v_med3_f32 v141, v144, s69, v217
	v_rcp_f32_e32 v144, v1
	v_add_f32_e32 v1, 1.0, v145
	v_exp_f32_e32 v3, v2
	v_exp_f32_e32 v141, v141
	v_rcp_f32_e32 v145, v1
	v_lshlrev_b32_e32 v1, 16, v146
	v_mul_f32_e32 v1, 0xbfb8aa3b, v1
	v_med3_f32 v1, v1, s69, v217
	v_exp_f32_e32 v2, v1
	v_add_f32_e32 v1, 1.0, v3
	v_and_b32_e32 v3, 0xffff0000, v142
	v_pk_add_f32 v[140:141], v[140:141], 1.0 op_sel_hi:[1,0]
	v_mul_f32_e32 v3, 0xbfb8aa3b, v3
	v_mul_f32_e32 v140, v140, v144
	v_mul_f32_e32 v141, v141, v145
	v_med3_f32 v3, v3, s69, v217
	v_mul_f32_e32 v18, v18, v140
	v_mul_f32_e32 v19, v19, v141
	v_exp_f32_e32 v141, v3
	v_rcp_f32_e32 v140, v1
	v_and_b32_e32 v1, 0xffff0000, v146
	v_mul_f32_e32 v1, 0xbfb8aa3b, v1
	v_med3_f32 v1, v1, s69, v217
	v_exp_f32_e32 v3, v1
	v_add_f32_e32 v1, 1.0, v141
	v_lshlrev_b32_e32 v142, 16, v143
	v_rcp_f32_e32 v141, v1
	v_mul_f32_e32 v142, 0xbfb8aa3b, v142
	v_med3_f32 v142, v142, s69, v217
; __device__ __forceinline__ float bf_lo(unsigned w) { return __uint_as_float(w << 16); }
; __device__ __forceinline__ float bf_hi(unsigned w) { return __uint_as_float(w & 0xffff0000u); }
;     __device__ __forceinline__ static float e2(float x) { return __builtin_amdgcn_exp2f(fminf(fmaxf(-x * LOG2E, -60.f), 60.f)); }
; #define PG8_BAR __builtin_amdgcn_s_barrier()
;     __device__ __forceinline__ void mid(f32x4 (&acc)[2][2][4][2], const Unit& u, int wr, int wc, int fr_in, int fq) const {
;     ...
;             for (int m = 0; m < 4; ++m)
; #pragma unroll
;                 for (int bj = 0; bj < 2; ++bj)
; #pragma unroll
;                     for (int q = 0; q < 4; ++q) {
;                         const float r0 = (1.0f + e2(bf_lo(gb[m][bj][q]))) * __builtin_amdgcn_rcpf(1.0f + e2(bf_lo(ga[m][bj][q]))), r1 = (1.0f + e2(bf_hi(gb[m][bj][q]))) * __builtin_amdgcn_rcpf(1.0f + e2(bf_hi(ga[m][bj][q])));
;                         acc[ai][bj][m][q >> 1][(2 * q) & 3] *= r0; acc[ai][bj][m][q >> 1][(2 * q + 1) & 3] *= r1; }
; template <class Epi, class Sched, bool ALIGN_EPI = false, bool SP2 = false>
; __device__ __forceinline__ void gemm_phase(PG8_LAS unsigned char* lds, const Gemm g, const Sched& S, const Epi& E, int tid_in) {
;     ...
;             if constexpr (Epi::MIDK) { if (t == Epi::MIDK_T) { if (wr == 0) PG8_BAR; E.mid(acc, cur, wr, wc, fr, fq); if (wr == 1) PG8_BAR; } }
	v_and_b32_e32 v143, 0xffff0000, v143
	v_exp_f32_e32 v144, v142
	v_mul_f32_e32 v143, 0xbfb8aa3b, v143
	v_lshlrev_b32_e32 v1, 16, v147
	v_med3_f32 v143, v143, s69, v217
	v_pk_add_f32 v[2:3], v[2:3], 1.0 op_sel_hi:[1,0]
	v_mul_f32_e32 v1, 0xbfb8aa3b, v1
	v_exp_f32_e32 v145, v143
	v_mul_f32_e32 v2, v2, v140
	v_mul_f32_e32 v3, v3, v141
	v_med3_f32 v1, v1, s69, v217
	v_mul_f32_e32 v12, v12, v2
	v_mul_f32_e32 v13, v13, v3
	v_lshlrev_b32_e32 v2, 16, v132
	v_exp_f32_e32 v142, v1
	v_add_f32_e32 v1, 1.0, v144
	v_and_b32_e32 v144, 0xffff0000, v147
	v_mul_f32_e32 v2, 0xbfb8aa3b, v2
	v_mul_f32_e32 v144, 0xbfb8aa3b, v144
	v_med3_f32 v2, v2, s69, v217
	v_med3_f32 v143, v144, s69, v217
	v_rcp_f32_e32 v144, v1
	v_add_f32_e32 v1, 1.0, v145
	v_exp_f32_e32 v3, v2
	v_rcp_f32_e32 v145, v1
	v_lshlrev_b32_e32 v1, 16, v136
	v_exp_f32_e32 v143, v143
	v_mul_f32_e32 v1, 0xbfb8aa3b, v1
	v_med3_f32 v1, v1, s69, v217
	v_exp_f32_e32 v2, v1
	v_add_f32_e32 v1, 1.0, v3
	v_and_b32_e32 v3, 0xffff0000, v132
	v_mul_f32_e32 v3, 0xbfb8aa3b, v3
	v_pk_add_f32 v[142:143], v[142:143], 1.0 op_sel_hi:[1,0]
	v_med3_f32 v3, v3, s69, v217
	v_mul_f32_e32 v140, v142, v144
	v_mul_f32_e32 v141, v143, v145
	v_exp_f32_e32 v132, v3
	v_mul_f32_e32 v14, v14, v140
	v_mul_f32_e32 v15, v15, v141
	v_rcp_f32_e32 v140, v1
	v_and_b32_e32 v1, 0xffff0000, v136
	v_mul_f32_e32 v1, 0xbfb8aa3b, v1
	v_med3_f32 v1, v1, s69, v217
	v_exp_f32_e32 v3, v1
	v_add_f32_e32 v1, 1.0, v132
	v_lshlrev_b32_e32 v132, 16, v133
	v_mul_f32_e32 v132, 0xbfb8aa3b, v132
	v_med3_f32 v132, v132, s69, v217
	v_rcp_f32_e32 v141, v1
	v_exp_f32_e32 v136, v132
	v_lshlrev_b32_e32 v1, 16, v137
	v_and_b32_e32 v133, 0xffff0000, v133
	v_mul_f32_e32 v1, 0xbfb8aa3b, v1
	v_mul_f32_e32 v133, 0xbfb8aa3b, v133
	v_med3_f32 v1, v1, s69, v217
	v_med3_f32 v133, v133, s69, v217
	v_pk_add_f32 v[2:3], v[2:3], 1.0 op_sel_hi:[1,0]
	v_exp_f32_e32 v132, v1
	v_add_f32_e32 v1, 1.0, v136
	v_and_b32_e32 v136, 0xffff0000, v137
	v_exp_f32_e32 v137, v133
	v_mul_f32_e32 v2, v2, v140
	v_mul_f32_e32 v3, v3, v141
	v_mul_f32_e32 v136, 0xbfb8aa3b, v136
	v_mul_f32_e32 v8, v8, v2
	v_mul_f32_e32 v9, v9, v3
	v_lshlrev_b32_e32 v2, 16, v134
	v_mul_f32_e32 v2, 0xbfb8aa3b, v2
	v_med3_f32 v2, v2, s69, v217
	v_med3_f32 v133, v136, s69, v217
	v_rcp_f32_e32 v136, v1
	v_add_f32_e32 v1, 1.0, v137
	v_exp_f32_e32 v3, v2
	v_exp_f32_e32 v133, v133
	v_rcp_f32_e32 v137, v1
	v_lshlrev_b32_e32 v1, 16, v138
	v_mul_f32_e32 v1, 0xbfb8aa3b, v1
	v_med3_f32 v1, v1, s69, v217
	v_exp_f32_e32 v2, v1
	v_add_f32_e32 v1, 1.0, v3
	v_and_b32_e32 v3, 0xffff0000, v134
	v_pk_add_f32 v[132:133], v[132:133], 1.0 op_sel_hi:[1,0]
	v_mul_f32_e32 v3, 0xbfb8aa3b, v3
	v_mul_f32_e32 v132, v132, v136
	v_mul_f32_e32 v133, v133, v137
	v_med3_f32 v3, v3, s69, v217
	v_mul_f32_e32 v10, v10, v132
	v_mul_f32_e32 v11, v11, v133
	v_exp_f32_e32 v133, v3
	v_rcp_f32_e32 v132, v1
	v_and_b32_e32 v1, 0xffff0000, v138
	v_lshlrev_b32_e32 v134, 16, v135
	v_mul_f32_e32 v1, 0xbfb8aa3b, v1
	v_mul_f32_e32 v134, 0xbfb8aa3b, v134
	v_med3_f32 v1, v1, s69, v217
	v_med3_f32 v134, v134, s69, v217
	v_exp_f32_e32 v3, v1
	v_add_f32_e32 v1, 1.0, v133
	v_exp_f32_e32 v136, v134
	v_and_b32_e32 v135, 0xffff0000, v135
	v_rcp_f32_e32 v133, v1
	v_lshlrev_b32_e32 v1, 16, v139
	v_mul_f32_e32 v135, 0xbfb8aa3b, v135
	v_mul_f32_e32 v1, 0xbfb8aa3b, v1
	v_med3_f32 v135, v135, s69, v217
	v_med3_f32 v1, v1, s69, v217
	v_exp_f32_e32 v137, v135
	v_exp_f32_e32 v134, v1
	v_add_f32_e32 v1, 1.0, v136
	v_and_b32_e32 v136, 0xffff0000, v139
	v_mul_f32_e32 v136, 0xbfb8aa3b, v136
	v_med3_f32 v135, v136, s69, v217
	v_exp_f32_e32 v135, v135
	v_rcp_f32_e32 v136, v1
	v_add_f32_e32 v1, 1.0, v137
	v_rcp_f32_e32 v137, v1
	v_pk_add_f32 v[134:135], v[134:135], 1.0 op_sel_hi:[1,0]
	v_pk_add_f32 v[2:3], v[2:3], 1.0 op_sel_hi:[1,0]
	s_andn2_b64 vcc, exec, s[6:7]
	v_mul_f32_e32 v2, v2, v132
	v_mul_f32_e32 v3, v3, v133
	v_mul_f32_e32 v132, v134, v136
	v_mul_f32_e32 v133, v135, v137
	v_mul_f32_e32 v4, v4, v2
	v_mul_f32_e32 v5, v5, v3
	v_mul_f32_e32 v6, v6, v132
	v_mul_f32_e32 v7, v7, v133
	s_cbranch_vccnz .LBB0_1062
	s_barrier
	s_branch .LBB0_1062

; __device__ __forceinline__ unsigned cvt_pk_bf16(float lo, float hi) { f32x2 v = {lo, hi}; bf16x2_t b = __builtin_convertvector(v, bf16x2_t); return __builtin_bit_cast(unsigned, b); }
; __device__ __forceinline__ float bf_lo(unsigned w) { return __uint_as_float(w << 16); }
; __device__ __forceinline__ float bf_hi(unsigned w) { return __uint_as_float(w & 0xffff0000u); }
;     __device__ __forceinline__ static float e2(float x) { return __builtin_amdgcn_exp2f(fminf(fmaxf(-x * LOG2E, -60.f), 60.f)); }
;     __device__ __forceinline__ void operator()(const f32x4 (&acc)[2][2][4][2], const Unit& u, int wr, int wc, int fr, int fq) const {
;     ...
;             u32x4 gb[4][2];
; #pragma unroll
;             for (int m = 0; m < 4; ++m)
; #pragma unroll
;                 for (int bj = 0; bj < 2; ++bj) gb[m][bj] = *(const u32x4*)(gate + (size_t)(row0 + ai * HALF + m * 16) * 2048 + 1024 + col0 + bj * HALF);
;             asm volatile("" ::: "memory");
; #pragma unroll
;             for (int m = 0; m < 4; ++m)
; #pragma unroll
;                 for (int bj = 0; bj < 2; ++bj) { float o[8];
; #pragma unroll
;                     for (int q = 0; q < 4; ++q) { o[2 * q] = __builtin_amdgcn_rcpf(1.0f + e2(bf_lo(gb[m][bj][q]))) * acc[ai][bj][m][q >> 1][(2 * q) & 3]; o[2 * q + 1] = __builtin_amdgcn_rcpf(1.0f + e2(bf_hi(gb[m][bj][q]))) * acc[ai][bj][m][q >> 1][(2 * q + 1) & 3]; }
;                     u32x4 w; w.x = cvt_pk_bf16(o[0], o[1]); w.y = cvt_pk_bf16(o[2], o[3]); w.z = cvt_pk_bf16(o[4], o[5]); w.w = cvt_pk_bf16(o[6], o[7]);
;                     *(u32x4*)(T + (size_t)(row0 + ai * HALF + m * 16) * 1024 + col0 + bj * HALF) = w; }
.LBB0_1070:
	v_add_u32_e32 v152, s31, v213
	v_ashrrev_i32_e32 v153, 31, v152
	v_lshlrev_b64 v[2:3], 12, v[152:153]
	v_lshl_add_u64 v[132:133], s[10:11], 0, v[2:3]
	v_lshlrev_b64 v[2:3], 1, v[204:205]
	v_lshl_add_u64 v[132:133], v[132:133], 0, v[2:3]
	global_load_dwordx4 v[160:163], v[132:133], off offset:2048
	global_load_dwordx4 v[164:167], v[132:133], off offset:2304
	v_or_b32_e32 v158, 16, v152
	v_or_b32_e32 v156, 32, v152
	v_or_b32_e32 v154, 48, v152
	v_ashrrev_i32_e32 v159, 31, v158
	v_ashrrev_i32_e32 v157, 31, v156
	v_ashrrev_i32_e32 v155, 31, v154
	v_lshlrev_b64 v[132:133], 11, v[152:153]
	v_lshlrev_b64 v[134:135], 12, v[158:159]
	v_lshlrev_b64 v[136:137], 12, v[156:157]
	v_lshlrev_b64 v[138:139], 12, v[154:155]
	v_lshl_add_u64 v[132:133], s[8:9], 0, v[132:133]
	v_lshl_add_u64 v[134:135], s[10:11], 0, v[134:135]
	v_lshl_add_u64 v[136:137], s[10:11], 0, v[136:137]
	v_lshl_add_u64 v[138:139], s[10:11], 0, v[138:139]
	v_lshl_add_u64 v[172:173], v[132:133], 0, v[2:3]
	v_lshl_add_u64 v[132:133], v[134:135], 0, v[2:3]
	v_lshl_add_u64 v[134:135], v[136:137], 0, v[2:3]
	v_lshl_add_u64 v[174:175], v[138:139], 0, v[2:3]
	global_load_dwordx4 v[168:171], v[132:133], off offset:2048
	global_load_dwordx4 v[148:151], v[132:133], off offset:2304
	global_load_dwordx4 v[144:147], v[134:135], off offset:2048
	global_load_dwordx4 v[140:143], v[134:135], off offset:2304
	global_load_dwordx4 v[136:139], v[174:175], off offset:2048
	s_nop 0
	global_load_dwordx4 v[132:135], v[174:175], off offset:2304
	s_andn2_b64 vcc, exec, s[2:3]
	s_mov_b64 s[2:3], -1
	s_waitcnt vmcnt(0)
	v_lshlrev_b32_e32 v1, 16, v160
	v_and_b32_e32 v153, 0xffff0000, v160
	v_lshlrev_b32_e32 v160, 16, v161
	v_and_b32_e32 v161, 0xffff0000, v161
	v_lshlrev_b32_e32 v174, 16, v162
	v_and_b32_e32 v162, 0xffff0000, v162
	v_lshlrev_b32_e32 v175, 16, v163
	v_and_b32_e32 v163, 0xffff0000, v163
	v_lshlrev_b32_e32 v176, 16, v164
	v_mul_f32_e32 v1, 0xbfb8aa3b, v1
	v_mul_f32_e32 v153, 0xbfb8aa3b, v153
	v_mul_f32_e32 v160, 0xbfb8aa3b, v160
	v_mul_f32_e32 v161, 0xbfb8aa3b, v161
	v_mul_f32_e32 v174, 0xbfb8aa3b, v174
	v_mul_f32_e32 v162, 0xbfb8aa3b, v162
	v_mul_f32_e32 v175, 0xbfb8aa3b, v175
	v_mul_f32_e32 v163, 0xbfb8aa3b, v163
	v_mul_f32_e32 v176, 0xbfb8aa3b, v176
	v_med3_f32 v1, v1, s69, v217
	v_med3_f32 v153, v153, s69, v217
	v_med3_f32 v160, v160, s69, v217
	v_med3_f32 v161, v161, s69, v217
	v_med3_f32 v174, v174, s69, v217
	v_med3_f32 v162, v162, s69, v217
	v_med3_f32 v175, v175, s69, v217
	v_med3_f32 v163, v163, s69, v217
	v_med3_f32 v176, v176, s69, v217
	v_exp_f32_e32 v1, v1
	v_exp_f32_e32 v153, v153
	v_exp_f32_e32 v160, v160
	v_exp_f32_e32 v161, v161
	v_exp_f32_e32 v174, v174
	v_exp_f32_e32 v162, v162
	v_exp_f32_e32 v175, v175
	v_exp_f32_e32 v163, v163
	v_and_b32_e32 v164, 0xffff0000, v164
	v_exp_f32_e32 v176, v176
	v_mul_f32_e32 v164, 0xbfb8aa3b, v164
	v_med3_f32 v164, v164, s69, v217
	v_exp_f32_e32 v178, v164
	v_add_f32_e32 v1, 1.0, v1
	v_add_f32_e32 v153, 1.0, v153
	v_add_f32_e32 v164, 1.0, v160
	v_add_f32_e32 v177, 1.0, v161
	v_add_f32_e32 v174, 1.0, v174
	v_add_f32_e32 v179, 1.0, v162
	v_add_f32_e32 v180, 1.0, v175
	v_add_f32_e32 v181, 1.0, v163
	v_add_f32_e32 v182, 1.0, v176
	v_rcp_f32_e32 v160, v1
	v_rcp_f32_e32 v161, v153
	v_rcp_f32_e32 v162, v164
	v_rcp_f32_e32 v163, v177
	v_rcp_f32_e32 v174, v174
	v_rcp_f32_e32 v175, v179
	v_rcp_f32_e32 v176, v180
	v_rcp_f32_e32 v177, v181
	v_mul_f32_e32 v128, v128, v160
	v_mul_f32_e32 v129, v129, v161
	v_mul_f32_e32 v130, v130, v162
	v_mul_f32_e32 v131, v131, v163
	v_mul_f32_e32 v160, v124, v174
	v_mul_f32_e32 v161, v125, v175
	v_mul_f32_e32 v162, v126, v176
	v_mul_f32_e32 v163, v127, v177
	v_cvt_pk_bf16_f32 v124, v128, v129
	v_cvt_pk_bf16_f32 v125, v130, v131
	v_cvt_pk_bf16_f32 v126, v160, v161
	v_cvt_pk_bf16_f32 v127, v162, v163
	global_store_dwordx4 v[172:173], v[124:127], off
	v_add_f32_e32 v1, 1.0, v178
	v_rcp_f32_e32 v164, v182
	v_lshlrev_b32_e32 v124, 16, v165
	v_mul_f32_e32 v124, 0xbfb8aa3b, v124
	v_and_b32_e32 v125, 0xffff0000, v165
	v_med3_f32 v124, v124, s69, v217
	v_mul_f32_e32 v125, 0xbfb8aa3b, v125
	v_exp_f32_e32 v124, v124
	v_med3_f32 v125, v125, s69, v217
	v_exp_f32_e32 v125, v125
	v_rcp_f32_e32 v165, v1
	v_add_f32_e32 v1, 1.0, v124
	v_rcp_f32_e32 v124, v1
	v_add_f32_e32 v1, 1.0, v125
	v_lshlrev_b32_e32 v125, 16, v166
	v_mul_f32_e32 v125, 0xbfb8aa3b, v125
	v_med3_f32 v125, v125, s69, v217
	v_exp_f32_e32 v126, v125
	v_and_b32_e32 v125, 0xffff0000, v166
	v_mul_f32_e32 v125, 0xbfb8aa3b, v125
	v_med3_f32 v125, v125, s69, v217
	v_exp_f32_e32 v127, v125
	v_rcp_f32_e32 v125, v1
	v_add_f32_e32 v1, 1.0, v126
	v_rcp_f32_e32 v126, v1
	v_add_f32_e32 v1, 1.0, v127
	v_lshlrev_b32_e32 v127, 16, v167
	v_mul_f32_e32 v127, 0xbfb8aa3b, v127
	v_med3_f32 v127, v127, s69, v217
	v_exp_f32_e32 v128, v127
	v_and_b32_e32 v127, 0xffff0000, v167
	v_mul_f32_e32 v127, 0xbfb8aa3b, v127
	v_med3_f32 v127, v127, s69, v217
	v_exp_f32_e32 v129, v127
	v_rcp_f32_e32 v127, v1
	v_add_f32_e32 v1, 1.0, v128
	v_rcp_f32_e32 v128, v1
	v_add_f32_e32 v1, 1.0, v129
	v_rcp_f32_e32 v129, v1
	v_mul_f32_e32 v120, v120, v164
	v_mul_f32_e32 v121, v121, v165
	v_mul_f32_e32 v122, v122, v124
	v_mul_f32_e32 v123, v123, v125
	v_mul_f32_e32 v124, v116, v126
	v_mul_f32_e32 v125, v117, v127
	v_mul_f32_e32 v126, v118, v128
	v_mul_f32_e32 v127, v119, v129
	v_cvt_pk_bf16_f32 v116, v120, v121
	v_cvt_pk_bf16_f32 v117, v122, v123
	v_cvt_pk_bf16_f32 v118, v124, v125
	v_cvt_pk_bf16_f32 v119, v126, v127
	v_lshlrev_b32_e32 v1, 16, v168
	global_store_dwordx4 v[172:173], v[116:119], off offset:256
	v_mul_f32_e32 v1, 0xbfb8aa3b, v1
	v_med3_f32 v1, v1, s69, v217
	v_and_b32_e32 v116, 0xffff0000, v168
; __device__ __forceinline__ unsigned cvt_pk_bf16(float lo, float hi) { f32x2 v = {lo, hi}; bf16x2_t b = __builtin_convertvector(v, bf16x2_t); return __builtin_bit_cast(unsigned, b); }
; __device__ __forceinline__ float bf_lo(unsigned w) { return __uint_as_float(w << 16); }
; __device__ __forceinline__ float bf_hi(unsigned w) { return __uint_as_float(w & 0xffff0000u); }
;     __device__ __forceinline__ static float e2(float x) { return __builtin_amdgcn_exp2f(fminf(fmaxf(-x * LOG2E, -60.f), 60.f)); }
;     __device__ __forceinline__ void operator()(const f32x4 (&acc)[2][2][4][2], const Unit& u, int wr, int wc, int fr, int fq) const {
;     ...
;             for (int m = 0; m < 4; ++m)
; #pragma unroll
;                 for (int bj = 0; bj < 2; ++bj) { float o[8];
; #pragma unroll
;                     for (int q = 0; q < 4; ++q) { o[2 * q] = __builtin_amdgcn_rcpf(1.0f + e2(bf_lo(gb[m][bj][q]))) * acc[ai][bj][m][q >> 1][(2 * q) & 3]; o[2 * q + 1] = __builtin_amdgcn_rcpf(1.0f + e2(bf_hi(gb[m][bj][q]))) * acc[ai][bj][m][q >> 1][(2 * q + 1) & 3]; }
;                     u32x4 w; w.x = cvt_pk_bf16(o[0], o[1]); w.y = cvt_pk_bf16(o[2], o[3]); w.z = cvt_pk_bf16(o[4], o[5]); w.w = cvt_pk_bf16(o[6], o[7]);
;                     *(u32x4*)(T + (size_t)(row0 + ai * HALF + m * 16) * 1024 + col0 + bj * HALF) = w; }
	v_mul_f32_e32 v116, 0xbfb8aa3b, v116
	v_exp_f32_e32 v1, v1
	v_med3_f32 v116, v116, s69, v217
	v_exp_f32_e32 v119, v116
	v_lshlrev_b64 v[116:117], 11, v[158:159]
	v_add_f32_e32 v1, 1.0, v1
	v_rcp_f32_e32 v118, v1
	v_add_f32_e32 v1, 1.0, v119
	v_lshlrev_b32_e32 v119, 16, v169
	v_mul_f32_e32 v119, 0xbfb8aa3b, v119
	v_med3_f32 v119, v119, s69, v217
	v_exp_f32_e32 v120, v119
	v_and_b32_e32 v119, 0xffff0000, v169
	v_mul_f32_e32 v119, 0xbfb8aa3b, v119
	v_med3_f32 v119, v119, s69, v217
	v_exp_f32_e32 v121, v119
	v_rcp_f32_e32 v119, v1
	v_add_f32_e32 v1, 1.0, v120
	v_rcp_f32_e32 v120, v1
	v_add_f32_e32 v1, 1.0, v121
	v_lshlrev_b32_e32 v121, 16, v170
	v_mul_f32_e32 v121, 0xbfb8aa3b, v121
	v_med3_f32 v121, v121, s69, v217
	v_exp_f32_e32 v122, v121
	v_and_b32_e32 v121, 0xffff0000, v170
	v_mul_f32_e32 v121, 0xbfb8aa3b, v121
	v_med3_f32 v121, v121, s69, v217
	v_exp_f32_e32 v123, v121
	v_rcp_f32_e32 v121, v1
	v_add_f32_e32 v1, 1.0, v122
	v_rcp_f32_e32 v122, v1
	v_add_f32_e32 v1, 1.0, v123
	v_lshlrev_b32_e32 v123, 16, v171
	v_mul_f32_e32 v123, 0xbfb8aa3b, v123
	v_med3_f32 v123, v123, s69, v217
	v_exp_f32_e32 v124, v123
	v_and_b32_e32 v123, 0xffff0000, v171
	v_mul_f32_e32 v123, 0xbfb8aa3b, v123
	v_med3_f32 v123, v123, s69, v217
	v_exp_f32_e32 v125, v123
	v_rcp_f32_e32 v123, v1
	v_add_f32_e32 v1, 1.0, v124
	v_rcp_f32_e32 v124, v1
	v_add_f32_e32 v1, 1.0, v125
	v_rcp_f32_e32 v125, v1
	v_mul_f32_e32 v112, v112, v118
	v_mul_f32_e32 v113, v113, v119
	v_mul_f32_e32 v114, v114, v120
	v_mul_f32_e32 v115, v115, v121
	v_mul_f32_e32 v118, v108, v122
	v_mul_f32_e32 v119, v109, v123
	v_mul_f32_e32 v120, v110, v124
	v_mul_f32_e32 v121, v111, v125
	v_cvt_pk_bf16_f32 v108, v112, v113
	v_lshl_add_u64 v[112:113], s[8:9], 0, v[116:117]
	v_cvt_pk_bf16_f32 v109, v114, v115
	v_cvt_pk_bf16_f32 v110, v118, v119
	v_cvt_pk_bf16_f32 v111, v120, v121
	v_lshl_add_u64 v[112:113], v[112:113], 0, v[2:3]
	v_lshlrev_b32_e32 v1, 16, v148
	global_store_dwordx4 v[112:113], v[108:111], off
	v_mul_f32_e32 v1, 0xbfb8aa3b, v1
	v_and_b32_e32 v114, 0xffff0000, v148
	v_lshlrev_b32_e32 v109, 16, v149
	v_mul_f32_e32 v109, 0xbfb8aa3b, v109
	v_med3_f32 v1, v1, s69, v217
	v_mul_f32_e32 v114, 0xbfb8aa3b, v114
	v_med3_f32 v109, v109, s69, v217
	v_exp_f32_e32 v1, v1
	v_med3_f32 v114, v114, s69, v217
	v_exp_f32_e32 v110, v109
	v_and_b32_e32 v109, 0xffff0000, v149
	v_exp_f32_e32 v114, v114
	v_mul_f32_e32 v109, 0xbfb8aa3b, v109
	v_med3_f32 v109, v109, s69, v217
	v_exp_f32_e32 v111, v109
	v_add_f32_e32 v1, 1.0, v1
	v_rcp_f32_e32 v108, v1
	v_add_f32_e32 v1, 1.0, v114
	v_rcp_f32_e32 v109, v1
	v_add_f32_e32 v1, 1.0, v110
	v_rcp_f32_e32 v110, v1
	v_add_f32_e32 v1, 1.0, v111
	v_lshlrev_b32_e32 v111, 16, v150
	v_mul_f32_e32 v111, 0xbfb8aa3b, v111
	v_med3_f32 v111, v111, s69, v217
	v_exp_f32_e32 v114, v111
	v_and_b32_e32 v111, 0xffff0000, v150
	v_mul_f32_e32 v111, 0xbfb8aa3b, v111
	v_med3_f32 v111, v111, s69, v217
	v_exp_f32_e32 v115, v111
	v_rcp_f32_e32 v111, v1
	v_add_f32_e32 v1, 1.0, v114
	v_rcp_f32_e32 v114, v1
	v_add_f32_e32 v1, 1.0, v115
	v_lshlrev_b32_e32 v115, 16, v151
	v_mul_f32_e32 v115, 0xbfb8aa3b, v115
	v_med3_f32 v115, v115, s69, v217
	v_exp_f32_e32 v116, v115
	v_and_b32_e32 v115, 0xffff0000, v151
	v_mul_f32_e32 v115, 0xbfb8aa3b, v115
	v_med3_f32 v115, v115, s69, v217
	v_exp_f32_e32 v117, v115
	v_rcp_f32_e32 v115, v1
	v_add_f32_e32 v1, 1.0, v116
	v_rcp_f32_e32 v116, v1
	v_add_f32_e32 v1, 1.0, v117
	v_rcp_f32_e32 v117, v1
	v_mul_f32_e32 v104, v104, v108
	v_mul_f32_e32 v105, v105, v109
	v_mul_f32_e32 v106, v106, v110
	v_mul_f32_e32 v107, v107, v111
	v_mul_f32_e32 v108, v100, v114
	v_mul_f32_e32 v109, v101, v115
	v_mul_f32_e32 v110, v102, v116
	v_mul_f32_e32 v111, v103, v117
	v_cvt_pk_bf16_f32 v100, v104, v105
	v_cvt_pk_bf16_f32 v101, v106, v107
	v_cvt_pk_bf16_f32 v102, v108, v109
	v_cvt_pk_bf16_f32 v103, v110, v111
	v_lshlrev_b32_e32 v1, 16, v144
	global_store_dwordx4 v[112:113], v[100:103], off offset:256
	v_mul_f32_e32 v1, 0xbfb8aa3b, v1
	v_med3_f32 v1, v1, s69, v217
	v_and_b32_e32 v100, 0xffff0000, v144
	v_mul_f32_e32 v100, 0xbfb8aa3b, v100
	v_exp_f32_e32 v1, v1
	v_med3_f32 v100, v100, s69, v217
	v_exp_f32_e32 v103, v100
	v_lshlrev_b64 v[100:101], 11, v[156:157]
	v_add_f32_e32 v1, 1.0, v1
	v_rcp_f32_e32 v102, v1
	v_add_f32_e32 v1, 1.0, v103
	v_lshlrev_b32_e32 v103, 16, v145
	v_mul_f32_e32 v103, 0xbfb8aa3b, v103
	v_med3_f32 v103, v103, s69, v217
	v_exp_f32_e32 v104, v103
	v_and_b32_e32 v103, 0xffff0000, v145
	v_mul_f32_e32 v103, 0xbfb8aa3b, v103
	v_med3_f32 v103, v103, s69, v217
	v_exp_f32_e32 v105, v103
	v_rcp_f32_e32 v103, v1
	v_add_f32_e32 v1, 1.0, v104
	v_rcp_f32_e32 v104, v1
	v_add_f32_e32 v1, 1.0, v105
	v_lshlrev_b32_e32 v105, 16, v146
	v_mul_f32_e32 v105, 0xbfb8aa3b, v105
	v_med3_f32 v105, v105, s69, v217
	v_exp_f32_e32 v106, v105
	v_and_b32_e32 v105, 0xffff0000, v146
	v_mul_f32_e32 v105, 0xbfb8aa3b, v105
	v_med3_f32 v105, v105, s69, v217
	v_exp_f32_e32 v107, v105
	v_rcp_f32_e32 v105, v1
	v_add_f32_e32 v1, 1.0, v106
	v_rcp_f32_e32 v106, v1
	v_add_f32_e32 v1, 1.0, v107
	v_lshlrev_b32_e32 v107, 16, v147
	v_mul_f32_e32 v107, 0xbfb8aa3b, v107
	v_med3_f32 v107, v107, s69, v217
	v_exp_f32_e32 v108, v107
	v_and_b32_e32 v107, 0xffff0000, v147
	v_mul_f32_e32 v107, 0xbfb8aa3b, v107
	v_med3_f32 v107, v107, s69, v217
	v_exp_f32_e32 v109, v107
	v_rcp_f32_e32 v107, v1
	v_add_f32_e32 v1, 1.0, v108
	v_rcp_f32_e32 v108, v1
	v_add_f32_e32 v1, 1.0, v109
	v_rcp_f32_e32 v109, v1
	v_mul_f32_e32 v96, v96, v102
	v_mul_f32_e32 v97, v97, v103
	v_mul_f32_e32 v98, v98, v104
	v_mul_f32_e32 v99, v99, v105
	v_mul_f32_e32 v102, v92, v106
	v_mul_f32_e32 v103, v93, v107
	v_mul_f32_e32 v104, v94, v108
	v_mul_f32_e32 v105, v95, v109
; __device__ __forceinline__ unsigned cvt_pk_bf16(float lo, float hi) { f32x2 v = {lo, hi}; bf16x2_t b = __builtin_convertvector(v, bf16x2_t); return __builtin_bit_cast(unsigned, b); }
; __device__ __forceinline__ float bf_lo(unsigned w) { return __uint_as_float(w << 16); }
; __device__ __forceinline__ float bf_hi(unsigned w) { return __uint_as_float(w & 0xffff0000u); }
;     __device__ __forceinline__ static float e2(float x) { return __builtin_amdgcn_exp2f(fminf(fmaxf(-x * LOG2E, -60.f), 60.f)); }
;     __device__ __forceinline__ void operator()(const f32x4 (&acc)[2][2][4][2], const Unit& u, int wr, int wc, int fr, int fq) const {
;     ...
;             for (int m = 0; m < 4; ++m)
; #pragma unroll
;                 for (int bj = 0; bj < 2; ++bj) { float o[8];
; #pragma unroll
;                     for (int q = 0; q < 4; ++q) { o[2 * q] = __builtin_amdgcn_rcpf(1.0f + e2(bf_lo(gb[m][bj][q]))) * acc[ai][bj][m][q >> 1][(2 * q) & 3]; o[2 * q + 1] = __builtin_amdgcn_rcpf(1.0f + e2(bf_hi(gb[m][bj][q]))) * acc[ai][bj][m][q >> 1][(2 * q + 1) & 3]; }
;                     u32x4 w; w.x = cvt_pk_bf16(o[0], o[1]); w.y = cvt_pk_bf16(o[2], o[3]); w.z = cvt_pk_bf16(o[4], o[5]); w.w = cvt_pk_bf16(o[6], o[7]);
;                     *(u32x4*)(T + (size_t)(row0 + ai * HALF + m * 16) * 1024 + col0 + bj * HALF) = w; }
	v_cvt_pk_bf16_f32 v92, v96, v97
	v_lshl_add_u64 v[96:97], s[8:9], 0, v[100:101]
	v_cvt_pk_bf16_f32 v93, v98, v99
	v_cvt_pk_bf16_f32 v94, v102, v103
	v_cvt_pk_bf16_f32 v95, v104, v105
	v_lshl_add_u64 v[96:97], v[96:97], 0, v[2:3]
	v_lshlrev_b32_e32 v1, 16, v140
	global_store_dwordx4 v[96:97], v[92:95], off
	v_mul_f32_e32 v1, 0xbfb8aa3b, v1
	v_and_b32_e32 v98, 0xffff0000, v140
	v_lshlrev_b32_e32 v93, 16, v141
	v_mul_f32_e32 v93, 0xbfb8aa3b, v93
	v_med3_f32 v1, v1, s69, v217
	v_mul_f32_e32 v98, 0xbfb8aa3b, v98
	v_med3_f32 v93, v93, s69, v217
	v_exp_f32_e32 v1, v1
	v_med3_f32 v98, v98, s69, v217
	v_exp_f32_e32 v94, v93
	v_and_b32_e32 v93, 0xffff0000, v141
	v_exp_f32_e32 v98, v98
	v_mul_f32_e32 v93, 0xbfb8aa3b, v93
	v_med3_f32 v93, v93, s69, v217
	v_exp_f32_e32 v95, v93
	v_add_f32_e32 v1, 1.0, v1
	v_rcp_f32_e32 v92, v1
	v_add_f32_e32 v1, 1.0, v98
	v_rcp_f32_e32 v93, v1
	v_add_f32_e32 v1, 1.0, v94
	v_rcp_f32_e32 v94, v1
	v_add_f32_e32 v1, 1.0, v95
	v_lshlrev_b32_e32 v95, 16, v142
	v_mul_f32_e32 v95, 0xbfb8aa3b, v95
	v_med3_f32 v95, v95, s69, v217
	v_exp_f32_e32 v98, v95
	v_and_b32_e32 v95, 0xffff0000, v142
	v_mul_f32_e32 v95, 0xbfb8aa3b, v95
	v_med3_f32 v95, v95, s69, v217
	v_exp_f32_e32 v99, v95
	v_rcp_f32_e32 v95, v1
	v_add_f32_e32 v1, 1.0, v98
	v_rcp_f32_e32 v98, v1
	v_add_f32_e32 v1, 1.0, v99
	v_lshlrev_b32_e32 v99, 16, v143
	v_mul_f32_e32 v99, 0xbfb8aa3b, v99
	v_med3_f32 v99, v99, s69, v217
	v_exp_f32_e32 v100, v99
	v_and_b32_e32 v99, 0xffff0000, v143
	v_mul_f32_e32 v99, 0xbfb8aa3b, v99
	v_med3_f32 v99, v99, s69, v217
	v_exp_f32_e32 v101, v99
	v_rcp_f32_e32 v99, v1
	v_add_f32_e32 v1, 1.0, v100
	v_rcp_f32_e32 v100, v1
	v_add_f32_e32 v1, 1.0, v101
	v_rcp_f32_e32 v101, v1
	v_mul_f32_e32 v88, v88, v92
	v_mul_f32_e32 v89, v89, v93
	v_mul_f32_e32 v90, v90, v94
	v_mul_f32_e32 v91, v91, v95
	v_mul_f32_e32 v92, v84, v98
	v_mul_f32_e32 v93, v85, v99
	v_mul_f32_e32 v94, v86, v100
	v_mul_f32_e32 v95, v87, v101
	v_cvt_pk_bf16_f32 v84, v88, v89
	v_cvt_pk_bf16_f32 v85, v90, v91
	v_cvt_pk_bf16_f32 v86, v92, v93
	v_cvt_pk_bf16_f32 v87, v94, v95
	v_lshlrev_b32_e32 v1, 16, v136
	global_store_dwordx4 v[96:97], v[84:87], off offset:256
	v_mul_f32_e32 v1, 0xbfb8aa3b, v1
	v_med3_f32 v1, v1, s69, v217
	v_and_b32_e32 v84, 0xffff0000, v136
	v_mul_f32_e32 v84, 0xbfb8aa3b, v84
	v_exp_f32_e32 v1, v1
	v_med3_f32 v84, v84, s69, v217
	v_exp_f32_e32 v87, v84
	v_lshlrev_b64 v[84:85], 11, v[154:155]
	v_add_f32_e32 v1, 1.0, v1
	v_rcp_f32_e32 v86, v1
	v_add_f32_e32 v1, 1.0, v87
	v_lshlrev_b32_e32 v87, 16, v137
	v_mul_f32_e32 v87, 0xbfb8aa3b, v87
	v_med3_f32 v87, v87, s69, v217
	v_exp_f32_e32 v88, v87
	v_and_b32_e32 v87, 0xffff0000, v137
	v_mul_f32_e32 v87, 0xbfb8aa3b, v87
	v_med3_f32 v87, v87, s69, v217
	v_exp_f32_e32 v89, v87
	v_rcp_f32_e32 v87, v1
	v_add_f32_e32 v1, 1.0, v88
	v_rcp_f32_e32 v88, v1
	v_add_f32_e32 v1, 1.0, v89
	v_lshlrev_b32_e32 v89, 16, v138
	v_mul_f32_e32 v89, 0xbfb8aa3b, v89
	v_med3_f32 v89, v89, s69, v217
	v_exp_f32_e32 v90, v89
	v_and_b32_e32 v89, 0xffff0000, v138
	v_mul_f32_e32 v89, 0xbfb8aa3b, v89
	v_med3_f32 v89, v89, s69, v217
	v_exp_f32_e32 v91, v89
	v_rcp_f32_e32 v89, v1
	v_add_f32_e32 v1, 1.0, v90
	v_rcp_f32_e32 v90, v1
	v_add_f32_e32 v1, 1.0, v91
	v_lshlrev_b32_e32 v91, 16, v139
	v_mul_f32_e32 v91, 0xbfb8aa3b, v91
	v_med3_f32 v91, v91, s69, v217
	v_exp_f32_e32 v92, v91
	v_and_b32_e32 v91, 0xffff0000, v139
	v_mul_f32_e32 v91, 0xbfb8aa3b, v91
	v_med3_f32 v91, v91, s69, v217
	v_exp_f32_e32 v93, v91
	v_rcp_f32_e32 v91, v1
	v_add_f32_e32 v1, 1.0, v92
	v_rcp_f32_e32 v92, v1
	v_add_f32_e32 v1, 1.0, v93
	v_rcp_f32_e32 v93, v1
	v_mul_f32_e32 v80, v80, v86
	v_mul_f32_e32 v81, v81, v87
	v_mul_f32_e32 v82, v82, v88
	v_mul_f32_e32 v83, v83, v89
	v_mul_f32_e32 v86, v76, v90
	v_mul_f32_e32 v87, v77, v91
	v_mul_f32_e32 v88, v78, v92
	v_mul_f32_e32 v89, v79, v93
	v_cvt_pk_bf16_f32 v76, v80, v81
	v_lshl_add_u64 v[80:81], s[8:9], 0, v[84:85]
	v_cvt_pk_bf16_f32 v77, v82, v83
	v_cvt_pk_bf16_f32 v78, v86, v87
	v_cvt_pk_bf16_f32 v79, v88, v89
	v_lshl_add_u64 v[80:81], v[80:81], 0, v[2:3]
	v_lshlrev_b32_e32 v1, 16, v132
	global_store_dwordx4 v[80:81], v[76:79], off
	v_mul_f32_e32 v1, 0xbfb8aa3b, v1
	v_and_b32_e32 v82, 0xffff0000, v132
	v_lshlrev_b32_e32 v77, 16, v133
	v_mul_f32_e32 v77, 0xbfb8aa3b, v77
	v_med3_f32 v1, v1, s69, v217
	v_mul_f32_e32 v82, 0xbfb8aa3b, v82
	v_med3_f32 v77, v77, s69, v217
	v_exp_f32_e32 v1, v1
	v_med3_f32 v82, v82, s69, v217
	v_exp_f32_e32 v78, v77
	v_and_b32_e32 v77, 0xffff0000, v133
	v_exp_f32_e32 v82, v82
	v_mul_f32_e32 v77, 0xbfb8aa3b, v77
	v_med3_f32 v77, v77, s69, v217
	v_exp_f32_e32 v79, v77
	v_add_f32_e32 v1, 1.0, v1
	v_rcp_f32_e32 v76, v1
	v_add_f32_e32 v1, 1.0, v82
	v_rcp_f32_e32 v77, v1
	v_add_f32_e32 v1, 1.0, v78
	v_rcp_f32_e32 v78, v1
	v_add_f32_e32 v1, 1.0, v79
	v_lshlrev_b32_e32 v79, 16, v134
	v_mul_f32_e32 v79, 0xbfb8aa3b, v79
	v_med3_f32 v79, v79, s69, v217
	v_exp_f32_e32 v82, v79
	v_and_b32_e32 v79, 0xffff0000, v134
	v_mul_f32_e32 v79, 0xbfb8aa3b, v79
	v_med3_f32 v79, v79, s69, v217
	v_exp_f32_e32 v83, v79
	v_rcp_f32_e32 v79, v1
	v_add_f32_e32 v1, 1.0, v82
	v_rcp_f32_e32 v82, v1
	v_add_f32_e32 v1, 1.0, v83
	v_lshlrev_b32_e32 v83, 16, v135
	v_mul_f32_e32 v83, 0xbfb8aa3b, v83
	v_med3_f32 v83, v83, s69, v217
	v_exp_f32_e32 v84, v83
	v_and_b32_e32 v83, 0xffff0000, v135
	v_mul_f32_e32 v83, 0xbfb8aa3b, v83
	v_med3_f32 v83, v83, s69, v217
	v_exp_f32_e32 v85, v83
	v_rcp_f32_e32 v83, v1
	v_add_f32_e32 v1, 1.0, v84
	v_rcp_f32_e32 v84, v1
	v_add_f32_e32 v1, 1.0, v85
	v_rcp_f32_e32 v85, v1
	v_mul_f32_e32 v72, v72, v76
	v_mul_f32_e32 v73, v73, v77
	v_mul_f32_e32 v74, v74, v78
	v_mul_f32_e32 v75, v75, v79
	v_mul_f32_e32 v76, v68, v82
; __device__ __forceinline__ unsigned cvt_pk_bf16(float lo, float hi) { f32x2 v = {lo, hi}; bf16x2_t b = __builtin_convertvector(v, bf16x2_t); return __builtin_bit_cast(unsigned, b); }
; __device__ __forceinline__ float bf_lo(unsigned w) { return __uint_as_float(w << 16); }
; __device__ __forceinline__ float bf_hi(unsigned w) { return __uint_as_float(w & 0xffff0000u); }
;     __device__ __forceinline__ static float e2(float x) { return __builtin_amdgcn_exp2f(fminf(fmaxf(-x * LOG2E, -60.f), 60.f)); }
;     __device__ __forceinline__ void operator()(const f32x4 (&acc)[2][2][4][2], const Unit& u, int wr, int wc, int fr, int fq) const {
;     ...
;                 for (int bj = 0; bj < 2; ++bj) gb[m][bj] = *(const u32x4*)(gate + (size_t)(row0 + ai * HALF + m * 16) * 2048 + 1024 + col0 + bj * HALF);
;             asm volatile("" ::: "memory");
; #pragma unroll
;             for (int m = 0; m < 4; ++m)
; #pragma unroll
;                 for (int bj = 0; bj < 2; ++bj) { float o[8];
; #pragma unroll
;                     for (int q = 0; q < 4; ++q) { o[2 * q] = __builtin_amdgcn_rcpf(1.0f + e2(bf_lo(gb[m][bj][q]))) * acc[ai][bj][m][q >> 1][(2 * q) & 3]; o[2 * q + 1] = __builtin_amdgcn_rcpf(1.0f + e2(bf_hi(gb[m][bj][q]))) * acc[ai][bj][m][q >> 1][(2 * q + 1) & 3]; }
;                     u32x4 w; w.x = cvt_pk_bf16(o[0], o[1]); w.y = cvt_pk_bf16(o[2], o[3]); w.z = cvt_pk_bf16(o[4], o[5]); w.w = cvt_pk_bf16(o[6], o[7]);
;                     *(u32x4*)(T + (size_t)(row0 + ai * HALF + m * 16) * 1024 + col0 + bj * HALF) = w; }
	v_mul_f32_e32 v77, v69, v83
	v_mul_f32_e32 v78, v70, v84
	v_mul_f32_e32 v79, v71, v85
	v_add_u32_e32 v104, 0x80, v152
	v_cvt_pk_bf16_f32 v68, v72, v73
	v_cvt_pk_bf16_f32 v69, v74, v75
	v_cvt_pk_bf16_f32 v70, v76, v77
	v_cvt_pk_bf16_f32 v71, v78, v79
	v_ashrrev_i32_e32 v105, 31, v104
	global_store_dwordx4 v[80:81], v[68:71], off offset:256
	v_add_u32_e32 v106, 0x90, v152
	v_ashrrev_i32_e32 v107, 31, v106
	v_lshlrev_b64 v[68:69], 12, v[104:105]
	v_lshl_add_u64 v[68:69], s[10:11], 0, v[68:69]
	v_lshl_add_u64 v[68:69], v[68:69], 0, v[2:3]
	global_load_dwordx4 v[96:99], v[68:69], off offset:2048
	global_load_dwordx4 v[100:103], v[68:69], off offset:2304
	v_lshlrev_b64 v[68:69], 12, v[106:107]
	v_lshl_add_u64 v[68:69], s[10:11], 0, v[68:69]
	v_lshl_add_u64 v[68:69], v[68:69], 0, v[2:3]
	global_load_dwordx4 v[88:91], v[68:69], off offset:2048
	global_load_dwordx4 v[84:87], v[68:69], off offset:2304
	v_add_u32_e32 v94, 0xa0, v152
	v_ashrrev_i32_e32 v95, 31, v94
	v_lshlrev_b64 v[68:69], 12, v[94:95]
	v_lshl_add_u64 v[68:69], s[10:11], 0, v[68:69]
	v_add_u32_e32 v92, 0xb0, v152
	v_lshl_add_u64 v[68:69], v[68:69], 0, v[2:3]
	v_ashrrev_i32_e32 v93, 31, v92
	global_load_dwordx4 v[80:83], v[68:69], off offset:2048
	global_load_dwordx4 v[76:79], v[68:69], off offset:2304
	v_lshlrev_b64 v[68:69], 12, v[92:93]
	v_lshlrev_b64 v[104:105], 11, v[104:105]
	v_lshl_add_u64 v[68:69], s[10:11], 0, v[68:69]
	v_lshl_add_u64 v[68:69], v[68:69], 0, v[2:3]
	global_load_dwordx4 v[72:75], v[68:69], off offset:2048
	s_nop 0
	global_load_dwordx4 v[68:71], v[68:69], off offset:2304
	s_waitcnt vmcnt(7)
	v_lshlrev_b32_e32 v1, 16, v96
	v_mul_f32_e32 v1, 0xbfb8aa3b, v1
	v_and_b32_e32 v96, 0xffff0000, v96
	v_med3_f32 v1, v1, s69, v217
	v_mul_f32_e32 v96, 0xbfb8aa3b, v96
	v_exp_f32_e32 v1, v1
	v_med3_f32 v96, v96, s69, v217
	v_exp_f32_e32 v108, v96
	v_add_f32_e32 v1, 1.0, v1
	v_rcp_f32_e32 v96, v1
	v_add_f32_e32 v1, 1.0, v108
	v_lshlrev_b32_e32 v108, 16, v97
	v_mul_f32_e32 v108, 0xbfb8aa3b, v108
	v_and_b32_e32 v97, 0xffff0000, v97
	v_med3_f32 v108, v108, s69, v217
	v_mul_f32_e32 v97, 0xbfb8aa3b, v97
	v_exp_f32_e32 v108, v108
	v_med3_f32 v97, v97, s69, v217
	v_exp_f32_e32 v109, v97
	v_rcp_f32_e32 v97, v1
	v_add_f32_e32 v1, 1.0, v108
	v_rcp_f32_e32 v108, v1
	v_add_f32_e32 v1, 1.0, v109
	v_lshlrev_b32_e32 v109, 16, v98
	v_mul_f32_e32 v109, 0xbfb8aa3b, v109
	v_med3_f32 v109, v109, s69, v217
	v_exp_f32_e32 v110, v109
	v_and_b32_e32 v98, 0xffff0000, v98
	v_mul_f32_e32 v98, 0xbfb8aa3b, v98
	v_med3_f32 v98, v98, s69, v217
	v_exp_f32_e32 v111, v98
	v_rcp_f32_e32 v109, v1
	v_add_f32_e32 v1, 1.0, v110
	v_lshlrev_b32_e32 v110, 16, v99
	v_mul_f32_e32 v110, 0xbfb8aa3b, v110
	v_and_b32_e32 v99, 0xffff0000, v99
	v_med3_f32 v110, v110, s69, v217
	v_mul_f32_e32 v99, 0xbfb8aa3b, v99
	v_exp_f32_e32 v110, v110
	v_med3_f32 v99, v99, s69, v217
	v_rcp_f32_e32 v98, v1
	v_add_f32_e32 v1, 1.0, v111
	v_exp_f32_e32 v111, v99
	v_rcp_f32_e32 v99, v1
	v_add_f32_e32 v1, 1.0, v110
	v_rcp_f32_e32 v110, v1
	v_add_f32_e32 v1, 1.0, v111
	v_rcp_f32_e32 v111, v1
	v_mul_f32_e32 v64, v64, v96
	v_mul_f32_e32 v65, v65, v97
	v_mul_f32_e32 v66, v66, v108
	v_mul_f32_e32 v67, v67, v109
	v_mul_f32_e32 v96, v60, v98
	v_mul_f32_e32 v97, v61, v99
	v_mul_f32_e32 v98, v62, v110
	v_mul_f32_e32 v99, v63, v111
	v_cvt_pk_bf16_f32 v60, v64, v65
	v_lshl_add_u64 v[64:65], s[8:9], 0, v[104:105]
	v_cvt_pk_bf16_f32 v61, v66, v67
	v_cvt_pk_bf16_f32 v62, v96, v97
	v_cvt_pk_bf16_f32 v63, v98, v99
	v_lshl_add_u64 v[64:65], v[64:65], 0, v[2:3]
	s_waitcnt vmcnt(6)
	v_lshlrev_b32_e32 v1, 16, v100
	global_store_dwordx4 v[64:65], v[60:63], off
	v_mul_f32_e32 v1, 0xbfb8aa3b, v1
	v_and_b32_e32 v66, 0xffff0000, v100
	v_lshlrev_b32_e32 v61, 16, v101
	v_mul_f32_e32 v61, 0xbfb8aa3b, v61
	v_med3_f32 v1, v1, s69, v217
	v_mul_f32_e32 v66, 0xbfb8aa3b, v66
	v_med3_f32 v61, v61, s69, v217
	v_exp_f32_e32 v1, v1
	v_med3_f32 v66, v66, s69, v217
	v_exp_f32_e32 v62, v61
	v_and_b32_e32 v61, 0xffff0000, v101
	v_exp_f32_e32 v66, v66
	v_mul_f32_e32 v61, 0xbfb8aa3b, v61
	v_med3_f32 v61, v61, s69, v217
	v_exp_f32_e32 v63, v61
	v_add_f32_e32 v1, 1.0, v1
	v_rcp_f32_e32 v60, v1
	v_add_f32_e32 v1, 1.0, v66
	v_rcp_f32_e32 v61, v1
	v_add_f32_e32 v1, 1.0, v62
	v_rcp_f32_e32 v62, v1
	v_add_f32_e32 v1, 1.0, v63
	v_lshlrev_b32_e32 v63, 16, v102
	v_mul_f32_e32 v63, 0xbfb8aa3b, v63
	v_med3_f32 v63, v63, s69, v217
	v_exp_f32_e32 v66, v63
	v_and_b32_e32 v63, 0xffff0000, v102
	v_mul_f32_e32 v63, 0xbfb8aa3b, v63
	v_med3_f32 v63, v63, s69, v217
	v_exp_f32_e32 v67, v63
	v_rcp_f32_e32 v63, v1
	v_add_f32_e32 v1, 1.0, v66
	v_rcp_f32_e32 v66, v1
	v_add_f32_e32 v1, 1.0, v67
	v_lshlrev_b32_e32 v67, 16, v103
	v_mul_f32_e32 v67, 0xbfb8aa3b, v67
	v_med3_f32 v67, v67, s69, v217
	v_exp_f32_e32 v96, v67
	v_and_b32_e32 v67, 0xffff0000, v103
	v_mul_f32_e32 v67, 0xbfb8aa3b, v67
	v_med3_f32 v67, v67, s69, v217
	v_exp_f32_e32 v97, v67
	v_rcp_f32_e32 v67, v1
	v_add_f32_e32 v1, 1.0, v96
	v_rcp_f32_e32 v96, v1
	v_add_f32_e32 v1, 1.0, v97
	v_rcp_f32_e32 v97, v1
	v_mul_f32_e32 v56, v56, v60
	v_mul_f32_e32 v57, v57, v61
	v_mul_f32_e32 v58, v58, v62
	v_mul_f32_e32 v59, v59, v63
	v_mul_f32_e32 v60, v52, v66
	v_mul_f32_e32 v61, v53, v67
	v_mul_f32_e32 v62, v54, v96
	v_mul_f32_e32 v63, v55, v97
	v_cvt_pk_bf16_f32 v52, v56, v57
	v_cvt_pk_bf16_f32 v53, v58, v59
	v_cvt_pk_bf16_f32 v54, v60, v61
	v_cvt_pk_bf16_f32 v55, v62, v63
	s_waitcnt vmcnt(6)
; __device__ __forceinline__ unsigned cvt_pk_bf16(float lo, float hi) { f32x2 v = {lo, hi}; bf16x2_t b = __builtin_convertvector(v, bf16x2_t); return __builtin_bit_cast(unsigned, b); }
; __device__ __forceinline__ float bf_lo(unsigned w) { return __uint_as_float(w << 16); }
; __device__ __forceinline__ float bf_hi(unsigned w) { return __uint_as_float(w & 0xffff0000u); }
;     __device__ __forceinline__ static float e2(float x) { return __builtin_amdgcn_exp2f(fminf(fmaxf(-x * LOG2E, -60.f), 60.f)); }
;     __device__ __forceinline__ void operator()(const f32x4 (&acc)[2][2][4][2], const Unit& u, int wr, int wc, int fr, int fq) const {
;     ...
;             for (int m = 0; m < 4; ++m)
; #pragma unroll
;                 for (int bj = 0; bj < 2; ++bj) { float o[8];
; #pragma unroll
;                     for (int q = 0; q < 4; ++q) { o[2 * q] = __builtin_amdgcn_rcpf(1.0f + e2(bf_lo(gb[m][bj][q]))) * acc[ai][bj][m][q >> 1][(2 * q) & 3]; o[2 * q + 1] = __builtin_amdgcn_rcpf(1.0f + e2(bf_hi(gb[m][bj][q]))) * acc[ai][bj][m][q >> 1][(2 * q + 1) & 3]; }
;                     u32x4 w; w.x = cvt_pk_bf16(o[0], o[1]); w.y = cvt_pk_bf16(o[2], o[3]); w.z = cvt_pk_bf16(o[4], o[5]); w.w = cvt_pk_bf16(o[6], o[7]);
;                     *(u32x4*)(T + (size_t)(row0 + ai * HALF + m * 16) * 1024 + col0 + bj * HALF) = w; }
	v_lshlrev_b32_e32 v1, 16, v88
	global_store_dwordx4 v[64:65], v[52:55], off offset:256
	v_mul_f32_e32 v1, 0xbfb8aa3b, v1
	v_med3_f32 v1, v1, s69, v217
	v_and_b32_e32 v52, 0xffff0000, v88
	v_mul_f32_e32 v52, 0xbfb8aa3b, v52
	v_exp_f32_e32 v1, v1
	v_med3_f32 v52, v52, s69, v217
	v_exp_f32_e32 v55, v52
	v_lshlrev_b64 v[52:53], 11, v[106:107]
	v_add_f32_e32 v1, 1.0, v1
	v_rcp_f32_e32 v54, v1
	v_add_f32_e32 v1, 1.0, v55
	v_lshlrev_b32_e32 v55, 16, v89
	v_mul_f32_e32 v55, 0xbfb8aa3b, v55
	v_med3_f32 v55, v55, s69, v217
	v_exp_f32_e32 v56, v55
	v_and_b32_e32 v55, 0xffff0000, v89
	v_mul_f32_e32 v55, 0xbfb8aa3b, v55
	v_med3_f32 v55, v55, s69, v217
	v_exp_f32_e32 v57, v55
	v_rcp_f32_e32 v55, v1
	v_add_f32_e32 v1, 1.0, v56
	v_rcp_f32_e32 v56, v1
	v_add_f32_e32 v1, 1.0, v57
	v_lshlrev_b32_e32 v57, 16, v90
	v_mul_f32_e32 v57, 0xbfb8aa3b, v57
	v_med3_f32 v57, v57, s69, v217
	v_exp_f32_e32 v58, v57
	v_and_b32_e32 v57, 0xffff0000, v90
	v_mul_f32_e32 v57, 0xbfb8aa3b, v57
	v_med3_f32 v57, v57, s69, v217
	v_exp_f32_e32 v59, v57
	v_rcp_f32_e32 v57, v1
	v_add_f32_e32 v1, 1.0, v58
	v_rcp_f32_e32 v58, v1
	v_add_f32_e32 v1, 1.0, v59
	v_lshlrev_b32_e32 v59, 16, v91
	v_mul_f32_e32 v59, 0xbfb8aa3b, v59
	v_med3_f32 v59, v59, s69, v217
	v_exp_f32_e32 v60, v59
	v_and_b32_e32 v59, 0xffff0000, v91
	v_mul_f32_e32 v59, 0xbfb8aa3b, v59
	v_med3_f32 v59, v59, s69, v217
	v_exp_f32_e32 v61, v59
	v_rcp_f32_e32 v59, v1
	v_add_f32_e32 v1, 1.0, v60
	v_rcp_f32_e32 v60, v1
	v_add_f32_e32 v1, 1.0, v61
	v_rcp_f32_e32 v61, v1
	v_mul_f32_e32 v48, v48, v54
	v_mul_f32_e32 v49, v49, v55
	v_mul_f32_e32 v50, v50, v56
	v_mul_f32_e32 v51, v51, v57
	v_mul_f32_e32 v54, v44, v58
	v_mul_f32_e32 v55, v45, v59
	v_mul_f32_e32 v56, v46, v60
	v_mul_f32_e32 v57, v47, v61
	v_cvt_pk_bf16_f32 v44, v48, v49
	v_lshl_add_u64 v[48:49], s[8:9], 0, v[52:53]
	v_cvt_pk_bf16_f32 v45, v50, v51
	v_cvt_pk_bf16_f32 v46, v54, v55
	v_cvt_pk_bf16_f32 v47, v56, v57
	v_lshl_add_u64 v[48:49], v[48:49], 0, v[2:3]
	s_waitcnt vmcnt(6)
	v_lshlrev_b32_e32 v1, 16, v84
	global_store_dwordx4 v[48:49], v[44:47], off
	v_mul_f32_e32 v1, 0xbfb8aa3b, v1
	v_and_b32_e32 v50, 0xffff0000, v84
	v_lshlrev_b32_e32 v45, 16, v85
	v_mul_f32_e32 v45, 0xbfb8aa3b, v45
	v_med3_f32 v1, v1, s69, v217
	v_mul_f32_e32 v50, 0xbfb8aa3b, v50
	v_med3_f32 v45, v45, s69, v217
	v_exp_f32_e32 v1, v1
	v_med3_f32 v50, v50, s69, v217
	v_exp_f32_e32 v46, v45
	v_and_b32_e32 v45, 0xffff0000, v85
	v_exp_f32_e32 v50, v50
	v_mul_f32_e32 v45, 0xbfb8aa3b, v45
	v_med3_f32 v45, v45, s69, v217
	v_exp_f32_e32 v47, v45
	v_add_f32_e32 v1, 1.0, v1
	v_rcp_f32_e32 v44, v1
	v_add_f32_e32 v1, 1.0, v50
	v_rcp_f32_e32 v45, v1
	v_add_f32_e32 v1, 1.0, v46
	v_rcp_f32_e32 v46, v1
	v_add_f32_e32 v1, 1.0, v47
	v_lshlrev_b32_e32 v47, 16, v86
	v_mul_f32_e32 v47, 0xbfb8aa3b, v47
	v_med3_f32 v47, v47, s69, v217
	v_exp_f32_e32 v50, v47
	v_and_b32_e32 v47, 0xffff0000, v86
	v_mul_f32_e32 v47, 0xbfb8aa3b, v47
	v_med3_f32 v47, v47, s69, v217
	v_exp_f32_e32 v51, v47
	v_rcp_f32_e32 v47, v1
	v_add_f32_e32 v1, 1.0, v50
	v_rcp_f32_e32 v50, v1
	v_add_f32_e32 v1, 1.0, v51
	v_lshlrev_b32_e32 v51, 16, v87
	v_mul_f32_e32 v51, 0xbfb8aa3b, v51
	v_med3_f32 v51, v51, s69, v217
	v_exp_f32_e32 v52, v51
	v_and_b32_e32 v51, 0xffff0000, v87
	v_mul_f32_e32 v51, 0xbfb8aa3b, v51
	v_med3_f32 v51, v51, s69, v217
	v_exp_f32_e32 v53, v51
	v_rcp_f32_e32 v51, v1
	v_add_f32_e32 v1, 1.0, v52
	v_rcp_f32_e32 v52, v1
	v_add_f32_e32 v1, 1.0, v53
	v_rcp_f32_e32 v53, v1
	v_mul_f32_e32 v40, v40, v44
	v_mul_f32_e32 v41, v41, v45
	v_mul_f32_e32 v42, v42, v46
	v_mul_f32_e32 v43, v43, v47
	v_mul_f32_e32 v44, v36, v50
	v_mul_f32_e32 v45, v37, v51
	v_mul_f32_e32 v46, v38, v52
	v_mul_f32_e32 v47, v39, v53
	v_cvt_pk_bf16_f32 v36, v40, v41
	v_cvt_pk_bf16_f32 v37, v42, v43
	v_cvt_pk_bf16_f32 v38, v44, v45
	v_cvt_pk_bf16_f32 v39, v46, v47
	s_waitcnt vmcnt(6)
	v_lshlrev_b32_e32 v1, 16, v80
	global_store_dwordx4 v[48:49], v[36:39], off offset:256
	v_mul_f32_e32 v1, 0xbfb8aa3b, v1
	v_med3_f32 v1, v1, s69, v217
	v_and_b32_e32 v36, 0xffff0000, v80
	v_mul_f32_e32 v36, 0xbfb8aa3b, v36
	v_exp_f32_e32 v1, v1
	v_med3_f32 v36, v36, s69, v217
	v_exp_f32_e32 v39, v36
	v_lshlrev_b64 v[36:37], 11, v[94:95]
	v_add_f32_e32 v1, 1.0, v1
	v_rcp_f32_e32 v38, v1
	v_add_f32_e32 v1, 1.0, v39
	v_lshlrev_b32_e32 v39, 16, v81
	v_mul_f32_e32 v39, 0xbfb8aa3b, v39
	v_med3_f32 v39, v39, s69, v217
	v_exp_f32_e32 v40, v39
	v_and_b32_e32 v39, 0xffff0000, v81
	v_mul_f32_e32 v39, 0xbfb8aa3b, v39
	v_med3_f32 v39, v39, s69, v217
	v_exp_f32_e32 v41, v39
	v_rcp_f32_e32 v39, v1
	v_add_f32_e32 v1, 1.0, v40
	v_rcp_f32_e32 v40, v1
	v_add_f32_e32 v1, 1.0, v41
	v_lshlrev_b32_e32 v41, 16, v82
	v_mul_f32_e32 v41, 0xbfb8aa3b, v41
	v_med3_f32 v41, v41, s69, v217
	v_exp_f32_e32 v42, v41
	v_and_b32_e32 v41, 0xffff0000, v82
	v_mul_f32_e32 v41, 0xbfb8aa3b, v41
	v_med3_f32 v41, v41, s69, v217
	v_exp_f32_e32 v43, v41
	v_rcp_f32_e32 v41, v1
	v_add_f32_e32 v1, 1.0, v42
	v_rcp_f32_e32 v42, v1
	v_add_f32_e32 v1, 1.0, v43
	v_lshlrev_b32_e32 v43, 16, v83
	v_mul_f32_e32 v43, 0xbfb8aa3b, v43
	v_med3_f32 v43, v43, s69, v217
	v_exp_f32_e32 v44, v43
	v_and_b32_e32 v43, 0xffff0000, v83
	v_mul_f32_e32 v43, 0xbfb8aa3b, v43
	v_med3_f32 v43, v43, s69, v217
	v_exp_f32_e32 v45, v43
	v_rcp_f32_e32 v43, v1
	v_add_f32_e32 v1, 1.0, v44
	v_rcp_f32_e32 v44, v1
	v_add_f32_e32 v1, 1.0, v45
	v_rcp_f32_e32 v45, v1
	v_mul_f32_e32 v32, v32, v38
	v_mul_f32_e32 v33, v33, v39
	v_mul_f32_e32 v34, v34, v40
	v_mul_f32_e32 v35, v35, v41
	v_mul_f32_e32 v38, v28, v42
	v_mul_f32_e32 v39, v29, v43
	v_mul_f32_e32 v40, v30, v44
	v_mul_f32_e32 v41, v31, v45
	v_cvt_pk_bf16_f32 v28, v32, v33
	v_lshl_add_u64 v[32:33], s[8:9], 0, v[36:37]
	v_cvt_pk_bf16_f32 v29, v34, v35
	v_cvt_pk_bf16_f32 v30, v38, v39
	v_cvt_pk_bf16_f32 v31, v40, v41
	v_lshl_add_u64 v[32:33], v[32:33], 0, v[2:3]
	s_waitcnt vmcnt(6)
; __device__ __forceinline__ unsigned cvt_pk_bf16(float lo, float hi) { f32x2 v = {lo, hi}; bf16x2_t b = __builtin_convertvector(v, bf16x2_t); return __builtin_bit_cast(unsigned, b); }
; __device__ __forceinline__ float bf_lo(unsigned w) { return __uint_as_float(w << 16); }
; __device__ __forceinline__ float bf_hi(unsigned w) { return __uint_as_float(w & 0xffff0000u); }
;     __device__ __forceinline__ static float e2(float x) { return __builtin_amdgcn_exp2f(fminf(fmaxf(-x * LOG2E, -60.f), 60.f)); }
; #define PG8_BAR __builtin_amdgcn_s_barrier()
;     __device__ __forceinline__ void operator()(const f32x4 (&acc)[2][2][4][2], const Unit& u, int wr, int wc, int fr, int fq) const {
;     ...
;             for (int m = 0; m < 4; ++m)
; #pragma unroll
;                 for (int bj = 0; bj < 2; ++bj) { float o[8];
; #pragma unroll
;                     for (int q = 0; q < 4; ++q) { o[2 * q] = __builtin_amdgcn_rcpf(1.0f + e2(bf_lo(gb[m][bj][q]))) * acc[ai][bj][m][q >> 1][(2 * q) & 3]; o[2 * q + 1] = __builtin_amdgcn_rcpf(1.0f + e2(bf_hi(gb[m][bj][q]))) * acc[ai][bj][m][q >> 1][(2 * q + 1) & 3]; }
;                     u32x4 w; w.x = cvt_pk_bf16(o[0], o[1]); w.y = cvt_pk_bf16(o[2], o[3]); w.z = cvt_pk_bf16(o[4], o[5]); w.w = cvt_pk_bf16(o[6], o[7]);
;                     *(u32x4*)(T + (size_t)(row0 + ai * HALF + m * 16) * 1024 + col0 + bj * HALF) = w; }
;             asm volatile("" ::: "memory");
; template <class Epi, class Sched, bool ALIGN_EPI = false, bool SP2 = false>
; __device__ __forceinline__ void gemm_phase(PG8_LAS unsigned char* lds, const Gemm g, const Sched& S, const Epi& E, int tid_in) {
;     ...
;         if constexpr (!Epi::AFTER_DRAIN) { E(acc, cur, wr, wc, fr, fq); S.done(cur); }
;         if (!has_next) break;
; #pragma unroll
;         for (int a = 0; a < 2; ++a)
; #pragma unroll
;             for (int b = 0; b < 2; ++b)
; #pragma unroll
;                 for (int m = 0; m < 4; ++m)
; #pragma unroll
;                     for (int n = 0; n < 2; ++n) acc[a][b][m][n] = (f32x4){0.f, 0.f, 0.f, 0.f};
;         cur = nxt; cA = nA; cB = nB; ++ui;
;         if constexpr (ALIGN_EPI) { if (wr == 1) PG8_BAR; }
	v_lshlrev_b32_e32 v1, 16, v76
	global_store_dwordx4 v[32:33], v[28:31], off
	v_mul_f32_e32 v1, 0xbfb8aa3b, v1
	v_and_b32_e32 v34, 0xffff0000, v76
	v_lshlrev_b32_e32 v29, 16, v77
	v_mul_f32_e32 v29, 0xbfb8aa3b, v29
	v_med3_f32 v1, v1, s69, v217
	v_mul_f32_e32 v34, 0xbfb8aa3b, v34
	v_med3_f32 v29, v29, s69, v217
	v_exp_f32_e32 v1, v1
	v_med3_f32 v34, v34, s69, v217
	v_exp_f32_e32 v30, v29
	v_and_b32_e32 v29, 0xffff0000, v77
	v_exp_f32_e32 v34, v34
	v_mul_f32_e32 v29, 0xbfb8aa3b, v29
	v_med3_f32 v29, v29, s69, v217
	v_exp_f32_e32 v31, v29
	v_add_f32_e32 v1, 1.0, v1
	v_rcp_f32_e32 v28, v1
	v_add_f32_e32 v1, 1.0, v34
	v_rcp_f32_e32 v29, v1
	v_add_f32_e32 v1, 1.0, v30
	v_rcp_f32_e32 v30, v1
	v_add_f32_e32 v1, 1.0, v31
	v_lshlrev_b32_e32 v31, 16, v78
	v_mul_f32_e32 v31, 0xbfb8aa3b, v31
	v_med3_f32 v31, v31, s69, v217
	v_exp_f32_e32 v34, v31
	v_and_b32_e32 v31, 0xffff0000, v78
	v_mul_f32_e32 v31, 0xbfb8aa3b, v31
	v_med3_f32 v31, v31, s69, v217
	v_exp_f32_e32 v35, v31
	v_rcp_f32_e32 v31, v1
	v_add_f32_e32 v1, 1.0, v34
	v_rcp_f32_e32 v34, v1
	v_add_f32_e32 v1, 1.0, v35
	v_lshlrev_b32_e32 v35, 16, v79
	v_mul_f32_e32 v35, 0xbfb8aa3b, v35
	v_med3_f32 v35, v35, s69, v217
	v_exp_f32_e32 v36, v35
	v_and_b32_e32 v35, 0xffff0000, v79
	v_mul_f32_e32 v35, 0xbfb8aa3b, v35
	v_med3_f32 v35, v35, s69, v217
	v_exp_f32_e32 v37, v35
	v_rcp_f32_e32 v35, v1
	v_add_f32_e32 v1, 1.0, v36
	v_rcp_f32_e32 v36, v1
	v_add_f32_e32 v1, 1.0, v37
	v_rcp_f32_e32 v37, v1
	v_mul_f32_e32 v24, v24, v28
	v_mul_f32_e32 v25, v25, v29
	v_mul_f32_e32 v26, v26, v30
	v_mul_f32_e32 v27, v27, v31
	v_mul_f32_e32 v28, v20, v34
	v_mul_f32_e32 v29, v21, v35
	v_mul_f32_e32 v30, v22, v36
	v_mul_f32_e32 v31, v23, v37
	v_cvt_pk_bf16_f32 v20, v24, v25
	v_cvt_pk_bf16_f32 v21, v26, v27
	v_cvt_pk_bf16_f32 v22, v28, v29
	v_cvt_pk_bf16_f32 v23, v30, v31
	s_waitcnt vmcnt(6)
	v_lshlrev_b32_e32 v1, 16, v72
	global_store_dwordx4 v[32:33], v[20:23], off offset:256
	v_mul_f32_e32 v1, 0xbfb8aa3b, v1
	v_med3_f32 v1, v1, s69, v217
	v_and_b32_e32 v20, 0xffff0000, v72
	v_mul_f32_e32 v20, 0xbfb8aa3b, v20
	v_exp_f32_e32 v1, v1
	v_med3_f32 v20, v20, s69, v217
	v_exp_f32_e32 v23, v20
	v_lshlrev_b64 v[20:21], 11, v[92:93]
	v_add_f32_e32 v1, 1.0, v1
	v_rcp_f32_e32 v22, v1
	v_add_f32_e32 v1, 1.0, v23
	v_lshlrev_b32_e32 v23, 16, v73
	v_mul_f32_e32 v23, 0xbfb8aa3b, v23
	v_med3_f32 v23, v23, s69, v217
	v_exp_f32_e32 v24, v23
	v_and_b32_e32 v23, 0xffff0000, v73
	v_mul_f32_e32 v23, 0xbfb8aa3b, v23
	v_med3_f32 v23, v23, s69, v217
	v_exp_f32_e32 v25, v23
	v_rcp_f32_e32 v23, v1
	v_add_f32_e32 v1, 1.0, v24
	v_rcp_f32_e32 v24, v1
	v_add_f32_e32 v1, 1.0, v25
	v_lshlrev_b32_e32 v25, 16, v74
	v_mul_f32_e32 v25, 0xbfb8aa3b, v25
	v_med3_f32 v25, v25, s69, v217
	v_exp_f32_e32 v26, v25
	v_and_b32_e32 v25, 0xffff0000, v74
	v_mul_f32_e32 v25, 0xbfb8aa3b, v25
	v_med3_f32 v25, v25, s69, v217
	v_exp_f32_e32 v27, v25
	v_rcp_f32_e32 v25, v1
	v_add_f32_e32 v1, 1.0, v26
	v_rcp_f32_e32 v26, v1
	v_add_f32_e32 v1, 1.0, v27
	v_lshlrev_b32_e32 v27, 16, v75
	v_mul_f32_e32 v27, 0xbfb8aa3b, v27
	v_med3_f32 v27, v27, s69, v217
	v_exp_f32_e32 v28, v27
	v_and_b32_e32 v27, 0xffff0000, v75
	v_mul_f32_e32 v27, 0xbfb8aa3b, v27
	v_med3_f32 v27, v27, s69, v217
	v_exp_f32_e32 v29, v27
	v_rcp_f32_e32 v27, v1
	v_add_f32_e32 v1, 1.0, v28
	v_rcp_f32_e32 v28, v1
	v_add_f32_e32 v1, 1.0, v29
	v_mul_f32_e32 v16, v16, v22
	v_mul_f32_e32 v17, v17, v23
	v_rcp_f32_e32 v29, v1
	v_mul_f32_e32 v22, v12, v26
	v_mul_f32_e32 v23, v13, v27
	v_cvt_pk_bf16_f32 v12, v16, v17
	v_lshl_add_u64 v[16:17], s[8:9], 0, v[20:21]
	s_waitcnt vmcnt(6)
	v_lshlrev_b32_e32 v1, 16, v68
	v_lshl_add_u64 v[16:17], v[16:17], 0, v[2:3]
	v_mul_f32_e32 v1, 0xbfb8aa3b, v1
	v_and_b32_e32 v2, 0xffff0000, v68
	v_med3_f32 v1, v1, s69, v217
	v_mul_f32_e32 v2, 0xbfb8aa3b, v2
	v_exp_f32_e32 v1, v1
	v_med3_f32 v2, v2, s69, v217
	v_exp_f32_e32 v3, v2
	v_mul_f32_e32 v18, v18, v24
	v_mul_f32_e32 v19, v19, v25
	v_add_f32_e32 v1, 1.0, v1
	v_rcp_f32_e32 v2, v1
	v_add_f32_e32 v1, 1.0, v3
	v_lshlrev_b32_e32 v3, 16, v69
	v_mul_f32_e32 v24, v14, v28
	v_mul_f32_e32 v25, v15, v29
	v_mul_f32_e32 v3, 0xbfb8aa3b, v3
	v_cvt_pk_bf16_f32 v13, v18, v19
	v_cvt_pk_bf16_f32 v14, v22, v23
	v_cvt_pk_bf16_f32 v15, v24, v25
	v_med3_f32 v3, v3, s69, v217
	global_store_dwordx4 v[16:17], v[12:15], off
	s_nop 1
	v_exp_f32_e32 v12, v3
	v_and_b32_e32 v3, 0xffff0000, v69
	v_mul_f32_e32 v3, 0xbfb8aa3b, v3
	v_med3_f32 v3, v3, s69, v217
	v_exp_f32_e32 v13, v3
	v_rcp_f32_e32 v3, v1
	v_add_f32_e32 v1, 1.0, v12
	v_rcp_f32_e32 v12, v1
	v_add_f32_e32 v1, 1.0, v13
	v_lshlrev_b32_e32 v13, 16, v70
	v_mul_f32_e32 v13, 0xbfb8aa3b, v13
	v_med3_f32 v13, v13, s69, v217
	v_exp_f32_e32 v14, v13
	v_and_b32_e32 v13, 0xffff0000, v70
	v_mul_f32_e32 v13, 0xbfb8aa3b, v13
	v_med3_f32 v13, v13, s69, v217
	v_exp_f32_e32 v15, v13
	v_rcp_f32_e32 v13, v1
	v_add_f32_e32 v1, 1.0, v14
	v_rcp_f32_e32 v14, v1
	v_add_f32_e32 v1, 1.0, v15
	v_lshlrev_b32_e32 v15, 16, v71
	v_mul_f32_e32 v15, 0xbfb8aa3b, v15
	v_med3_f32 v15, v15, s69, v217
	v_exp_f32_e32 v18, v15
	v_and_b32_e32 v15, 0xffff0000, v71
	v_mul_f32_e32 v15, 0xbfb8aa3b, v15
	v_med3_f32 v15, v15, s69, v217
	v_exp_f32_e32 v19, v15
	v_rcp_f32_e32 v15, v1
	v_add_f32_e32 v1, 1.0, v18
	v_rcp_f32_e32 v18, v1
	v_add_f32_e32 v1, 1.0, v19
	v_rcp_f32_e32 v19, v1
	v_mul_f32_e32 v2, v8, v2
	v_mul_f32_e32 v3, v9, v3
	v_mul_f32_e32 v8, v10, v12
	v_mul_f32_e32 v9, v11, v13
	v_mul_f32_e32 v4, v4, v14
	v_mul_f32_e32 v5, v5, v15
	v_mul_f32_e32 v6, v6, v18
	v_mul_f32_e32 v7, v7, v19
	v_cvt_pk_bf16_f32 v2, v2, v3
	v_cvt_pk_bf16_f32 v3, v8, v9
	v_cvt_pk_bf16_f32 v4, v4, v5
	v_cvt_pk_bf16_f32 v5, v6, v7
	global_store_dwordx4 v[16:17], v[2:5], off offset:256
	s_cbranch_vccnz .LBB0_1054
	s_andn2_b64 vcc, exec, s[6:7]
	s_cbranch_vccnz .LBB0_1053
	s_barrier
	s_branch .LBB0_1053

; __device__ __forceinline__ unsigned cvt_pk_bf16(float lo, float hi) { f32x2 v = {lo, hi}; bf16x2_t b = __builtin_convertvector(v, bf16x2_t); return __builtin_bit_cast(unsigned, b); }
; __device__ __forceinline__ float bf_lo(unsigned w) { return __uint_as_float(w << 16); }
; __device__ __forceinline__ float bf_hi(unsigned w) { return __uint_as_float(w & 0xffff0000u); }
;     __device__ __forceinline__ void operator()(const f32x4 (&acc)[2][2][4][2], const Unit& u, int wr, int wc, int fr, int fq) const {
;     ...
;                 u32x4 bw[4][2];
; #pragma unroll
;                 for (int m = 0; m < 4; ++m) { const size_t off = (size_t)(row0 + ai * HALF + m * 16) * 1024 + col0;
; #pragma unroll
;                     for (int bj = 0; bj < 2; ++bj) bw[m][bj] = *(const u32x4*)(bb + off + bj * HALF); }
; #pragma unroll
;                 for (int m = 0; m < 4; ++m)
; #pragma unroll
;                     for (int bj = 0; bj < 2; ++bj) { bs[m][bj][0] = (f32x4){bf_lo(bw[m][bj][0]), bf_hi(bw[m][bj][0]), bf_lo(bw[m][bj][1]), bf_hi(bw[m][bj][1])};
;                         bs[m][bj][1] = (f32x4){bf_lo(bw[m][bj][2]), bf_hi(bw[m][bj][2]), bf_lo(bw[m][bj][3]), bf_hi(bw[m][bj][3])}; }
;             }
;             asm volatile("" ::: "memory");
; #pragma unroll
;             for (int m = 0; m < 4; ++m) { const int row = row0 + ai * HALF + m * 16; const size_t off = (size_t)row * 1024 + col0; float ss = 0.f;
; #pragma unroll
;                 for (int bj = 0; bj < 2; ++bj) { const f32x4 v0 = bs[m][bj][0] + acc[ai][bj][m][0] * alpha, v1 = bs[m][bj][1] + acc[ai][bj][m][1] * alpha;
;                     ss += ((v0[0] * v0[0] + v0[1] * v0[1]) + (v0[2] * v0[2] + v0[3] * v0[3])) + ((v1[0] * v1[0] + v1[1] * v1[1]) + (v1[2] * v1[2] + v1[3] * v1[3]));
;                     if (of) { *(f32x4*)(of + off + bj * HALF) = v0; *(f32x4*)(of + off + bj * HALF + 4) = v1; }
;                     if (ob) { u32x4 w; w.x = cvt_pk_bf16(v0[0], v0[1]); w.y = cvt_pk_bf16(v0[2], v0[3]); w.z = cvt_pk_bf16(v1[0], v1[1]); w.w = cvt_pk_bf16(v1[2], v1[3]); *(u32x4*)(ob + off + bj * HALF) = w; } }
;                 if (ssq) { ss += __shfl_xor(ss, 16); ss += __shfl_xor(ss, 32); if (fq == 0) ssq[(size_t)row * 16 + 4 * u.pn + wc] = ss; } }
.LBB0_1151:
	v_lshl_or_b32 v168, s8, 8, v188
	v_lshl_add_u32 v172, s28, 8, v186
	v_ashrrev_i32_e32 v169, 31, v168
	v_lshlrev_b64 v[202:203], 1, v[168:169]
	v_ashrrev_i32_e32 v173, 31, v172
	v_lshl_add_u64 v[170:171], s[12:13], 0, v[202:203]
	v_lshlrev_b64 v[204:205], 11, v[172:173]
	v_lshl_add_u64 v[128:129], v[170:171], 0, v[204:205]
	global_load_dwordx4 v[194:197], v[128:129], off
	global_load_dwordx4 v[198:201], v[128:129], off offset:256
	v_or_b32_e32 v182, 16, v172
	v_or_b32_e32 v178, 32, v172
	v_or_b32_e32 v174, 48, v172
	v_ashrrev_i32_e32 v183, 31, v182
	v_ashrrev_i32_e32 v179, 31, v178
	v_ashrrev_i32_e32 v175, 31, v174
	v_lshlrev_b64 v[184:185], 11, v[182:183]
	v_lshlrev_b64 v[180:181], 11, v[178:179]
	v_lshlrev_b64 v[176:177], 11, v[174:175]
	v_lshl_add_u64 v[128:129], v[170:171], 0, v[184:185]
	v_lshl_add_u64 v[130:131], v[170:171], 0, v[180:181]
	v_lshl_add_u64 v[206:207], v[170:171], 0, v[176:177]
	global_load_dwordx4 v[148:151], v[128:129], off
	global_load_dwordx4 v[144:147], v[128:129], off offset:256
	global_load_dwordx4 v[140:143], v[130:131], off
	global_load_dwordx4 v[136:139], v[130:131], off offset:256
	global_load_dwordx4 v[132:135], v[206:207], off
	s_nop 0
	global_load_dwordx4 v[128:131], v[206:207], off offset:256
	s_lshl_b32 s28, s8, 2
	s_ashr_i32 s29, s28, 31
	s_waitcnt vmcnt(0)
	v_lshlrev_b32_e32 v206, 16, v194
	v_and_b32_e32 v207, 0xffff0000, v194
	v_lshlrev_b32_e32 v194, 16, v195
	v_and_b32_e32 v195, 0xffff0000, v195
	v_lshlrev_b32_e32 v208, 16, v196
	v_and_b32_e32 v209, 0xffff0000, v196
	v_lshlrev_b32_e32 v196, 16, v197
	v_and_b32_e32 v197, 0xffff0000, v197
	v_lshlrev_b32_e32 v210, 16, v198
	v_and_b32_e32 v211, 0xffff0000, v198
	v_lshlrev_b32_e32 v198, 16, v199
	v_and_b32_e32 v199, 0xffff0000, v199
	v_lshlrev_b32_e32 v212, 16, v200
	v_and_b32_e32 v213, 0xffff0000, v200
	v_lshlrev_b32_e32 v200, 16, v201
	v_and_b32_e32 v201, 0xffff0000, v201
	v_add_f32_e32 v126, v126, v194
	v_add_f32_e32 v127, v127, v195
	v_add_f32_e32 v124, v124, v206
	v_add_f32_e32 v125, v125, v207
	v_add_f32_e32 v122, v122, v196
	v_add_f32_e32 v123, v123, v197
	v_add_f32_e32 v120, v120, v208
	v_add_f32_e32 v121, v121, v209
	v_add_f32_e32 v118, v118, v198
	v_add_f32_e32 v119, v119, v199
	v_add_f32_e32 v116, v116, v210
	v_add_f32_e32 v117, v117, v211
	v_add_f32_e32 v194, v114, v200
	v_add_f32_e32 v195, v115, v201
	v_add_f32_e32 v196, v112, v212
	v_add_f32_e32 v197, v113, v213
	v_mul_f32_e32 v198, v125, v125
	v_mul_f32_e32 v199, v127, v127
	v_mul_f32_e32 v200, v121, v121
	v_mul_f32_e32 v201, v123, v123
	v_cvt_pk_bf16_f32 v112, v124, v125
	v_cvt_pk_bf16_f32 v113, v126, v127
	v_cvt_pk_bf16_f32 v114, v120, v121
	v_cvt_pk_bf16_f32 v115, v122, v123
	v_mul_f32_e32 v121, v117, v117
	v_mul_f32_e32 v123, v119, v119
	v_mul_f32_e32 v125, v197, v197
	v_mul_f32_e32 v127, v195, v195
	v_fmac_f32_e32 v198, v124, v124
	v_fmac_f32_e32 v199, v126, v126
	v_fmac_f32_e32 v200, v120, v120
	v_fmac_f32_e32 v201, v122, v122
	v_fmac_f32_e32 v121, v116, v116
	v_fmac_f32_e32 v123, v118, v118
	v_fmac_f32_e32 v125, v196, v196
	v_fmac_f32_e32 v127, v194, v194
	v_add_f32_e32 v120, v198, v199
	v_add_f32_e32 v122, v200, v201
	v_add_f32_e32 v121, v121, v123
	v_add_f32_e32 v123, v125, v127
	v_add_f32_e32 v120, v120, v122
	v_add_f32_e32 v121, v121, v123
	v_add_f32_e32 v122, v120, v121
	ds_bpermute_b32 v123, v189, v122
	v_lshl_add_u64 v[120:121], s[12:13], 0, v[204:205]
	v_lshl_add_u64 v[120:121], v[120:121], 0, v[202:203]
	global_store_dwordx4 v[120:121], v[112:115], off
	s_waitcnt lgkmcnt(0)
	s_nop 0
	v_add_f32_e32 v112, v122, v123
	ds_bpermute_b32 v113, v190, v112
	v_cvt_pk_bf16_f32 v114, v116, v117
	v_cvt_pk_bf16_f32 v115, v118, v119
	v_cvt_pk_bf16_f32 v116, v196, v197
	v_cvt_pk_bf16_f32 v117, v194, v195
	global_store_dwordx4 v[120:121], v[114:117], off offset:256
	s_and_saveexec_b64 s[30:31], s[2:3]
	s_cbranch_execz .LBB0_1153
	v_lshlrev_b64 v[114:115], 6, v[172:173]
	v_lshl_add_u64 v[114:115], s[14:15], 0, v[114:115]
	v_lshl_add_u64 v[114:115], s[28:29], 2, v[114:115]
	s_lshl_b32 s8, s49, 2
	v_lshl_add_u64 v[114:115], v[114:115], 0, s[8:9]
	s_waitcnt lgkmcnt(0)
	v_add_f32_e32 v112, v112, v113
	global_store_dword v[114:115], v112, off
.LBB0_1153:
	s_or_b64 exec, exec, s[30:31]
	v_lshlrev_b32_e32 v112, 16, v148
	s_waitcnt lgkmcnt(0)
	v_and_b32_e32 v113, 0xffff0000, v148
	v_lshlrev_b32_e32 v114, 16, v149
	v_and_b32_e32 v115, 0xffff0000, v149
	v_lshlrev_b32_e32 v116, 16, v150
	v_and_b32_e32 v117, 0xffff0000, v150
	v_lshlrev_b32_e32 v118, 16, v151
	v_and_b32_e32 v119, 0xffff0000, v151
	v_add_f32_e32 v110, v110, v114
	v_add_f32_e32 v111, v111, v115
	v_add_f32_e32 v108, v108, v112
	v_add_f32_e32 v109, v109, v113
	v_add_f32_e32 v112, v106, v118
	v_add_f32_e32 v113, v107, v119
	v_add_f32_e32 v106, v104, v116
	v_add_f32_e32 v107, v105, v117
	v_mul_f32_e32 v104, v109, v109
	v_mul_f32_e32 v105, v111, v111
	v_fmac_f32_e32 v104, v108, v108
	v_fmac_f32_e32 v105, v110, v110
	v_add_f32_e32 v104, v104, v105
	v_mul_f32_e32 v105, v107, v107
	v_mul_f32_e32 v114, v113, v113
	v_lshlrev_b32_e32 v120, 16, v144
	v_and_b32_e32 v121, 0xffff0000, v144
	v_lshlrev_b32_e32 v122, 16, v145
	v_and_b32_e32 v123, 0xffff0000, v145
	v_fmac_f32_e32 v105, v106, v106
	v_fmac_f32_e32 v114, v112, v112
	v_lshlrev_b32_e32 v124, 16, v146
	v_and_b32_e32 v125, 0xffff0000, v146
	v_add_f32_e32 v105, v105, v114
	v_add_f32_e32 v102, v102, v122
	v_add_f32_e32 v103, v103, v123
	v_add_f32_e32 v100, v100, v120
	v_add_f32_e32 v101, v101, v121
	v_lshlrev_b32_e32 v126, 16, v147
	v_and_b32_e32 v127, 0xffff0000, v147
	v_add_f32_e32 v114, v104, v105
	v_cvt_pk_bf16_f32 v105, v110, v111
	v_add_f32_e32 v110, v96, v124
	v_add_f32_e32 v111, v97, v125
	v_mul_f32_e32 v96, v101, v101
	v_mul_f32_e32 v97, v103, v103
	v_cvt_pk_bf16_f32 v104, v108, v109
	v_add_f32_e32 v108, v98, v126
	v_add_f32_e32 v109, v99, v127
	v_fmac_f32_e32 v96, v100, v100
	v_fmac_f32_e32 v97, v102, v102
	v_add_f32_e32 v96, v96, v97
	v_mul_f32_e32 v97, v111, v111
	v_mul_f32_e32 v98, v109, v109
	v_fmac_f32_e32 v97, v110, v110
	v_fmac_f32_e32 v98, v108, v108
	v_add_f32_e32 v97, v97, v98
	v_add_f32_e32 v96, v96, v97
	v_add_f32_e32 v99, v114, v96
	ds_bpermute_b32 v114, v189, v99
	v_lshl_add_u64 v[96:97], s[12:13], 0, v[184:185]
	v_cvt_pk_bf16_f32 v106, v106, v107
	v_cvt_pk_bf16_f32 v107, v112, v113
	v_lshl_add_u64 v[112:113], v[168:169], 1, v[96:97]
	s_waitcnt lgkmcnt(0)
	v_add_f32_e32 v96, v99, v114
	ds_bpermute_b32 v97, v190, v96
	v_cvt_pk_bf16_f32 v98, v100, v101
	v_cvt_pk_bf16_f32 v99, v102, v103
	v_cvt_pk_bf16_f32 v100, v110, v111
	v_cvt_pk_bf16_f32 v101, v108, v109
	global_store_dwordx4 v[112:113], v[104:107], off
	global_store_dwordx4 v[112:113], v[98:101], off offset:256
	s_and_saveexec_b64 s[30:31], s[2:3]
	s_cbranch_execz .LBB0_1155
	v_lshlrev_b64 v[98:99], 6, v[182:183]
	v_lshl_add_u64 v[98:99], s[14:15], 0, v[98:99]
	v_lshl_add_u64 v[98:99], s[28:29], 2, v[98:99]
	s_lshl_b32 s8, s49, 2
	v_lshl_add_u64 v[98:99], v[98:99], 0, s[8:9]
	s_waitcnt lgkmcnt(0)
	v_add_f32_e32 v96, v96, v97
	global_store_dword v[98:99], v96, off
; __device__ __forceinline__ unsigned cvt_pk_bf16(float lo, float hi) { f32x2 v = {lo, hi}; bf16x2_t b = __builtin_convertvector(v, bf16x2_t); return __builtin_bit_cast(unsigned, b); }
; __device__ __forceinline__ float bf_lo(unsigned w) { return __uint_as_float(w << 16); }
; __device__ __forceinline__ float bf_hi(unsigned w) { return __uint_as_float(w & 0xffff0000u); }
;     __device__ __forceinline__ void operator()(const f32x4 (&acc)[2][2][4][2], const Unit& u, int wr, int wc, int fr, int fq) const {
;     ...
;                 for (int m = 0; m < 4; ++m)
; #pragma unroll
;                     for (int bj = 0; bj < 2; ++bj) { bs[m][bj][0] = (f32x4){bf_lo(bw[m][bj][0]), bf_hi(bw[m][bj][0]), bf_lo(bw[m][bj][1]), bf_hi(bw[m][bj][1])};
;                         bs[m][bj][1] = (f32x4){bf_lo(bw[m][bj][2]), bf_hi(bw[m][bj][2]), bf_lo(bw[m][bj][3]), bf_hi(bw[m][bj][3])}; }
;             }
;             asm volatile("" ::: "memory");
; #pragma unroll
;             for (int m = 0; m < 4; ++m) { const int row = row0 + ai * HALF + m * 16; const size_t off = (size_t)row * 1024 + col0; float ss = 0.f;
; #pragma unroll
;                 for (int bj = 0; bj < 2; ++bj) { const f32x4 v0 = bs[m][bj][0] + acc[ai][bj][m][0] * alpha, v1 = bs[m][bj][1] + acc[ai][bj][m][1] * alpha;
;                     ss += ((v0[0] * v0[0] + v0[1] * v0[1]) + (v0[2] * v0[2] + v0[3] * v0[3])) + ((v1[0] * v1[0] + v1[1] * v1[1]) + (v1[2] * v1[2] + v1[3] * v1[3]));
;                     if (of) { *(f32x4*)(of + off + bj * HALF) = v0; *(f32x4*)(of + off + bj * HALF + 4) = v1; }
;                     if (ob) { u32x4 w; w.x = cvt_pk_bf16(v0[0], v0[1]); w.y = cvt_pk_bf16(v0[2], v0[3]); w.z = cvt_pk_bf16(v1[0], v1[1]); w.w = cvt_pk_bf16(v1[2], v1[3]); *(u32x4*)(ob + off + bj * HALF) = w; } }
;                 if (ssq) { ss += __shfl_xor(ss, 16); ss += __shfl_xor(ss, 32); if (fq == 0) ssq[(size_t)row * 16 + 4 * u.pn + wc] = ss; } }
.LBB0_1155:
	s_or_b64 exec, exec, s[30:31]
	v_lshlrev_b32_e32 v96, 16, v140
	s_waitcnt lgkmcnt(0)
	v_and_b32_e32 v97, 0xffff0000, v140
	v_lshlrev_b32_e32 v98, 16, v141
	v_and_b32_e32 v99, 0xffff0000, v141
	v_lshlrev_b32_e32 v100, 16, v142
	v_and_b32_e32 v101, 0xffff0000, v142
	v_lshlrev_b32_e32 v102, 16, v143
	v_and_b32_e32 v103, 0xffff0000, v143
	v_add_f32_e32 v94, v94, v98
	v_add_f32_e32 v95, v95, v99
	v_add_f32_e32 v92, v92, v96
	v_add_f32_e32 v93, v93, v97
	v_add_f32_e32 v96, v90, v102
	v_add_f32_e32 v97, v91, v103
	v_add_f32_e32 v90, v88, v100
	v_add_f32_e32 v91, v89, v101
	v_mul_f32_e32 v88, v93, v93
	v_mul_f32_e32 v89, v95, v95
	v_fmac_f32_e32 v88, v92, v92
	v_fmac_f32_e32 v89, v94, v94
	v_add_f32_e32 v88, v88, v89
	v_mul_f32_e32 v89, v91, v91
	v_mul_f32_e32 v98, v97, v97
	v_lshlrev_b32_e32 v104, 16, v136
	v_and_b32_e32 v105, 0xffff0000, v136
	v_lshlrev_b32_e32 v106, 16, v137
	v_and_b32_e32 v107, 0xffff0000, v137
	v_fmac_f32_e32 v89, v90, v90
	v_fmac_f32_e32 v98, v96, v96
	v_lshlrev_b32_e32 v108, 16, v138
	v_and_b32_e32 v109, 0xffff0000, v138
	v_add_f32_e32 v89, v89, v98
	v_add_f32_e32 v86, v86, v106
	v_add_f32_e32 v87, v87, v107
	v_add_f32_e32 v84, v84, v104
	v_add_f32_e32 v85, v85, v105
	v_lshlrev_b32_e32 v110, 16, v139
	v_and_b32_e32 v111, 0xffff0000, v139
	v_add_f32_e32 v98, v88, v89
	v_cvt_pk_bf16_f32 v89, v94, v95
	v_add_f32_e32 v94, v80, v108
	v_add_f32_e32 v95, v81, v109
	v_mul_f32_e32 v80, v85, v85
	v_mul_f32_e32 v81, v87, v87
	v_cvt_pk_bf16_f32 v88, v92, v93
	v_add_f32_e32 v92, v82, v110
	v_add_f32_e32 v93, v83, v111
	v_fmac_f32_e32 v80, v84, v84
	v_fmac_f32_e32 v81, v86, v86
	v_add_f32_e32 v80, v80, v81
	v_mul_f32_e32 v81, v95, v95
	v_mul_f32_e32 v82, v93, v93
	v_fmac_f32_e32 v81, v94, v94
	v_fmac_f32_e32 v82, v92, v92
	v_add_f32_e32 v81, v81, v82
	v_add_f32_e32 v80, v80, v81
	v_add_f32_e32 v83, v98, v80
	ds_bpermute_b32 v98, v189, v83
	v_lshl_add_u64 v[80:81], s[12:13], 0, v[180:181]
	v_cvt_pk_bf16_f32 v90, v90, v91
	v_cvt_pk_bf16_f32 v91, v96, v97
	v_lshl_add_u64 v[96:97], v[168:169], 1, v[80:81]
	s_waitcnt lgkmcnt(0)
	v_add_f32_e32 v80, v83, v98
	ds_bpermute_b32 v81, v190, v80
	v_cvt_pk_bf16_f32 v82, v84, v85
	v_cvt_pk_bf16_f32 v83, v86, v87
	v_cvt_pk_bf16_f32 v84, v94, v95
	v_cvt_pk_bf16_f32 v85, v92, v93
	global_store_dwordx4 v[96:97], v[88:91], off
	global_store_dwordx4 v[96:97], v[82:85], off offset:256
	s_and_saveexec_b64 s[30:31], s[2:3]
	s_cbranch_execz .LBB0_1157
	v_lshlrev_b64 v[82:83], 6, v[178:179]
	v_lshl_add_u64 v[82:83], s[14:15], 0, v[82:83]
	v_lshl_add_u64 v[82:83], s[28:29], 2, v[82:83]
	s_lshl_b32 s8, s49, 2
	v_lshl_add_u64 v[82:83], v[82:83], 0, s[8:9]
	s_waitcnt lgkmcnt(0)
	v_add_f32_e32 v80, v80, v81
	global_store_dword v[82:83], v80, off
.LBB0_1157:
	s_or_b64 exec, exec, s[30:31]
	v_lshlrev_b32_e32 v80, 16, v132
	s_waitcnt lgkmcnt(0)
	v_and_b32_e32 v81, 0xffff0000, v132
	v_lshlrev_b32_e32 v82, 16, v133
	v_and_b32_e32 v83, 0xffff0000, v133
	v_lshlrev_b32_e32 v84, 16, v134
	v_and_b32_e32 v85, 0xffff0000, v134
	v_lshlrev_b32_e32 v86, 16, v135
	v_and_b32_e32 v87, 0xffff0000, v135
	v_add_f32_e32 v78, v78, v82
	v_add_f32_e32 v79, v79, v83
	v_add_f32_e32 v76, v76, v80
	v_add_f32_e32 v77, v77, v81
	v_add_f32_e32 v80, v74, v86
	v_add_f32_e32 v81, v75, v87
	v_add_f32_e32 v74, v72, v84
	v_add_f32_e32 v75, v73, v85
	v_mul_f32_e32 v72, v77, v77
	v_mul_f32_e32 v73, v79, v79
	v_fmac_f32_e32 v72, v76, v76
	v_fmac_f32_e32 v73, v78, v78
	v_add_f32_e32 v72, v72, v73
	v_mul_f32_e32 v73, v75, v75
	v_mul_f32_e32 v82, v81, v81
	v_lshlrev_b32_e32 v88, 16, v128
	v_and_b32_e32 v89, 0xffff0000, v128
	v_lshlrev_b32_e32 v90, 16, v129
	v_and_b32_e32 v91, 0xffff0000, v129
	v_fmac_f32_e32 v73, v74, v74
	v_fmac_f32_e32 v82, v80, v80
	v_lshlrev_b32_e32 v92, 16, v130
	v_and_b32_e32 v93, 0xffff0000, v130
	v_add_f32_e32 v73, v73, v82
	v_add_f32_e32 v70, v70, v90
	v_add_f32_e32 v71, v71, v91
	v_add_f32_e32 v68, v68, v88
	v_add_f32_e32 v69, v69, v89
	v_lshlrev_b32_e32 v94, 16, v131
	v_and_b32_e32 v95, 0xffff0000, v131
	v_add_f32_e32 v82, v72, v73
	v_cvt_pk_bf16_f32 v73, v78, v79
	v_add_f32_e32 v78, v64, v92
	v_add_f32_e32 v79, v65, v93
	v_mul_f32_e32 v64, v69, v69
	v_mul_f32_e32 v65, v71, v71
	v_cvt_pk_bf16_f32 v72, v76, v77
	v_add_f32_e32 v76, v66, v94
	v_add_f32_e32 v77, v67, v95
	v_fmac_f32_e32 v64, v68, v68
	v_fmac_f32_e32 v65, v70, v70
	v_add_f32_e32 v64, v64, v65
	v_mul_f32_e32 v65, v79, v79
	v_mul_f32_e32 v66, v77, v77
	v_fmac_f32_e32 v65, v78, v78
	v_fmac_f32_e32 v66, v76, v76
	v_add_f32_e32 v65, v65, v66
	v_add_f32_e32 v64, v64, v65
	v_add_f32_e32 v67, v82, v64
	ds_bpermute_b32 v82, v189, v67
	v_lshl_add_u64 v[64:65], s[12:13], 0, v[176:177]
	v_cvt_pk_bf16_f32 v74, v74, v75
	v_cvt_pk_bf16_f32 v75, v80, v81
	v_lshl_add_u64 v[80:81], v[168:169], 1, v[64:65]
	s_waitcnt lgkmcnt(0)
	v_add_f32_e32 v64, v67, v82
	ds_bpermute_b32 v65, v190, v64
	v_cvt_pk_bf16_f32 v66, v68, v69
	v_cvt_pk_bf16_f32 v67, v70, v71
	v_cvt_pk_bf16_f32 v68, v78, v79
	v_cvt_pk_bf16_f32 v69, v76, v77
	global_store_dwordx4 v[80:81], v[72:75], off
	global_store_dwordx4 v[80:81], v[66:69], off offset:256
	s_and_saveexec_b64 s[30:31], s[2:3]
	s_cbranch_execz .LBB0_1159
	v_lshlrev_b64 v[66:67], 6, v[174:175]
	v_lshl_add_u64 v[66:67], s[14:15], 0, v[66:67]
	v_lshl_add_u64 v[66:67], s[28:29], 2, v[66:67]
	s_lshl_b32 s8, s49, 2
	v_lshl_add_u64 v[66:67], v[66:67], 0, s[8:9]
	s_waitcnt lgkmcnt(0)
	v_add_f32_e32 v64, v64, v65
	global_store_dword v[66:67], v64, off
; __device__ __forceinline__ unsigned cvt_pk_bf16(float lo, float hi) { f32x2 v = {lo, hi}; bf16x2_t b = __builtin_convertvector(v, bf16x2_t); return __builtin_bit_cast(unsigned, b); }
; __device__ __forceinline__ float bf_lo(unsigned w) { return __uint_as_float(w << 16); }
; __device__ __forceinline__ float bf_hi(unsigned w) { return __uint_as_float(w & 0xffff0000u); }
;     __device__ __forceinline__ void operator()(const f32x4 (&acc)[2][2][4][2], const Unit& u, int wr, int wc, int fr, int fq) const {
;     ...
;                 for (int m = 0; m < 4; ++m) { const size_t off = (size_t)(row0 + ai * HALF + m * 16) * 1024 + col0;
; #pragma unroll
;                     for (int bj = 0; bj < 2; ++bj) bw[m][bj] = *(const u32x4*)(bb + off + bj * HALF); }
; #pragma unroll
;                 for (int m = 0; m < 4; ++m)
; #pragma unroll
;                     for (int bj = 0; bj < 2; ++bj) { bs[m][bj][0] = (f32x4){bf_lo(bw[m][bj][0]), bf_hi(bw[m][bj][0]), bf_lo(bw[m][bj][1]), bf_hi(bw[m][bj][1])};
;                         bs[m][bj][1] = (f32x4){bf_lo(bw[m][bj][2]), bf_hi(bw[m][bj][2]), bf_lo(bw[m][bj][3]), bf_hi(bw[m][bj][3])}; }
;             }
;             asm volatile("" ::: "memory");
; #pragma unroll
;             for (int m = 0; m < 4; ++m) { const int row = row0 + ai * HALF + m * 16; const size_t off = (size_t)row * 1024 + col0; float ss = 0.f;
; #pragma unroll
;                 for (int bj = 0; bj < 2; ++bj) { const f32x4 v0 = bs[m][bj][0] + acc[ai][bj][m][0] * alpha, v1 = bs[m][bj][1] + acc[ai][bj][m][1] * alpha;
;                     ss += ((v0[0] * v0[0] + v0[1] * v0[1]) + (v0[2] * v0[2] + v0[3] * v0[3])) + ((v1[0] * v1[0] + v1[1] * v1[1]) + (v1[2] * v1[2] + v1[3] * v1[3]));
;                     if (of) { *(f32x4*)(of + off + bj * HALF) = v0; *(f32x4*)(of + off + bj * HALF + 4) = v1; }
;                     if (ob) { u32x4 w; w.x = cvt_pk_bf16(v0[0], v0[1]); w.y = cvt_pk_bf16(v0[2], v0[3]); w.z = cvt_pk_bf16(v1[0], v1[1]); w.w = cvt_pk_bf16(v1[2], v1[3]); *(u32x4*)(ob + off + bj * HALF) = w; } }
;                 if (ssq) { ss += __shfl_xor(ss, 16); ss += __shfl_xor(ss, 32); if (fq == 0) ssq[(size_t)row * 16 + 4 * u.pn + wc] = ss; } }
.LBB0_1159:
	s_or_b64 exec, exec, s[30:31]
	v_add_u32_e32 v100, 0x80, v172
	v_ashrrev_i32_e32 v101, 31, v100
	v_lshlrev_b64 v[110:111], 11, v[100:101]
	s_waitcnt lgkmcnt(0)
	v_lshl_add_u64 v[64:65], v[170:171], 0, v[110:111]
	global_load_dwordx4 v[102:105], v[64:65], off
	global_load_dwordx4 v[106:109], v[64:65], off offset:256
	v_add_u32_e32 v96, 0x90, v172
	v_add_u32_e32 v92, 0xa0, v172
	v_add_u32_e32 v88, 0xb0, v172
	v_ashrrev_i32_e32 v97, 31, v96
	v_ashrrev_i32_e32 v93, 31, v92
	v_ashrrev_i32_e32 v89, 31, v88
	v_lshlrev_b64 v[98:99], 11, v[96:97]
	v_lshlrev_b64 v[94:95], 11, v[92:93]
	v_lshlrev_b64 v[90:91], 11, v[88:89]
	v_lshl_add_u64 v[64:65], v[170:171], 0, v[98:99]
	v_lshl_add_u64 v[66:67], v[170:171], 0, v[94:95]
	v_lshl_add_u64 v[112:113], v[170:171], 0, v[90:91]
	global_load_dwordx4 v[84:87], v[64:65], off
	global_load_dwordx4 v[80:83], v[64:65], off offset:256
	global_load_dwordx4 v[76:79], v[66:67], off
	global_load_dwordx4 v[72:75], v[66:67], off offset:256
	global_load_dwordx4 v[68:71], v[112:113], off
	s_nop 0
	global_load_dwordx4 v[64:67], v[112:113], off offset:256
	s_waitcnt vmcnt(7)
	v_lshlrev_b32_e32 v112, 16, v102
	v_and_b32_e32 v113, 0xffff0000, v102
	v_lshlrev_b32_e32 v102, 16, v103
	v_and_b32_e32 v103, 0xffff0000, v103
	v_lshlrev_b32_e32 v114, 16, v104
	v_and_b32_e32 v115, 0xffff0000, v104
	v_lshlrev_b32_e32 v104, 16, v105
	v_and_b32_e32 v105, 0xffff0000, v105
	s_waitcnt vmcnt(6)
	v_lshlrev_b32_e32 v116, 16, v106
	v_and_b32_e32 v117, 0xffff0000, v106
	v_lshlrev_b32_e32 v106, 16, v107
	v_and_b32_e32 v107, 0xffff0000, v107
	v_lshlrev_b32_e32 v118, 16, v108
	v_and_b32_e32 v119, 0xffff0000, v108
	v_lshlrev_b32_e32 v108, 16, v109
	v_and_b32_e32 v109, 0xffff0000, v109
	v_add_f32_e32 v62, v62, v102
	v_add_f32_e32 v63, v63, v103
	v_add_f32_e32 v60, v60, v112
	v_add_f32_e32 v61, v61, v113
	v_add_f32_e32 v58, v58, v104
	v_add_f32_e32 v59, v59, v105
	v_add_f32_e32 v56, v56, v114
	v_add_f32_e32 v57, v57, v115
	v_add_f32_e32 v54, v54, v106
	v_add_f32_e32 v55, v55, v107
	v_add_f32_e32 v52, v52, v116
	v_add_f32_e32 v53, v53, v117
	v_add_f32_e32 v102, v50, v108
	v_add_f32_e32 v103, v51, v109
	v_add_f32_e32 v104, v48, v118
	v_add_f32_e32 v105, v49, v119
	v_mul_f32_e32 v106, v61, v61
	v_mul_f32_e32 v107, v63, v63
	v_mul_f32_e32 v108, v57, v57
	v_mul_f32_e32 v109, v59, v59
	v_cvt_pk_bf16_f32 v48, v60, v61
	v_cvt_pk_bf16_f32 v49, v62, v63
	v_cvt_pk_bf16_f32 v50, v56, v57
	v_cvt_pk_bf16_f32 v51, v58, v59
	v_mul_f32_e32 v57, v53, v53
	v_mul_f32_e32 v59, v55, v55
	v_mul_f32_e32 v61, v105, v105
	v_mul_f32_e32 v63, v103, v103
	v_fmac_f32_e32 v106, v60, v60
	v_fmac_f32_e32 v107, v62, v62
	v_fmac_f32_e32 v108, v56, v56
	v_fmac_f32_e32 v109, v58, v58
	v_fmac_f32_e32 v57, v52, v52
	v_fmac_f32_e32 v59, v54, v54
	v_fmac_f32_e32 v61, v104, v104
	v_fmac_f32_e32 v63, v102, v102
	v_add_f32_e32 v56, v106, v107
	v_add_f32_e32 v58, v108, v109
	v_add_f32_e32 v57, v57, v59
	v_add_f32_e32 v59, v61, v63
	v_add_f32_e32 v56, v56, v58
	v_add_f32_e32 v57, v57, v59
	v_add_f32_e32 v58, v56, v57
	ds_bpermute_b32 v59, v189, v58
	v_lshl_add_u64 v[56:57], s[12:13], 0, v[110:111]
	v_lshl_add_u64 v[56:57], v[168:169], 1, v[56:57]
	global_store_dwordx4 v[56:57], v[48:51], off
	s_waitcnt lgkmcnt(0)
	s_nop 0
	v_add_f32_e32 v48, v58, v59
	ds_bpermute_b32 v49, v190, v48
	v_cvt_pk_bf16_f32 v50, v52, v53
	v_cvt_pk_bf16_f32 v51, v54, v55
	v_cvt_pk_bf16_f32 v52, v104, v105
	v_cvt_pk_bf16_f32 v53, v102, v103
	global_store_dwordx4 v[56:57], v[50:53], off offset:256
	s_and_saveexec_b64 s[30:31], s[2:3]
	s_cbranch_execz .LBB0_1161
	v_lshlrev_b64 v[50:51], 6, v[100:101]
	v_lshl_add_u64 v[50:51], s[14:15], 0, v[50:51]
	v_lshl_add_u64 v[50:51], s[28:29], 2, v[50:51]
	s_lshl_b32 s8, s49, 2
	v_lshl_add_u64 v[50:51], v[50:51], 0, s[8:9]
	s_waitcnt lgkmcnt(0)
	v_add_f32_e32 v48, v48, v49
	global_store_dword v[50:51], v48, off
.LBB0_1161:
	s_or_b64 exec, exec, s[30:31]
	s_waitcnt vmcnt(7)
	v_lshlrev_b32_e32 v48, 16, v84
	s_waitcnt lgkmcnt(0)
	v_and_b32_e32 v49, 0xffff0000, v84
	v_lshlrev_b32_e32 v50, 16, v85
	v_and_b32_e32 v51, 0xffff0000, v85
	v_lshlrev_b32_e32 v52, 16, v86
	v_and_b32_e32 v53, 0xffff0000, v86
	v_lshlrev_b32_e32 v54, 16, v87
	v_and_b32_e32 v55, 0xffff0000, v87
	v_add_f32_e32 v46, v46, v50
	v_add_f32_e32 v47, v47, v51
	v_add_f32_e32 v44, v44, v48
	v_add_f32_e32 v45, v45, v49
	v_add_f32_e32 v48, v42, v54
	v_add_f32_e32 v49, v43, v55
	v_add_f32_e32 v42, v40, v52
	v_add_f32_e32 v43, v41, v53
	v_mul_f32_e32 v40, v45, v45
	v_mul_f32_e32 v41, v47, v47
	v_fmac_f32_e32 v40, v44, v44
	v_fmac_f32_e32 v41, v46, v46
	v_add_f32_e32 v40, v40, v41
	v_mul_f32_e32 v41, v43, v43
	v_mul_f32_e32 v50, v49, v49
	s_waitcnt vmcnt(6)
	v_lshlrev_b32_e32 v56, 16, v80
	v_and_b32_e32 v57, 0xffff0000, v80
	v_lshlrev_b32_e32 v58, 16, v81
	v_and_b32_e32 v59, 0xffff0000, v81
	v_fmac_f32_e32 v41, v42, v42
	v_fmac_f32_e32 v50, v48, v48
	v_lshlrev_b32_e32 v60, 16, v82
	v_and_b32_e32 v61, 0xffff0000, v82
	v_add_f32_e32 v41, v41, v50
	v_add_f32_e32 v38, v38, v58
	v_add_f32_e32 v39, v39, v59
	v_add_f32_e32 v36, v36, v56
	v_add_f32_e32 v37, v37, v57
	v_lshlrev_b32_e32 v62, 16, v83
	v_and_b32_e32 v63, 0xffff0000, v83
	v_add_f32_e32 v50, v40, v41
	v_cvt_pk_bf16_f32 v41, v46, v47
	v_add_f32_e32 v46, v32, v60
	v_add_f32_e32 v47, v33, v61
	v_mul_f32_e32 v32, v37, v37
	v_mul_f32_e32 v33, v39, v39
	v_cvt_pk_bf16_f32 v40, v44, v45
	v_add_f32_e32 v44, v34, v62
	v_add_f32_e32 v45, v35, v63
	v_fmac_f32_e32 v32, v36, v36
	v_fmac_f32_e32 v33, v38, v38
	v_add_f32_e32 v32, v32, v33
	v_mul_f32_e32 v33, v47, v47
	v_mul_f32_e32 v34, v45, v45
	v_fmac_f32_e32 v33, v46, v46
	v_fmac_f32_e32 v34, v44, v44
	v_add_f32_e32 v33, v33, v34
	v_add_f32_e32 v32, v32, v33
	v_add_f32_e32 v35, v50, v32
	ds_bpermute_b32 v50, v189, v35
	v_lshl_add_u64 v[32:33], s[12:13], 0, v[98:99]
	v_cvt_pk_bf16_f32 v42, v42, v43
	v_cvt_pk_bf16_f32 v43, v48, v49
	v_lshl_add_u64 v[48:49], v[168:169], 1, v[32:33]
	s_waitcnt lgkmcnt(0)
	v_add_f32_e32 v32, v35, v50
	ds_bpermute_b32 v33, v190, v32
	v_cvt_pk_bf16_f32 v34, v36, v37
	v_cvt_pk_bf16_f32 v35, v38, v39
	v_cvt_pk_bf16_f32 v36, v46, v47
	v_cvt_pk_bf16_f32 v37, v44, v45
	global_store_dwordx4 v[48:49], v[40:43], off
	global_store_dwordx4 v[48:49], v[34:37], off offset:256
	s_and_saveexec_b64 s[30:31], s[2:3]
	s_cbranch_execz .LBB0_1163
	v_lshlrev_b64 v[34:35], 6, v[96:97]
	v_lshl_add_u64 v[34:35], s[14:15], 0, v[34:35]
	v_lshl_add_u64 v[34:35], s[28:29], 2, v[34:35]
	s_lshl_b32 s8, s49, 2
	v_lshl_add_u64 v[34:35], v[34:35], 0, s[8:9]
	s_waitcnt lgkmcnt(0)
	v_add_f32_e32 v32, v32, v33
	global_store_dword v[34:35], v32, off
; __device__ __forceinline__ unsigned cvt_pk_bf16(float lo, float hi) { f32x2 v = {lo, hi}; bf16x2_t b = __builtin_convertvector(v, bf16x2_t); return __builtin_bit_cast(unsigned, b); }
; __device__ __forceinline__ float bf_lo(unsigned w) { return __uint_as_float(w << 16); }
; __device__ __forceinline__ float bf_hi(unsigned w) { return __uint_as_float(w & 0xffff0000u); }
;     __device__ __forceinline__ void operator()(const f32x4 (&acc)[2][2][4][2], const Unit& u, int wr, int wc, int fr, int fq) const {
;     ...
;                 for (int m = 0; m < 4; ++m)
; #pragma unroll
;                     for (int bj = 0; bj < 2; ++bj) { bs[m][bj][0] = (f32x4){bf_lo(bw[m][bj][0]), bf_hi(bw[m][bj][0]), bf_lo(bw[m][bj][1]), bf_hi(bw[m][bj][1])};
;                         bs[m][bj][1] = (f32x4){bf_lo(bw[m][bj][2]), bf_hi(bw[m][bj][2]), bf_lo(bw[m][bj][3]), bf_hi(bw[m][bj][3])}; }
;             }
;             asm volatile("" ::: "memory");
; #pragma unroll
;             for (int m = 0; m < 4; ++m) { const int row = row0 + ai * HALF + m * 16; const size_t off = (size_t)row * 1024 + col0; float ss = 0.f;
; #pragma unroll
;                 for (int bj = 0; bj < 2; ++bj) { const f32x4 v0 = bs[m][bj][0] + acc[ai][bj][m][0] * alpha, v1 = bs[m][bj][1] + acc[ai][bj][m][1] * alpha;
;                     ss += ((v0[0] * v0[0] + v0[1] * v0[1]) + (v0[2] * v0[2] + v0[3] * v0[3])) + ((v1[0] * v1[0] + v1[1] * v1[1]) + (v1[2] * v1[2] + v1[3] * v1[3]));
;                     if (of) { *(f32x4*)(of + off + bj * HALF) = v0; *(f32x4*)(of + off + bj * HALF + 4) = v1; }
;                     if (ob) { u32x4 w; w.x = cvt_pk_bf16(v0[0], v0[1]); w.y = cvt_pk_bf16(v0[2], v0[3]); w.z = cvt_pk_bf16(v1[0], v1[1]); w.w = cvt_pk_bf16(v1[2], v1[3]); *(u32x4*)(ob + off + bj * HALF) = w; } }
;                 if (ssq) { ss += __shfl_xor(ss, 16); ss += __shfl_xor(ss, 32); if (fq == 0) ssq[(size_t)row * 16 + 4 * u.pn + wc] = ss; } }
.LBB0_1163:
	s_or_b64 exec, exec, s[30:31]
	s_waitcnt vmcnt(7)
	v_lshlrev_b32_e32 v32, 16, v76
	s_waitcnt lgkmcnt(0)
	v_and_b32_e32 v33, 0xffff0000, v76
	v_lshlrev_b32_e32 v34, 16, v77
	v_and_b32_e32 v35, 0xffff0000, v77
	v_lshlrev_b32_e32 v36, 16, v78
	v_and_b32_e32 v37, 0xffff0000, v78
	v_lshlrev_b32_e32 v38, 16, v79
	v_and_b32_e32 v39, 0xffff0000, v79
	v_add_f32_e32 v30, v30, v34
	v_add_f32_e32 v31, v31, v35
	v_add_f32_e32 v28, v28, v32
	v_add_f32_e32 v29, v29, v33
	v_add_f32_e32 v32, v26, v38
	v_add_f32_e32 v33, v27, v39
	v_add_f32_e32 v26, v24, v36
	v_add_f32_e32 v27, v25, v37
	v_mul_f32_e32 v24, v29, v29
	v_mul_f32_e32 v25, v31, v31
	v_fmac_f32_e32 v24, v28, v28
	v_fmac_f32_e32 v25, v30, v30
	v_add_f32_e32 v24, v24, v25
	v_mul_f32_e32 v25, v27, v27
	v_mul_f32_e32 v34, v33, v33
	s_waitcnt vmcnt(6)
	v_lshlrev_b32_e32 v40, 16, v72
	v_and_b32_e32 v41, 0xffff0000, v72
	v_lshlrev_b32_e32 v42, 16, v73
	v_and_b32_e32 v43, 0xffff0000, v73
	v_fmac_f32_e32 v25, v26, v26
	v_fmac_f32_e32 v34, v32, v32
	v_lshlrev_b32_e32 v44, 16, v74
	v_and_b32_e32 v45, 0xffff0000, v74
	v_add_f32_e32 v25, v25, v34
	v_add_f32_e32 v22, v22, v42
	v_add_f32_e32 v23, v23, v43
	v_add_f32_e32 v20, v20, v40
	v_add_f32_e32 v21, v21, v41
	v_lshlrev_b32_e32 v46, 16, v75
	v_and_b32_e32 v47, 0xffff0000, v75
	v_add_f32_e32 v34, v24, v25
	v_cvt_pk_bf16_f32 v25, v30, v31
	v_add_f32_e32 v30, v16, v44
	v_add_f32_e32 v31, v17, v45
	v_mul_f32_e32 v16, v21, v21
	v_mul_f32_e32 v17, v23, v23
	v_cvt_pk_bf16_f32 v24, v28, v29
	v_add_f32_e32 v28, v18, v46
	v_add_f32_e32 v29, v19, v47
	v_fmac_f32_e32 v16, v20, v20
	v_fmac_f32_e32 v17, v22, v22
	v_add_f32_e32 v16, v16, v17
	v_mul_f32_e32 v17, v31, v31
	v_mul_f32_e32 v18, v29, v29
	v_fmac_f32_e32 v17, v30, v30
	v_fmac_f32_e32 v18, v28, v28
	v_add_f32_e32 v17, v17, v18
	v_add_f32_e32 v16, v16, v17
	v_add_f32_e32 v19, v34, v16
	ds_bpermute_b32 v34, v189, v19
	v_lshl_add_u64 v[16:17], s[12:13], 0, v[94:95]
	v_cvt_pk_bf16_f32 v26, v26, v27
	v_cvt_pk_bf16_f32 v27, v32, v33
	v_lshl_add_u64 v[32:33], v[168:169], 1, v[16:17]
	s_waitcnt lgkmcnt(0)
	v_add_f32_e32 v16, v19, v34
	ds_bpermute_b32 v17, v190, v16
	v_cvt_pk_bf16_f32 v18, v20, v21
	v_cvt_pk_bf16_f32 v19, v22, v23
	v_cvt_pk_bf16_f32 v20, v30, v31
	v_cvt_pk_bf16_f32 v21, v28, v29
	global_store_dwordx4 v[32:33], v[24:27], off
	global_store_dwordx4 v[32:33], v[18:21], off offset:256
	s_and_saveexec_b64 s[30:31], s[2:3]
	s_cbranch_execz .LBB0_1165
	v_lshlrev_b64 v[18:19], 6, v[92:93]
	v_lshl_add_u64 v[18:19], s[14:15], 0, v[18:19]
	v_lshl_add_u64 v[18:19], s[28:29], 2, v[18:19]
	s_lshl_b32 s8, s49, 2
	v_lshl_add_u64 v[18:19], v[18:19], 0, s[8:9]
	s_waitcnt lgkmcnt(0)
	v_add_f32_e32 v16, v16, v17
	global_store_dword v[18:19], v16, off
.LBB0_1165:
	s_or_b64 exec, exec, s[30:31]
	s_waitcnt vmcnt(7)
	v_lshlrev_b32_e32 v16, 16, v68
	s_waitcnt lgkmcnt(0)
	v_and_b32_e32 v17, 0xffff0000, v68
	v_lshlrev_b32_e32 v18, 16, v69
	v_and_b32_e32 v19, 0xffff0000, v69
	v_lshlrev_b32_e32 v20, 16, v70
	v_and_b32_e32 v21, 0xffff0000, v70
	v_lshlrev_b32_e32 v22, 16, v71
	v_and_b32_e32 v23, 0xffff0000, v71
	v_add_f32_e32 v14, v14, v18
	v_add_f32_e32 v15, v15, v19
	v_add_f32_e32 v12, v12, v16
	v_add_f32_e32 v13, v13, v17
	v_add_f32_e32 v16, v10, v22
	v_add_f32_e32 v17, v11, v23
	v_add_f32_e32 v10, v8, v20
	v_add_f32_e32 v11, v9, v21
	v_mul_f32_e32 v8, v13, v13
	v_mul_f32_e32 v9, v15, v15
	v_fmac_f32_e32 v8, v12, v12
	v_fmac_f32_e32 v9, v14, v14
	v_add_f32_e32 v8, v8, v9
	v_mul_f32_e32 v9, v11, v11
	v_mul_f32_e32 v18, v17, v17
	s_waitcnt vmcnt(6)
	v_lshlrev_b32_e32 v24, 16, v64
	v_and_b32_e32 v25, 0xffff0000, v64
	v_lshlrev_b32_e32 v26, 16, v65
	v_and_b32_e32 v27, 0xffff0000, v65
	v_fmac_f32_e32 v9, v10, v10
	v_fmac_f32_e32 v18, v16, v16
	v_lshlrev_b32_e32 v28, 16, v66
	v_and_b32_e32 v29, 0xffff0000, v66
	v_add_f32_e32 v9, v9, v18
	v_add_f32_e32 v6, v6, v26
	v_add_f32_e32 v7, v7, v27
	v_add_f32_e32 v4, v4, v24
	v_add_f32_e32 v5, v5, v25
	v_lshlrev_b32_e32 v30, 16, v67
	v_and_b32_e32 v31, 0xffff0000, v67
	v_add_f32_e32 v18, v8, v9
	v_cvt_pk_bf16_f32 v9, v14, v15
	v_add_f32_e32 v14, v0, v28
	v_add_f32_e32 v15, v1, v29
	v_mul_f32_e32 v0, v5, v5
	v_mul_f32_e32 v1, v7, v7
	v_cvt_pk_bf16_f32 v8, v12, v13
	v_add_f32_e32 v12, v2, v30
	v_add_f32_e32 v13, v3, v31
	v_fmac_f32_e32 v0, v4, v4
	v_fmac_f32_e32 v1, v6, v6
	v_add_f32_e32 v0, v0, v1
	v_mul_f32_e32 v1, v15, v15
	v_mul_f32_e32 v2, v13, v13
	v_fmac_f32_e32 v1, v14, v14
	v_fmac_f32_e32 v2, v12, v12
	v_add_f32_e32 v1, v1, v2
	v_add_f32_e32 v0, v0, v1
	v_add_f32_e32 v3, v18, v0
	ds_bpermute_b32 v18, v189, v3
	v_lshl_add_u64 v[0:1], s[12:13], 0, v[90:91]
	v_cvt_pk_bf16_f32 v10, v10, v11
	v_cvt_pk_bf16_f32 v11, v16, v17
	v_lshl_add_u64 v[16:17], v[168:169], 1, v[0:1]
	s_waitcnt lgkmcnt(0)
	v_add_f32_e32 v0, v3, v18
	ds_bpermute_b32 v1, v190, v0
	v_cvt_pk_bf16_f32 v2, v4, v5
	v_cvt_pk_bf16_f32 v3, v6, v7
	v_cvt_pk_bf16_f32 v4, v14, v15
	v_cvt_pk_bf16_f32 v5, v12, v13
	global_store_dwordx4 v[16:17], v[8:11], off
	global_store_dwordx4 v[16:17], v[2:5], off offset:256
	s_and_saveexec_b64 s[30:31], s[2:3]
	s_cbranch_execz .LBB0_1167
	v_lshlrev_b64 v[2:3], 6, v[88:89]
	v_lshl_add_u64 v[2:3], s[14:15], 0, v[2:3]
	v_lshl_add_u64 v[2:3], s[28:29], 2, v[2:3]
	s_lshl_b32 s8, s49, 2
	v_lshl_add_u64 v[2:3], v[2:3], 0, s[8:9]
	s_waitcnt lgkmcnt(0)
	v_add_f32_e32 v0, v0, v1
	global_store_dword v[2:3], v0, off

.LBB0_1228:
	v_ashrrev_i32_e32 v6, 8, v0
	v_mul_lo_u32 v6, v6, s66
	v_add_u32_e32 v7, s33, v6
	v_ashrrev_i32_e32 v6, 31, v7
	v_lshrrev_b32_e32 v6, 29, v6
	v_add_u32_e32 v9, v7, v6
	v_ashrrev_i32_e32 v6, 3, v9
	v_and_b32_e32 v9, -8, v9
	v_sub_u32_e32 v7, v7, v9
	v_cmp_gt_i32_e32 vcc, 0, v7
	v_add_u32_e32 v0, 0x200, v0
	s_nop 0
	v_cndmask_b32_e32 v9, v3, v4, vcc
	v_mad_u64_u32 v[6:7], s[12:13], v7, v9, v[6:7]
	v_mul_hi_i32 v7, v6, s1
	v_lshrrev_b32_e32 v9, 31, v7
	v_ashrrev_i32_e32 v7, 5, v7
	v_add_u32_e32 v7, v7, v9
	v_lshlrev_b32_e32 v9, 3, v7
	v_mul_lo_u32 v7, v7, s10
	v_sub_u32_e32 v10, 0x80, v9
	v_sub_u32_e32 v6, v6, v7
	v_min_i32_e32 v7, 8, v10
	v_sub_u32_e32 v11, 0, v6
	v_ashrrev_i32_e32 v10, 31, v6
	v_max_i32_e32 v6, v6, v11
	v_sub_u32_e32 v11, 0, v7
	v_max_i32_e32 v7, v7, v11
	v_cvt_f32_u32_e32 v11, v7
	v_sub_u32_e32 v12, 0, v7
	v_rcp_iflag_f32_e32 v11, v11
	s_nop 0
	v_mul_f32_e32 v11, 0x4f7ffffe, v11
	v_cvt_u32_f32_e32 v11, v11
	v_mul_lo_u32 v12, v12, v11
	v_mul_hi_u32 v12, v11, v12
	v_add_u32_e32 v11, v11, v12
	v_mul_hi_u32 v11, v6, v11
	v_mul_lo_u32 v11, v11, v7
	v_sub_u32_e32 v6, v6, v11
	v_sub_u32_e32 v11, v6, v7
	v_cmp_ge_u32_e32 vcc, v6, v7
	s_nop 1
	v_cndmask_b32_e32 v6, v6, v11, vcc
	v_sub_u32_e32 v11, v6, v7
	v_cmp_ge_u32_e32 vcc, v6, v7
	s_nop 1
	v_cndmask_b32_e32 v6, v6, v11, vcc
	v_xor_b32_e32 v6, v6, v10
	v_sub_u32_e32 v6, v6, v10
	v_add_u32_e32 v6, v9, v6
	v_lshl_or_b32 v6, v6, 8, v1
	v_ashrrev_i32_e32 v7, 31, v6
	v_lshlrev_b64 v[6:7], 6, v[6:7]
	v_lshl_add_u64 v[6:7], s[6:7], 0, v[6:7]
	global_load_dwordx4 v[10:13], v[6:7], off
	global_load_dwordx4 v[14:17], v[6:7], off offset:32
	global_load_dwordx4 v[18:21], v[6:7], off offset:16
	global_load_dwordx4 v[22:25], v[6:7], off offset:48
	v_cmp_le_i32_e32 vcc, s0, v0
	s_or_b64 s[8:9], vcc, s[8:9]
	s_waitcnt vmcnt(0)
	v_mov_b32_e32 v6, v10
	v_mov_b32_e32 v7, v14
	v_mov_b32_e32 v14, v11
	v_mov_b32_e32 v10, v12
	v_mov_b32_e32 v11, v16
	v_mov_b32_e32 v16, v13
	v_mov_b32_e32 v12, v18
	v_mov_b32_e32 v13, v22
	v_mov_b32_e32 v22, v19
	v_mov_b32_e32 v18, v20
	v_mov_b32_e32 v19, v24
	v_mov_b32_e32 v24, v21
	v_add_f32_e32 v6, v6, v14
	v_add_f32_e32 v7, v7, v15
	v_add_f32_e32 v10, v10, v16
	v_add_f32_e32 v11, v11, v17
	v_add_f32_e32 v12, v12, v22
	v_add_f32_e32 v13, v13, v23
	v_add_f32_e32 v14, v18, v24
	v_add_f32_e32 v15, v19, v25
	v_add_f32_e32 v6, v6, v10
	v_add_f32_e32 v7, v7, v11
	v_add_f32_e32 v10, v12, v14
	v_add_f32_e32 v11, v13, v15
	s_nop 0
	v_add_f32_e32 v6, v6, v10
	v_add_f32_e32 v7, v7, v11
	s_nop 0
	v_add_f32_e32 v6, v6, v7
	v_fmamk_f32 v6, v6, 0x3a800000, v5
	v_rsq_f32_e32 v6, v6
	ds_write_b32 v2, v6
	v_add_u32_e32 v2, 0x800, v2
	s_andn2_b64 exec, exec, s[8:9]
	s_cbranch_execnz .LBB0_1228

; __device__ __forceinline__ unsigned cvt_pk_bf16(float lo, float hi) { f32x2 v = {lo, hi}; bf16x2_t b = __builtin_convertvector(v, bf16x2_t); return __builtin_bit_cast(unsigned, b); }
; __device__ __forceinline__ float silu_f(float x) { return x * fast_sigmoid(x); }
;     __device__ __forceinline__ void operator()(const f32x4 (&acc)[2][2][4][2], const Unit& u, int wr, int wc, int fr, int fq) const {
;     ...
;         for (int q8 = 0; q8 < 8; ++q8) rsv[q8] = rt ? rt[u.ord * BM + (q8 >> 2) * HALF + wr * 64 + (q8 & 3) * 16 + fr] : 1.0f;
; #pragma unroll
;         for (int ai = 0; ai < 2; ++ai)
; #pragma unroll
;             for (int m = 0; m < 4; ++m) { const int row = row0 + ai * HALF + m * 16; const float rs = rsv[ai * 4 + m];
;                 float o[8];
; #pragma unroll
;                 for (int n = 0; n < 2; ++n)
; #pragma unroll
;                     for (int i = 0; i < 4; ++i) { const float g = acc[ai][0][m][n][i] * rs, up = acc[ai][1][m][n][i] * rs; o[4 * n + i] = silu_f(g) * up; }
;                 u32x4 w; w.x = cvt_pk_bf16(o[0], o[1]); w.y = cvt_pk_bf16(o[2], o[3]); w.z = cvt_pk_bf16(o[4], o[5]); w.w = cvt_pk_bf16(o[6], o[7]);
;                 *(u32x4*)(H + (size_t)row * ldh + col0) = w; }
.LBB0_1241:
	v_lshl_add_u32 v144, s52, 10, v153
	ds_read2_b32 v[158:159], v144 offset1:16
	ds_read2_b32 v[148:149], v144 offset0:32 offset1:48
	ds_read2_b32 v[146:147], v144 offset0:128 offset1:144
	ds_read2_b32 v[144:145], v144 offset0:160 offset1:176
	v_lshl_or_b32 v160, s53, 7, v152
	s_waitcnt lgkmcnt(0)
	v_mul_f32_e32 v124, v124, v158
	v_mul_f32_e32 v125, v125, v158
	v_mul_f32_e32 v126, v126, v158
	v_mul_f32_e32 v127, v127, v158
	v_mul_f32_e32 v161, 0xbfb8aa3b, v124
	v_mul_f32_e32 v163, 0xbfb8aa3b, v125
	v_exp_f32_e32 v162, v161
	v_exp_f32_e32 v163, v163
	v_mul_f32_e32 v164, 0xbfb8aa3b, v126
	v_mul_f32_e32 v165, 0xbfb8aa3b, v127
	v_exp_f32_e32 v164, v164
	v_exp_f32_e32 v165, v165
	v_add_f32_e32 v162, 1.0, v162
	v_add_f32_e32 v163, 1.0, v163
	v_rcp_f32_e32 v162, v162
	v_rcp_f32_e32 v163, v163
	v_add_f32_e32 v164, 1.0, v164
	v_add_f32_e32 v165, 1.0, v165
	v_rcp_f32_e32 v164, v164
	v_rcp_f32_e32 v165, v165
	v_mul_f32_e32 v116, v116, v158
	v_mul_f32_e32 v117, v117, v158
	v_mul_f32_e32 v124, v124, v162
	v_mul_f32_e32 v125, v125, v163
	v_mul_f32_e32 v120, v120, v158
	v_mul_f32_e32 v121, v121, v158
	v_mul_f32_e32 v116, v116, v124
	v_mul_f32_e32 v117, v117, v125
	v_mul_f32_e32 v124, v126, v164
	v_mul_f32_e32 v125, v127, v165
	v_mul_f32_e32 v126, 0xbfb8aa3b, v120
	v_exp_f32_e32 v126, v126
	v_mul_f32_e32 v118, v118, v158
	v_mul_f32_e32 v119, v119, v158
	v_mul_f32_e32 v122, v122, v158
	v_mul_f32_e32 v123, v123, v158
	v_mul_f32_e32 v118, v118, v124
	v_mul_f32_e32 v119, v119, v125
	v_mul_f32_e32 v124, 0xbfb8aa3b, v121
	v_exp_f32_e32 v125, v124
	v_add_f32_e32 v124, 1.0, v126
	v_mul_f32_e32 v126, 0xbfb8aa3b, v122
	v_mul_f32_e32 v127, 0xbfb8aa3b, v123
	v_exp_f32_e32 v126, v126
	v_exp_f32_e32 v127, v127
	v_add_f32_e32 v125, 1.0, v125
	v_rcp_f32_e32 v124, v124
	v_rcp_f32_e32 v125, v125
	v_add_f32_e32 v126, 1.0, v126
	v_add_f32_e32 v127, 1.0, v127
	v_rcp_f32_e32 v126, v126
	v_rcp_f32_e32 v127, v127
	v_mul_f32_e32 v112, v112, v158
	v_mul_f32_e32 v113, v113, v158
	v_mul_f32_e32 v120, v120, v124
	v_mul_f32_e32 v121, v121, v125
	v_mul_f32_e32 v114, v114, v158
	v_mul_f32_e32 v115, v115, v158
	v_mul_f32_e32 v112, v112, v120
	v_mul_f32_e32 v113, v113, v121
	v_mul_f32_e32 v120, v122, v126
	v_mul_f32_e32 v121, v123, v127
	v_mov_b32_e32 v122, v159
	v_mul_f32_e32 v108, v108, v122
	v_mul_f32_e32 v109, v109, v122
	v_lshl_add_u32 v157, s22, 8, v150
	v_mul_f32_e32 v123, 0xbfb8aa3b, v108
	v_exp_f32_e32 v123, v123
	v_ashrrev_i32_e32 v161, 31, v160
	v_mul_f32_e32 v114, v114, v120
	v_mul_f32_e32 v115, v115, v121
	v_cvt_pk_bf16_f32 v116, v116, v117
	v_cvt_pk_bf16_f32 v117, v118, v119
	v_cvt_pk_bf16_f32 v118, v112, v113
	v_mov_b64_e32 v[112:113], s[8:9]
	v_cvt_pk_bf16_f32 v119, v114, v115
	v_mad_i64_i32 v[120:121], s[24:25], v157, s49, v[112:113]
	v_lshlrev_b64 v[114:115], 1, v[160:161]
	v_lshl_add_u64 v[120:121], v[120:121], 0, v[114:115]
	global_store_dwordx4 v[120:121], v[116:119], off
	v_mul_f32_e32 v110, v110, v122
	v_mul_f32_e32 v111, v111, v122
	v_mul_f32_e32 v100, v100, v122
	v_mul_f32_e32 v101, v101, v122
	v_mul_f32_e32 v116, 0xbfb8aa3b, v109
	v_exp_f32_e32 v117, v116
	v_mul_f32_e32 v118, 0xbfb8aa3b, v110
	v_mul_f32_e32 v119, 0xbfb8aa3b, v111
	v_exp_f32_e32 v118, v118
	v_exp_f32_e32 v119, v119
	v_add_f32_e32 v116, 1.0, v123
	v_add_f32_e32 v117, 1.0, v117
	v_rcp_f32_e32 v116, v116
	v_rcp_f32_e32 v117, v117
	v_add_f32_e32 v118, 1.0, v118
	v_add_f32_e32 v119, 1.0, v119
	v_rcp_f32_e32 v118, v118
	v_rcp_f32_e32 v119, v119
	v_mul_f32_e32 v108, v108, v116
	v_mul_f32_e32 v109, v109, v117
	v_mul_f32_e32 v104, v104, v122
	v_mul_f32_e32 v105, v105, v122
	v_mul_f32_e32 v100, v100, v108
	v_mul_f32_e32 v101, v101, v109
	v_mul_f32_e32 v108, v110, v118
	v_mul_f32_e32 v109, v111, v119
	v_mul_f32_e32 v110, 0xbfb8aa3b, v104
	v_exp_f32_e32 v110, v110
	v_mul_f32_e32 v102, v102, v122
	v_mul_f32_e32 v103, v103, v122
	v_mul_f32_e32 v106, v106, v122
	v_mul_f32_e32 v107, v107, v122
	v_mul_f32_e32 v102, v102, v108
	v_mul_f32_e32 v103, v103, v109
	v_mul_f32_e32 v108, 0xbfb8aa3b, v105
	v_exp_f32_e32 v109, v108
	v_add_f32_e32 v108, 1.0, v110
	v_mul_f32_e32 v110, 0xbfb8aa3b, v106
	v_mul_f32_e32 v111, 0xbfb8aa3b, v107
	v_exp_f32_e32 v110, v110
	v_exp_f32_e32 v111, v111
	v_add_f32_e32 v109, 1.0, v109
	v_rcp_f32_e32 v108, v108
	v_rcp_f32_e32 v109, v109
	v_add_f32_e32 v110, 1.0, v110
	v_add_f32_e32 v111, 1.0, v111
	v_rcp_f32_e32 v110, v110
	v_rcp_f32_e32 v111, v111
	v_mul_f32_e32 v96, v96, v122
	v_mul_f32_e32 v97, v97, v122
	v_mul_f32_e32 v104, v104, v108
	v_mul_f32_e32 v105, v105, v109
	v_or_b32_e32 v108, 16, v157
	v_mul_f32_e32 v104, v96, v104
	v_mul_f32_e32 v105, v97, v105
	v_mul_f32_e32 v96, v98, v122
	v_mul_f32_e32 v97, v99, v122
	v_mul_f32_e32 v98, v106, v110
	v_mul_f32_e32 v99, v107, v111
	v_mul_f32_e32 v92, v92, v148
	v_mul_f32_e32 v93, v93, v148
	v_mul_f32_e32 v106, v96, v98
	v_mul_f32_e32 v107, v97, v99
	v_cvt_pk_bf16_f32 v96, v100, v101
	v_mad_i64_i32 v[100:101], s[24:25], v108, s49, v[112:113]
	v_cvt_pk_bf16_f32 v97, v102, v103
	v_cvt_pk_bf16_f32 v98, v104, v105
	v_cvt_pk_bf16_f32 v99, v106, v107
	v_lshl_add_u64 v[100:101], v[100:101], 0, v[114:115]
	v_mul_f32_e32 v102, 0xbfb8aa3b, v92
	global_store_dwordx4 v[100:101], v[96:99], off
	v_mul_f32_e32 v94, v94, v148
	v_mul_f32_e32 v95, v95, v148
	v_exp_f32_e32 v102, v102
	v_mul_f32_e32 v96, 0xbfb8aa3b, v93
	v_exp_f32_e32 v97, v96
	v_mul_f32_e32 v98, 0xbfb8aa3b, v94
	v_mul_f32_e32 v99, 0xbfb8aa3b, v95
	v_exp_f32_e32 v98, v98
	v_exp_f32_e32 v99, v99
	v_add_f32_e32 v96, 1.0, v102
	v_add_f32_e32 v97, 1.0, v97
	v_rcp_f32_e32 v96, v96
	v_rcp_f32_e32 v97, v97
	v_add_f32_e32 v98, 1.0, v98
	v_add_f32_e32 v99, 1.0, v99
	v_rcp_f32_e32 v98, v98
; __device__ __forceinline__ unsigned cvt_pk_bf16(float lo, float hi) { f32x2 v = {lo, hi}; bf16x2_t b = __builtin_convertvector(v, bf16x2_t); return __builtin_bit_cast(unsigned, b); }
; __device__ __forceinline__ float silu_f(float x) { return x * fast_sigmoid(x); }
;     __device__ __forceinline__ void operator()(const f32x4 (&acc)[2][2][4][2], const Unit& u, int wr, int wc, int fr, int fq) const {
;     ...
;             for (int m = 0; m < 4; ++m) { const int row = row0 + ai * HALF + m * 16; const float rs = rsv[ai * 4 + m];
;                 float o[8];
; #pragma unroll
;                 for (int n = 0; n < 2; ++n)
; #pragma unroll
;                     for (int i = 0; i < 4; ++i) { const float g = acc[ai][0][m][n][i] * rs, up = acc[ai][1][m][n][i] * rs; o[4 * n + i] = silu_f(g) * up; }
;                 u32x4 w; w.x = cvt_pk_bf16(o[0], o[1]); w.y = cvt_pk_bf16(o[2], o[3]); w.z = cvt_pk_bf16(o[4], o[5]); w.w = cvt_pk_bf16(o[6], o[7]);
;                 *(u32x4*)(H + (size_t)row * ldh + col0) = w; }
	v_rcp_f32_e32 v99, v99
	v_mul_f32_e32 v84, v84, v148
	v_mul_f32_e32 v85, v85, v148
	v_mul_f32_e32 v92, v92, v96
	v_mul_f32_e32 v93, v93, v97
	v_mul_f32_e32 v88, v88, v148
	v_mul_f32_e32 v89, v89, v148
	v_mul_f32_e32 v84, v84, v92
	v_mul_f32_e32 v85, v85, v93
	v_mul_f32_e32 v92, v94, v98
	v_mul_f32_e32 v93, v95, v99
	v_mul_f32_e32 v94, 0xbfb8aa3b, v88
	v_exp_f32_e32 v94, v94
	v_mul_f32_e32 v86, v86, v148
	v_mul_f32_e32 v87, v87, v148
	v_mul_f32_e32 v90, v90, v148
	v_mul_f32_e32 v91, v91, v148
	v_mul_f32_e32 v86, v86, v92
	v_mul_f32_e32 v87, v87, v93
	v_mul_f32_e32 v92, 0xbfb8aa3b, v89
	v_exp_f32_e32 v93, v92
	v_add_f32_e32 v92, 1.0, v94
	v_mul_f32_e32 v94, 0xbfb8aa3b, v90
	v_mul_f32_e32 v95, 0xbfb8aa3b, v91
	v_exp_f32_e32 v94, v94
	v_exp_f32_e32 v95, v95
	v_add_f32_e32 v93, 1.0, v93
	v_rcp_f32_e32 v92, v92
	v_rcp_f32_e32 v93, v93
	v_add_f32_e32 v94, 1.0, v94
	v_add_f32_e32 v95, 1.0, v95
	v_rcp_f32_e32 v94, v94
	v_rcp_f32_e32 v95, v95
	v_mul_f32_e32 v80, v80, v148
	v_mul_f32_e32 v81, v81, v148
	v_mul_f32_e32 v88, v88, v92
	v_mul_f32_e32 v89, v89, v93
	v_or_b32_e32 v92, 32, v157
	v_mul_f32_e32 v88, v80, v88
	v_mul_f32_e32 v89, v81, v89
	v_mul_f32_e32 v80, v82, v148
	v_mul_f32_e32 v81, v83, v148
	v_mul_f32_e32 v82, v90, v94
	v_mul_f32_e32 v83, v91, v95
	v_mul_f32_e32 v60, v60, v146
	v_mul_f32_e32 v61, v61, v146
	v_mul_f32_e32 v90, v80, v82
	v_mul_f32_e32 v91, v81, v83
	v_cvt_pk_bf16_f32 v81, v86, v87
	v_mov_b32_e32 v86, v149
	v_mul_f32_e32 v76, v76, v86
	v_mul_f32_e32 v77, v77, v86
	v_cvt_pk_bf16_f32 v80, v84, v85
	v_mul_f32_e32 v87, 0xbfb8aa3b, v76
	v_exp_f32_e32 v87, v87
	v_mad_i64_i32 v[84:85], s[24:25], v92, s49, v[112:113]
	v_cvt_pk_bf16_f32 v82, v88, v89
	v_cvt_pk_bf16_f32 v83, v90, v91
	v_lshl_add_u64 v[84:85], v[84:85], 0, v[114:115]
	global_store_dwordx4 v[84:85], v[80:83], off
	v_mul_f32_e32 v78, v78, v86
	v_mul_f32_e32 v79, v79, v86
	v_mul_f32_e32 v68, v68, v86
	v_mul_f32_e32 v69, v69, v86
	v_mul_f32_e32 v80, 0xbfb8aa3b, v77
	v_exp_f32_e32 v81, v80
	v_mul_f32_e32 v82, 0xbfb8aa3b, v78
	v_mul_f32_e32 v83, 0xbfb8aa3b, v79
	v_exp_f32_e32 v82, v82
	v_exp_f32_e32 v83, v83
	v_add_f32_e32 v80, 1.0, v87
	v_add_f32_e32 v81, 1.0, v81
	v_rcp_f32_e32 v80, v80
	v_rcp_f32_e32 v81, v81
	v_add_f32_e32 v82, 1.0, v82
	v_add_f32_e32 v83, 1.0, v83
	v_rcp_f32_e32 v82, v82
	v_rcp_f32_e32 v83, v83
	v_mul_f32_e32 v76, v76, v80
	v_mul_f32_e32 v77, v77, v81
	v_mul_f32_e32 v72, v72, v86
	v_mul_f32_e32 v73, v73, v86
	v_mul_f32_e32 v68, v68, v76
	v_mul_f32_e32 v69, v69, v77
	v_mul_f32_e32 v76, v78, v82
	v_mul_f32_e32 v77, v79, v83
	v_mul_f32_e32 v78, 0xbfb8aa3b, v72
	v_exp_f32_e32 v78, v78
	v_mul_f32_e32 v70, v70, v86
	v_mul_f32_e32 v71, v71, v86
	v_mul_f32_e32 v74, v74, v86
	v_mul_f32_e32 v75, v75, v86
	v_mul_f32_e32 v70, v70, v76
	v_mul_f32_e32 v71, v71, v77
	v_mul_f32_e32 v76, 0xbfb8aa3b, v73
	v_exp_f32_e32 v77, v76
	v_add_f32_e32 v76, 1.0, v78
	v_mul_f32_e32 v78, 0xbfb8aa3b, v74
	v_mul_f32_e32 v79, 0xbfb8aa3b, v75
	v_exp_f32_e32 v78, v78
	v_exp_f32_e32 v79, v79
	v_add_f32_e32 v77, 1.0, v77
	v_rcp_f32_e32 v76, v76
	v_rcp_f32_e32 v77, v77
	v_add_f32_e32 v78, 1.0, v78
	v_add_f32_e32 v79, 1.0, v79
	v_rcp_f32_e32 v78, v78
	v_rcp_f32_e32 v79, v79
	v_mul_f32_e32 v64, v64, v86
	v_mul_f32_e32 v65, v65, v86
	v_mul_f32_e32 v72, v72, v76
	v_mul_f32_e32 v73, v73, v77
	v_or_b32_e32 v76, 48, v157
	v_mul_f32_e32 v72, v64, v72
	v_mul_f32_e32 v73, v65, v73
	v_mul_f32_e32 v64, v66, v86
	v_mul_f32_e32 v65, v67, v86
	v_mul_f32_e32 v66, v74, v78
	v_mul_f32_e32 v67, v75, v79
	v_mul_f32_e32 v62, v62, v146
	v_mul_f32_e32 v63, v63, v146
	v_mul_f32_e32 v74, v64, v66
	v_mul_f32_e32 v75, v65, v67
	v_cvt_pk_bf16_f32 v64, v68, v69
	v_mad_i64_i32 v[68:69], s[24:25], v76, s49, v[112:113]
	v_cvt_pk_bf16_f32 v65, v70, v71
	v_cvt_pk_bf16_f32 v66, v72, v73
	v_cvt_pk_bf16_f32 v67, v74, v75
	v_lshl_add_u64 v[68:69], v[68:69], 0, v[114:115]
	global_store_dwordx4 v[68:69], v[64:67], off
	v_mul_f32_e32 v52, v52, v146
	v_mul_f32_e32 v53, v53, v146
	v_mul_f32_e32 v56, v56, v146
	v_mul_f32_e32 v57, v57, v146
	v_mul_f32_e32 v64, 0xbfb8aa3b, v60
	v_mul_f32_e32 v65, 0xbfb8aa3b, v61
	v_exp_f32_e32 v64, v64
	v_exp_f32_e32 v65, v65
	v_mul_f32_e32 v66, 0xbfb8aa3b, v62
	v_mul_f32_e32 v67, 0xbfb8aa3b, v63
	v_exp_f32_e32 v66, v66
	v_exp_f32_e32 v67, v67
	v_add_f32_e32 v64, 1.0, v64
	v_add_f32_e32 v65, 1.0, v65
	v_rcp_f32_e32 v64, v64
	v_rcp_f32_e32 v65, v65
	v_add_f32_e32 v66, 1.0, v66
	v_add_f32_e32 v67, 1.0, v67
	v_rcp_f32_e32 v66, v66
	v_rcp_f32_e32 v67, v67
	v_mul_f32_e32 v60, v60, v64
	v_mul_f32_e32 v61, v61, v65
	v_mul_f32_e32 v54, v54, v146
	v_mul_f32_e32 v55, v55, v146
	v_mul_f32_e32 v52, v52, v60
	v_mul_f32_e32 v53, v53, v61
	v_mul_f32_e32 v60, v62, v66
	v_mul_f32_e32 v61, v63, v67
	v_mul_f32_e32 v62, 0xbfb8aa3b, v56
	v_exp_f32_e32 v62, v62
	v_mul_f32_e32 v54, v54, v60
	v_mul_f32_e32 v55, v55, v61
	v_mul_f32_e32 v60, 0xbfb8aa3b, v57
	v_mul_f32_e32 v58, v58, v146
	v_mul_f32_e32 v59, v59, v146
	v_exp_f32_e32 v61, v60
	v_add_f32_e32 v60, 1.0, v62
	v_mul_f32_e32 v62, 0xbfb8aa3b, v58
	v_mul_f32_e32 v63, 0xbfb8aa3b, v59
	v_exp_f32_e32 v62, v62
	v_exp_f32_e32 v63, v63
	v_add_f32_e32 v61, 1.0, v61
	v_rcp_f32_e32 v60, v60
	v_rcp_f32_e32 v61, v61
	v_add_f32_e32 v62, 1.0, v62
	v_add_f32_e32 v63, 1.0, v63
	v_rcp_f32_e32 v62, v62
	v_rcp_f32_e32 v63, v63
	v_mul_f32_e32 v48, v48, v146
	v_mul_f32_e32 v49, v49, v146
	v_mul_f32_e32 v56, v56, v60
	v_mul_f32_e32 v57, v57, v61
	v_add_u32_e32 v68, 0x80, v157
	v_mul_f32_e32 v56, v48, v56
	v_mul_f32_e32 v57, v49, v57
	v_mul_f32_e32 v48, v50, v146
	v_mul_f32_e32 v49, v51, v146
	v_mul_f32_e32 v50, v58, v62
	v_mul_f32_e32 v51, v59, v63
	v_mul_f32_e32 v28, v28, v144
; __device__ __forceinline__ unsigned cvt_pk_bf16(float lo, float hi) { f32x2 v = {lo, hi}; bf16x2_t b = __builtin_convertvector(v, bf16x2_t); return __builtin_bit_cast(unsigned, b); }
; __device__ __forceinline__ float silu_f(float x) { return x * fast_sigmoid(x); }
;     __device__ __forceinline__ void operator()(const f32x4 (&acc)[2][2][4][2], const Unit& u, int wr, int wc, int fr, int fq) const {
;     ...
;             for (int m = 0; m < 4; ++m) { const int row = row0 + ai * HALF + m * 16; const float rs = rsv[ai * 4 + m];
;                 float o[8];
; #pragma unroll
;                 for (int n = 0; n < 2; ++n)
; #pragma unroll
;                     for (int i = 0; i < 4; ++i) { const float g = acc[ai][0][m][n][i] * rs, up = acc[ai][1][m][n][i] * rs; o[4 * n + i] = silu_f(g) * up; }
;                 u32x4 w; w.x = cvt_pk_bf16(o[0], o[1]); w.y = cvt_pk_bf16(o[2], o[3]); w.z = cvt_pk_bf16(o[4], o[5]); w.w = cvt_pk_bf16(o[6], o[7]);
;                 *(u32x4*)(H + (size_t)row * ldh + col0) = w; }
	v_mul_f32_e32 v29, v29, v144
	v_mul_f32_e32 v58, v48, v50
	v_mul_f32_e32 v59, v49, v51
	v_cvt_pk_bf16_f32 v49, v54, v55
	v_mov_b32_e32 v54, v147
	v_mul_f32_e32 v44, v44, v54
	v_mul_f32_e32 v45, v45, v54
	v_cvt_pk_bf16_f32 v48, v52, v53
	v_mul_f32_e32 v55, 0xbfb8aa3b, v44
	v_exp_f32_e32 v55, v55
	v_mad_i64_i32 v[52:53], s[24:25], v68, s49, v[112:113]
	v_cvt_pk_bf16_f32 v50, v56, v57
	v_cvt_pk_bf16_f32 v51, v58, v59
	v_lshl_add_u64 v[52:53], v[52:53], 0, v[114:115]
	global_store_dwordx4 v[52:53], v[48:51], off
	v_mul_f32_e32 v46, v46, v54
	v_mul_f32_e32 v47, v47, v54
	v_mul_f32_e32 v36, v36, v54
	v_mul_f32_e32 v37, v37, v54
	v_mul_f32_e32 v48, 0xbfb8aa3b, v45
	v_exp_f32_e32 v49, v48
	v_mul_f32_e32 v50, 0xbfb8aa3b, v46
	v_mul_f32_e32 v51, 0xbfb8aa3b, v47
	v_exp_f32_e32 v50, v50
	v_exp_f32_e32 v51, v51
	v_add_f32_e32 v48, 1.0, v55
	v_add_f32_e32 v49, 1.0, v49
	v_rcp_f32_e32 v48, v48
	v_rcp_f32_e32 v49, v49
	v_add_f32_e32 v50, 1.0, v50
	v_add_f32_e32 v51, 1.0, v51
	v_rcp_f32_e32 v50, v50
	v_rcp_f32_e32 v51, v51
	v_mul_f32_e32 v44, v44, v48
	v_mul_f32_e32 v45, v45, v49
	v_mul_f32_e32 v40, v40, v54
	v_mul_f32_e32 v41, v41, v54
	v_mul_f32_e32 v36, v36, v44
	v_mul_f32_e32 v37, v37, v45
	v_mul_f32_e32 v44, v46, v50
	v_mul_f32_e32 v45, v47, v51
	v_mul_f32_e32 v46, 0xbfb8aa3b, v40
	v_exp_f32_e32 v46, v46
	v_mul_f32_e32 v38, v38, v54
	v_mul_f32_e32 v39, v39, v54
	v_mul_f32_e32 v42, v42, v54
	v_mul_f32_e32 v43, v43, v54
	v_mul_f32_e32 v38, v38, v44
	v_mul_f32_e32 v39, v39, v45
	v_mul_f32_e32 v44, 0xbfb8aa3b, v41
	v_exp_f32_e32 v45, v44
	v_add_f32_e32 v44, 1.0, v46
	v_mul_f32_e32 v46, 0xbfb8aa3b, v42
	v_mul_f32_e32 v47, 0xbfb8aa3b, v43
	v_exp_f32_e32 v46, v46
	v_exp_f32_e32 v47, v47
	v_add_f32_e32 v45, 1.0, v45
	v_rcp_f32_e32 v44, v44
	v_rcp_f32_e32 v45, v45
	v_add_f32_e32 v46, 1.0, v46
	v_add_f32_e32 v47, 1.0, v47
	v_rcp_f32_e32 v46, v46
	v_rcp_f32_e32 v47, v47
	v_mul_f32_e32 v32, v32, v54
	v_mul_f32_e32 v33, v33, v54
	v_mul_f32_e32 v40, v40, v44
	v_mul_f32_e32 v41, v41, v45
	v_add_u32_e32 v44, 0x90, v157
	v_mul_f32_e32 v40, v32, v40
	v_mul_f32_e32 v41, v33, v41
	v_mul_f32_e32 v32, v34, v54
	v_mul_f32_e32 v33, v35, v54
	v_mul_f32_e32 v34, v42, v46
	v_mul_f32_e32 v35, v43, v47
	v_mul_f32_e32 v30, v30, v144
	v_mul_f32_e32 v31, v31, v144
	v_mul_f32_e32 v42, v32, v34
	v_mul_f32_e32 v43, v33, v35
	v_cvt_pk_bf16_f32 v32, v36, v37
	v_mad_i64_i32 v[36:37], s[24:25], v44, s49, v[112:113]
	v_cvt_pk_bf16_f32 v33, v38, v39
	v_cvt_pk_bf16_f32 v34, v40, v41
	v_cvt_pk_bf16_f32 v35, v42, v43
	v_lshl_add_u64 v[36:37], v[36:37], 0, v[114:115]
	v_mul_f32_e32 v38, 0xbfb8aa3b, v28
	global_store_dwordx4 v[36:37], v[32:35], off
	v_exp_f32_e32 v38, v38
	v_mul_f32_e32 v20, v20, v144
	v_mul_f32_e32 v21, v21, v144
	v_mul_f32_e32 v32, 0xbfb8aa3b, v29
	v_exp_f32_e32 v33, v32
	v_mul_f32_e32 v34, 0xbfb8aa3b, v30
	v_mul_f32_e32 v35, 0xbfb8aa3b, v31
	v_exp_f32_e32 v34, v34
	v_exp_f32_e32 v35, v35
	v_add_f32_e32 v32, 1.0, v38
	v_add_f32_e32 v33, 1.0, v33
	v_rcp_f32_e32 v32, v32
	v_rcp_f32_e32 v33, v33
	v_add_f32_e32 v34, 1.0, v34
	v_add_f32_e32 v35, 1.0, v35
	v_rcp_f32_e32 v34, v34
	v_rcp_f32_e32 v35, v35
	v_mul_f32_e32 v28, v28, v32
	v_mul_f32_e32 v29, v29, v33
	v_mul_f32_e32 v24, v24, v144
	v_mul_f32_e32 v25, v25, v144
	v_mul_f32_e32 v20, v20, v28
	v_mul_f32_e32 v21, v21, v29
	v_mul_f32_e32 v28, v30, v34
	v_mul_f32_e32 v29, v31, v35
	v_mul_f32_e32 v30, 0xbfb8aa3b, v24
	v_exp_f32_e32 v30, v30
	v_mul_f32_e32 v22, v22, v144
	v_mul_f32_e32 v23, v23, v144
	v_mul_f32_e32 v26, v26, v144
	v_mul_f32_e32 v27, v27, v144
	v_mul_f32_e32 v22, v22, v28
	v_mul_f32_e32 v23, v23, v29
	v_mul_f32_e32 v28, 0xbfb8aa3b, v25
	v_exp_f32_e32 v29, v28
	v_add_f32_e32 v28, 1.0, v30
	v_mul_f32_e32 v30, 0xbfb8aa3b, v26
	v_mul_f32_e32 v31, 0xbfb8aa3b, v27
	v_exp_f32_e32 v30, v30
	v_exp_f32_e32 v31, v31
	v_add_f32_e32 v29, 1.0, v29
	v_rcp_f32_e32 v28, v28
	v_rcp_f32_e32 v29, v29
	v_add_f32_e32 v30, 1.0, v30
	v_add_f32_e32 v31, 1.0, v31
	v_rcp_f32_e32 v30, v30
	v_rcp_f32_e32 v31, v31
	v_mul_f32_e32 v16, v16, v144
	v_mul_f32_e32 v17, v17, v144
	v_mul_f32_e32 v24, v24, v28
	v_mul_f32_e32 v25, v25, v29
	v_add_u32_e32 v28, 0xa0, v157
	v_mul_f32_e32 v24, v16, v24
	v_mul_f32_e32 v25, v17, v25
	v_mul_f32_e32 v16, v18, v144
	v_mul_f32_e32 v17, v19, v144
	v_mul_f32_e32 v18, v26, v30
	v_mul_f32_e32 v19, v27, v31
	s_andn2_b64 vcc, exec, s[2:3]
	v_mul_f32_e32 v26, v16, v18
	v_mul_f32_e32 v27, v17, v19
	v_cvt_pk_bf16_f32 v17, v22, v23
	v_mov_b32_e32 v22, v145
	v_mul_f32_e32 v12, v12, v22
	v_mul_f32_e32 v13, v13, v22
	v_cvt_pk_bf16_f32 v16, v20, v21
	v_mul_f32_e32 v23, 0xbfb8aa3b, v12
	v_exp_f32_e32 v23, v23
	v_mad_i64_i32 v[20:21], s[24:25], v28, s49, v[112:113]
	v_cvt_pk_bf16_f32 v18, v24, v25
	v_cvt_pk_bf16_f32 v19, v26, v27
	v_lshl_add_u64 v[20:21], v[20:21], 0, v[114:115]
	global_store_dwordx4 v[20:21], v[16:19], off
	v_mul_f32_e32 v14, v14, v22
	v_mul_f32_e32 v15, v15, v22
	v_mul_f32_e32 v4, v4, v22
	v_mul_f32_e32 v5, v5, v22
	v_mul_f32_e32 v16, 0xbfb8aa3b, v13
	v_exp_f32_e32 v17, v16
	v_mul_f32_e32 v18, 0xbfb8aa3b, v14
	v_mul_f32_e32 v19, 0xbfb8aa3b, v15
	v_exp_f32_e32 v18, v18
	v_exp_f32_e32 v19, v19
	v_add_f32_e32 v16, 1.0, v23
	v_add_f32_e32 v17, 1.0, v17
	v_rcp_f32_e32 v16, v16
	v_rcp_f32_e32 v17, v17
	v_add_f32_e32 v18, 1.0, v18
	v_add_f32_e32 v19, 1.0, v19
	v_rcp_f32_e32 v18, v18
	v_rcp_f32_e32 v19, v19
	v_mul_f32_e32 v12, v12, v16
	v_mul_f32_e32 v13, v13, v17
	v_mul_f32_e32 v8, v8, v22
	v_mul_f32_e32 v9, v9, v22
	v_mul_f32_e32 v4, v4, v12
	v_mul_f32_e32 v5, v5, v13
	v_mul_f32_e32 v12, v14, v18
	v_mul_f32_e32 v13, v15, v19
	v_mul_f32_e32 v14, 0xbfb8aa3b, v8
	v_exp_f32_e32 v14, v14
	v_mul_f32_e32 v6, v6, v22
	v_mul_f32_e32 v7, v7, v22
	v_mul_f32_e32 v10, v10, v22
	v_mul_f32_e32 v11, v11, v22
	v_mul_f32_e32 v6, v6, v12
	v_mul_f32_e32 v7, v7, v13
	v_mul_f32_e32 v12, 0xbfb8aa3b, v9
	v_exp_f32_e32 v13, v12
	v_add_f32_e32 v12, 1.0, v14
	v_mul_f32_e32 v14, 0xbfb8aa3b, v10
	v_mul_f32_e32 v15, 0xbfb8aa3b, v11
	v_exp_f32_e32 v14, v14
	v_exp_f32_e32 v15, v15
	v_add_f32_e32 v13, 1.0, v13
	v_rcp_f32_e32 v12, v12
	v_rcp_f32_e32 v13, v13
	v_add_f32_e32 v14, 1.0, v14
	v_add_f32_e32 v15, 1.0, v15
	v_rcp_f32_e32 v14, v14
	v_rcp_f32_e32 v15, v15
	v_mul_f32_e32 v0, v0, v22
	v_mul_f32_e32 v1, v1, v22
	v_mul_f32_e32 v8, v8, v12
	v_mul_f32_e32 v9, v9, v13
	v_add_u32_e32 v12, 0xb0, v157
	v_mul_f32_e32 v8, v0, v8
	v_mul_f32_e32 v9, v1, v9
	v_mul_f32_e32 v0, v2, v22
	v_mul_f32_e32 v1, v3, v22
	v_mul_f32_e32 v2, v10, v14
	v_mul_f32_e32 v3, v11, v15
	s_mov_b64 s[2:3], -1
	v_mul_f32_e32 v10, v0, v2
	v_mul_f32_e32 v11, v1, v3
	v_cvt_pk_bf16_f32 v0, v4, v5
	v_mad_i64_i32 v[4:5], s[24:25], v12, s49, v[112:113]
	v_cvt_pk_bf16_f32 v1, v6, v7
	v_cvt_pk_bf16_f32 v2, v8, v9
	v_cvt_pk_bf16_f32 v3, v10, v11
	v_lshl_add_u64 v[4:5], v[4:5], 0, v[114:115]
	global_store_dwordx4 v[4:5], v[0:3], off
	s_cbranch_vccnz .LBB0_1234
	s_andn2_b64 vcc, exec, s[6:7]
	s_cbranch_vccnz .LBB0_1233
	s_barrier
	s_branch .LBB0_1233
